# GEMM mainloops: staging interleaved into MFMA cluster + 2-deep register prefetch (x2 unroll); sigmoid 1/x via v_rcp_f32 instead of IEEE div expansion (f32, P8 epilogue et al)
# speedup vs baseline: 1.0147x; 1.0091x over previous
; DI int tidx() { int t = __builtin_amdgcn_workitem_id_x(); asm volatile("" : "+v"(t)); return t; }
;   DI unsigned rowoff(int r, int sch) const { const int g = r & 3, bc = r >> 2, b = bc / NCMP, c = bc - b * NCMP; return (unsigned)(b * Sn + c * 16) * 512u + g * 64 + sch; }
; template <int NI, class XL, class EP>
; DI void gemm_tile(const u16* __restrict__ W, int ldw, int f0, int t0, int K, XL xl, EP ep, unsigned char* smem) {
;     ...
;   const int tid = tidx(), lane = tid & 63, wave = tid >> 6;
;   const int wf = wave >> 1, wt = wave & 1, lr = lane & 15, lq = lane >> 4;
;   const int srow = tid >> 2, sch = (tid & 3) * 8;
;   f32x4 acc[4][NI];
; #pragma unroll
;   for (int i = 0; i < 4; ++i)
; #pragma unroll
;     for (int j = 0; j < NI; ++j) acc[i][j] = (f32x4){0.f, 0.f, 0.f, 0.f};
;   u32x4 wr[2], xr[XR];
;   const unsigned wbyte = ((unsigned)(f0 + srow * 2) * 32u + sch) * 2u;
;   const unsigned xbyte = xl.rowoff(t0 + srow * XR, sch) * 2u;
;   const int xrs = xl.rstride();
;   const int nk = K >> 5;
;   auto gload = [&](int it) {
;     const int k = it * 32;
;     const char* wb = (const char*)(W + (size_t)(k >> 5) * ldw * 32);
;     const char* xb = (const char*)xl.kbase(k);
; #pragma unroll
;     for (int i = 0; i < 2; ++i) wr[i] = *(const u32x4*)(wb + wbyte + i * 64);
; #pragma unroll
;     for (int i = 0; i < XR; ++i) xr[i] = *(const u32x4*)(xb + xbyte + i * xrs);
;   };
;   auto lstore = [&](int buf) {
;     u16* Ws = S0 + buf * BUF; u16* Xs = Ws + 128 * LST;
; #pragma unroll
;     for (int i = 0; i < 2; ++i) *(u32x4*)(Ws + (srow * 2 + i) * LST + sch) = wr[i];
; #pragma unroll
;     for (int i = 0; i < XR; ++i) *(u32x4*)(Xs + (srow * XR + i) * LST + sch) = xr[i];
;   };
;   gload(0);
;   __syncthreads();
;   lstore(0);
;   __syncthreads();
;   if (nk > 1) gload(1);
.LBB0_268:
	v_mov_b32_e32 v161, v218
	s_and_b32 s22, s59, 7
	s_or_b32 s61, s22, s53
	v_ashrrev_i32_e32 v44, 2, v161
	s_lshl_b32 s22, s59, 5
	v_lshlrev_b32_e32 v0, 3, v161
	v_lshlrev_b32_e32 v46, 6, v44
	s_and_b32 s60, s22, 0xffffff00
	v_and_b32_e32 v45, 24, v0
	v_lshl_add_u32 v0, s61, 12, v46
	s_add_i32 s60, s60, s54
	v_or_b32_e32 v0, v0, v45
	v_and_b32_e32 v48, 0x3fffffc, v161
	v_lshlrev_b32_e32 v47, 1, v0
	v_add_u32_e32 v0, s60, v48
	v_lshlrev_b32_e32 v162, 1, v45
	v_readlane_b32 s22, v245, 25
	v_lshl_or_b32 v49, v0, 6, v162
	v_readlane_b32 s23, v245, 26
	global_load_dwordx4 v[16:19], v47, s[42:43]
	global_load_dwordx4 v[20:23], v47, s[42:43] offset:64
	s_nop 2
	global_load_dwordx4 v[24:27], v49, s[22:23]
	global_load_dwordx4 v[28:31], v49, s[22:23] offset:64
	global_load_dwordx4 v[32:35], v49, s[22:23] offset:128
	global_load_dwordx4 v[36:39], v49, s[22:23] offset:192
	v_mul_lo_u32 v167, v44, s37
	v_or_b32_e32 v163, v167, v162
	v_add_u32_e32 v164, v163, v167
	s_barrier
	s_and_b32 s23, s58, 0x3ffff00
	s_and_b32 s24, s57, 7
	s_add_i32 s24, s56, s24
	s_add_i32 s23, s54, s23
	v_ashrrev_i32_e32 v51, 1, v161
	v_and_b32_e32 v50, 15, v161
	v_lshrrev_b32_e32 v52, 1, v161
	v_lshlrev_b32_e32 v53, 1, v161
	v_and_b32_e32 v159, 0xffffffc0, v51
	v_add_u32_e32 v44, s23, v48
	v_lshl_add_u32 v46, s24, 12, v46
	v_mov_b32_e32 v0, 0
	v_and_b32_e32 v158, 24, v52
	v_and_or_b32 v160, v53, s44, v50
	v_or_b32_e32 v48, v159, v50
	v_lshl_or_b32 v152, v44, 6, v162
	v_or_b32_e32 v44, v46, v45
	s_mov_b32 s22, 1
	v_mov_b32_e32 v155, v153
	v_mov_b32_e32 v1, v0
	v_mov_b32_e32 v2, v0
	v_mov_b32_e32 v3, v0
	v_mov_b32_e32 v4, v0
	v_mov_b32_e32 v5, v0
	v_mov_b32_e32 v6, v0
	v_mov_b32_e32 v7, v0
	v_mov_b32_e32 v8, v0
	v_mov_b32_e32 v9, v0
	v_mov_b32_e32 v10, v0
	v_mov_b32_e32 v11, v0
	v_mov_b32_e32 v12, v0
	v_mov_b32_e32 v13, v0
	v_mov_b32_e32 v14, v0
	v_mov_b32_e32 v15, v0
	v_mov_b32_e32 v40, v0
	v_mov_b32_e32 v41, v0
	v_mov_b32_e32 v42, v0
	v_mov_b32_e32 v43, v0
	v_mul_u32_u24_e32 v165, 48, v160
	v_lshlrev_b32_e32 v166, 1, v158
	v_mul_lo_u32 v168, v48, 48
	v_lshlrev_b32_e32 v154, 1, v44
	v_mov_b64_e32 v[156:157], v[152:153]
	v_mov_b32_e32 v56, v0
	v_mov_b32_e32 v57, v0
	v_mov_b32_e32 v58, v0
	v_mov_b32_e32 v59, v0
	v_mov_b32_e32 v68, v0
	v_mov_b32_e32 v69, v0
	v_mov_b32_e32 v70, v0
	v_mov_b32_e32 v71, v0
	v_mov_b32_e32 v80, v0
	v_mov_b32_e32 v81, v0
	v_mov_b32_e32 v82, v0
	v_mov_b32_e32 v83, v0
	v_mov_b32_e32 v44, v0
	v_mov_b32_e32 v45, v0
	v_mov_b32_e32 v46, v0
	v_mov_b32_e32 v48, v0
	s_waitcnt vmcnt(5)
	ds_write_b128 v163, v[16:19]
	s_waitcnt vmcnt(4)
	ds_write_b128 v163, v[20:23] offset:96
	s_waitcnt vmcnt(3)
	ds_write_b128 v164, v[24:27] offset:12288
	s_waitcnt vmcnt(2)
	ds_write_b128 v164, v[28:31] offset:12384
	s_waitcnt vmcnt(1)
	ds_write_b128 v164, v[32:35] offset:12480
	s_waitcnt vmcnt(0)
	ds_write_b128 v164, v[36:39] offset:12576
	s_waitcnt lgkmcnt(0)
	s_barrier
	global_load_dwordx4 v[20:23], v47, s[6:7]
	global_load_dwordx4 v[16:19], v47, s[6:7] offset:64
	global_load_dwordx4 v[36:39], v49, s[8:9]
	global_load_dwordx4 v[32:35], v49, s[8:9] offset:64
	global_load_dwordx4 v[28:31], v49, s[8:9] offset:128
	global_load_dwordx4 v[24:27], v49, s[8:9] offset:192
	s_add_u32 s98, s42, s45
	s_addc_u32 s99, s43, 0
	s_add_u32 s100, s42, s46
	s_addc_u32 s101, s43, 0
	global_load_dwordx4 v[200:203], v154, s[98:99]
	global_load_dwordx4 v[204:207], v154, s[98:99] offset:64
	global_load_dwordx4 v[208:211], v156, s[100:101] offset:2048
	global_load_dwordx4 v[212:215], v156, s[100:101] offset:2112
	global_load_dwordx4 v[220:223], v156, s[100:101] offset:2176
	global_load_dwordx4 v[224:227], v156, s[100:101] offset:2240
	s_add_u32 s98, s98, s4
	s_addc_u32 s99, s99, s5
	s_add_u32 s100, s100, s14
	s_addc_u32 s101, s101, s15
	v_mov_b32_e32 v47, v0
	v_mov_b32_e32 v49, v0
	v_mov_b32_e32 v50, v0
	v_mov_b32_e32 v51, v0
	v_mov_b32_e32 v52, v0
	v_mov_b32_e32 v53, v0
	v_mov_b32_e32 v54, v0
	v_mov_b32_e32 v55, v0
	v_mov_b32_e32 v64, v0
	v_mov_b32_e32 v65, v0
	v_mov_b32_e32 v66, v0
	v_mov_b32_e32 v67, v0
	v_mov_b32_e32 v76, v0
	v_mov_b32_e32 v77, v0
	v_mov_b32_e32 v78, v0
	v_mov_b32_e32 v79, v0
	v_mov_b32_e32 v88, v0
	v_mov_b32_e32 v89, v0
	v_mov_b32_e32 v90, v0
	v_mov_b32_e32 v91, v0
	v_mov_b32_e32 v100, v0
	v_mov_b32_e32 v101, v0
	v_mov_b32_e32 v102, v0
	v_mov_b32_e32 v103, v0
	v_mov_b32_e32 v112, v0
	v_mov_b32_e32 v113, v0
	v_mov_b32_e32 v114, v0
	v_mov_b32_e32 v115, v0
	v_mov_b32_e32 v60, v0
	v_mov_b32_e32 v61, v0
	v_mov_b32_e32 v62, v0
	v_mov_b32_e32 v63, v0
	v_mov_b32_e32 v72, v0
	v_mov_b32_e32 v73, v0
	v_mov_b32_e32 v74, v0
	v_mov_b32_e32 v75, v0
	v_mov_b32_e32 v84, v0
	v_mov_b32_e32 v85, v0
	v_mov_b32_e32 v86, v0
	v_mov_b32_e32 v87, v0
	v_mov_b32_e32 v96, v0
	v_mov_b32_e32 v97, v0
	v_mov_b32_e32 v98, v0
	v_mov_b32_e32 v99, v0
	v_mov_b32_e32 v108, v0
	v_mov_b32_e32 v109, v0
	v_mov_b32_e32 v110, v0
	v_mov_b32_e32 v111, v0
	v_mov_b32_e32 v120, v0
	v_mov_b32_e32 v121, v0
	v_mov_b32_e32 v122, v0
	v_mov_b32_e32 v123, v0
	v_mov_b32_e32 v128, v0
	v_mov_b32_e32 v129, v0
	v_mov_b32_e32 v130, v0
	v_mov_b32_e32 v131, v0
	v_mov_b32_e32 v136, v0
	v_mov_b32_e32 v137, v0
	v_mov_b32_e32 v138, v0
	v_mov_b32_e32 v139, v0
	v_mov_b32_e32 v92, v0
	v_mov_b32_e32 v93, v0
	v_mov_b32_e32 v94, v0
	v_mov_b32_e32 v95, v0
	v_mov_b32_e32 v104, v0
	v_mov_b32_e32 v105, v0
	v_mov_b32_e32 v106, v0
	v_mov_b32_e32 v107, v0
	v_mov_b32_e32 v116, v0
	v_mov_b32_e32 v117, v0
	v_mov_b32_e32 v118, v0
	v_mov_b32_e32 v119, v0
	v_mov_b32_e32 v124, v0
	v_mov_b32_e32 v125, v0
	v_mov_b32_e32 v126, v0
	v_mov_b32_e32 v127, v0
	v_mov_b32_e32 v132, v0
	v_mov_b32_e32 v133, v0
	v_mov_b32_e32 v134, v0
	v_mov_b32_e32 v135, v0
	v_mov_b32_e32 v140, v0
	v_mov_b32_e32 v141, v0
	v_mov_b32_e32 v142, v0
	v_mov_b32_e32 v143, v0
	v_mov_b32_e32 v144, v0
	v_mov_b32_e32 v145, v0
	v_mov_b32_e32 v146, v0
	v_mov_b32_e32 v147, v0
	v_mov_b32_e32 v148, v0
	v_mov_b32_e32 v149, v0
	v_mov_b32_e32 v150, v0
	v_mov_b32_e32 v151, v0
; DI f32x4 mfma16(bf16x8 a, bf16x8 b, f32x4 c) { return __builtin_amdgcn_mfma_f32_16x16x32_bf16(a, b, c, 0, 0, 0); }
; template <int NI, class XL, class EP>
; DI void gemm_tile(const u16* __restrict__ W, int ldw, int f0, int t0, int K, XL xl, EP ep, unsigned char* smem) {
;     ...
;   for (int it = 0; it < nk; ++it) {
;     const u16* Ws = S0 + (it & 1) * BUF; const u16* Xs = Ws + 128 * LST;
;     __builtin_amdgcn_s_setprio(1);
;     bf16x8 a[4];
; #pragma unroll
;     for (int mi = 0; mi < 4; ++mi) a[mi] = *(const bf16x8*)(Ws + (wf * 64 + mi * 16 + lr) * LST + lq * 8);
; #pragma unroll
;     for (int ni = 0; ni < NI; ++ni) {
;       const bf16x8 b = *(const bf16x8*)(Xs + (wt * (NI * 16) + ni * 16 + lr) * LST + lq * 8);
; #pragma unroll
;       for (int mi = 0; mi < 4; ++mi) acc[mi][ni] = mfma16(a[mi], b, acc[mi][ni]);
;     }
;     __builtin_amdgcn_sched_group_barrier(0x100, 6, 0);
; #pragma unroll
;     for (int ni = 0; ni < NI; ++ni) { __builtin_amdgcn_sched_group_barrier(0x008, 4, 0); if (ni + 2 < NI) __builtin_amdgcn_sched_group_barrier(0x100, 1, 0); }
;     __builtin_amdgcn_s_setprio(0);
;     if (it + 1 < nk) lstore((it + 1) & 1);
;     if (it + 2 < nk) gload(it + 2);
;     __syncthreads();
;   }
.LBB0_269:
	s_bitcmp1_b32 s22, 0
	s_cselect_b32 s23, 0, 0x9000
	s_setprio 1
	v_or_b32_e32 v152, s23, v166
	v_lshl_add_u32 v169, v168, 1, v152
	ds_read_b128 v[170:173], v169
	ds_read_b128 v[174:177], v169 offset:1536
	ds_read_b128 v[182:185], v169 offset:3072
	ds_read_b128 v[186:189], v169 offset:4608
	v_lshl_add_u32 v152, v165, 1, v152
	ds_read_b128 v[178:181], v152 offset:12288
	ds_read_b128 v[190:193], v152 offset:13824
	s_xor_b32 s23, s23, 0x9000
	v_add3_u32 v228, v167, s23, v162
	s_waitcnt lgkmcnt(1)
	v_mfma_f32_16x16x32_bf16 v[148:151], v[170:173], v[178:181], v[148:151]
	v_mfma_f32_16x16x32_bf16 v[136:139], v[174:177], v[178:181], v[136:139]
	v_mfma_f32_16x16x32_bf16 v[112:115], v[182:185], v[178:181], v[112:115]
	v_mfma_f32_16x16x32_bf16 v[80:83], v[186:189], v[178:181], v[80:83]
	ds_read_b128 v[178:181], v152 offset:15360
	s_waitcnt vmcnt(11)
	ds_write_b128 v228, v[20:23]
	s_waitcnt lgkmcnt(2)
	v_mfma_f32_16x16x32_bf16 v[144:147], v[170:173], v[190:193], v[144:147]
	v_mfma_f32_16x16x32_bf16 v[128:131], v[174:177], v[190:193], v[128:131]
	v_mfma_f32_16x16x32_bf16 v[100:103], v[182:185], v[190:193], v[100:103]
	v_mfma_f32_16x16x32_bf16 v[68:71], v[186:189], v[190:193], v[68:71]
	ds_read_b128 v[190:193], v152 offset:16896
	s_waitcnt vmcnt(10)
	ds_write_b128 v228, v[16:19] offset:96
	v_add_u32_e32 v228, v228, v167
	global_load_dwordx4 v[20:23], v154, s[98:99]
	global_load_dwordx4 v[16:19], v154, s[98:99] offset:64
	s_waitcnt lgkmcnt(3)
	v_mfma_f32_16x16x32_bf16 v[140:143], v[170:173], v[178:181], v[140:143]
	v_mfma_f32_16x16x32_bf16 v[120:123], v[174:177], v[178:181], v[120:123]
	v_mfma_f32_16x16x32_bf16 v[88:91], v[182:185], v[178:181], v[88:91]
	v_mfma_f32_16x16x32_bf16 v[56:59], v[186:189], v[178:181], v[56:59]
	ds_read_b128 v[178:181], v152 offset:18432
	s_waitcnt vmcnt(11)
	ds_write_b128 v228, v[36:39] offset:12288
	global_load_dwordx4 v[36:39], v156, s[100:101] offset:2048
	s_waitcnt lgkmcnt(3)
	v_mfma_f32_16x16x32_bf16 v[132:135], v[170:173], v[190:193], v[132:135]
	v_mfma_f32_16x16x32_bf16 v[108:111], v[174:177], v[190:193], v[108:111]
	v_mfma_f32_16x16x32_bf16 v[76:79], v[182:185], v[190:193], v[76:79]
	v_mfma_f32_16x16x32_bf16 v[40:43], v[186:189], v[190:193], v[40:43]
	ds_read_b128 v[190:193], v152 offset:19968
	s_waitcnt vmcnt(11)
	ds_write_b128 v228, v[32:35] offset:12384
	global_load_dwordx4 v[32:35], v156, s[100:101] offset:2112
	s_waitcnt lgkmcnt(3)
	v_mfma_f32_16x16x32_bf16 v[124:127], v[170:173], v[178:181], v[124:127]
	v_mfma_f32_16x16x32_bf16 v[96:99], v[174:177], v[178:181], v[96:99]
	v_mfma_f32_16x16x32_bf16 v[64:67], v[182:185], v[178:181], v[64:67]
	v_mfma_f32_16x16x32_bf16 v[12:15], v[186:189], v[178:181], v[12:15]
	ds_read_b128 v[178:181], v152 offset:21504
	s_waitcnt vmcnt(11)
	ds_write_b128 v228, v[28:31] offset:12480
	global_load_dwordx4 v[28:31], v156, s[100:101] offset:2176
	s_waitcnt lgkmcnt(3)
	v_mfma_f32_16x16x32_bf16 v[116:119], v[170:173], v[190:193], v[116:119]
	v_mfma_f32_16x16x32_bf16 v[84:87], v[174:177], v[190:193], v[84:87]
	v_mfma_f32_16x16x32_bf16 v[52:55], v[182:185], v[190:193], v[52:55]
	v_mfma_f32_16x16x32_bf16 v[8:11], v[186:189], v[190:193], v[8:11]
	ds_read_b128 v[190:193], v152 offset:23040
	s_waitcnt vmcnt(11)
	ds_write_b128 v228, v[24:27] offset:12576
	global_load_dwordx4 v[24:27], v156, s[100:101] offset:2240
	s_waitcnt lgkmcnt(3)
	v_mfma_f32_16x16x32_bf16 v[104:107], v[170:173], v[178:181], v[104:107]
	v_mfma_f32_16x16x32_bf16 v[72:75], v[174:177], v[178:181], v[72:75]
	v_mfma_f32_16x16x32_bf16 v[48:51], v[182:185], v[178:181], v[48:51]
	v_mfma_f32_16x16x32_bf16 v[4:7], v[186:189], v[178:181], v[4:7]
	s_add_u32 s98, s98, s4
	s_addc_u32 s99, s99, s5
	s_add_u32 s100, s100, s14
	s_addc_u32 s101, s101, s15
	s_add_i32 s22, s22, 1
	s_waitcnt lgkmcnt(1)
	v_mfma_f32_16x16x32_bf16 v[92:95], v[170:173], v[190:193], v[92:95]
	v_mfma_f32_16x16x32_bf16 v[60:63], v[174:177], v[190:193], v[60:63]
	v_mfma_f32_16x16x32_bf16 v[44:47], v[182:185], v[190:193], v[44:47]
	v_mfma_f32_16x16x32_bf16 v[0:3], v[186:189], v[190:193], v[0:3]
	s_setprio 0
	s_waitcnt lgkmcnt(0)
	s_barrier
	s_bitcmp1_b32 s22, 0
	s_cselect_b32 s23, 0, 0x9000
	s_setprio 1
	v_or_b32_e32 v152, s23, v166
	v_lshl_add_u32 v169, v168, 1, v152
	ds_read_b128 v[170:173], v169
	ds_read_b128 v[174:177], v169 offset:1536
	ds_read_b128 v[182:185], v169 offset:3072
	ds_read_b128 v[186:189], v169 offset:4608
	v_lshl_add_u32 v152, v165, 1, v152
	ds_read_b128 v[178:181], v152 offset:12288
	ds_read_b128 v[190:193], v152 offset:13824
	s_xor_b32 s23, s23, 0x9000
	v_add3_u32 v228, v167, s23, v162
	s_waitcnt lgkmcnt(1)
	v_mfma_f32_16x16x32_bf16 v[148:151], v[170:173], v[178:181], v[148:151]
	v_mfma_f32_16x16x32_bf16 v[136:139], v[174:177], v[178:181], v[136:139]
	v_mfma_f32_16x16x32_bf16 v[112:115], v[182:185], v[178:181], v[112:115]
	v_mfma_f32_16x16x32_bf16 v[80:83], v[186:189], v[178:181], v[80:83]
	ds_read_b128 v[178:181], v152 offset:15360
	s_waitcnt vmcnt(11)
	ds_write_b128 v228, v[200:203]
	s_waitcnt lgkmcnt(2)
	v_mfma_f32_16x16x32_bf16 v[144:147], v[170:173], v[190:193], v[144:147]
	v_mfma_f32_16x16x32_bf16 v[128:131], v[174:177], v[190:193], v[128:131]
	v_mfma_f32_16x16x32_bf16 v[100:103], v[182:185], v[190:193], v[100:103]
	v_mfma_f32_16x16x32_bf16 v[68:71], v[186:189], v[190:193], v[68:71]
	ds_read_b128 v[190:193], v152 offset:16896
	s_waitcnt vmcnt(10)
	ds_write_b128 v228, v[204:207] offset:96
	v_add_u32_e32 v228, v228, v167
	global_load_dwordx4 v[200:203], v154, s[98:99]
	global_load_dwordx4 v[204:207], v154, s[98:99] offset:64
	s_waitcnt lgkmcnt(3)
; DI f32x4 mfma16(bf16x8 a, bf16x8 b, f32x4 c) { return __builtin_amdgcn_mfma_f32_16x16x32_bf16(a, b, c, 0, 0, 0); }
; template <int NI, class XL, class EP>
; DI void gemm_tile(const u16* __restrict__ W, int ldw, int f0, int t0, int K, XL xl, EP ep, unsigned char* smem) {
;     ...
;   for (int it = 0; it < nk; ++it) {
;     const u16* Ws = S0 + (it & 1) * BUF; const u16* Xs = Ws + 128 * LST;
;     __builtin_amdgcn_s_setprio(1);
;     bf16x8 a[4];
; #pragma unroll
;     for (int mi = 0; mi < 4; ++mi) a[mi] = *(const bf16x8*)(Ws + (wf * 64 + mi * 16 + lr) * LST + lq * 8);
; #pragma unroll
;     for (int ni = 0; ni < NI; ++ni) {
;       const bf16x8 b = *(const bf16x8*)(Xs + (wt * (NI * 16) + ni * 16 + lr) * LST + lq * 8);
; #pragma unroll
;       for (int mi = 0; mi < 4; ++mi) acc[mi][ni] = mfma16(a[mi], b, acc[mi][ni]);
;     }
;     __builtin_amdgcn_sched_group_barrier(0x100, 6, 0);
; #pragma unroll
;     for (int ni = 0; ni < NI; ++ni) { __builtin_amdgcn_sched_group_barrier(0x008, 4, 0); if (ni + 2 < NI) __builtin_amdgcn_sched_group_barrier(0x100, 1, 0); }
;     __builtin_amdgcn_s_setprio(0);
;     if (it + 1 < nk) lstore((it + 1) & 1);
;     if (it + 2 < nk) gload(it + 2);
;     __syncthreads();
;   }
	v_mfma_f32_16x16x32_bf16 v[140:143], v[170:173], v[178:181], v[140:143]
	v_mfma_f32_16x16x32_bf16 v[120:123], v[174:177], v[178:181], v[120:123]
	v_mfma_f32_16x16x32_bf16 v[88:91], v[182:185], v[178:181], v[88:91]
	v_mfma_f32_16x16x32_bf16 v[56:59], v[186:189], v[178:181], v[56:59]
	ds_read_b128 v[178:181], v152 offset:18432
	s_waitcnt vmcnt(11)
	ds_write_b128 v228, v[208:211] offset:12288
	global_load_dwordx4 v[208:211], v156, s[100:101] offset:2048
	s_waitcnt lgkmcnt(3)
	v_mfma_f32_16x16x32_bf16 v[132:135], v[170:173], v[190:193], v[132:135]
	v_mfma_f32_16x16x32_bf16 v[108:111], v[174:177], v[190:193], v[108:111]
	v_mfma_f32_16x16x32_bf16 v[76:79], v[182:185], v[190:193], v[76:79]
	v_mfma_f32_16x16x32_bf16 v[40:43], v[186:189], v[190:193], v[40:43]
	ds_read_b128 v[190:193], v152 offset:19968
	s_waitcnt vmcnt(11)
	ds_write_b128 v228, v[212:215] offset:12384
	global_load_dwordx4 v[212:215], v156, s[100:101] offset:2112
	s_waitcnt lgkmcnt(3)
	v_mfma_f32_16x16x32_bf16 v[124:127], v[170:173], v[178:181], v[124:127]
	v_mfma_f32_16x16x32_bf16 v[96:99], v[174:177], v[178:181], v[96:99]
	v_mfma_f32_16x16x32_bf16 v[64:67], v[182:185], v[178:181], v[64:67]
	v_mfma_f32_16x16x32_bf16 v[12:15], v[186:189], v[178:181], v[12:15]
	ds_read_b128 v[178:181], v152 offset:21504
	s_waitcnt vmcnt(11)
	ds_write_b128 v228, v[220:223] offset:12480
	global_load_dwordx4 v[220:223], v156, s[100:101] offset:2176
	s_waitcnt lgkmcnt(3)
	v_mfma_f32_16x16x32_bf16 v[116:119], v[170:173], v[190:193], v[116:119]
	v_mfma_f32_16x16x32_bf16 v[84:87], v[174:177], v[190:193], v[84:87]
	v_mfma_f32_16x16x32_bf16 v[52:55], v[182:185], v[190:193], v[52:55]
	v_mfma_f32_16x16x32_bf16 v[8:11], v[186:189], v[190:193], v[8:11]
	ds_read_b128 v[190:193], v152 offset:23040
	s_waitcnt vmcnt(11)
	ds_write_b128 v228, v[224:227] offset:12576
	global_load_dwordx4 v[224:227], v156, s[100:101] offset:2240
	s_waitcnt lgkmcnt(3)
	v_mfma_f32_16x16x32_bf16 v[104:107], v[170:173], v[178:181], v[104:107]
	v_mfma_f32_16x16x32_bf16 v[72:75], v[174:177], v[178:181], v[72:75]
	v_mfma_f32_16x16x32_bf16 v[48:51], v[182:185], v[178:181], v[48:51]
	v_mfma_f32_16x16x32_bf16 v[4:7], v[186:189], v[178:181], v[4:7]
	s_add_u32 s98, s98, s4
	s_addc_u32 s99, s99, s5
	s_add_u32 s100, s100, s14
	s_addc_u32 s101, s101, s15
	s_add_i32 s22, s22, 1
	s_waitcnt lgkmcnt(1)
	v_mfma_f32_16x16x32_bf16 v[92:95], v[170:173], v[190:193], v[92:95]
	v_mfma_f32_16x16x32_bf16 v[60:63], v[174:177], v[190:193], v[60:63]
	v_mfma_f32_16x16x32_bf16 v[44:47], v[182:185], v[190:193], v[44:47]
	v_mfma_f32_16x16x32_bf16 v[0:3], v[186:189], v[190:193], v[0:3]
	s_setprio 0
	s_cmp_eq_u32 s22, 29
	s_waitcnt lgkmcnt(0)
	s_barrier
	s_cbranch_scc0 .LBB0_269
	s_bitcmp1_b32 s22, 0
	s_cselect_b32 s23, 0, 0x9000
	s_setprio 1
	v_or_b32_e32 v152, s23, v166
	v_lshl_add_u32 v169, v168, 1, v152
	ds_read_b128 v[170:173], v169
	ds_read_b128 v[174:177], v169 offset:1536
	ds_read_b128 v[182:185], v169 offset:3072
	ds_read_b128 v[186:189], v169 offset:4608
	v_lshl_add_u32 v152, v165, 1, v152
	ds_read_b128 v[178:181], v152 offset:12288
	ds_read_b128 v[190:193], v152 offset:13824
	s_xor_b32 s23, s23, 0x9000
	v_add3_u32 v228, v167, s23, v162
	s_waitcnt lgkmcnt(1)
	v_mfma_f32_16x16x32_bf16 v[148:151], v[170:173], v[178:181], v[148:151]
	v_mfma_f32_16x16x32_bf16 v[136:139], v[174:177], v[178:181], v[136:139]
	v_mfma_f32_16x16x32_bf16 v[112:115], v[182:185], v[178:181], v[112:115]
	v_mfma_f32_16x16x32_bf16 v[80:83], v[186:189], v[178:181], v[80:83]
	ds_read_b128 v[178:181], v152 offset:15360
	s_waitcnt vmcnt(11)
	ds_write_b128 v228, v[20:23]
	s_waitcnt lgkmcnt(2)
	v_mfma_f32_16x16x32_bf16 v[144:147], v[170:173], v[190:193], v[144:147]
	v_mfma_f32_16x16x32_bf16 v[128:131], v[174:177], v[190:193], v[128:131]
	v_mfma_f32_16x16x32_bf16 v[100:103], v[182:185], v[190:193], v[100:103]
	v_mfma_f32_16x16x32_bf16 v[68:71], v[186:189], v[190:193], v[68:71]
	ds_read_b128 v[190:193], v152 offset:16896
	s_waitcnt vmcnt(10)
	ds_write_b128 v228, v[16:19] offset:96
	v_add_u32_e32 v228, v228, v167
	global_load_dwordx4 v[20:23], v154, s[98:99]
	global_load_dwordx4 v[16:19], v154, s[98:99] offset:64
	s_waitcnt lgkmcnt(3)
	v_mfma_f32_16x16x32_bf16 v[140:143], v[170:173], v[178:181], v[140:143]
	v_mfma_f32_16x16x32_bf16 v[120:123], v[174:177], v[178:181], v[120:123]
	v_mfma_f32_16x16x32_bf16 v[88:91], v[182:185], v[178:181], v[88:91]
	v_mfma_f32_16x16x32_bf16 v[56:59], v[186:189], v[178:181], v[56:59]
	ds_read_b128 v[178:181], v152 offset:18432
	s_waitcnt vmcnt(11)
	ds_write_b128 v228, v[36:39] offset:12288
	global_load_dwordx4 v[36:39], v156, s[100:101] offset:2048
	s_waitcnt lgkmcnt(3)
	v_mfma_f32_16x16x32_bf16 v[132:135], v[170:173], v[190:193], v[132:135]
	v_mfma_f32_16x16x32_bf16 v[108:111], v[174:177], v[190:193], v[108:111]
	v_mfma_f32_16x16x32_bf16 v[76:79], v[182:185], v[190:193], v[76:79]
	v_mfma_f32_16x16x32_bf16 v[40:43], v[186:189], v[190:193], v[40:43]
	ds_read_b128 v[190:193], v152 offset:19968
	s_waitcnt vmcnt(11)
	ds_write_b128 v228, v[32:35] offset:12384
	global_load_dwordx4 v[32:35], v156, s[100:101] offset:2112
	s_waitcnt lgkmcnt(3)
	v_mfma_f32_16x16x32_bf16 v[124:127], v[170:173], v[178:181], v[124:127]
	v_mfma_f32_16x16x32_bf16 v[96:99], v[174:177], v[178:181], v[96:99]
	v_mfma_f32_16x16x32_bf16 v[64:67], v[182:185], v[178:181], v[64:67]
	v_mfma_f32_16x16x32_bf16 v[12:15], v[186:189], v[178:181], v[12:15]
	ds_read_b128 v[178:181], v152 offset:21504
	s_waitcnt vmcnt(11)
	ds_write_b128 v228, v[28:31] offset:12480
	global_load_dwordx4 v[28:31], v156, s[100:101] offset:2176
	s_waitcnt lgkmcnt(3)
	v_mfma_f32_16x16x32_bf16 v[116:119], v[170:173], v[190:193], v[116:119]
	v_mfma_f32_16x16x32_bf16 v[84:87], v[174:177], v[190:193], v[84:87]
	v_mfma_f32_16x16x32_bf16 v[52:55], v[182:185], v[190:193], v[52:55]
	v_mfma_f32_16x16x32_bf16 v[8:11], v[186:189], v[190:193], v[8:11]
	ds_read_b128 v[190:193], v152 offset:23040
	s_waitcnt vmcnt(11)
	ds_write_b128 v228, v[24:27] offset:12576
	global_load_dwordx4 v[24:27], v156, s[100:101] offset:2240
	s_waitcnt lgkmcnt(3)
	v_mfma_f32_16x16x32_bf16 v[104:107], v[170:173], v[178:181], v[104:107]
	v_mfma_f32_16x16x32_bf16 v[72:75], v[174:177], v[178:181], v[72:75]
	v_mfma_f32_16x16x32_bf16 v[48:51], v[182:185], v[178:181], v[48:51]
	v_mfma_f32_16x16x32_bf16 v[4:7], v[186:189], v[178:181], v[4:7]
	s_add_u32 s98, s98, s4
	s_addc_u32 s99, s99, s5
	s_add_u32 s100, s100, s14
	s_addc_u32 s101, s101, s15
	s_add_i32 s22, s22, 1
	s_waitcnt lgkmcnt(1)
	v_mfma_f32_16x16x32_bf16 v[92:95], v[170:173], v[190:193], v[92:95]
	v_mfma_f32_16x16x32_bf16 v[60:63], v[174:177], v[190:193], v[60:63]
	v_mfma_f32_16x16x32_bf16 v[44:47], v[182:185], v[190:193], v[44:47]
	v_mfma_f32_16x16x32_bf16 v[0:3], v[186:189], v[190:193], v[0:3]
	s_setprio 0
	s_waitcnt lgkmcnt(0)
	s_barrier
; DI f32x4 mfma16(bf16x8 a, bf16x8 b, f32x4 c) { return __builtin_amdgcn_mfma_f32_16x16x32_bf16(a, b, c, 0, 0, 0); }
; template <int NI, class XL, class EP>
; DI void gemm_tile(const u16* __restrict__ W, int ldw, int f0, int t0, int K, XL xl, EP ep, unsigned char* smem) {
;     ...
;   for (int it = 0; it < nk; ++it) {
;     const u16* Ws = S0 + (it & 1) * BUF; const u16* Xs = Ws + 128 * LST;
;     __builtin_amdgcn_s_setprio(1);
;     bf16x8 a[4];
; #pragma unroll
;     for (int mi = 0; mi < 4; ++mi) a[mi] = *(const bf16x8*)(Ws + (wf * 64 + mi * 16 + lr) * LST + lq * 8);
; #pragma unroll
;     for (int ni = 0; ni < NI; ++ni) {
;       const bf16x8 b = *(const bf16x8*)(Xs + (wt * (NI * 16) + ni * 16 + lr) * LST + lq * 8);
; #pragma unroll
;       for (int mi = 0; mi < 4; ++mi) acc[mi][ni] = mfma16(a[mi], b, acc[mi][ni]);
;     }
;     __builtin_amdgcn_sched_group_barrier(0x100, 6, 0);
; #pragma unroll
;     for (int ni = 0; ni < NI; ++ni) { __builtin_amdgcn_sched_group_barrier(0x008, 4, 0); if (ni + 2 < NI) __builtin_amdgcn_sched_group_barrier(0x100, 1, 0); }
;     __builtin_amdgcn_s_setprio(0);
;     if (it + 1 < nk) lstore((it + 1) & 1);
;     if (it + 2 < nk) gload(it + 2);
;     __syncthreads();
;   }
	s_bitcmp1_b32 s22, 0
	s_cselect_b32 s23, 0, 0x9000
	s_setprio 1
	v_or_b32_e32 v152, s23, v166
	v_lshl_add_u32 v169, v168, 1, v152
	ds_read_b128 v[170:173], v169
	ds_read_b128 v[174:177], v169 offset:1536
	ds_read_b128 v[182:185], v169 offset:3072
	ds_read_b128 v[186:189], v169 offset:4608
	v_lshl_add_u32 v152, v165, 1, v152
	ds_read_b128 v[178:181], v152 offset:12288
	ds_read_b128 v[190:193], v152 offset:13824
	s_xor_b32 s23, s23, 0x9000
	v_add3_u32 v228, v167, s23, v162
	s_waitcnt lgkmcnt(1)
	v_mfma_f32_16x16x32_bf16 v[148:151], v[170:173], v[178:181], v[148:151]
	v_mfma_f32_16x16x32_bf16 v[136:139], v[174:177], v[178:181], v[136:139]
	v_mfma_f32_16x16x32_bf16 v[112:115], v[182:185], v[178:181], v[112:115]
	v_mfma_f32_16x16x32_bf16 v[80:83], v[186:189], v[178:181], v[80:83]
	ds_read_b128 v[178:181], v152 offset:15360
	s_waitcnt vmcnt(11)
	ds_write_b128 v228, v[200:203]
	s_waitcnt lgkmcnt(2)
	v_mfma_f32_16x16x32_bf16 v[144:147], v[170:173], v[190:193], v[144:147]
	v_mfma_f32_16x16x32_bf16 v[128:131], v[174:177], v[190:193], v[128:131]
	v_mfma_f32_16x16x32_bf16 v[100:103], v[182:185], v[190:193], v[100:103]
	v_mfma_f32_16x16x32_bf16 v[68:71], v[186:189], v[190:193], v[68:71]
	ds_read_b128 v[190:193], v152 offset:16896
	s_waitcnt vmcnt(10)
	ds_write_b128 v228, v[204:207] offset:96
	v_add_u32_e32 v228, v228, v167
	s_waitcnt lgkmcnt(3)
	v_mfma_f32_16x16x32_bf16 v[140:143], v[170:173], v[178:181], v[140:143]
	v_mfma_f32_16x16x32_bf16 v[120:123], v[174:177], v[178:181], v[120:123]
	v_mfma_f32_16x16x32_bf16 v[88:91], v[182:185], v[178:181], v[88:91]
	v_mfma_f32_16x16x32_bf16 v[56:59], v[186:189], v[178:181], v[56:59]
	ds_read_b128 v[178:181], v152 offset:18432
	s_waitcnt vmcnt(9)
	ds_write_b128 v228, v[208:211] offset:12288
	s_waitcnt lgkmcnt(3)
	v_mfma_f32_16x16x32_bf16 v[132:135], v[170:173], v[190:193], v[132:135]
	v_mfma_f32_16x16x32_bf16 v[108:111], v[174:177], v[190:193], v[108:111]
	v_mfma_f32_16x16x32_bf16 v[76:79], v[182:185], v[190:193], v[76:79]
	v_mfma_f32_16x16x32_bf16 v[40:43], v[186:189], v[190:193], v[40:43]
	ds_read_b128 v[190:193], v152 offset:19968
	s_waitcnt vmcnt(8)
	ds_write_b128 v228, v[212:215] offset:12384
	s_waitcnt lgkmcnt(3)
	v_mfma_f32_16x16x32_bf16 v[124:127], v[170:173], v[178:181], v[124:127]
	v_mfma_f32_16x16x32_bf16 v[96:99], v[174:177], v[178:181], v[96:99]
	v_mfma_f32_16x16x32_bf16 v[64:67], v[182:185], v[178:181], v[64:67]
	v_mfma_f32_16x16x32_bf16 v[12:15], v[186:189], v[178:181], v[12:15]
	ds_read_b128 v[178:181], v152 offset:21504
	s_waitcnt vmcnt(7)
	ds_write_b128 v228, v[220:223] offset:12480
	s_waitcnt lgkmcnt(3)
	v_mfma_f32_16x16x32_bf16 v[116:119], v[170:173], v[190:193], v[116:119]
	v_mfma_f32_16x16x32_bf16 v[84:87], v[174:177], v[190:193], v[84:87]
	v_mfma_f32_16x16x32_bf16 v[52:55], v[182:185], v[190:193], v[52:55]
	v_mfma_f32_16x16x32_bf16 v[8:11], v[186:189], v[190:193], v[8:11]
	ds_read_b128 v[190:193], v152 offset:23040
	s_waitcnt vmcnt(6)
	ds_write_b128 v228, v[224:227] offset:12576
	s_waitcnt lgkmcnt(3)
	v_mfma_f32_16x16x32_bf16 v[104:107], v[170:173], v[178:181], v[104:107]
	v_mfma_f32_16x16x32_bf16 v[72:75], v[174:177], v[178:181], v[72:75]
	v_mfma_f32_16x16x32_bf16 v[48:51], v[182:185], v[178:181], v[48:51]
	v_mfma_f32_16x16x32_bf16 v[4:7], v[186:189], v[178:181], v[4:7]
	s_add_u32 s98, s98, s4
	s_addc_u32 s99, s99, s5
	s_add_u32 s100, s100, s14
	s_addc_u32 s101, s101, s15
	s_add_i32 s22, s22, 1
	s_waitcnt lgkmcnt(1)
	v_mfma_f32_16x16x32_bf16 v[92:95], v[170:173], v[190:193], v[92:95]
	v_mfma_f32_16x16x32_bf16 v[60:63], v[174:177], v[190:193], v[60:63]
	v_mfma_f32_16x16x32_bf16 v[44:47], v[182:185], v[190:193], v[44:47]
	v_mfma_f32_16x16x32_bf16 v[0:3], v[186:189], v[190:193], v[0:3]
	s_setprio 0
	s_waitcnt lgkmcnt(0)
	s_barrier
	s_setprio 1
	v_lshl_add_u32 v152, v168, 1, v166
	ds_read_b128 v[154:157], v152
	v_lshl_add_u32 v228, v165, 1, v166
	ds_read_b128 v[166:169], v152 offset:1536
	ds_read_b128 v[174:177], v152 offset:3072
	ds_read_b128 v[178:181], v152 offset:4608
	ds_read_b128 v[170:173], v228 offset:12288
	ds_read_b128 v[182:185], v228 offset:13824
	s_waitcnt lgkmcnt(1)
	v_mfma_f32_16x16x32_bf16 v[148:151], v[154:157], v[170:173], v[148:151]
	v_mfma_f32_16x16x32_bf16 v[136:139], v[166:169], v[170:173], v[136:139]
	v_mfma_f32_16x16x32_bf16 v[112:115], v[174:177], v[170:173], v[112:115]
	v_mfma_f32_16x16x32_bf16 v[170:173], v[178:181], v[170:173], v[80:83]
	s_nop 2
	ds_read_b128 v[80:83], v228 offset:15360
	s_waitcnt lgkmcnt(1)
	v_mfma_f32_16x16x32_bf16 v[144:147], v[154:157], v[182:185], v[144:147]
	v_mfma_f32_16x16x32_bf16 v[128:131], v[166:169], v[182:185], v[128:131]
	v_mfma_f32_16x16x32_bf16 v[100:103], v[174:177], v[182:185], v[100:103]
	v_mfma_f32_16x16x32_bf16 v[68:71], v[178:181], v[182:185], v[68:71]
	ds_read_b128 v[182:185], v228 offset:16896
	s_waitcnt lgkmcnt(1)
	v_mfma_f32_16x16x32_bf16 v[140:143], v[154:157], v[80:83], v[140:143]
	v_mfma_f32_16x16x32_bf16 v[186:189], v[166:169], v[80:83], v[120:123]
	v_mfma_f32_16x16x32_bf16 v[88:91], v[174:177], v[80:83], v[88:91]
	v_mfma_f32_16x16x32_bf16 v[56:59], v[178:181], v[80:83], v[56:59]
	ds_read_b128 v[80:83], v228 offset:18432
	s_waitcnt lgkmcnt(1)
	v_mfma_f32_16x16x32_bf16 v[132:135], v[154:157], v[182:185], v[132:135]
	v_mfma_f32_16x16x32_bf16 v[108:111], v[166:169], v[182:185], v[108:111]
	v_mfma_f32_16x16x32_bf16 v[76:79], v[174:177], v[182:185], v[76:79]
	v_mfma_f32_16x16x32_bf16 v[182:185], v[178:181], v[182:185], v[40:43]
	s_nop 2
	ds_read_b128 v[40:43], v228 offset:19968
	s_waitcnt lgkmcnt(1)
; DI f32x4 mfma16(bf16x8 a, bf16x8 b, f32x4 c) { return __builtin_amdgcn_mfma_f32_16x16x32_bf16(a, b, c, 0, 0, 0); }
; template <int NI, class XL, class EP>
; DI void gemm_tile(const u16* __restrict__ W, int ldw, int f0, int t0, int K, XL xl, EP ep, unsigned char* smem) {
;     ...
;   for (int it = 0; it < nk; ++it) {
;     const u16* Ws = S0 + (it & 1) * BUF; const u16* Xs = Ws + 128 * LST;
;     __builtin_amdgcn_s_setprio(1);
;     bf16x8 a[4];
; #pragma unroll
;     for (int mi = 0; mi < 4; ++mi) a[mi] = *(const bf16x8*)(Ws + (wf * 64 + mi * 16 + lr) * LST + lq * 8);
; #pragma unroll
;     for (int ni = 0; ni < NI; ++ni) {
;       const bf16x8 b = *(const bf16x8*)(Xs + (wt * (NI * 16) + ni * 16 + lr) * LST + lq * 8);
; #pragma unroll
;       for (int mi = 0; mi < 4; ++mi) acc[mi][ni] = mfma16(a[mi], b, acc[mi][ni]);
;     }
;     __builtin_amdgcn_sched_group_barrier(0x100, 6, 0);
; #pragma unroll
;     for (int ni = 0; ni < NI; ++ni) { __builtin_amdgcn_sched_group_barrier(0x008, 4, 0); if (ni + 2 < NI) __builtin_amdgcn_sched_group_barrier(0x100, 1, 0); }
;     __builtin_amdgcn_s_setprio(0);
;     if (it + 1 < nk) lstore((it + 1) & 1);
;     if (it + 2 < nk) gload(it + 2);
;     __syncthreads();
;   }
; DI void phase1(const Params& p, const Sched& sched, unsigned char* smem) {
;     ...
;       u16* dst; int ld, cb;
;       if (tn < 8) { dst = (u16*)(p.ws + OFF_QB); ld = 1024; cb = 0; }
;       else if (tn < 12) { dst = (u16*)(p.ws + OFF_KVC); ld = 512; cb = 1024; }
;       else if (tn < 16) { dst = (u16*)(p.ws + OFF_KVS); ld = 512; cb = 1536; }
;       else if (tn < 20) { dst = (u16*)(p.ws + OFF_KVW); ld = 512; cb = 2048; }
;       else if (tn < 22) { dst = (u16*)(p.ws + OFF_MQ); ld = 256; cb = 2560; }
;       else if (tn < 24) { dst = (u16*)(p.ws + OFF_MKV); ld = 256; cb = 2816; }
;       else if (tn < 32) { dst = (u16*)(p.ws + OFF_MA); ld = 1024; cb = 3072; }
;       else { dst = (u16*)(p.ws + OFF_MB); ld = 1024; cb = 4096; }
	v_mfma_f32_16x16x32_bf16 v[190:193], v[154:157], v[80:83], v[124:127]
	v_mfma_f32_16x16x32_bf16 v[96:99], v[166:169], v[80:83], v[96:99]
	v_mfma_f32_16x16x32_bf16 v[194:197], v[174:177], v[80:83], v[64:67]
	v_mfma_f32_16x16x32_bf16 v[198:201], v[178:181], v[80:83], v[12:15]
	s_nop 2
	ds_read_b128 v[12:15], v228 offset:21504
	s_waitcnt lgkmcnt(1)
	v_mfma_f32_16x16x32_bf16 v[202:205], v[154:157], v[40:43], v[116:119]
	v_mfma_f32_16x16x32_bf16 v[84:87], v[166:169], v[40:43], v[84:87]
	v_mfma_f32_16x16x32_bf16 v[52:55], v[174:177], v[40:43], v[52:55]
	v_mfma_f32_16x16x32_bf16 v[206:209], v[178:181], v[40:43], v[8:11]
	s_nop 2
	ds_read_b128 v[8:11], v228 offset:23040
	s_waitcnt lgkmcnt(1)
	v_mfma_f32_16x16x32_bf16 v[210:213], v[154:157], v[12:15], v[104:107]
	v_mfma_f32_16x16x32_bf16 v[214:217], v[166:169], v[12:15], v[72:75]
	v_mfma_f32_16x16x32_bf16 v[220:223], v[174:177], v[12:15], v[48:51]
	v_mfma_f32_16x16x32_bf16 v[224:227], v[178:181], v[12:15], v[4:7]
	s_waitcnt lgkmcnt(0)
	v_mfma_f32_16x16x32_bf16 v[92:95], v[154:157], v[8:11], v[92:95]
	v_mfma_f32_16x16x32_bf16 v[60:63], v[166:169], v[8:11], v[60:63]
	v_mfma_f32_16x16x32_bf16 v[154:157], v[174:177], v[8:11], v[44:47]
	v_mfma_f32_16x16x32_bf16 v[166:169], v[178:181], v[8:11], v[0:3]
	s_setprio 0
	s_waitcnt vmcnt(5)
	ds_write_b128 v163, v[20:23] offset:36864
	s_waitcnt vmcnt(4)
	ds_write_b128 v163, v[16:19] offset:36960
	s_waitcnt vmcnt(3)
	ds_write_b128 v164, v[36:39] offset:49152
	s_waitcnt vmcnt(2)
	ds_write_b128 v164, v[32:35] offset:49248
	s_waitcnt vmcnt(1)
	ds_write_b128 v164, v[28:31] offset:49344
	s_waitcnt vmcnt(0)
	ds_write_b128 v164, v[24:27] offset:49440
	s_waitcnt lgkmcnt(0)
	s_barrier
	s_setprio 1
	ds_read_b128 v[36:39], v152 offset:36864
	ds_read_b128 v[162:165], v152 offset:38400
	ds_read_b128 v[174:177], v152 offset:39936
	ds_read_b128 v[178:181], v152 offset:41472
	ds_read_b128 v[0:3], v228 offset:49152
	ds_read_b128 v[4:7], v228 offset:50688
	s_waitcnt lgkmcnt(1)
	v_mfma_f32_16x16x32_bf16 v[124:127], v[36:39], v[0:3], v[148:151]
	v_mfma_f32_16x16x32_bf16 v[80:83], v[162:165], v[0:3], v[136:139]
	v_mfma_f32_16x16x32_bf16 v[28:31], v[174:177], v[0:3], v[112:115]
	v_mfma_f32_16x16x32_bf16 v[0:3], v[178:181], v[0:3], v[170:173]
	ds_read_b128 v[8:11], v228 offset:52224
	s_waitcnt lgkmcnt(1)
	v_mfma_f32_16x16x32_bf16 v[120:123], v[36:39], v[4:7], v[144:147]
	v_mfma_f32_16x16x32_bf16 v[72:75], v[162:165], v[4:7], v[128:131]
	v_mfma_f32_16x16x32_bf16 v[32:35], v[174:177], v[4:7], v[100:103]
	v_mfma_f32_16x16x32_bf16 v[4:7], v[178:181], v[4:7], v[68:71]
	ds_read_b128 v[12:15], v228 offset:53760
	s_waitcnt lgkmcnt(1)
	v_mfma_f32_16x16x32_bf16 v[116:119], v[36:39], v[8:11], v[140:143]
	v_mfma_f32_16x16x32_bf16 v[64:67], v[162:165], v[8:11], v[186:189]
	v_mfma_f32_16x16x32_bf16 v[40:43], v[174:177], v[8:11], v[88:91]
	v_mfma_f32_16x16x32_bf16 v[8:11], v[178:181], v[8:11], v[56:59]
	ds_read_b128 v[16:19], v228 offset:55296
	s_waitcnt lgkmcnt(1)
	v_mfma_f32_16x16x32_bf16 v[112:115], v[36:39], v[12:15], v[132:135]
	v_mfma_f32_16x16x32_bf16 v[68:71], v[162:165], v[12:15], v[108:111]
	v_mfma_f32_16x16x32_bf16 v[44:47], v[174:177], v[12:15], v[76:79]
	v_mfma_f32_16x16x32_bf16 v[12:15], v[178:181], v[12:15], v[182:185]
	ds_read_b128 v[20:23], v228 offset:56832
	s_waitcnt lgkmcnt(1)
	v_mfma_f32_16x16x32_bf16 v[108:111], v[36:39], v[16:19], v[190:193]
	v_mfma_f32_16x16x32_bf16 v[76:79], v[162:165], v[16:19], v[96:99]
	v_mfma_f32_16x16x32_bf16 v[48:51], v[174:177], v[16:19], v[194:197]
	v_mfma_f32_16x16x32_bf16 v[16:19], v[178:181], v[16:19], v[198:201]
	ds_read_b128 v[24:27], v228 offset:58368
	s_waitcnt lgkmcnt(1)
	v_mfma_f32_16x16x32_bf16 v[104:107], v[36:39], v[20:23], v[202:205]
	v_mfma_f32_16x16x32_bf16 v[84:87], v[162:165], v[20:23], v[84:87]
	v_mfma_f32_16x16x32_bf16 v[52:55], v[174:177], v[20:23], v[52:55]
	v_mfma_f32_16x16x32_bf16 v[20:23], v[178:181], v[20:23], v[206:209]
	ds_read_b128 v[128:131], v228 offset:59904
	s_waitcnt lgkmcnt(1)
	v_mfma_f32_16x16x32_bf16 v[100:103], v[36:39], v[24:27], v[210:213]
	v_mfma_f32_16x16x32_bf16 v[88:91], v[162:165], v[24:27], v[214:217]
	v_mfma_f32_16x16x32_bf16 v[56:59], v[174:177], v[24:27], v[220:223]
	v_mfma_f32_16x16x32_bf16 v[24:27], v[178:181], v[24:27], v[224:227]
	s_waitcnt lgkmcnt(0)
	v_mfma_f32_16x16x32_bf16 v[96:99], v[36:39], v[128:131], v[92:95]
	v_mfma_f32_16x16x32_bf16 v[92:95], v[162:165], v[128:131], v[60:63]
	v_mfma_f32_16x16x32_bf16 v[60:63], v[174:177], v[128:131], v[154:157]
	v_mfma_f32_16x16x32_bf16 v[36:39], v[178:181], v[128:131], v[166:169]
	s_setprio 0
	s_cmp_lt_i32 s61, 8
	s_barrier
	s_cbranch_scc1 .LBB0_275
	s_cmp_lt_u32 s61, 12
	s_cselect_b64 s[22:23], -1, 0
	s_or_b64 s[24:25], s[22:23], s[16:17]
	s_and_b64 s[22:23], s[22:23], exec
	s_cselect_b32 s22, s48, 0x17b00800
	s_cselect_b32 s62, s47, 0xfffffa00
	s_add_u32 s22, s42, s22
	s_addc_u32 s23, s43, 0
	s_and_b64 vcc, exec, s[24:25]
	s_cbranch_vccnz .LBB0_276
	s_cmp_lt_u32 s61, 20
	s_cbranch_scc1 .LBB0_277
	s_cmp_lt_u32 s61, 22
	s_cselect_b64 s[22:23], -1, 0
	s_or_b64 s[24:25], s[22:23], s[18:19]
	s_and_b64 s[22:23], s[22:23], exec
	s_cselect_b32 s22, s50, 0x21b00800
	s_cselect_b32 s62, s49, 0xfffff500
	s_add_u32 s22, s42, s22
	s_addc_u32 s23, s43, 0
	s_and_b64 vcc, exec, s[24:25]
	s_cbranch_vccnz .LBB0_278
	s_mov_b64 s[24:25], 0x400
	s_mov_b64 s[22:23], s[20:21]
	s_mov_b32 s62, s55
	s_branch .LBB0_279

; DI void store4(u16* dst, f32x4 v) { uint2 w; w.x = cvtpk(v[0], v[1]); w.y = cvtpk(v[2], v[3]); *(uint2*)dst = w; }
; DI f32x4 load4bf(const u16* src) { uint2 w = *(const uint2*)src; return (f32x4){bflo(w.x), bfhi(w.x), bflo(w.y), bfhi(w.y)}; }
; DI float sigmoidf_(float x) { return 1.0f / (1.0f + __expf(-x)); }
; DI void mla_item(const Params& p, int it, unsigned char* smem, u16* mb_out) {
;     ...
;   const u16* mb = (const u16*)(p.ws + OFF_MB);
; #pragma unroll
;   for (int nt = 0; nt < 2; ++nt) {
;     float lt = l[nt]; lt += __shfl_xor(lt, 16); lt += __shfl_xor(lt, 32);
;     const float inv = 1.0f / lt;
;     const size_t t = tb0 + q0 + wave * 32 + nt * 16 + lr;
; #pragma unroll
;     for (int dt = 0; dt < 8; ++dt) {
;       const size_t oidx = t * 1024 + hp * 128 + dt * 16 + lq * 4;
;       const f32x4 gm = load4bf(mb + oidx);
;       const f32x4 ov = (dt < 4) ? Oa[dt & 3][nt] : Ob[dt & 3][nt];
;       f32x4 o;
; #pragma unroll
;       for (int j = 0; j < 4; ++j) o[j] = sigmoidf_(gm[j]) * ov[j] * inv;
;       store4(mb_out + oidx, o);
;     }
;   }
.LBB0_418:
	v_lshl_add_u32 v0, s72, 7, v100
	s_waitcnt vmcnt(7)
	v_lshlrev_b64 v[68:69], 11, v[170:171]
	v_lshl_add_u64 v[2:3], s[2:3], 0, v[68:69]
	v_lshlrev_b64 v[70:71], 1, v[0:1]
	v_lshl_add_u64 v[2:3], v[2:3], 0, v[70:71]
	global_load_dwordx2 v[74:75], v[2:3], off
	s_waitcnt vmcnt(7)
	v_and_b32_e32 v72, 64, v220
	v_xor_b32_e32 v0, 16, v220
	v_add_u32_e32 v72, 64, v72
	v_cmp_lt_i32_e32 vcc, v0, v72
	v_xor_b32_e32 v73, 32, v220
	v_or_b32_e32 v68, 0x8000, v68
	v_cndmask_b32_e32 v0, v220, v0, vcc
	s_waitcnt vmcnt(6)
	v_lshlrev_b32_e32 v79, 2, v0
	ds_bpermute_b32 v0, v79, v169
	v_cmp_lt_i32_e32 vcc, v73, v72
	s_add_i32 s71, s71, s92
	s_waitcnt lgkmcnt(0)
	v_add_f32_e32 v0, v169, v0
	v_cndmask_b32_e32 v72, v220, v73, vcc
	v_lshlrev_b32_e32 v78, 2, v72
	ds_bpermute_b32 v72, v78, v0
	s_waitcnt lgkmcnt(0)
	v_add_f32_e32 v0, v0, v72
	global_load_dwordx2 v[76:77], v[2:3], off offset:32
	global_load_dwordx2 v[80:81], v[2:3], off offset:64
	global_load_dwordx2 v[72:73], v[2:3], off offset:96
	s_waitcnt vmcnt(8)
	s_waitcnt vmcnt(7)
	v_rcp_f32_e32 v0, v0
	s_waitcnt vmcnt(3)
	v_lshlrev_b32_e32 v82, 16, v74
	v_and_b32_e32 v74, 0xffff0000, v74
	v_lshlrev_b32_e32 v83, 16, v75
	v_and_b32_e32 v75, 0xffff0000, v75
	v_mul_f32_e32 v82, 0xbfb8aa3b, v82
	v_mul_f32_e32 v87, 0xbfb8aa3b, v74
	v_mul_f32_e32 v88, 0xbfb8aa3b, v75
	v_exp_f32_e32 v74, v82
	v_exp_f32_e32 v75, v87
	v_mul_f32_e32 v83, 0xbfb8aa3b, v83
	v_exp_f32_e32 v82, v83
	v_exp_f32_e32 v83, v88
	v_pk_add_f32 v[74:75], v[74:75], 1.0 op_sel_hi:[1,0]
	v_pk_add_f32 v[82:83], v[82:83], 1.0 op_sel_hi:[1,0]
	s_mov_b64 vcc, s[0:1]
	v_rcp_f32_e32 v75, v75
	s_mov_b64 vcc, s[4:5]
	v_rcp_f32_e32 v74, v74
	s_mov_b64 vcc, s[6:7]
	v_pk_mul_f32 v[64:65], v[64:65], v[74:75]
	v_rcp_f32_e32 v75, v83
	v_rcp_f32_e32 v74, v82
	s_nop 0
	v_pk_mul_f32 v[66:67], v[66:67], v[74:75]
	s_waitcnt vmcnt(2)
	v_lshlrev_b32_e32 v74, 16, v76
	v_and_b32_e32 v75, 0xffff0000, v76
	v_mul_f32_e32 v74, 0xbfb8aa3b, v74
	v_mul_f32_e32 v75, 0xbfb8aa3b, v75
	v_exp_f32_e32 v74, v74
	v_exp_f32_e32 v75, v75
	v_pk_mul_f32 v[64:65], v[0:1], v[64:65] op_sel_hi:[0,1]
	v_pk_mul_f32 v[66:67], v[0:1], v[66:67] op_sel_hi:[0,1]
	v_cvt_pk_bf16_f32 v64, v64, v65
	v_cvt_pk_bf16_f32 v65, v66, v67
	v_pk_add_f32 v[66:67], v[74:75], 1.0 op_sel_hi:[1,0]
	global_store_dwordx2 v[2:3], v[64:65], off
	v_lshlrev_b32_e32 v64, 16, v77
	v_and_b32_e32 v76, 0xffff0000, v77
	v_mul_f32_e32 v64, 0xbfb8aa3b, v64
	v_rcp_f32_e32 v65, v67
	v_exp_f32_e32 v74, v64
	v_mul_f32_e32 v64, 0xbfb8aa3b, v76
	v_exp_f32_e32 v75, v64
	v_rcp_f32_e32 v64, v66
	v_pk_add_f32 v[74:75], v[74:75], 1.0 op_sel_hi:[1,0]
	v_pk_mul_f32 v[60:61], v[60:61], v[64:65]
	v_pk_mul_f32 v[60:61], v[0:1], v[60:61] op_sel_hi:[0,1]
	v_cvt_pk_bf16_f32 v60, v60, v61
	v_rcp_f32_e32 v65, v75
	v_rcp_f32_e32 v64, v74
	s_nop 0
	v_pk_mul_f32 v[62:63], v[62:63], v[64:65]
	s_waitcnt vmcnt(2)
	v_lshlrev_b32_e32 v64, 16, v80
	v_and_b32_e32 v65, 0xffff0000, v80
	v_mul_f32_e32 v64, 0xbfb8aa3b, v64
	v_mul_f32_e32 v65, 0xbfb8aa3b, v65
	v_exp_f32_e32 v64, v64
	v_exp_f32_e32 v65, v65
	v_pk_mul_f32 v[62:63], v[0:1], v[62:63] op_sel_hi:[0,1]
	v_cvt_pk_bf16_f32 v61, v62, v63
	global_store_dwordx2 v[2:3], v[60:61], off offset:32
	v_pk_add_f32 v[62:63], v[64:65], 1.0 op_sel_hi:[1,0]
	v_lshlrev_b32_e32 v60, 16, v81
	v_and_b32_e32 v66, 0xffff0000, v81
	v_mul_f32_e32 v60, 0xbfb8aa3b, v60
	v_rcp_f32_e32 v61, v63
	v_exp_f32_e32 v64, v60
	v_mul_f32_e32 v60, 0xbfb8aa3b, v66
	v_exp_f32_e32 v65, v60
	v_rcp_f32_e32 v60, v62
	v_pk_add_f32 v[64:65], v[64:65], 1.0 op_sel_hi:[1,0]
	v_pk_mul_f32 v[56:57], v[56:57], v[60:61]
	v_pk_mul_f32 v[60:61], v[0:1], v[56:57] op_sel_hi:[0,1]
	v_cvt_pk_bf16_f32 v60, v60, v61
	v_rcp_f32_e32 v57, v65
	v_rcp_f32_e32 v56, v64
	s_nop 0
	v_pk_mul_f32 v[58:59], v[58:59], v[56:57]
	global_load_dwordx2 v[56:57], v[2:3], off offset:128
	s_waitcnt vmcnt(3)
	v_lshlrev_b32_e32 v62, 16, v72
	v_and_b32_e32 v63, 0xffff0000, v72
	v_mul_f32_e32 v62, 0xbfb8aa3b, v62
	v_mul_f32_e32 v63, 0xbfb8aa3b, v63
	v_exp_f32_e32 v62, v62
	v_exp_f32_e32 v63, v63
	v_pk_mul_f32 v[58:59], v[0:1], v[58:59] op_sel_hi:[0,1]
	v_cvt_pk_bf16_f32 v61, v58, v59
	global_store_dwordx2 v[2:3], v[60:61], off offset:64
	v_pk_add_f32 v[58:59], v[62:63], 1.0 op_sel_hi:[1,0]
	v_lshlrev_b32_e32 v60, 16, v73
	v_and_b32_e32 v61, 0xffff0000, v73
	v_mul_f32_e32 v60, 0xbfb8aa3b, v60
	v_mul_f32_e32 v61, 0xbfb8aa3b, v61
	v_rcp_f32_e32 v59, v59
	v_exp_f32_e32 v60, v60
	v_exp_f32_e32 v61, v61
	s_nop 0
	v_pk_add_f32 v[60:61], v[60:61], 1.0 op_sel_hi:[1,0]
	v_rcp_f32_e32 v58, v58
	s_nop 0
	v_pk_mul_f32 v[52:53], v[52:53], v[58:59]
	v_rcp_f32_e32 v59, v61
	v_pk_mul_f32 v[52:53], v[0:1], v[52:53] op_sel_hi:[0,1]
	v_rcp_f32_e32 v58, v60
	s_nop 0
	v_pk_mul_f32 v[54:55], v[54:55], v[58:59]
	global_load_dwordx2 v[58:59], v[2:3], off offset:160
	global_load_dwordx2 v[60:61], v[2:3], off offset:192
	global_load_dwordx2 v[62:63], v[2:3], off offset:224
	v_pk_mul_f32 v[54:55], v[0:1], v[54:55] op_sel_hi:[0,1]
	v_cvt_pk_bf16_f32 v52, v52, v53
	v_cvt_pk_bf16_f32 v53, v54, v55
	global_store_dwordx2 v[2:3], v[52:53], off offset:96
	s_waitcnt vmcnt(5)
	v_lshlrev_b32_e32 v64, 16, v56
	v_and_b32_e32 v56, 0xffff0000, v56
	v_mul_f32_e32 v64, 0xbfb8aa3b, v64
	v_mul_f32_e32 v56, 0xbfb8aa3b, v56
	v_exp_f32_e32 v64, v64
	v_exp_f32_e32 v65, v56
	v_lshlrev_b32_e32 v52, 16, v57
	v_and_b32_e32 v57, 0xffff0000, v57
	v_mul_f32_e32 v52, 0xbfb8aa3b, v52
	v_pk_add_f32 v[54:55], v[64:65], 1.0 op_sel_hi:[1,0]
	s_nop 0
	s_nop 0
	v_rcp_f32_e32 v53, v55
	v_exp_f32_e32 v56, v52
	v_mul_f32_e32 v52, 0xbfb8aa3b, v57
	v_exp_f32_e32 v57, v52
	v_rcp_f32_e32 v52, v54
	v_pk_add_f32 v[56:57], v[56:57], 1.0 op_sel_hi:[1,0]
	v_pk_mul_f32 v[48:49], v[48:49], v[52:53]
	v_pk_mul_f32 v[48:49], v[0:1], v[48:49] op_sel_hi:[0,1]
	v_cvt_pk_bf16_f32 v48, v48, v49
	v_rcp_f32_e32 v53, v57
	v_rcp_f32_e32 v52, v56
	s_nop 0
	v_pk_mul_f32 v[50:51], v[50:51], v[52:53]
	s_waitcnt vmcnt(3)
; DI void store4(u16* dst, f32x4 v) { uint2 w; w.x = cvtpk(v[0], v[1]); w.y = cvtpk(v[2], v[3]); *(uint2*)dst = w; }
; DI f32x4 load4bf(const u16* src) { uint2 w = *(const uint2*)src; return (f32x4){bflo(w.x), bfhi(w.x), bflo(w.y), bfhi(w.y)}; }
; DI float sigmoidf_(float x) { return 1.0f / (1.0f + __expf(-x)); }
; DI void mla_item(const Params& p, int it, unsigned char* smem, u16* mb_out) {
;     ...
;   const u16* mb = (const u16*)(p.ws + OFF_MB);
; #pragma unroll
;   for (int nt = 0; nt < 2; ++nt) {
;     float lt = l[nt]; lt += __shfl_xor(lt, 16); lt += __shfl_xor(lt, 32);
;     const float inv = 1.0f / lt;
;     const size_t t = tb0 + q0 + wave * 32 + nt * 16 + lr;
; #pragma unroll
;     for (int dt = 0; dt < 8; ++dt) {
;       const size_t oidx = t * 1024 + hp * 128 + dt * 16 + lq * 4;
;       const f32x4 gm = load4bf(mb + oidx);
;       const f32x4 ov = (dt < 4) ? Oa[dt & 3][nt] : Ob[dt & 3][nt];
;       f32x4 o;
; #pragma unroll
;       for (int j = 0; j < 4; ++j) o[j] = sigmoidf_(gm[j]) * ov[j] * inv;
;       store4(mb_out + oidx, o);
;     }
;   }
	v_lshlrev_b32_e32 v52, 16, v58
	v_and_b32_e32 v53, 0xffff0000, v58
	v_mul_f32_e32 v52, 0xbfb8aa3b, v52
	v_mul_f32_e32 v53, 0xbfb8aa3b, v53
	v_exp_f32_e32 v52, v52
	v_exp_f32_e32 v53, v53
	v_pk_mul_f32 v[50:51], v[0:1], v[50:51] op_sel_hi:[0,1]
	v_cvt_pk_bf16_f32 v49, v50, v51
	global_store_dwordx2 v[2:3], v[48:49], off offset:128
	v_pk_add_f32 v[50:51], v[52:53], 1.0 op_sel_hi:[1,0]
	v_lshlrev_b32_e32 v48, 16, v59
	v_and_b32_e32 v54, 0xffff0000, v59
	v_mul_f32_e32 v48, 0xbfb8aa3b, v48
	v_rcp_f32_e32 v49, v51
	v_exp_f32_e32 v52, v48
	v_mul_f32_e32 v48, 0xbfb8aa3b, v54
	v_exp_f32_e32 v53, v48
	v_rcp_f32_e32 v48, v50
	v_pk_add_f32 v[52:53], v[52:53], 1.0 op_sel_hi:[1,0]
	v_pk_mul_f32 v[44:45], v[44:45], v[48:49]
	v_pk_mul_f32 v[44:45], v[0:1], v[44:45] op_sel_hi:[0,1]
	v_cvt_pk_bf16_f32 v44, v44, v45
	v_rcp_f32_e32 v49, v53
	v_rcp_f32_e32 v48, v52
	s_nop 0
	v_pk_mul_f32 v[46:47], v[46:47], v[48:49]
	s_waitcnt vmcnt(3)
	v_lshlrev_b32_e32 v48, 16, v60
	v_and_b32_e32 v49, 0xffff0000, v60
	v_mul_f32_e32 v48, 0xbfb8aa3b, v48
	v_mul_f32_e32 v49, 0xbfb8aa3b, v49
	v_exp_f32_e32 v48, v48
	v_exp_f32_e32 v49, v49
	v_pk_mul_f32 v[46:47], v[0:1], v[46:47] op_sel_hi:[0,1]
	v_cvt_pk_bf16_f32 v45, v46, v47
	global_store_dwordx2 v[2:3], v[44:45], off offset:160
	v_pk_add_f32 v[46:47], v[48:49], 1.0 op_sel_hi:[1,0]
	v_lshlrev_b32_e32 v44, 16, v61
	v_and_b32_e32 v50, 0xffff0000, v61
	v_mul_f32_e32 v44, 0xbfb8aa3b, v44
	v_rcp_f32_e32 v45, v47
	v_exp_f32_e32 v48, v44
	v_mul_f32_e32 v44, 0xbfb8aa3b, v50
	v_exp_f32_e32 v49, v44
	v_rcp_f32_e32 v44, v46
	v_pk_add_f32 v[48:49], v[48:49], 1.0 op_sel_hi:[1,0]
	v_pk_mul_f32 v[40:41], v[40:41], v[44:45]
	v_pk_mul_f32 v[40:41], v[0:1], v[40:41] op_sel_hi:[0,1]
	v_cvt_pk_bf16_f32 v40, v40, v41
	v_rcp_f32_e32 v45, v49
	v_rcp_f32_e32 v44, v48
	s_nop 0
	v_pk_mul_f32 v[42:43], v[42:43], v[44:45]
	s_waitcnt vmcnt(3)
	v_lshlrev_b32_e32 v44, 16, v62
	v_and_b32_e32 v45, 0xffff0000, v62
	v_mul_f32_e32 v44, 0xbfb8aa3b, v44
	v_mul_f32_e32 v45, 0xbfb8aa3b, v45
	v_exp_f32_e32 v44, v44
	v_exp_f32_e32 v45, v45
	v_pk_mul_f32 v[42:43], v[0:1], v[42:43] op_sel_hi:[0,1]
	v_cvt_pk_bf16_f32 v41, v42, v43
	global_store_dwordx2 v[2:3], v[40:41], off offset:192
	v_pk_add_f32 v[44:45], v[44:45], 1.0 op_sel_hi:[1,0]
	v_lshlrev_b32_e32 v48, 16, v63
	v_and_b32_e32 v49, 0xffff0000, v63
	v_lshl_add_u64 v[40:41], s[2:3], 0, v[68:69]
	v_lshl_add_u64 v[40:41], v[40:41], 0, v[70:71]
	global_load_dwordx2 v[42:43], v[40:41], off
	v_rcp_f32_e32 v45, v45
	v_mul_f32_e32 v46, 0xbfb8aa3b, v48
	v_mul_f32_e32 v47, 0xbfb8aa3b, v49
	v_exp_f32_e32 v46, v46
	v_exp_f32_e32 v47, v47
	v_rcp_f32_e32 v44, v44
	v_pk_add_f32 v[46:47], v[46:47], 1.0 op_sel_hi:[1,0]
	v_pk_mul_f32 v[36:37], v[36:37], v[44:45]
	v_pk_mul_f32 v[36:37], v[0:1], v[36:37] op_sel_hi:[0,1]
	v_cvt_pk_bf16_f32 v36, v36, v37
	v_rcp_f32_e32 v45, v47
	ds_bpermute_b32 v47, v79, v168
	s_waitcnt lgkmcnt(0)
	v_add_f32_e32 v47, v168, v47
	ds_bpermute_b32 v48, v78, v47
	v_rcp_f32_e32 v44, v46
	s_nop 0
	v_pk_mul_f32 v[38:39], v[38:39], v[44:45]
	s_waitcnt vmcnt(0)
	v_lshlrev_b32_e32 v44, 16, v42
	v_pk_mul_f32 v[38:39], v[0:1], v[38:39] op_sel_hi:[0,1]
	s_waitcnt lgkmcnt(0)
	v_add_f32_e32 v0, v47, v48
	v_cvt_pk_bf16_f32 v37, v38, v39
	global_store_dwordx2 v[2:3], v[36:37], off offset:224
	global_load_dwordx2 v[2:3], v[40:41], off offset:32
	global_load_dwordx2 v[38:39], v[40:41], off offset:64
	global_load_dwordx2 v[36:37], v[40:41], off offset:96
	v_and_b32_e32 v42, 0xffff0000, v42
	v_mul_f32_e32 v44, 0xbfb8aa3b, v44
	v_mul_f32_e32 v42, 0xbfb8aa3b, v42
	v_exp_f32_e32 v44, v44
	v_exp_f32_e32 v45, v42
	v_rcp_f32_e32 v0, v0
	v_pk_add_f32 v[44:45], v[44:45], 1.0 op_sel_hi:[1,0]
	v_lshlrev_b32_e32 v42, 16, v43
	v_and_b32_e32 v48, 0xffff0000, v43
	v_mul_f32_e32 v42, 0xbfb8aa3b, v42
	v_rcp_f32_e32 v43, v45
	v_exp_f32_e32 v46, v42
	v_mul_f32_e32 v42, 0xbfb8aa3b, v48
	v_exp_f32_e32 v47, v42
	v_rcp_f32_e32 v42, v44
	v_pk_add_f32 v[46:47], v[46:47], 1.0 op_sel_hi:[1,0]
	v_pk_mul_f32 v[32:33], v[32:33], v[42:43]
	v_pk_mul_f32 v[32:33], v[0:1], v[32:33] op_sel_hi:[0,1]
	v_cvt_pk_bf16_f32 v32, v32, v33
	v_rcp_f32_e32 v43, v47
	v_rcp_f32_e32 v42, v46
	s_nop 0
	v_pk_mul_f32 v[34:35], v[34:35], v[42:43]
	s_waitcnt vmcnt(2)
	v_lshlrev_b32_e32 v42, 16, v2
	v_and_b32_e32 v2, 0xffff0000, v2
	v_mul_f32_e32 v42, 0xbfb8aa3b, v42
	v_mul_f32_e32 v2, 0xbfb8aa3b, v2
	v_exp_f32_e32 v42, v42
	v_exp_f32_e32 v43, v2
	v_pk_mul_f32 v[34:35], v[0:1], v[34:35] op_sel_hi:[0,1]
	v_cvt_pk_bf16_f32 v33, v34, v35
	global_store_dwordx2 v[40:41], v[32:33], off
	v_pk_add_f32 v[34:35], v[42:43], 1.0 op_sel_hi:[1,0]
	v_lshlrev_b32_e32 v32, 16, v3
	v_and_b32_e32 v33, 0xffff0000, v3
	v_mul_f32_e32 v32, 0xbfb8aa3b, v32
	v_mul_f32_e32 v33, 0xbfb8aa3b, v33
	v_rcp_f32_e32 v3, v35
	v_exp_f32_e32 v32, v32
	v_exp_f32_e32 v33, v33
	s_nop 0
	v_pk_add_f32 v[32:33], v[32:33], 1.0 op_sel_hi:[1,0]
	v_rcp_f32_e32 v2, v34
	s_nop 0
	v_pk_mul_f32 v[2:3], v[28:29], v[2:3]
	v_rcp_f32_e32 v29, v33
	v_pk_mul_f32 v[2:3], v[0:1], v[2:3] op_sel_hi:[0,1]
	v_rcp_f32_e32 v28, v32
	s_nop 0
	v_pk_mul_f32 v[28:29], v[30:31], v[28:29]
	s_waitcnt vmcnt(2)
	v_lshlrev_b32_e32 v30, 16, v38
	v_and_b32_e32 v31, 0xffff0000, v38
	v_mul_f32_e32 v30, 0xbfb8aa3b, v30
	v_mul_f32_e32 v31, 0xbfb8aa3b, v31
	v_exp_f32_e32 v30, v30
	v_exp_f32_e32 v31, v31
	v_pk_mul_f32 v[28:29], v[0:1], v[28:29] op_sel_hi:[0,1]
	v_cvt_pk_bf16_f32 v2, v2, v3
	v_cvt_pk_bf16_f32 v3, v28, v29
	v_pk_add_f32 v[28:29], v[30:31], 1.0 op_sel_hi:[1,0]
	global_store_dwordx2 v[40:41], v[2:3], off offset:32
	v_lshlrev_b32_e32 v2, 16, v39
	v_and_b32_e32 v32, 0xffff0000, v39
	v_mul_f32_e32 v2, 0xbfb8aa3b, v2
	v_rcp_f32_e32 v3, v29
	v_exp_f32_e32 v30, v2
	v_mul_f32_e32 v2, 0xbfb8aa3b, v32
	v_exp_f32_e32 v31, v2
	v_rcp_f32_e32 v2, v28
	v_pk_add_f32 v[30:31], v[30:31], 1.0 op_sel_hi:[1,0]
	v_pk_mul_f32 v[2:3], v[24:25], v[2:3]
	v_pk_mul_f32 v[24:25], v[0:1], v[2:3] op_sel_hi:[0,1]
	v_cvt_pk_bf16_f32 v24, v24, v25
	v_rcp_f32_e32 v3, v31
	s_waitcnt vmcnt(2)
; DI float sigmoidf_(float x) { return 1.0f / (1.0f + __expf(-x)); }
; DI void store4(u16* dst, f32x4 v) { uint2 w; w.x = cvtpk(v[0], v[1]); w.y = cvtpk(v[2], v[3]); *(uint2*)dst = w; }
; DI f32x4 load4bf(const u16* src) { uint2 w = *(const uint2*)src; return (f32x4){bflo(w.x), bfhi(w.x), bflo(w.y), bfhi(w.y)}; }
; DI void mla_item(const Params& p, int it, unsigned char* smem, u16* mb_out) {
;     ...
;   const u16* mb = (const u16*)(p.ws + OFF_MB);
; #pragma unroll
;   for (int nt = 0; nt < 2; ++nt) {
;     float lt = l[nt]; lt += __shfl_xor(lt, 16); lt += __shfl_xor(lt, 32);
;     const float inv = 1.0f / lt;
;     const size_t t = tb0 + q0 + wave * 32 + nt * 16 + lr;
; #pragma unroll
;     for (int dt = 0; dt < 8; ++dt) {
;       const size_t oidx = t * 1024 + hp * 128 + dt * 16 + lq * 4;
;       const f32x4 gm = load4bf(mb + oidx);
;       const f32x4 ov = (dt < 4) ? Oa[dt & 3][nt] : Ob[dt & 3][nt];
;       f32x4 o;
; #pragma unroll
;       for (int j = 0; j < 4; ++j) o[j] = sigmoidf_(gm[j]) * ov[j] * inv;
;       store4(mb_out + oidx, o);
;     }
;   }
; DI void phase3(const Params& p, int bid, int nblk, unsigned char* smem, u16* mb_out) {
;     ...
;   for (int it = bid; it < 4096; it += nblk) { mla_item(p, it, smem, mb_out); __syncthreads(); }
	v_lshlrev_b32_e32 v28, 16, v36
	v_and_b32_e32 v29, 0xffff0000, v36
	v_rcp_f32_e32 v2, v30
	v_mul_f32_e32 v28, 0xbfb8aa3b, v28
	v_mul_f32_e32 v29, 0xbfb8aa3b, v29
	v_pk_mul_f32 v[26:27], v[26:27], v[2:3]
	global_load_dwordx2 v[2:3], v[40:41], off offset:128
	v_exp_f32_e32 v28, v28
	v_exp_f32_e32 v29, v29
	v_pk_mul_f32 v[26:27], v[0:1], v[26:27] op_sel_hi:[0,1]
	v_cvt_pk_bf16_f32 v25, v26, v27
	global_store_dwordx2 v[40:41], v[24:25], off offset:64
	v_pk_add_f32 v[26:27], v[28:29], 1.0 op_sel_hi:[1,0]
	v_lshlrev_b32_e32 v24, 16, v37
	v_and_b32_e32 v30, 0xffff0000, v37
	v_mul_f32_e32 v24, 0xbfb8aa3b, v24
	v_rcp_f32_e32 v25, v27
	v_exp_f32_e32 v28, v24
	v_mul_f32_e32 v24, 0xbfb8aa3b, v30
	v_exp_f32_e32 v29, v24
	v_rcp_f32_e32 v24, v26
	v_pk_add_f32 v[28:29], v[28:29], 1.0 op_sel_hi:[1,0]
	v_pk_mul_f32 v[20:21], v[20:21], v[24:25]
	v_pk_mul_f32 v[20:21], v[0:1], v[20:21] op_sel_hi:[0,1]
	v_cvt_pk_bf16_f32 v20, v20, v21
	v_rcp_f32_e32 v25, v29
	v_rcp_f32_e32 v24, v28
	s_nop 0
	v_pk_mul_f32 v[22:23], v[22:23], v[24:25]
	global_load_dwordx2 v[24:25], v[40:41], off offset:160
	global_load_dwordx2 v[26:27], v[40:41], off offset:192
	global_load_dwordx2 v[28:29], v[40:41], off offset:224
	v_pk_mul_f32 v[22:23], v[0:1], v[22:23] op_sel_hi:[0,1]
	v_cvt_pk_bf16_f32 v21, v22, v23
	global_store_dwordx2 v[40:41], v[20:21], off offset:96
	s_waitcnt vmcnt(5)
	v_lshlrev_b32_e32 v30, 16, v2
	v_and_b32_e32 v2, 0xffff0000, v2
	v_mul_f32_e32 v30, 0xbfb8aa3b, v30
	v_mul_f32_e32 v2, 0xbfb8aa3b, v2
	v_exp_f32_e32 v30, v30
	v_exp_f32_e32 v31, v2
	v_lshlrev_b32_e32 v20, 16, v3
	v_and_b32_e32 v21, 0xffff0000, v3
	v_mul_f32_e32 v20, 0xbfb8aa3b, v20
	v_pk_add_f32 v[22:23], v[30:31], 1.0 op_sel_hi:[1,0]
	v_mul_f32_e32 v21, 0xbfb8aa3b, v21
	v_exp_f32_e32 v20, v20
	v_exp_f32_e32 v21, v21
	v_rcp_f32_e32 v3, v23
	v_pk_add_f32 v[20:21], v[20:21], 1.0 op_sel_hi:[1,0]
	v_rcp_f32_e32 v2, v22
	s_nop 0
	v_pk_mul_f32 v[2:3], v[16:17], v[2:3]
	v_rcp_f32_e32 v17, v21
	v_pk_mul_f32 v[2:3], v[0:1], v[2:3] op_sel_hi:[0,1]
	v_rcp_f32_e32 v16, v20
	s_nop 0
	v_pk_mul_f32 v[16:17], v[18:19], v[16:17]
	s_waitcnt vmcnt(3)
	v_lshlrev_b32_e32 v18, 16, v24
	v_and_b32_e32 v19, 0xffff0000, v24
	v_mul_f32_e32 v18, 0xbfb8aa3b, v18
	v_mul_f32_e32 v19, 0xbfb8aa3b, v19
	v_exp_f32_e32 v18, v18
	v_exp_f32_e32 v19, v19
	v_pk_mul_f32 v[16:17], v[0:1], v[16:17] op_sel_hi:[0,1]
	v_cvt_pk_bf16_f32 v2, v2, v3
	v_cvt_pk_bf16_f32 v3, v16, v17
	v_pk_add_f32 v[16:17], v[18:19], 1.0 op_sel_hi:[1,0]
	global_store_dwordx2 v[40:41], v[2:3], off offset:128
	v_lshlrev_b32_e32 v2, 16, v25
	v_and_b32_e32 v20, 0xffff0000, v25
	v_mul_f32_e32 v2, 0xbfb8aa3b, v2
	v_rcp_f32_e32 v3, v17
	v_exp_f32_e32 v18, v2
	v_mul_f32_e32 v2, 0xbfb8aa3b, v20
	v_exp_f32_e32 v19, v2
	v_rcp_f32_e32 v2, v16
	v_pk_add_f32 v[18:19], v[18:19], 1.0 op_sel_hi:[1,0]
	v_pk_mul_f32 v[2:3], v[12:13], v[2:3]
	v_pk_mul_f32 v[2:3], v[0:1], v[2:3] op_sel_hi:[0,1]
	v_cvt_pk_bf16_f32 v2, v2, v3
	v_rcp_f32_e32 v13, v19
	v_rcp_f32_e32 v12, v18
	s_nop 0
	v_pk_mul_f32 v[12:13], v[14:15], v[12:13]
	s_waitcnt vmcnt(3)
	v_lshlrev_b32_e32 v14, 16, v26
	v_and_b32_e32 v15, 0xffff0000, v26
	v_mul_f32_e32 v14, 0xbfb8aa3b, v14
	v_mul_f32_e32 v15, 0xbfb8aa3b, v15
	v_exp_f32_e32 v14, v14
	v_exp_f32_e32 v15, v15
	v_pk_mul_f32 v[12:13], v[0:1], v[12:13] op_sel_hi:[0,1]
	v_cvt_pk_bf16_f32 v3, v12, v13
	global_store_dwordx2 v[40:41], v[2:3], off offset:160
	v_pk_add_f32 v[12:13], v[14:15], 1.0 op_sel_hi:[1,0]
	v_lshlrev_b32_e32 v2, 16, v27
	v_and_b32_e32 v16, 0xffff0000, v27
	v_mul_f32_e32 v2, 0xbfb8aa3b, v2
	v_rcp_f32_e32 v3, v13
	v_exp_f32_e32 v14, v2
	v_mul_f32_e32 v2, 0xbfb8aa3b, v16
	v_exp_f32_e32 v15, v2
	v_rcp_f32_e32 v2, v12
	v_pk_add_f32 v[14:15], v[14:15], 1.0 op_sel_hi:[1,0]
	v_pk_mul_f32 v[2:3], v[8:9], v[2:3]
	v_pk_mul_f32 v[2:3], v[0:1], v[2:3] op_sel_hi:[0,1]
	v_cvt_pk_bf16_f32 v2, v2, v3
	v_rcp_f32_e32 v9, v15
	v_rcp_f32_e32 v8, v14
	s_nop 0
	v_pk_mul_f32 v[8:9], v[10:11], v[8:9]
	s_waitcnt vmcnt(3)
	v_lshlrev_b32_e32 v10, 16, v28
	v_and_b32_e32 v11, 0xffff0000, v28
	v_mul_f32_e32 v10, 0xbfb8aa3b, v10
	v_mul_f32_e32 v11, 0xbfb8aa3b, v11
	v_exp_f32_e32 v10, v10
	v_exp_f32_e32 v11, v11
	v_pk_mul_f32 v[8:9], v[0:1], v[8:9] op_sel_hi:[0,1]
	v_cvt_pk_bf16_f32 v3, v8, v9
	global_store_dwordx2 v[40:41], v[2:3], off offset:192
	v_pk_add_f32 v[8:9], v[10:11], 1.0 op_sel_hi:[1,0]
	v_lshlrev_b32_e32 v2, 16, v29
	v_and_b32_e32 v12, 0xffff0000, v29
	v_mul_f32_e32 v2, 0xbfb8aa3b, v2
	v_rcp_f32_e32 v3, v9
	v_exp_f32_e32 v10, v2
	v_mul_f32_e32 v2, 0xbfb8aa3b, v12
	v_exp_f32_e32 v11, v2
	v_rcp_f32_e32 v2, v8
	v_pk_add_f32 v[10:11], v[10:11], 1.0 op_sel_hi:[1,0]
	v_pk_mul_f32 v[2:3], v[4:5], v[2:3]
	v_pk_mul_f32 v[2:3], v[0:1], v[2:3] op_sel_hi:[0,1]
	v_cvt_pk_bf16_f32 v2, v2, v3
	v_rcp_f32_e32 v5, v11
	v_readlane_b32 s0, v245, 23
	v_rcp_f32_e32 v4, v10
	s_nop 0
	v_pk_mul_f32 v[4:5], v[6:7], v[4:5]
	s_add_i32 s70, s70, s0
	v_pk_mul_f32 v[4:5], v[0:1], v[4:5] op_sel_hi:[0,1]
	v_cvt_pk_bf16_f32 v3, v4, v5
	s_cmpk_lt_i32 s71, 0x1000
	global_store_dwordx2 v[40:41], v[2:3], off offset:224
	s_barrier
	v_readlane_b32 s1, v245, 24
	s_cbranch_scc0 .LBB0_463

; DI float ex2(float x) { return __builtin_amdgcn_exp2f(x); }
; DI void cmp_item(const Params& p, int it, unsigned char* smem) {
;     ...
;     mx = fmaxf(mx, __shfl_xor(mx, 16)); mx = fmaxf(mx, __shfl_xor(mx, 32));
;     float sum = 0.f;
; #pragma unroll
;     for (int mt = 0; mt < 8; ++mt)
; #pragma unroll
;       for (int j = 0; j < 4; ++j) { const float s2 = S[mt][j]; const float pv = (s2 > -1e29f) ? ex2(s2 - mx) : 0.f; S[mt][j] = pv; sum += pv; }
;     sum += __shfl_xor(sum, 16); sum += __shfl_xor(sum, 32);
.LBB0_535:
	s_or_b64 exec, exec, vcc
	s_nop 1
	ds_bpermute_b32 v12, v40, v36
	v_max_f32_e32 v13, v36, v36
	v_cmp_lt_f32_e32 vcc, s33, v0
	s_waitcnt lgkmcnt(0)
	v_max_f32_e32 v12, v12, v12
	v_max_f32_e32 v12, v13, v12
	ds_bpermute_b32 v13, v91, v12
	s_waitcnt lgkmcnt(0)
	v_max_f32_e32 v13, v13, v13
	v_max_f32_e32 v36, v12, v13
	v_sub_f32_e32 v12, v0, v36
	v_sub_f32_e32 v13, v1, v36
	v_exp_f32_e32 v12, v12
	v_sub_f32_e32 v14, v2, v36
	v_exp_f32_e32 v13, v13
	v_exp_f32_e32 v14, v14
	v_sub_f32_e32 v15, v3, v36
	v_cndmask_b32_e32 v0, 0, v12, vcc
	v_cmp_lt_f32_e32 vcc, s33, v1
	v_exp_f32_e32 v15, v15
	v_add_f32_e32 v12, 0, v0
	v_cndmask_b32_e32 v1, 0, v13, vcc
	v_cmp_lt_f32_e32 vcc, s33, v2
	v_sub_f32_e32 v13, v4, v36
	v_exp_f32_e32 v13, v13
	v_cndmask_b32_e32 v2, 0, v14, vcc
	v_sub_f32_e32 v14, v5, v36
	v_exp_f32_e32 v14, v14
	v_cmp_lt_f32_e32 vcc, s33, v3
	v_add_f32_e32 v12, v1, v12
	v_add_f32_e32 v12, v2, v12
	v_cndmask_b32_e32 v3, 0, v15, vcc
	v_cmp_lt_f32_e32 vcc, s33, v4
	v_add_f32_e32 v12, v3, v12
	s_nop 0
	v_cndmask_b32_e32 v4, 0, v13, vcc
	v_cmp_lt_f32_e32 vcc, s33, v5
	v_sub_f32_e32 v13, v6, v36
	v_exp_f32_e32 v13, v13
	v_cndmask_b32_e32 v5, 0, v14, vcc
	v_sub_f32_e32 v14, v7, v36
	v_exp_f32_e32 v14, v14
	v_add_f32_e32 v12, v4, v12
	v_cmp_lt_f32_e32 vcc, s33, v6
	v_add_f32_e32 v12, v5, v12
	s_nop 0
	v_cndmask_b32_e32 v6, 0, v13, vcc
	v_cmp_lt_f32_e32 vcc, s33, v7
	v_add_f32_e32 v12, v6, v12
	s_nop 0
	v_cndmask_b32_e32 v7, 0, v14, vcc
	v_add_f32_e32 v13, v7, v12
	v_sub_f32_e32 v12, v16, v36
	v_exp_f32_e32 v12, v12
	v_sub_f32_e32 v14, v17, v36
	v_exp_f32_e32 v14, v14
	v_cmp_lt_f32_e32 vcc, s33, v16
	v_sub_f32_e32 v16, v19, v36
	v_exp_f32_e32 v16, v16
	v_cndmask_b32_e32 v12, 0, v12, vcc
	v_cmp_lt_f32_e32 vcc, s33, v17
	v_add_f32_e32 v15, v12, v13
	s_nop 0
	v_cndmask_b32_e32 v13, 0, v14, vcc
	v_sub_f32_e32 v14, v18, v36
	v_exp_f32_e32 v14, v14
	v_cmp_lt_f32_e32 vcc, s33, v18
	v_add_f32_e32 v15, v13, v15
	v_sub_f32_e32 v18, v21, v36
	v_cndmask_b32_e32 v14, 0, v14, vcc
	v_cmp_lt_f32_e32 vcc, s33, v19
	v_add_f32_e32 v17, v14, v15
	v_exp_f32_e32 v18, v18
	v_cndmask_b32_e32 v15, 0, v16, vcc
	v_sub_f32_e32 v16, v20, v36
	v_exp_f32_e32 v16, v16
	v_cmp_lt_f32_e32 vcc, s33, v20
	v_add_f32_e32 v17, v15, v17
	v_sub_f32_e32 v20, v23, v36
	v_cndmask_b32_e32 v16, 0, v16, vcc
	v_cmp_lt_f32_e32 vcc, s33, v21
	v_add_f32_e32 v19, v16, v17
	v_exp_f32_e32 v20, v20
	v_cndmask_b32_e32 v17, 0, v18, vcc
	v_sub_f32_e32 v18, v22, v36
	v_exp_f32_e32 v18, v18
	v_cmp_lt_f32_e32 vcc, s33, v22
	v_add_f32_e32 v19, v17, v19
	v_sub_f32_e32 v22, v25, v36
	v_cndmask_b32_e32 v18, 0, v18, vcc
	v_cmp_lt_f32_e32 vcc, s33, v23
	v_add_f32_e32 v21, v18, v19
	v_exp_f32_e32 v22, v22
	v_cndmask_b32_e32 v19, 0, v20, vcc
	v_sub_f32_e32 v20, v24, v36
	v_exp_f32_e32 v20, v20
	v_cmp_lt_f32_e32 vcc, s33, v24
	v_add_f32_e32 v21, v19, v21
	v_sub_f32_e32 v24, v27, v36
	v_cndmask_b32_e32 v20, 0, v20, vcc
	v_cmp_lt_f32_e32 vcc, s33, v25
	v_add_f32_e32 v23, v20, v21
	v_exp_f32_e32 v24, v24
	v_cndmask_b32_e32 v21, 0, v22, vcc
	v_sub_f32_e32 v22, v26, v36
	v_exp_f32_e32 v22, v22
	v_cmp_lt_f32_e32 vcc, s33, v26
	v_add_f32_e32 v23, v21, v23
	v_sub_f32_e32 v26, v29, v36
	v_cndmask_b32_e32 v22, 0, v22, vcc
	v_cmp_lt_f32_e32 vcc, s33, v27
	v_add_f32_e32 v25, v22, v23
	v_exp_f32_e32 v26, v26
	v_cndmask_b32_e32 v23, 0, v24, vcc
	v_sub_f32_e32 v24, v28, v36
	v_exp_f32_e32 v24, v24
	v_cmp_lt_f32_e32 vcc, s33, v28
	v_add_f32_e32 v25, v23, v25
	v_sub_f32_e32 v28, v31, v36
	v_cndmask_b32_e32 v24, 0, v24, vcc
	v_cmp_lt_f32_e32 vcc, s33, v29
	v_add_f32_e32 v27, v24, v25
	v_exp_f32_e32 v28, v28
	v_cndmask_b32_e32 v25, 0, v26, vcc
	v_sub_f32_e32 v26, v30, v36
	v_exp_f32_e32 v26, v26
	v_cmp_lt_f32_e32 vcc, s33, v30
	v_add_f32_e32 v27, v25, v27
	v_sub_f32_e32 v30, v33, v36
	v_cndmask_b32_e32 v26, 0, v26, vcc
	v_cmp_lt_f32_e32 vcc, s33, v31
	v_add_f32_e32 v29, v26, v27
	v_exp_f32_e32 v30, v30
	v_cndmask_b32_e32 v27, 0, v28, vcc
	v_sub_f32_e32 v28, v32, v36
	v_exp_f32_e32 v28, v28
	v_cmp_lt_f32_e32 vcc, s33, v32
	v_add_f32_e32 v29, v27, v29
	v_sub_f32_e32 v32, v35, v36
	v_cndmask_b32_e32 v28, 0, v28, vcc
	v_cmp_lt_f32_e32 vcc, s33, v33
	v_add_f32_e32 v31, v28, v29
	v_exp_f32_e32 v32, v32
	v_cndmask_b32_e32 v29, 0, v30, vcc
	v_sub_f32_e32 v30, v34, v36
	v_exp_f32_e32 v30, v30
	v_cmp_lt_f32_e32 vcc, s33, v34
	v_add_f32_e32 v31, v29, v31
	v_sub_f32_e32 v34, v9, v36
	v_cndmask_b32_e32 v30, 0, v30, vcc
	v_cmp_lt_f32_e32 vcc, s33, v35
	v_add_f32_e32 v33, v30, v31
	v_exp_f32_e32 v34, v34
	v_cndmask_b32_e32 v31, 0, v32, vcc
	v_add_f32_e32 v32, v31, v33
	v_sub_f32_e32 v33, v8, v36
	v_exp_f32_e32 v33, v33
	v_cmp_lt_f32_e32 vcc, s33, v8
	s_nop 1
	v_cndmask_b32_e32 v8, 0, v33, vcc
	v_cmp_lt_f32_e32 vcc, s33, v9
	v_sub_f32_e32 v33, v10, v36
	v_exp_f32_e32 v33, v33
	v_cndmask_b32_e32 v9, 0, v34, vcc
	v_sub_f32_e32 v34, v11, v36
	v_exp_f32_e32 v34, v34
	v_add_f32_e32 v32, v8, v32
	v_cmp_lt_f32_e32 vcc, s33, v10
	v_add_f32_e32 v32, v9, v32
	s_nop 0
	v_cndmask_b32_e32 v10, 0, v33, vcc
	v_cmp_lt_f32_e32 vcc, s33, v11
	v_add_f32_e32 v32, v10, v32
	s_nop 0
	v_cndmask_b32_e32 v11, 0, v34, vcc
	v_add_f32_e32 v32, v11, v32
	ds_bpermute_b32 v33, v40, v32
	s_waitcnt lgkmcnt(0)
	v_add_f32_e32 v32, v32, v33
	ds_bpermute_b32 v33, v91, v32
	s_waitcnt lgkmcnt(0)
; DI float bf2f(u16 v) { return __uint_as_float(((unsigned)v) << 16); }
; DI float sigmoidf_(float x) { return 1.0f / (1.0f + __expf(-x)); }
; DI void store4(u16* dst, f32x4 v) { uint2 w; w.x = cvtpk(v[0], v[1]); w.y = cvtpk(v[2], v[3]); *(uint2*)dst = w; }
; DI float ex2(float x) { return __builtin_amdgcn_exp2f(x); }
; DI void cmp_item(const Params& p, int it, unsigned char* smem) {
;     ...
;       for (int j = 0; j < 4; ++j) { const float s2 = S[mt][j]; const float pv = (s2 > -1e29f) ? ex2(s2 - mx) : 0.f; S[mt][j] = pv; sum += pv; }
;     sum += __shfl_xor(sum, 16); sum += __shfl_xor(sum, 32);
;     const float inv = sum > 0.f ? 1.0f / sum : 0.f;
; #pragma unroll
;     for (int mt = 0; mt < 8; ++mt) { S[mt] = S[mt] * inv; Ps[mt] = Ps[mt] + S[mt]; }
;     f32x4 O[4][1];
; #pragma unroll
;     for (int dt = 0; dt < 4; ++dt) O[dt][0] = (f32x4){0.f, 0.f, 0.f, 0.f};
;     __builtin_amdgcn_s_setprio(1);
; #pragma unroll
;     for (int kk = 0; kk < 4; ++kk) { bf16x8 pb[1]; pb[0] = pack8(S[2 * kk], S[2 * kk + 1]); pv32<1, KST>(O, Vs, kk * 32, 0, pb, lr, lq); }
;     __builtin_amdgcn_s_setprio(0);
;     const float g0 = sigmoidf_(bf2f(mkv[t * 256 + 160 + h * 3 + 0]));
; #pragma unroll
;     for (int dt = 0; dt < 4; ++dt) store4(abuf + t * 1024 + h * 64 + dt * 16 + lq * 4, O[dt][0] * g0);
	v_add_f32_e32 v32, v32, v33
	s_nop 0
	v_rcp_f32_e32 v33, v32
	v_cmp_lt_f32_e32 vcc, 0, v32
	s_nop 1
	v_cndmask_b32_e32 v32, 0, v33, vcc
	v_pk_fma_f32 v[52:53], v[2:3], v[32:33], v[52:53] op_sel_hi:[1,0,1]
	v_pk_fma_f32 v[50:51], v[0:1], v[32:33], v[50:51] op_sel_hi:[1,0,1]
	v_pk_fma_f32 v[54:55], v[6:7], v[32:33], v[54:55] op_sel_hi:[1,0,1]
	v_pk_fma_f32 v[56:57], v[4:5], v[32:33], v[56:57] op_sel_hi:[1,0,1]
	v_pk_fma_f32 v[58:59], v[14:15], v[32:33], v[58:59] op_sel_hi:[1,0,1]
	v_pk_fma_f32 v[62:63], v[12:13], v[32:33], v[62:63] op_sel_hi:[1,0,1]
	v_pk_fma_f32 v[60:61], v[18:19], v[32:33], v[60:61] op_sel_hi:[1,0,1]
	v_pk_fma_f32 v[64:65], v[16:17], v[32:33], v[64:65] op_sel_hi:[1,0,1]
	v_pk_fma_f32 v[66:67], v[22:23], v[32:33], v[66:67] op_sel_hi:[1,0,1]
	v_pk_fma_f32 v[70:71], v[20:21], v[32:33], v[70:71] op_sel_hi:[1,0,1]
	v_pk_fma_f32 v[68:69], v[26:27], v[32:33], v[68:69] op_sel_hi:[1,0,1]
	v_pk_fma_f32 v[72:73], v[24:25], v[32:33], v[72:73] op_sel_hi:[1,0,1]
	v_pk_fma_f32 v[74:75], v[30:31], v[32:33], v[74:75] op_sel_hi:[1,0,1]
	v_pk_fma_f32 v[78:79], v[28:29], v[32:33], v[78:79] op_sel_hi:[1,0,1]
	v_pk_fma_f32 v[76:77], v[10:11], v[32:33], v[76:77] op_sel_hi:[1,0,1]
	v_pk_fma_f32 v[80:81], v[8:9], v[32:33], v[80:81] op_sel_hi:[1,0,1]
	v_pk_mul_f32 v[34:35], v[2:3], v[32:33] op_sel_hi:[1,0]
	v_pk_mul_f32 v[36:37], v[0:1], v[32:33] op_sel_hi:[1,0]
	v_pk_mul_f32 v[38:39], v[6:7], v[32:33] op_sel_hi:[1,0]
	v_pk_mul_f32 v[2:3], v[4:5], v[32:33] op_sel_hi:[1,0]
	v_pk_mul_f32 v[134:135], v[14:15], v[32:33] op_sel_hi:[1,0]
	v_pk_mul_f32 v[136:137], v[12:13], v[32:33] op_sel_hi:[1,0]
	v_pk_mul_f32 v[138:139], v[18:19], v[32:33] op_sel_hi:[1,0]
	v_pk_mul_f32 v[140:141], v[16:17], v[32:33] op_sel_hi:[1,0]
	v_pk_mul_f32 v[142:143], v[22:23], v[32:33] op_sel_hi:[1,0]
	v_pk_mul_f32 v[144:145], v[20:21], v[32:33] op_sel_hi:[1,0]
	v_pk_mul_f32 v[146:147], v[26:27], v[32:33] op_sel_hi:[1,0]
	v_pk_mul_f32 v[148:149], v[24:25], v[32:33] op_sel_hi:[1,0]
	v_pk_mul_f32 v[150:151], v[30:31], v[32:33] op_sel_hi:[1,0]
	v_pk_mul_f32 v[152:153], v[28:29], v[32:33] op_sel_hi:[1,0]
	v_pk_mul_f32 v[154:155], v[10:11], v[32:33] op_sel_hi:[1,0]
	v_pk_mul_f32 v[156:157], v[8:9], v[32:33] op_sel_hi:[1,0]
	s_setprio 1
	v_cvt_pk_bf16_f32 v0, v36, v37
	v_cvt_pk_bf16_f32 v1, v34, v35
	v_cvt_pk_bf16_f32 v2, v2, v3
	v_cvt_pk_bf16_f32 v3, v38, v39
	ds_read_b64_tr_b16 v[16:17], v97
	ds_read_b64_tr_b16 v[18:19], v97 offset:0xa00
	ds_read_b64_tr_b16 v[12:13], v97 offset:32
	ds_read_b64_tr_b16 v[14:15], v97 offset:0xa20
	ds_read_b64_tr_b16 v[8:9], v97 offset:64
	ds_read_b64_tr_b16 v[10:11], v97 offset:0xa40
	ds_read_b64_tr_b16 v[4:5], v97 offset:96
	ds_read_b64_tr_b16 v[6:7], v97 offset:0xa60
	s_waitcnt lgkmcnt(0)
	ds_read_b64_tr_b16 v[32:33], v98
	ds_read_b64_tr_b16 v[34:35], v98 offset:0xa00
	ds_read_b64_tr_b16 v[28:29], v98 offset:32
	ds_read_b64_tr_b16 v[30:31], v98 offset:0xa20
	ds_read_b64_tr_b16 v[24:25], v98 offset:64
	ds_read_b64_tr_b16 v[26:27], v98 offset:0xa40
	ds_read_b64_tr_b16 v[20:21], v98 offset:96
	ds_read_b64_tr_b16 v[22:23], v98 offset:0xa60
	s_waitcnt lgkmcnt(0)
	s_nop 1
	v_mfma_f32_16x16x32_bf16 v[16:19], v[16:19], v[0:3], 0
	v_mfma_f32_16x16x32_bf16 v[12:15], v[12:15], v[0:3], 0
	v_mfma_f32_16x16x32_bf16 v[8:11], v[8:11], v[0:3], 0
	v_mfma_f32_16x16x32_bf16 v[0:3], v[4:7], v[0:3], 0
	v_cvt_pk_bf16_f32 v4, v136, v137
	v_cvt_pk_bf16_f32 v5, v134, v135
	v_cvt_pk_bf16_f32 v6, v140, v141
	v_cvt_pk_bf16_f32 v7, v138, v139
	s_nop 1
	v_mfma_f32_16x16x32_bf16 v[16:19], v[32:35], v[4:7], v[16:19]
	v_mfma_f32_16x16x32_bf16 v[12:15], v[28:31], v[4:7], v[12:15]
	v_mfma_f32_16x16x32_bf16 v[8:11], v[24:27], v[4:7], v[8:11]
	v_mfma_f32_16x16x32_bf16 v[0:3], v[20:23], v[4:7], v[0:3]
	v_cvt_pk_bf16_f32 v4, v144, v145
	v_cvt_pk_bf16_f32 v5, v142, v143
	v_cvt_pk_bf16_f32 v6, v148, v149
	v_cvt_pk_bf16_f32 v7, v146, v147
	ds_read_b64_tr_b16 v[32:33], v99
	ds_read_b64_tr_b16 v[34:35], v99 offset:0xa00
	ds_read_b64_tr_b16 v[28:29], v99 offset:32
	ds_read_b64_tr_b16 v[30:31], v99 offset:0xa20
	ds_read_b64_tr_b16 v[24:25], v99 offset:64
	ds_read_b64_tr_b16 v[26:27], v99 offset:0xa40
	ds_read_b64_tr_b16 v[20:21], v99 offset:96
	ds_read_b64_tr_b16 v[22:23], v99 offset:0xa60
	s_waitcnt lgkmcnt(0)
	s_nop 1
	v_mfma_f32_16x16x32_bf16 v[16:19], v[32:35], v[4:7], v[16:19]
	v_mfma_f32_16x16x32_bf16 v[12:15], v[28:31], v[4:7], v[12:15]
	v_mfma_f32_16x16x32_bf16 v[8:11], v[24:27], v[4:7], v[8:11]
	v_mfma_f32_16x16x32_bf16 v[0:3], v[20:23], v[4:7], v[0:3]
	v_cvt_pk_bf16_f32 v4, v152, v153
	v_cvt_pk_bf16_f32 v5, v150, v151
	v_cvt_pk_bf16_f32 v6, v156, v157
	v_cvt_pk_bf16_f32 v7, v154, v155
	ds_read_b64_tr_b16 v[32:33], v100
	ds_read_b64_tr_b16 v[34:35], v100 offset:0xa00
	ds_read_b64_tr_b16 v[28:29], v100 offset:32
	ds_read_b64_tr_b16 v[30:31], v100 offset:0xa20
	ds_read_b64_tr_b16 v[24:25], v100 offset:64
	ds_read_b64_tr_b16 v[26:27], v100 offset:0xa40
	ds_read_b64_tr_b16 v[20:21], v100 offset:96
	ds_read_b64_tr_b16 v[22:23], v100 offset:0xa60
	s_waitcnt lgkmcnt(0)
	s_nop 1
	v_mfma_f32_16x16x32_bf16 v[16:19], v[32:35], v[4:7], v[16:19]
	v_mfma_f32_16x16x32_bf16 v[12:15], v[28:31], v[4:7], v[12:15]
	v_mfma_f32_16x16x32_bf16 v[8:11], v[24:27], v[4:7], v[8:11]
	v_mfma_f32_16x16x32_bf16 v[0:3], v[20:23], v[4:7], v[0:3]
	s_setprio 0
	v_lshl_add_u64 v[4:5], s[42:43], 0, v[82:83]
	global_load_ushort v4, v[4:5], off
	s_addk_i32 s97, 0x200
	v_lshl_add_u64 v[82:83], v[82:83], 0, 6
	v_lshl_add_u64 v[46:47], v[46:47], 0, s[94:95]
	s_cmpk_eq_i32 s97, 0x800
	s_waitcnt vmcnt(0)
	v_lshlrev_b32_e32 v4, 16, v4
	v_mul_f32_e32 v4, 0xbfb8aa3b, v4
	v_exp_f32_e32 v4, v4
	s_nop 0
	v_add_f32_e32 v4, 1.0, v4
	v_div_scale_f32 v5, s[4:5], v4, v4, 1.0
	v_rcp_f32_e32 v6, v5
	s_nop 0
	v_fma_f32 v7, -v5, v6, 1.0
	v_fmac_f32_e32 v6, v7, v6
	v_div_scale_f32 v7, vcc, 1.0, v4, 1.0
	v_mul_f32_e32 v20, v7, v6
	v_fma_f32 v21, -v5, v20, v7
	v_fmac_f32_e32 v20, v21, v6
	v_fma_f32 v5, -v5, v20, v7
	v_div_fmas_f32 v5, v5, v6, v20
	v_rcp_f32_e32 v4, v4
	s_nop 0
	v_pk_mul_f32 v[18:19], v[18:19], v[4:5] op_sel_hi:[1,0]
	v_pk_mul_f32 v[16:17], v[16:17], v[4:5] op_sel_hi:[1,0]
	v_pk_mul_f32 v[14:15], v[14:15], v[4:5] op_sel_hi:[1,0]
	v_pk_mul_f32 v[12:13], v[12:13], v[4:5] op_sel_hi:[1,0]
	v_pk_mul_f32 v[10:11], v[10:11], v[4:5] op_sel_hi:[1,0]
	v_pk_mul_f32 v[8:9], v[8:9], v[4:5] op_sel_hi:[1,0]
	v_pk_mul_f32 v[2:3], v[2:3], v[4:5] op_sel_hi:[1,0]
	v_pk_mul_f32 v[0:1], v[0:1], v[4:5] op_sel_hi:[1,0]
	v_lshl_add_u64 v[6:7], s[42:43], 0, v[48:49]
	v_cvt_pk_bf16_f32 v16, v16, v17
	v_cvt_pk_bf16_f32 v17, v18, v19
	v_cvt_pk_bf16_f32 v12, v12, v13
	v_cvt_pk_bf16_f32 v13, v14, v15
	v_cvt_pk_bf16_f32 v8, v8, v9
	v_cvt_pk_bf16_f32 v9, v10, v11
	v_cvt_pk_bf16_f32 v0, v0, v1
	v_cvt_pk_bf16_f32 v1, v2, v3
	v_lshl_add_u64 v[48:49], v[48:49], 0, s[94:95]
	global_store_dwordx2 v[6:7], v[16:17], off offset:-64
	global_store_dwordx2 v[6:7], v[12:13], off offset:-32
	global_store_dwordx2 v[6:7], v[8:9], off
	global_store_dwordx2 v[6:7], v[0:1], off offset:32
	s_cbranch_scc1 .LBB0_632

; DI void store4(u16* dst, f32x4 v) { uint2 w; w.x = cvtpk(v[0], v[1]); w.y = cvtpk(v[2], v[3]); *(uint2*)dst = w; }
; DI f32x4 load4bf(const u16* src) { uint2 w = *(const uint2*)src; return (f32x4){bflo(w.x), bfhi(w.x), bflo(w.y), bfhi(w.y)}; }
; DI float sigmoidf_(float x) { return 1.0f / (1.0f + __expf(-x)); }
; DI void selwin_item(const Params& p, int it, unsigned char* smem, u16* y_out) {
;     ...
;   const u16* ma = (const u16*)(p.ws + OFF_MA); const u16* mbp = (const u16*)(p.ws + OFF_MB); const u16* ab = (const u16*)(p.ws + OFF_HBUF);
; #pragma unroll
;   for (int nt = 0; nt < 2; ++nt) {
;     const size_t t = tb0 + s0 + nt * 16 + lr;
; #pragma unroll
;     for (int dt = 0; dt < 4; ++dt) {
;       const size_t idx = t * 1024 + h * 64 + dt * 16 + lq * 4;
;       const f32x4 a = load4bf(ab + idx), mav = load4bf(ma + idx), mbv = load4bf(mbp + idx);
;       f32x4 y;
; #pragma unroll
;       for (int j = 0; j < 4; ++j) y[j] = sigmoidf_(mav[j]) * (a[j] + Ores[dt][nt][j]) + mbv[j];
;       { const int col = h * 64 + dt * 16 + lq * 4; store4(y_out + ((size_t)(col >> 5) * Tn + t) * 32 + (col & 31), y); }
;     }
;   }
.LBB0_691:
	v_or_b32_e32 v136, v136, v151
	v_lshlrev_b64 v[0:1], 10, v[152:153]
	v_lshl_add_u64 v[0:1], v[0:1], 0, v[136:137]
	v_readlane_b32 s8, v245, 25
	v_lshlrev_b64 v[4:5], 1, v[0:1]
	v_readlane_b32 s9, v245, 26
	v_lshlrev_b64 v[2:3], 6, v[152:153]
	v_lshl_add_u64 v[6:7], s[16:17], 0, v[2:3]
	v_lshl_add_u64 v[0:1], s[8:9], 0, v[4:5]
	global_load_dwordx2 v[10:11], v[0:1], off
	v_lshl_add_u64 v[0:1], s[22:23], 0, v[4:5]
	global_load_dwordx2 v[12:13], v[0:1], off
	v_lshl_add_u64 v[0:1], s[2:3], 0, v[4:5]
	global_load_dwordx2 v[14:15], v[0:1], off
	v_lshlrev_b32_e32 v0, 1, v150
	v_ashrrev_i32_e32 v1, 31, v0
	v_lshlrev_b64 v[2:3], 22, v[0:1]
	v_pk_add_f32 v[16:17], v[160:161], v[78:79]
	v_pk_add_f32 v[18:19], v[162:163], v[76:77]
	v_lshlrev_b32_e32 v120, 1, v151
	v_lshl_add_u64 v[8:9], v[6:7], 0, v[2:3]
	v_or_b32_e32 v20, 32, v4
	v_mov_b32_e32 v21, v5
	v_lshl_add_u64 v[8:9], v[8:9], 0, v[120:121]
	v_lshl_add_u64 v[22:23], s[8:9], 0, v[20:21]
	v_or_b32_e32 v0, 1, v0
	s_add_i32 s58, s58, s92
	s_cmpk_lt_i32 s58, 0x2000
	s_waitcnt vmcnt(2)
	v_lshlrev_b32_e32 v24, 16, v10
	v_and_b32_e32 v25, 0xffff0000, v10
	s_waitcnt vmcnt(1)
	v_lshlrev_b32_e32 v1, 16, v12
	v_and_b32_e32 v26, 0xffff0000, v12
	v_lshlrev_b32_e32 v27, 16, v13
	v_mul_f32_e32 v1, 0xbfb8aa3b, v1
	v_mul_f32_e32 v29, 0xbfb8aa3b, v26
	v_and_b32_e32 v28, 0xffff0000, v13
	v_mul_f32_e32 v30, 0xbfb8aa3b, v27
	v_exp_f32_e32 v26, v1
	v_exp_f32_e32 v27, v29
	v_mul_f32_e32 v31, 0xbfb8aa3b, v28
	v_exp_f32_e32 v28, v30
	v_exp_f32_e32 v29, v31
	v_lshlrev_b32_e32 v10, 16, v11
	v_and_b32_e32 v11, 0xffff0000, v11
	v_pk_add_f32 v[10:11], v[16:17], v[10:11]
	v_pk_add_f32 v[16:17], v[26:27], 1.0 op_sel_hi:[1,0]
	v_pk_add_f32 v[18:19], v[18:19], v[24:25]
	v_pk_add_f32 v[24:25], v[28:29], 1.0 op_sel_hi:[1,0]
	s_mov_b64 vcc, s[0:1]
	v_rcp_f32_e32 v17, v17
	s_mov_b64 vcc, s[4:5]
	s_waitcnt vmcnt(0)
	v_lshlrev_b32_e32 v12, 16, v14
	v_and_b32_e32 v13, 0xffff0000, v14
	v_rcp_f32_e32 v16, v16
	s_mov_b64 vcc, s[6:7]
	v_pk_fma_f32 v[12:13], v[18:19], v[16:17], v[12:13]
	v_rcp_f32_e32 v17, v25
	v_lshlrev_b32_e32 v14, 16, v15
	v_and_b32_e32 v15, 0xffff0000, v15
	v_rcp_f32_e32 v16, v24
	s_nop 0
	v_pk_fma_f32 v[10:11], v[10:11], v[16:17], v[14:15]
	v_cvt_pk_bf16_f32 v12, v12, v13
	v_cvt_pk_bf16_f32 v13, v10, v11
	global_store_dwordx2 v[8:9], v[12:13], off
	v_lshl_add_u64 v[12:13], s[22:23], 0, v[20:21]
	global_load_dwordx2 v[12:13], v[12:13], off
	v_lshl_add_u64 v[14:15], s[2:3], 0, v[20:21]
	global_load_dwordx2 v[10:11], v[22:23], off
	v_pk_add_f32 v[16:17], v[154:155], v[74:75]
	global_load_dwordx2 v[14:15], v[14:15], off
	v_pk_add_f32 v[18:19], v[156:157], v[72:73]
	v_or_b32_e32 v20, 64, v4
	v_lshl_add_u64 v[22:23], s[8:9], 0, v[20:21]
	v_or_b32_e32 v4, 0x60, v4
	s_waitcnt vmcnt(2)
	v_lshlrev_b32_e32 v1, 16, v12
	v_and_b32_e32 v26, 0xffff0000, v12
	v_lshlrev_b32_e32 v27, 16, v13
	v_mul_f32_e32 v1, 0xbfb8aa3b, v1
	v_mul_f32_e32 v29, 0xbfb8aa3b, v26
	v_and_b32_e32 v28, 0xffff0000, v13
	v_mul_f32_e32 v30, 0xbfb8aa3b, v27
	v_exp_f32_e32 v26, v1
	v_exp_f32_e32 v27, v29
	v_mul_f32_e32 v31, 0xbfb8aa3b, v28
	v_exp_f32_e32 v28, v30
	v_exp_f32_e32 v29, v31
	s_waitcnt vmcnt(1)
	v_lshlrev_b32_e32 v24, 16, v10
	v_and_b32_e32 v25, 0xffff0000, v10
	v_lshlrev_b32_e32 v10, 16, v11
	v_and_b32_e32 v11, 0xffff0000, v11
	v_pk_add_f32 v[10:11], v[16:17], v[10:11]
	v_pk_add_f32 v[16:17], v[26:27], 1.0 op_sel_hi:[1,0]
	v_pk_add_f32 v[18:19], v[18:19], v[24:25]
	v_pk_add_f32 v[24:25], v[28:29], 1.0 op_sel_hi:[1,0]
	s_mov_b64 vcc, s[0:1]
	v_rcp_f32_e32 v17, v17
	s_mov_b64 vcc, s[4:5]
	s_waitcnt vmcnt(0)
	v_lshlrev_b32_e32 v12, 16, v14
	v_and_b32_e32 v13, 0xffff0000, v14
	v_rcp_f32_e32 v16, v16
	s_mov_b64 vcc, s[6:7]
	v_pk_fma_f32 v[12:13], v[18:19], v[16:17], v[12:13]
	v_rcp_f32_e32 v17, v25
	v_lshlrev_b32_e32 v14, 16, v15
	v_and_b32_e32 v15, 0xffff0000, v15
	v_rcp_f32_e32 v16, v24
	s_nop 0
	v_pk_fma_f32 v[10:11], v[10:11], v[16:17], v[14:15]
	v_cvt_pk_bf16_f32 v12, v12, v13
	v_cvt_pk_bf16_f32 v13, v10, v11
	global_store_dwordx2 v[8:9], v[12:13], off offset:32
	v_lshl_add_u64 v[10:11], s[22:23], 0, v[20:21]
	global_load_dwordx2 v[10:11], v[10:11], off
	v_lshl_add_u64 v[12:13], s[2:3], 0, v[20:21]
	global_load_dwordx2 v[8:9], v[22:23], off
	v_pk_add_f32 v[14:15], v[146:147], v[70:71]
	global_load_dwordx2 v[12:13], v[12:13], off
	v_pk_add_f32 v[16:17], v[148:149], v[68:69]
	v_ashrrev_i32_e32 v1, 31, v0
	v_lshlrev_b64 v[0:1], 22, v[0:1]
	v_lshl_add_u64 v[6:7], v[6:7], 0, v[0:1]
	v_lshl_add_u64 v[6:7], v[6:7], 0, v[120:121]
	v_lshl_add_u64 v[18:19], s[8:9], 0, v[4:5]
	s_waitcnt vmcnt(2)
	v_lshlrev_b32_e32 v22, 16, v10
	v_and_b32_e32 v23, 0xffff0000, v10
	v_mul_f32_e32 v22, 0xbfb8aa3b, v22
	v_mul_f32_e32 v23, 0xbfb8aa3b, v23
	v_lshlrev_b32_e32 v24, 16, v11
	v_and_b32_e32 v25, 0xffff0000, v11
	v_exp_f32_e32 v22, v22
	v_exp_f32_e32 v23, v23
	v_mul_f32_e32 v24, 0xbfb8aa3b, v24
	v_mul_f32_e32 v25, 0xbfb8aa3b, v25
	v_exp_f32_e32 v24, v24
	v_exp_f32_e32 v25, v25
	s_waitcnt vmcnt(1)
	v_lshlrev_b32_e32 v20, 16, v8
	v_and_b32_e32 v21, 0xffff0000, v8
	v_lshlrev_b32_e32 v8, 16, v9
	v_and_b32_e32 v9, 0xffff0000, v9
	v_pk_add_f32 v[8:9], v[14:15], v[8:9]
	v_pk_add_f32 v[14:15], v[22:23], 1.0 op_sel_hi:[1,0]
	v_pk_add_f32 v[16:17], v[16:17], v[20:21]
	v_pk_add_f32 v[20:21], v[24:25], 1.0 op_sel_hi:[1,0]
	s_mov_b64 vcc, s[0:1]
	v_rcp_f32_e32 v15, v15
	s_mov_b64 vcc, s[4:5]
	s_waitcnt vmcnt(0)
; DI void store4(u16* dst, f32x4 v) { uint2 w; w.x = cvtpk(v[0], v[1]); w.y = cvtpk(v[2], v[3]); *(uint2*)dst = w; }
; DI f32x4 load4bf(const u16* src) { uint2 w = *(const uint2*)src; return (f32x4){bflo(w.x), bfhi(w.x), bflo(w.y), bfhi(w.y)}; }
; DI float sigmoidf_(float x) { return 1.0f / (1.0f + __expf(-x)); }
; DI void selwin_item(const Params& p, int it, unsigned char* smem, u16* y_out) {
;     ...
;   const u16* ma = (const u16*)(p.ws + OFF_MA); const u16* mbp = (const u16*)(p.ws + OFF_MB); const u16* ab = (const u16*)(p.ws + OFF_HBUF);
; #pragma unroll
;   for (int nt = 0; nt < 2; ++nt) {
;     const size_t t = tb0 + s0 + nt * 16 + lr;
; #pragma unroll
;     for (int dt = 0; dt < 4; ++dt) {
;       const size_t idx = t * 1024 + h * 64 + dt * 16 + lq * 4;
;       const f32x4 a = load4bf(ab + idx), mav = load4bf(ma + idx), mbv = load4bf(mbp + idx);
;       f32x4 y;
; #pragma unroll
;       for (int j = 0; j < 4; ++j) y[j] = sigmoidf_(mav[j]) * (a[j] + Ores[dt][nt][j]) + mbv[j];
;       { const int col = h * 64 + dt * 16 + lq * 4; store4(y_out + ((size_t)(col >> 5) * Tn + t) * 32 + (col & 31), y); }
;     }
;   }
	v_lshlrev_b32_e32 v10, 16, v12
	v_and_b32_e32 v11, 0xffff0000, v12
	v_rcp_f32_e32 v14, v14
	s_mov_b64 vcc, s[6:7]
	v_pk_fma_f32 v[10:11], v[16:17], v[14:15], v[10:11]
	v_lshlrev_b32_e32 v12, 16, v13
	v_and_b32_e32 v13, 0xffff0000, v13
	v_rcp_f32_e32 v15, v21
	v_rcp_f32_e32 v14, v20
	s_nop 0
	v_pk_fma_f32 v[8:9], v[8:9], v[14:15], v[12:13]
	v_cvt_pk_bf16_f32 v10, v10, v11
	v_cvt_pk_bf16_f32 v11, v8, v9
	global_store_dwordx2 v[6:7], v[10:11], off
	v_lshl_add_u64 v[10:11], s[22:23], 0, v[4:5]
	global_load_dwordx2 v[10:11], v[10:11], off
	v_lshl_add_u64 v[4:5], s[2:3], 0, v[4:5]
	global_load_dwordx2 v[8:9], v[18:19], off
	global_load_dwordx2 v[12:13], v[4:5], off
	v_pk_add_f32 v[14:15], v[142:143], v[66:67]
	v_pk_add_f32 v[16:17], v[144:145], v[64:65]
	v_lshlrev_b64 v[4:5], 10, v[130:131]
	v_lshl_add_u64 v[4:5], v[4:5], 0, v[136:137]
	v_lshlrev_b64 v[4:5], 1, v[4:5]
	v_lshl_add_u64 v[18:19], s[8:9], 0, v[4:5]
	s_waitcnt vmcnt(2)
	v_lshlrev_b32_e32 v22, 16, v10
	v_and_b32_e32 v23, 0xffff0000, v10
	v_mul_f32_e32 v22, 0xbfb8aa3b, v22
	v_mul_f32_e32 v23, 0xbfb8aa3b, v23
	v_lshlrev_b32_e32 v24, 16, v11
	v_and_b32_e32 v25, 0xffff0000, v11
	v_exp_f32_e32 v22, v22
	v_exp_f32_e32 v23, v23
	v_mul_f32_e32 v24, 0xbfb8aa3b, v24
	v_mul_f32_e32 v25, 0xbfb8aa3b, v25
	v_exp_f32_e32 v24, v24
	v_exp_f32_e32 v25, v25
	s_waitcnt vmcnt(1)
	v_lshlrev_b32_e32 v20, 16, v8
	v_and_b32_e32 v21, 0xffff0000, v8
	v_lshlrev_b32_e32 v8, 16, v9
	v_and_b32_e32 v9, 0xffff0000, v9
	v_pk_add_f32 v[8:9], v[14:15], v[8:9]
	v_pk_add_f32 v[14:15], v[22:23], 1.0 op_sel_hi:[1,0]
	v_pk_add_f32 v[16:17], v[16:17], v[20:21]
	v_pk_add_f32 v[20:21], v[24:25], 1.0 op_sel_hi:[1,0]
	s_mov_b64 vcc, s[0:1]
	v_rcp_f32_e32 v15, v15
	s_mov_b64 vcc, s[4:5]
	s_waitcnt vmcnt(0)
	v_lshlrev_b32_e32 v10, 16, v12
	v_and_b32_e32 v11, 0xffff0000, v12
	v_rcp_f32_e32 v14, v14
	s_mov_b64 vcc, s[6:7]
	v_pk_fma_f32 v[10:11], v[16:17], v[14:15], v[10:11]
	v_lshlrev_b32_e32 v12, 16, v13
	v_and_b32_e32 v13, 0xffff0000, v13
	v_rcp_f32_e32 v15, v21
	v_rcp_f32_e32 v14, v20
	s_nop 0
	v_pk_fma_f32 v[8:9], v[8:9], v[14:15], v[12:13]
	v_cvt_pk_bf16_f32 v10, v10, v11
	v_cvt_pk_bf16_f32 v11, v8, v9
	global_store_dwordx2 v[6:7], v[10:11], off offset:32
	v_lshl_add_u64 v[6:7], s[22:23], 0, v[4:5]
	global_load_dwordx2 v[10:11], v[6:7], off
	global_load_dwordx2 v[8:9], v[18:19], off
	v_lshl_add_u64 v[6:7], s[2:3], 0, v[4:5]
	global_load_dwordx2 v[12:13], v[6:7], off
	v_pk_add_f32 v[14:15], v[138:139], v[62:63]
	v_pk_add_f32 v[16:17], v[140:141], v[60:61]
	v_lshlrev_b64 v[6:7], 6, v[130:131]
	v_lshl_add_u64 v[6:7], s[16:17], 0, v[6:7]
	v_lshl_add_u64 v[2:3], v[6:7], 0, v[2:3]
	v_or_b32_e32 v18, 32, v4
	v_mov_b32_e32 v19, v5
	v_lshl_add_u64 v[2:3], v[2:3], 0, v[120:121]
	v_lshl_add_u64 v[20:21], s[8:9], 0, v[18:19]
	v_lshl_add_u64 v[0:1], v[6:7], 0, v[0:1]
	v_lshl_add_u64 v[0:1], v[0:1], 0, v[120:121]
	s_waitcnt vmcnt(2)
	v_lshlrev_b32_e32 v24, 16, v10
	v_and_b32_e32 v25, 0xffff0000, v10
	v_mul_f32_e32 v24, 0xbfb8aa3b, v24
	v_mul_f32_e32 v25, 0xbfb8aa3b, v25
	v_lshlrev_b32_e32 v26, 16, v11
	v_and_b32_e32 v27, 0xffff0000, v11
	v_exp_f32_e32 v24, v24
	v_exp_f32_e32 v25, v25
	v_mul_f32_e32 v26, 0xbfb8aa3b, v26
	v_mul_f32_e32 v27, 0xbfb8aa3b, v27
	v_exp_f32_e32 v26, v26
	v_exp_f32_e32 v27, v27
	s_waitcnt vmcnt(1)
	v_lshlrev_b32_e32 v22, 16, v8
	v_and_b32_e32 v23, 0xffff0000, v8
	v_lshlrev_b32_e32 v8, 16, v9
	v_and_b32_e32 v9, 0xffff0000, v9
	v_pk_add_f32 v[8:9], v[14:15], v[8:9]
	v_pk_add_f32 v[14:15], v[24:25], 1.0 op_sel_hi:[1,0]
	v_pk_add_f32 v[16:17], v[16:17], v[22:23]
	v_pk_add_f32 v[22:23], v[26:27], 1.0 op_sel_hi:[1,0]
	s_mov_b64 vcc, s[0:1]
	v_rcp_f32_e32 v15, v15
	s_mov_b64 vcc, s[4:5]
	s_waitcnt vmcnt(0)
	v_lshlrev_b32_e32 v10, 16, v12
	v_and_b32_e32 v11, 0xffff0000, v12
	v_rcp_f32_e32 v14, v14
	s_mov_b64 vcc, s[6:7]
	v_pk_fma_f32 v[10:11], v[16:17], v[14:15], v[10:11]
	v_lshlrev_b32_e32 v12, 16, v13
	v_and_b32_e32 v13, 0xffff0000, v13
	v_rcp_f32_e32 v15, v23
	v_rcp_f32_e32 v14, v22
	s_nop 0
	v_pk_fma_f32 v[8:9], v[8:9], v[14:15], v[12:13]
	v_cvt_pk_bf16_f32 v10, v10, v11
	v_cvt_pk_bf16_f32 v11, v8, v9
	global_store_dwordx2 v[2:3], v[10:11], off
	v_lshl_add_u64 v[10:11], s[22:23], 0, v[18:19]
	global_load_dwordx2 v[10:11], v[10:11], off
	v_lshl_add_u64 v[12:13], s[2:3], 0, v[18:19]
	global_load_dwordx2 v[8:9], v[20:21], off
	v_pk_add_f32 v[14:15], v[132:133], v[58:59]
	global_load_dwordx2 v[12:13], v[12:13], off
	v_pk_add_f32 v[16:17], v[134:135], v[56:57]
	v_or_b32_e32 v18, 64, v4
	v_lshl_add_u64 v[20:21], s[8:9], 0, v[18:19]
	v_or_b32_e32 v4, 0x60, v4
	v_lshl_add_u64 v[6:7], s[8:9], 0, v[4:5]
	s_waitcnt vmcnt(2)
; DI void store4(u16* dst, f32x4 v) { uint2 w; w.x = cvtpk(v[0], v[1]); w.y = cvtpk(v[2], v[3]); *(uint2*)dst = w; }
; DI f32x4 load4bf(const u16* src) { uint2 w = *(const uint2*)src; return (f32x4){bflo(w.x), bfhi(w.x), bflo(w.y), bfhi(w.y)}; }
; DI float sigmoidf_(float x) { return 1.0f / (1.0f + __expf(-x)); }
; DI void selwin_item(const Params& p, int it, unsigned char* smem, u16* y_out) {
;     ...
;   const u16* ma = (const u16*)(p.ws + OFF_MA); const u16* mbp = (const u16*)(p.ws + OFF_MB); const u16* ab = (const u16*)(p.ws + OFF_HBUF);
; #pragma unroll
;   for (int nt = 0; nt < 2; ++nt) {
;     const size_t t = tb0 + s0 + nt * 16 + lr;
; #pragma unroll
;     for (int dt = 0; dt < 4; ++dt) {
;       const size_t idx = t * 1024 + h * 64 + dt * 16 + lq * 4;
;       const f32x4 a = load4bf(ab + idx), mav = load4bf(ma + idx), mbv = load4bf(mbp + idx);
;       f32x4 y;
; #pragma unroll
;       for (int j = 0; j < 4; ++j) y[j] = sigmoidf_(mav[j]) * (a[j] + Ores[dt][nt][j]) + mbv[j];
;       { const int col = h * 64 + dt * 16 + lq * 4; store4(y_out + ((size_t)(col >> 5) * Tn + t) * 32 + (col & 31), y); }
;     }
;   }
	v_lshlrev_b32_e32 v24, 16, v10
	v_and_b32_e32 v25, 0xffff0000, v10
	v_mul_f32_e32 v24, 0xbfb8aa3b, v24
	v_mul_f32_e32 v25, 0xbfb8aa3b, v25
	v_lshlrev_b32_e32 v26, 16, v11
	v_and_b32_e32 v27, 0xffff0000, v11
	v_exp_f32_e32 v24, v24
	v_exp_f32_e32 v25, v25
	v_mul_f32_e32 v26, 0xbfb8aa3b, v26
	v_mul_f32_e32 v27, 0xbfb8aa3b, v27
	v_exp_f32_e32 v26, v26
	v_exp_f32_e32 v27, v27
	s_waitcnt vmcnt(1)
	v_lshlrev_b32_e32 v22, 16, v8
	v_and_b32_e32 v23, 0xffff0000, v8
	v_lshlrev_b32_e32 v8, 16, v9
	v_and_b32_e32 v9, 0xffff0000, v9
	v_pk_add_f32 v[8:9], v[14:15], v[8:9]
	v_pk_add_f32 v[14:15], v[24:25], 1.0 op_sel_hi:[1,0]
	v_pk_add_f32 v[16:17], v[16:17], v[22:23]
	v_pk_add_f32 v[22:23], v[26:27], 1.0 op_sel_hi:[1,0]
	s_mov_b64 vcc, s[0:1]
	v_rcp_f32_e32 v15, v15
	s_mov_b64 vcc, s[4:5]
	s_waitcnt vmcnt(0)
	v_lshlrev_b32_e32 v10, 16, v12
	v_and_b32_e32 v11, 0xffff0000, v12
	v_rcp_f32_e32 v14, v14
	s_mov_b64 vcc, s[6:7]
	v_pk_fma_f32 v[10:11], v[16:17], v[14:15], v[10:11]
	v_lshlrev_b32_e32 v12, 16, v13
	v_and_b32_e32 v13, 0xffff0000, v13
	v_rcp_f32_e32 v15, v23
	v_rcp_f32_e32 v14, v22
	s_nop 0
	v_pk_fma_f32 v[8:9], v[8:9], v[14:15], v[12:13]
	v_cvt_pk_bf16_f32 v10, v10, v11
	v_cvt_pk_bf16_f32 v11, v8, v9
	global_store_dwordx2 v[2:3], v[10:11], off offset:32
	v_lshl_add_u64 v[8:9], s[22:23], 0, v[18:19]
	global_load_dwordx2 v[8:9], v[8:9], off
	v_lshl_add_u64 v[10:11], s[2:3], 0, v[18:19]
	global_load_dwordx2 v[2:3], v[20:21], off
	v_pk_add_f32 v[12:13], v[126:127], v[54:55]
	global_load_dwordx2 v[10:11], v[10:11], off
	v_pk_add_f32 v[14:15], v[128:129], v[52:53]
	s_waitcnt vmcnt(2)
	v_lshlrev_b32_e32 v18, 16, v8
	v_and_b32_e32 v19, 0xffff0000, v8
	v_mul_f32_e32 v18, 0xbfb8aa3b, v18
	v_mul_f32_e32 v19, 0xbfb8aa3b, v19
	v_lshlrev_b32_e32 v20, 16, v9
	v_and_b32_e32 v21, 0xffff0000, v9
	v_exp_f32_e32 v18, v18
	v_exp_f32_e32 v19, v19
	v_mul_f32_e32 v20, 0xbfb8aa3b, v20
	v_mul_f32_e32 v21, 0xbfb8aa3b, v21
	v_exp_f32_e32 v20, v20
	v_exp_f32_e32 v21, v21
	s_waitcnt vmcnt(1)
	v_lshlrev_b32_e32 v16, 16, v2
	v_and_b32_e32 v17, 0xffff0000, v2
	v_lshlrev_b32_e32 v2, 16, v3
	v_and_b32_e32 v3, 0xffff0000, v3
	v_pk_add_f32 v[2:3], v[12:13], v[2:3]
	v_pk_add_f32 v[12:13], v[18:19], 1.0 op_sel_hi:[1,0]
	v_pk_add_f32 v[14:15], v[14:15], v[16:17]
	v_pk_add_f32 v[16:17], v[20:21], 1.0 op_sel_hi:[1,0]
	s_mov_b64 vcc, s[0:1]
	v_rcp_f32_e32 v13, v13
	s_mov_b64 vcc, s[4:5]
	s_waitcnt vmcnt(0)
	v_lshlrev_b32_e32 v8, 16, v10
	v_and_b32_e32 v9, 0xffff0000, v10
	v_rcp_f32_e32 v12, v12
	s_mov_b64 vcc, s[6:7]
	v_pk_fma_f32 v[8:9], v[14:15], v[12:13], v[8:9]
	v_lshlrev_b32_e32 v10, 16, v11
	v_and_b32_e32 v11, 0xffff0000, v11
	v_rcp_f32_e32 v13, v17
	v_rcp_f32_e32 v12, v16
	s_nop 0
	v_pk_fma_f32 v[2:3], v[2:3], v[12:13], v[10:11]
	v_cvt_pk_bf16_f32 v8, v8, v9
	v_cvt_pk_bf16_f32 v9, v2, v3
	global_store_dwordx2 v[0:1], v[8:9], off
	global_load_dwordx2 v[2:3], v[6:7], off
	v_lshl_add_u64 v[6:7], s[22:23], 0, v[4:5]
	global_load_dwordx2 v[6:7], v[6:7], off
	v_lshl_add_u64 v[4:5], s[2:3], 0, v[4:5]
	global_load_dwordx2 v[4:5], v[4:5], off
	v_pk_add_f32 v[8:9], v[122:123], v[50:51]
	v_pk_add_f32 v[10:11], v[124:125], v[48:49]
	s_waitcnt vmcnt(2)
	v_lshlrev_b32_e32 v12, 16, v2
	v_and_b32_e32 v13, 0xffff0000, v2
	s_waitcnt vmcnt(1)
	v_lshlrev_b32_e32 v14, 16, v6
	v_and_b32_e32 v15, 0xffff0000, v6
	v_mul_f32_e32 v14, 0xbfb8aa3b, v14
	v_mul_f32_e32 v15, 0xbfb8aa3b, v15
	v_lshlrev_b32_e32 v16, 16, v7
	v_and_b32_e32 v17, 0xffff0000, v7
	v_exp_f32_e32 v14, v14
	v_exp_f32_e32 v15, v15
	v_mul_f32_e32 v16, 0xbfb8aa3b, v16
	v_mul_f32_e32 v17, 0xbfb8aa3b, v17
	v_exp_f32_e32 v16, v16
	v_exp_f32_e32 v17, v17
	v_lshlrev_b32_e32 v2, 16, v3
	v_and_b32_e32 v3, 0xffff0000, v3
	v_pk_add_f32 v[2:3], v[8:9], v[2:3]
	v_pk_add_f32 v[8:9], v[14:15], 1.0 op_sel_hi:[1,0]
	v_pk_add_f32 v[10:11], v[10:11], v[12:13]
	v_pk_add_f32 v[12:13], v[16:17], 1.0 op_sel_hi:[1,0]
	s_mov_b64 vcc, s[0:1]
	v_rcp_f32_e32 v9, v9
	s_mov_b64 vcc, s[4:5]
	s_waitcnt vmcnt(0)
	v_lshlrev_b32_e32 v6, 16, v4
	v_and_b32_e32 v7, 0xffff0000, v4
	v_rcp_f32_e32 v8, v8
	s_mov_b64 vcc, s[6:7]
	v_pk_fma_f32 v[6:7], v[10:11], v[8:9], v[6:7]
	v_lshlrev_b32_e32 v4, 16, v5
	v_and_b32_e32 v5, 0xffff0000, v5
	v_rcp_f32_e32 v9, v13
	v_rcp_f32_e32 v8, v12
	s_nop 0
	v_pk_fma_f32 v[2:3], v[2:3], v[8:9], v[4:5]
	v_cvt_pk_bf16_f32 v6, v6, v7
	v_cvt_pk_bf16_f32 v7, v2, v3
	global_store_dwordx2 v[0:1], v[6:7], off offset:32
	s_cbranch_scc0 .LBB0_754

; DI float bf2f(u16 v) { return __uint_as_float(((unsigned)v) << 16); }
; DI float sigmoidf_(float x) { return 1.0f / (1.0f + __expf(-x)); }
; DI void selwin_item(const Params& p, int it, unsigned char* smem, u16* y_out) {
;     ...
;     for (int nt = 0; nt < 2; ++nt) {
;       float lt = l[nt]; lt += __shfl_xor(lt, 16); lt += __shfl_xor(lt, 32);
;       const size_t t = tb0 + s0 + nt * 16 + lr;
;       const float gt = sigmoidf_(bf2f(((const u16*)(p.ws + OFF_MKV))[t * 256 + 160 + h * 3 + 1 + pass]));
;       const float f = gt / lt;
; #pragma unroll
;       for (int dt = 0; dt < 4; ++dt) { if (pass == 0) Ores[dt][nt] = O[dt][nt] * f; else Ores[dt][nt] = Ores[dt][nt] + O[dt][nt] * f; }
;     }
.LBB0_706:
	v_lshl_add_u64 v[80:81], s[30:31], 1, v[170:171]
	v_lshl_add_u64 v[82:83], v[80:81], 0, v[172:173]
	v_lshl_add_u64 v[80:81], v[80:81], 0, v[174:175]
	global_load_ushort v82, v[82:83], off
	s_nop 0
	global_load_ushort v80, v[80:81], off
	ds_bpermute_b32 v81, v213, v220
	ds_bpermute_b32 v83, v213, v225
	s_mov_b64 s[30:31], 1
	s_mov_b64 s[34:35], 0
	s_waitcnt lgkmcnt(1)
	v_add_f32_e32 v81, v220, v81
	ds_bpermute_b32 v84, v214, v81
	s_waitcnt lgkmcnt(1)
	v_add_f32_e32 v83, v225, v83
	ds_bpermute_b32 v85, v214, v83
	s_waitcnt lgkmcnt(1)
	v_add_f32_e32 v81, v81, v84
	s_waitcnt lgkmcnt(0)
	v_add_f32_e32 v83, v83, v85
	s_waitcnt vmcnt(1)
	v_lshlrev_b32_e32 v82, 16, v82
	s_waitcnt vmcnt(0)
	v_lshlrev_b32_e32 v80, 16, v80
	v_mul_f32_e32 v82, 0xbfb8aa3b, v82
	v_mul_f32_e32 v80, 0xbfb8aa3b, v80
	v_exp_f32_e32 v82, v82
	v_exp_f32_e32 v80, v80
	v_add_f32_e32 v82, 1.0, v82
	v_add_f32_e32 v84, 1.0, v80
	v_div_scale_f32 v86, s[0:1], v84, v84, 1.0
	v_rcp_f32_e32 v88, v86
	v_rcp_f32_e32 v80, v82
	v_fma_f32 v91, -v86, v88, 1.0
	v_div_scale_f32 v82, s[4:5], v81, v81, v80
	v_div_scale_f32 v89, s[0:1], 1.0, v84, 1.0
	v_fmac_f32_e32 v88, v91, v88
	v_rcp_f32_e32 v85, v82
	v_mul_f32_e32 v91, v89, v88
	v_fma_f32 v93, -v86, v91, v89
	v_fmac_f32_e32 v91, v93, v88
	v_fma_f32 v86, -v86, v91, v89
	v_fma_f32 v89, -v82, v85, 1.0
	v_div_scale_f32 v87, vcc, v80, v81, v80
	v_fmac_f32_e32 v85, v89, v85
	v_mul_f32_e32 v89, v87, v85
	v_fma_f32 v90, -v82, v89, v87
	v_fmac_f32_e32 v89, v90, v85
	v_fma_f32 v82, -v82, v89, v87
	v_div_fmas_f32 v82, v82, v85, v89
	s_mov_b64 vcc, s[0:1]
	v_div_fixup_f32 v80, v82, v81, v80
	v_div_fmas_f32 v81, v86, v88, v91
	v_pk_mul_f32 v[78:79], v[78:79], v[80:81] op_sel_hi:[1,0]
	v_pk_mul_f32 v[76:77], v[76:77], v[80:81] op_sel_hi:[1,0]
	v_pk_mul_f32 v[74:75], v[74:75], v[80:81] op_sel_hi:[1,0]
	v_pk_mul_f32 v[72:73], v[72:73], v[80:81] op_sel_hi:[1,0]
	v_pk_mul_f32 v[70:71], v[70:71], v[80:81] op_sel_hi:[1,0]
	v_pk_mul_f32 v[68:69], v[68:69], v[80:81] op_sel_hi:[1,0]
	v_pk_mul_f32 v[66:67], v[66:67], v[80:81] op_sel_hi:[1,0]
	v_rcp_f32_e32 v81, v84
	s_nop 0
	v_div_scale_f32 v82, s[0:1], v83, v83, v81
	v_rcp_f32_e32 v84, v82
	v_pk_mul_f32 v[64:65], v[64:65], v[80:81] op_sel_hi:[1,0]
	v_div_scale_f32 v80, vcc, v81, v83, v81
	v_fma_f32 v85, -v82, v84, 1.0
	v_fmac_f32_e32 v84, v85, v84
	v_mul_f32_e32 v85, v80, v84
	v_fma_f32 v86, -v82, v85, v80
	v_fmac_f32_e32 v85, v86, v84
	v_fma_f32 v80, -v82, v85, v80
	v_div_fmas_f32 v80, v80, v84, v85
	v_div_fixup_f32 v80, v80, v83, v81
	s_andn2_b64 vcc, exec, s[36:37]
	v_pk_mul_f32 v[62:63], v[62:63], v[80:81] op_sel_hi:[1,0]
	v_pk_mul_f32 v[60:61], v[60:61], v[80:81] op_sel_hi:[1,0]
	v_pk_mul_f32 v[58:59], v[58:59], v[80:81] op_sel_hi:[1,0]
	v_pk_mul_f32 v[56:57], v[56:57], v[80:81] op_sel_hi:[1,0]
	v_pk_mul_f32 v[54:55], v[54:55], v[80:81] op_sel_hi:[1,0]
	v_pk_mul_f32 v[52:53], v[52:53], v[80:81] op_sel_hi:[1,0]
	v_pk_mul_f32 v[50:51], v[50:51], v[80:81] op_sel_hi:[1,0]
	v_pk_mul_f32 v[48:49], v[48:49], v[80:81] op_sel_hi:[1,0]
	s_cbranch_vccz .LBB0_691

; DI int tidx() { int t = __builtin_amdgcn_workitem_id_x(); asm volatile("" : "+v"(t)); return t; }
;   DI unsigned rowoff(int r, int sch) const { const int g = r & 3, bc = r >> 2, b = bc / NCMP, c = bc - b * NCMP; return (unsigned)(b * Sn + c * 16) * 512u + g * 64 + sch; }
; template <int NI, class XL, class EP>
; DI void gemm_tile(const u16* __restrict__ W, int ldw, int f0, int t0, int K, XL xl, EP ep, unsigned char* smem) {
;     ...
;   const int tid = tidx(), lane = tid & 63, wave = tid >> 6;
;   const int wf = wave >> 1, wt = wave & 1, lr = lane & 15, lq = lane >> 4;
;   const int srow = tid >> 2, sch = (tid & 3) * 8;
;   f32x4 acc[4][NI];
; #pragma unroll
;   for (int i = 0; i < 4; ++i)
; #pragma unroll
;     for (int j = 0; j < NI; ++j) acc[i][j] = (f32x4){0.f, 0.f, 0.f, 0.f};
;   u32x4 wr[2], xr[XR];
;   const unsigned wbyte = ((unsigned)(f0 + srow * 2) * 32u + sch) * 2u;
;   const unsigned xbyte = xl.rowoff(t0 + srow * XR, sch) * 2u;
;   const int xrs = xl.rstride();
;   const int nk = K >> 5;
;   auto gload = [&](int it) {
;     const int k = it * 32;
;     const char* wb = (const char*)(W + (size_t)(k >> 5) * ldw * 32);
;     const char* xb = (const char*)xl.kbase(k);
; #pragma unroll
;     for (int i = 0; i < 2; ++i) wr[i] = *(const u32x4*)(wb + wbyte + i * 64);
; #pragma unroll
;     for (int i = 0; i < XR; ++i) xr[i] = *(const u32x4*)(xb + xbyte + i * xrs);
;   };
;   auto lstore = [&](int buf) {
;     u16* Ws = S0 + buf * BUF; u16* Xs = Ws + 128 * LST;
; #pragma unroll
;     for (int i = 0; i < 2; ++i) *(u32x4*)(Ws + (srow * 2 + i) * LST + sch) = wr[i];
; #pragma unroll
;     for (int i = 0; i < XR; ++i) *(u32x4*)(Xs + (srow * XR + i) * LST + sch) = xr[i];
;   };
;   gload(0);
;   __syncthreads();
;   lstore(0);
;   __syncthreads();
;   if (nk > 1) gload(1);
.LBB0_811:
	v_mov_b32_e32 v46, v218
	s_and_b32 s34, s31, 7
	v_ashrrev_i32_e32 v47, 2, v46
	v_lshlrev_b32_e32 v0, 3, v46
	v_lshlrev_b32_e32 v49, 6, v47
	s_ashr_i32 s37, s31, 3
	v_and_b32_e32 v48, 24, v0
	v_lshl_add_u32 v0, s34, 12, v49
	s_add_i32 s35, s37, s29
	v_or_b32_e32 v0, v0, v48
	s_lshl_b32 s33, s35, 8
	v_lshlrev_b32_e32 v50, 1, v0
	v_and_b32_e32 v0, 0x3fffffc, v46
	v_add_u32_e32 v0, s33, v0
	v_lshlrev_b32_e32 v161, 1, v48
	v_lshl_or_b32 v51, v0, 6, v161
	global_load_dwordx4 v[16:19], v50, s[4:5]
	global_load_dwordx4 v[20:23], v50, s[4:5] offset:64
	global_load_dwordx4 v[24:27], v51, s[16:17]
	global_load_dwordx4 v[28:31], v51, s[16:17] offset:64
	global_load_dwordx4 v[32:35], v51, s[16:17] offset:128
	global_load_dwordx4 v[36:39], v51, s[16:17] offset:192
	v_mul_lo_u32 v166, v47, s22
	v_or_b32_e32 v162, v166, v161
	v_add_u32_e32 v163, v162, v166
	s_barrier
	v_bfe_u32 v158, v46, 4, 2
	v_and_b32_e32 v52, 15, v46
	v_ashrrev_i32_e32 v53, 1, v46
	v_lshlrev_b32_e32 v54, 1, v46
	v_lshlrev_b32_e32 v46, 6, v46
	s_and_b32 s44, s30, 7
	s_add_i32 s37, s20, s37
	v_and_b32_e32 v46, 0xffffff00, v46
	v_and_b32_e32 v160, 0xffffffc0, v53
	v_lshl_add_u32 v46, s37, 14, v46
	v_lshl_add_u32 v49, s44, 12, v49
	v_mov_b32_e32 v0, 0
	v_and_or_b32 v159, v54, s23, v52
	v_or_b32_e32 v47, v160, v52
	v_or_b32_e32 v152, v46, v161
	v_or_b32_e32 v46, v49, v48
	s_mov_b32 s36, 1
	v_mov_b32_e32 v155, v153
	v_mov_b32_e32 v1, v0
	v_mov_b32_e32 v2, v0
	v_mov_b32_e32 v3, v0
	v_mov_b32_e32 v4, v0
	v_mov_b32_e32 v5, v0
	v_mov_b32_e32 v6, v0
	v_mov_b32_e32 v7, v0
	v_mov_b32_e32 v8, v0
	v_mov_b32_e32 v9, v0
	v_mov_b32_e32 v10, v0
	v_mov_b32_e32 v11, v0
	v_mov_b32_e32 v12, v0
	v_mov_b32_e32 v13, v0
	v_mov_b32_e32 v14, v0
	v_mov_b32_e32 v15, v0
	v_mov_b32_e32 v40, v0
	v_mov_b32_e32 v41, v0
	v_mov_b32_e32 v42, v0
	v_mov_b32_e32 v43, v0
	v_mov_b32_e32 v44, v0
	v_mov_b32_e32 v45, v0
	v_lshlrev_b32_e32 v164, 4, v158
	v_mul_u32_u24_e32 v165, 48, v159
	v_mul_lo_u32 v167, v47, 48
	v_lshlrev_b32_e32 v154, 1, v46
	v_mov_b64_e32 v[156:157], v[152:153]
	v_mov_b32_e32 v46, v0
	v_mov_b32_e32 v47, v0
	v_mov_b32_e32 v68, v0
	v_mov_b32_e32 v69, v0
	v_mov_b32_e32 v70, v0
	v_mov_b32_e32 v71, v0
	v_mov_b32_e32 v80, v0
	v_mov_b32_e32 v81, v0
	v_mov_b32_e32 v82, v0
	v_mov_b32_e32 v83, v0
	v_mov_b32_e32 v48, v0
	v_mov_b32_e32 v49, v0
	v_mov_b32_e32 v52, v0
	v_mov_b32_e32 v53, v0
	v_mov_b32_e32 v54, v0
	v_mov_b32_e32 v55, v0
	v_mov_b32_e32 v56, v0
	v_mov_b32_e32 v57, v0
	v_mov_b32_e32 v58, v0
	s_waitcnt vmcnt(5)
	ds_write_b128 v162, v[16:19]
	s_waitcnt vmcnt(4)
	ds_write_b128 v162, v[20:23] offset:96
	s_waitcnt vmcnt(3)
	ds_write_b128 v163, v[24:27] offset:12288
	s_waitcnt vmcnt(2)
	ds_write_b128 v163, v[28:31] offset:12384
	s_waitcnt vmcnt(1)
	ds_write_b128 v163, v[32:35] offset:12480
	s_waitcnt vmcnt(0)
	ds_write_b128 v163, v[36:39] offset:12576
	s_waitcnt lgkmcnt(0)
	s_barrier
	global_load_dwordx4 v[20:23], v50, s[8:9]
	global_load_dwordx4 v[16:19], v50, s[8:9] offset:64
	global_load_dwordx4 v[36:39], v51, s[6:7]
	global_load_dwordx4 v[32:35], v51, s[6:7] offset:64
	global_load_dwordx4 v[28:31], v51, s[6:7] offset:128
	global_load_dwordx4 v[24:27], v51, s[6:7] offset:192
	s_add_u32 s98, s42, s24
	s_addc_u32 s99, s43, 0
	s_add_u32 s100, s42, s25
	s_addc_u32 s101, s43, 0
	global_load_dwordx4 v[200:203], v154, s[98:99]
	global_load_dwordx4 v[204:207], v154, s[98:99] offset:64
	global_load_dwordx4 v[208:211], v156, s[100:101] offset:2048
	global_load_dwordx4 v[212:215], v156, s[100:101] offset:2112
	global_load_dwordx4 v[220:223], v156, s[100:101] offset:2176
	global_load_dwordx4 v[224:227], v156, s[100:101] offset:2240
	s_add_u32 s98, s98, s18
	s_addc_u32 s99, s99, s19
	s_add_u32 s100, s100, s10
	s_addc_u32 s101, s101, s11
	v_mov_b32_e32 v50, v0
	v_mov_b32_e32 v51, v0
	v_mov_b32_e32 v59, v0
	v_mov_b32_e32 v64, v0
	v_mov_b32_e32 v65, v0
	v_mov_b32_e32 v66, v0
	v_mov_b32_e32 v67, v0
	v_mov_b32_e32 v76, v0
	v_mov_b32_e32 v77, v0
	v_mov_b32_e32 v78, v0
	v_mov_b32_e32 v79, v0
	v_mov_b32_e32 v88, v0
	v_mov_b32_e32 v89, v0
	v_mov_b32_e32 v90, v0
	v_mov_b32_e32 v91, v0
	v_mov_b32_e32 v100, v0
	v_mov_b32_e32 v101, v0
	v_mov_b32_e32 v102, v0
	v_mov_b32_e32 v103, v0
	v_mov_b32_e32 v112, v0
	v_mov_b32_e32 v113, v0
	v_mov_b32_e32 v114, v0
	v_mov_b32_e32 v115, v0
	v_mov_b32_e32 v60, v0
	v_mov_b32_e32 v61, v0
	v_mov_b32_e32 v62, v0
	v_mov_b32_e32 v63, v0
	v_mov_b32_e32 v72, v0
	v_mov_b32_e32 v73, v0
	v_mov_b32_e32 v74, v0
	v_mov_b32_e32 v75, v0
	v_mov_b32_e32 v84, v0
	v_mov_b32_e32 v85, v0
	v_mov_b32_e32 v86, v0
	v_mov_b32_e32 v87, v0
	v_mov_b32_e32 v96, v0
	v_mov_b32_e32 v97, v0
	v_mov_b32_e32 v98, v0
	v_mov_b32_e32 v99, v0
	v_mov_b32_e32 v108, v0
	v_mov_b32_e32 v109, v0
	v_mov_b32_e32 v110, v0
	v_mov_b32_e32 v111, v0
	v_mov_b32_e32 v120, v0
	v_mov_b32_e32 v121, v0
	v_mov_b32_e32 v122, v0
	v_mov_b32_e32 v123, v0
	v_mov_b32_e32 v128, v0
	v_mov_b32_e32 v129, v0
	v_mov_b32_e32 v130, v0
	v_mov_b32_e32 v131, v0
	v_mov_b32_e32 v136, v0
	v_mov_b32_e32 v137, v0
	v_mov_b32_e32 v138, v0
	v_mov_b32_e32 v139, v0
	v_mov_b32_e32 v92, v0
	v_mov_b32_e32 v93, v0
	v_mov_b32_e32 v94, v0
	v_mov_b32_e32 v95, v0
	v_mov_b32_e32 v104, v0
	v_mov_b32_e32 v105, v0
	v_mov_b32_e32 v106, v0
	v_mov_b32_e32 v107, v0
	v_mov_b32_e32 v116, v0
	v_mov_b32_e32 v117, v0
	v_mov_b32_e32 v118, v0
	v_mov_b32_e32 v119, v0
	v_mov_b32_e32 v124, v0
	v_mov_b32_e32 v125, v0
	v_mov_b32_e32 v126, v0
	v_mov_b32_e32 v127, v0
	v_mov_b32_e32 v132, v0
	v_mov_b32_e32 v133, v0
	v_mov_b32_e32 v134, v0
	v_mov_b32_e32 v135, v0
	v_mov_b32_e32 v140, v0
	v_mov_b32_e32 v141, v0
	v_mov_b32_e32 v142, v0
	v_mov_b32_e32 v143, v0
	v_mov_b32_e32 v144, v0
	v_mov_b32_e32 v145, v0
	v_mov_b32_e32 v146, v0
	v_mov_b32_e32 v147, v0
	v_mov_b32_e32 v148, v0
	v_mov_b32_e32 v149, v0
	v_mov_b32_e32 v150, v0
	v_mov_b32_e32 v151, v0
; DI f32x4 mfma16(bf16x8 a, bf16x8 b, f32x4 c) { return __builtin_amdgcn_mfma_f32_16x16x32_bf16(a, b, c, 0, 0, 0); }
; template <int NI, class XL, class EP>
; DI void gemm_tile(const u16* __restrict__ W, int ldw, int f0, int t0, int K, XL xl, EP ep, unsigned char* smem) {
;     ...
;   for (int it = 0; it < nk; ++it) {
;     const u16* Ws = S0 + (it & 1) * BUF; const u16* Xs = Ws + 128 * LST;
;     __builtin_amdgcn_s_setprio(1);
;     bf16x8 a[4];
; #pragma unroll
;     for (int mi = 0; mi < 4; ++mi) a[mi] = *(const bf16x8*)(Ws + (wf * 64 + mi * 16 + lr) * LST + lq * 8);
; #pragma unroll
;     for (int ni = 0; ni < NI; ++ni) {
;       const bf16x8 b = *(const bf16x8*)(Xs + (wt * (NI * 16) + ni * 16 + lr) * LST + lq * 8);
; #pragma unroll
;       for (int mi = 0; mi < 4; ++mi) acc[mi][ni] = mfma16(a[mi], b, acc[mi][ni]);
;     }
;     __builtin_amdgcn_sched_group_barrier(0x100, 6, 0);
; #pragma unroll
;     for (int ni = 0; ni < NI; ++ni) { __builtin_amdgcn_sched_group_barrier(0x008, 4, 0); if (ni + 2 < NI) __builtin_amdgcn_sched_group_barrier(0x100, 1, 0); }
;     __builtin_amdgcn_s_setprio(0);
;     if (it + 1 < nk) lstore((it + 1) & 1);
;     if (it + 2 < nk) gload(it + 2);
;     __syncthreads();
;   }
.LBB0_812:
	s_bitcmp1_b32 s36, 0
	s_cselect_b32 s37, 0, 0x9000
	s_setprio 1
	v_or_b32_e32 v152, s37, v164
	v_lshl_add_u32 v184, v167, 1, v152
	ds_read_b128 v[168:171], v184
	ds_read_b128 v[172:175], v184 offset:1536
	ds_read_b128 v[180:183], v184 offset:3072
	ds_read_b128 v[184:187], v184 offset:4608
	v_lshl_add_u32 v152, v165, 1, v152
	ds_read_b128 v[176:179], v152 offset:12288
	ds_read_b128 v[188:191], v152 offset:13824
	s_xor_b32 s37, s37, 0x9000
	v_add3_u32 v228, v166, s37, v161
	s_waitcnt lgkmcnt(1)
	v_mfma_f32_16x16x32_bf16 v[148:151], v[168:171], v[176:179], v[148:151]
	v_mfma_f32_16x16x32_bf16 v[136:139], v[172:175], v[176:179], v[136:139]
	v_mfma_f32_16x16x32_bf16 v[112:115], v[180:183], v[176:179], v[112:115]
	v_mfma_f32_16x16x32_bf16 v[80:83], v[184:187], v[176:179], v[80:83]
	ds_read_b128 v[176:179], v152 offset:15360
	s_waitcnt vmcnt(11)
	ds_write_b128 v228, v[20:23]
	s_waitcnt lgkmcnt(2)
	v_mfma_f32_16x16x32_bf16 v[144:147], v[168:171], v[188:191], v[144:147]
	v_mfma_f32_16x16x32_bf16 v[128:131], v[172:175], v[188:191], v[128:131]
	v_mfma_f32_16x16x32_bf16 v[100:103], v[180:183], v[188:191], v[100:103]
	v_mfma_f32_16x16x32_bf16 v[68:71], v[184:187], v[188:191], v[68:71]
	ds_read_b128 v[188:191], v152 offset:16896
	s_waitcnt vmcnt(10)
	ds_write_b128 v228, v[16:19] offset:96
	v_add_u32_e32 v228, v228, v166
	global_load_dwordx4 v[20:23], v154, s[98:99]
	global_load_dwordx4 v[16:19], v154, s[98:99] offset:64
	s_waitcnt lgkmcnt(3)
	v_mfma_f32_16x16x32_bf16 v[140:143], v[168:171], v[176:179], v[140:143]
	v_mfma_f32_16x16x32_bf16 v[120:123], v[172:175], v[176:179], v[120:123]
	v_mfma_f32_16x16x32_bf16 v[88:91], v[180:183], v[176:179], v[88:91]
	v_mfma_f32_16x16x32_bf16 v[44:47], v[184:187], v[176:179], v[44:47]
	ds_read_b128 v[176:179], v152 offset:18432
	s_waitcnt vmcnt(11)
	ds_write_b128 v228, v[36:39] offset:12288
	global_load_dwordx4 v[36:39], v156, s[100:101] offset:2048
	s_waitcnt lgkmcnt(3)
	v_mfma_f32_16x16x32_bf16 v[132:135], v[168:171], v[188:191], v[132:135]
	v_mfma_f32_16x16x32_bf16 v[108:111], v[172:175], v[188:191], v[108:111]
	v_mfma_f32_16x16x32_bf16 v[76:79], v[180:183], v[188:191], v[76:79]
	v_mfma_f32_16x16x32_bf16 v[40:43], v[184:187], v[188:191], v[40:43]
	ds_read_b128 v[188:191], v152 offset:19968
	s_waitcnt vmcnt(11)
	ds_write_b128 v228, v[32:35] offset:12384
	global_load_dwordx4 v[32:35], v156, s[100:101] offset:2112
	s_waitcnt lgkmcnt(3)
	v_mfma_f32_16x16x32_bf16 v[124:127], v[168:171], v[176:179], v[124:127]
	v_mfma_f32_16x16x32_bf16 v[96:99], v[172:175], v[176:179], v[96:99]
	v_mfma_f32_16x16x32_bf16 v[64:67], v[180:183], v[176:179], v[64:67]
	v_mfma_f32_16x16x32_bf16 v[12:15], v[184:187], v[176:179], v[12:15]
	ds_read_b128 v[176:179], v152 offset:21504
	s_waitcnt vmcnt(11)
	ds_write_b128 v228, v[28:31] offset:12480
	global_load_dwordx4 v[28:31], v156, s[100:101] offset:2176
	s_waitcnt lgkmcnt(3)
	v_mfma_f32_16x16x32_bf16 v[116:119], v[168:171], v[188:191], v[116:119]
	v_mfma_f32_16x16x32_bf16 v[84:87], v[172:175], v[188:191], v[84:87]
	v_mfma_f32_16x16x32_bf16 v[56:59], v[180:183], v[188:191], v[56:59]
	v_mfma_f32_16x16x32_bf16 v[8:11], v[184:187], v[188:191], v[8:11]
	ds_read_b128 v[188:191], v152 offset:23040
	s_waitcnt vmcnt(11)
	ds_write_b128 v228, v[24:27] offset:12576
	global_load_dwordx4 v[24:27], v156, s[100:101] offset:2240
	s_waitcnt lgkmcnt(3)
	v_mfma_f32_16x16x32_bf16 v[104:107], v[168:171], v[176:179], v[104:107]
	v_mfma_f32_16x16x32_bf16 v[72:75], v[172:175], v[176:179], v[72:75]
	v_mfma_f32_16x16x32_bf16 v[52:55], v[180:183], v[176:179], v[52:55]
	v_mfma_f32_16x16x32_bf16 v[4:7], v[184:187], v[176:179], v[4:7]
	s_add_u32 s98, s98, s18
	s_addc_u32 s99, s99, s19
	s_add_u32 s100, s100, s10
	s_addc_u32 s101, s101, s11
	s_add_i32 s36, s36, 1
	s_waitcnt lgkmcnt(1)
	v_mfma_f32_16x16x32_bf16 v[92:95], v[168:171], v[188:191], v[92:95]
	v_mfma_f32_16x16x32_bf16 v[60:63], v[172:175], v[188:191], v[60:63]
	v_mfma_f32_16x16x32_bf16 v[48:51], v[180:183], v[188:191], v[48:51]
	v_mfma_f32_16x16x32_bf16 v[0:3], v[184:187], v[188:191], v[0:3]
	s_setprio 0
	s_waitcnt lgkmcnt(0)
	s_barrier
	s_bitcmp1_b32 s36, 0
	s_cselect_b32 s37, 0, 0x9000
	s_setprio 1
	v_or_b32_e32 v152, s37, v164
	v_lshl_add_u32 v184, v167, 1, v152
	ds_read_b128 v[168:171], v184
	ds_read_b128 v[172:175], v184 offset:1536
	ds_read_b128 v[180:183], v184 offset:3072
	ds_read_b128 v[184:187], v184 offset:4608
	v_lshl_add_u32 v152, v165, 1, v152
	ds_read_b128 v[176:179], v152 offset:12288
	ds_read_b128 v[188:191], v152 offset:13824
	s_xor_b32 s37, s37, 0x9000
	v_add3_u32 v228, v166, s37, v161
	s_waitcnt lgkmcnt(1)
	v_mfma_f32_16x16x32_bf16 v[148:151], v[168:171], v[176:179], v[148:151]
	v_mfma_f32_16x16x32_bf16 v[136:139], v[172:175], v[176:179], v[136:139]
	v_mfma_f32_16x16x32_bf16 v[112:115], v[180:183], v[176:179], v[112:115]
	v_mfma_f32_16x16x32_bf16 v[80:83], v[184:187], v[176:179], v[80:83]
	ds_read_b128 v[176:179], v152 offset:15360
	s_waitcnt vmcnt(11)
	ds_write_b128 v228, v[200:203]
	s_waitcnt lgkmcnt(2)
	v_mfma_f32_16x16x32_bf16 v[144:147], v[168:171], v[188:191], v[144:147]
	v_mfma_f32_16x16x32_bf16 v[128:131], v[172:175], v[188:191], v[128:131]
	v_mfma_f32_16x16x32_bf16 v[100:103], v[180:183], v[188:191], v[100:103]
	v_mfma_f32_16x16x32_bf16 v[68:71], v[184:187], v[188:191], v[68:71]
	ds_read_b128 v[188:191], v152 offset:16896
	s_waitcnt vmcnt(10)
	ds_write_b128 v228, v[204:207] offset:96
	v_add_u32_e32 v228, v228, v166
	global_load_dwordx4 v[200:203], v154, s[98:99]
	global_load_dwordx4 v[204:207], v154, s[98:99] offset:64
	s_waitcnt lgkmcnt(3)
; DI f32x4 mfma16(bf16x8 a, bf16x8 b, f32x4 c) { return __builtin_amdgcn_mfma_f32_16x16x32_bf16(a, b, c, 0, 0, 0); }
; template <int NI, class XL, class EP>
; DI void gemm_tile(const u16* __restrict__ W, int ldw, int f0, int t0, int K, XL xl, EP ep, unsigned char* smem) {
;     ...
;   for (int it = 0; it < nk; ++it) {
;     const u16* Ws = S0 + (it & 1) * BUF; const u16* Xs = Ws + 128 * LST;
;     __builtin_amdgcn_s_setprio(1);
;     bf16x8 a[4];
; #pragma unroll
;     for (int mi = 0; mi < 4; ++mi) a[mi] = *(const bf16x8*)(Ws + (wf * 64 + mi * 16 + lr) * LST + lq * 8);
; #pragma unroll
;     for (int ni = 0; ni < NI; ++ni) {
;       const bf16x8 b = *(const bf16x8*)(Xs + (wt * (NI * 16) + ni * 16 + lr) * LST + lq * 8);
; #pragma unroll
;       for (int mi = 0; mi < 4; ++mi) acc[mi][ni] = mfma16(a[mi], b, acc[mi][ni]);
;     }
;     __builtin_amdgcn_sched_group_barrier(0x100, 6, 0);
; #pragma unroll
;     for (int ni = 0; ni < NI; ++ni) { __builtin_amdgcn_sched_group_barrier(0x008, 4, 0); if (ni + 2 < NI) __builtin_amdgcn_sched_group_barrier(0x100, 1, 0); }
;     __builtin_amdgcn_s_setprio(0);
;     if (it + 1 < nk) lstore((it + 1) & 1);
;     if (it + 2 < nk) gload(it + 2);
;     __syncthreads();
;   }
	v_mfma_f32_16x16x32_bf16 v[140:143], v[168:171], v[176:179], v[140:143]
	v_mfma_f32_16x16x32_bf16 v[120:123], v[172:175], v[176:179], v[120:123]
	v_mfma_f32_16x16x32_bf16 v[88:91], v[180:183], v[176:179], v[88:91]
	v_mfma_f32_16x16x32_bf16 v[44:47], v[184:187], v[176:179], v[44:47]
	ds_read_b128 v[176:179], v152 offset:18432
	s_waitcnt vmcnt(11)
	ds_write_b128 v228, v[208:211] offset:12288
	global_load_dwordx4 v[208:211], v156, s[100:101] offset:2048
	s_waitcnt lgkmcnt(3)
	v_mfma_f32_16x16x32_bf16 v[132:135], v[168:171], v[188:191], v[132:135]
	v_mfma_f32_16x16x32_bf16 v[108:111], v[172:175], v[188:191], v[108:111]
	v_mfma_f32_16x16x32_bf16 v[76:79], v[180:183], v[188:191], v[76:79]
	v_mfma_f32_16x16x32_bf16 v[40:43], v[184:187], v[188:191], v[40:43]
	ds_read_b128 v[188:191], v152 offset:19968
	s_waitcnt vmcnt(11)
	ds_write_b128 v228, v[212:215] offset:12384
	global_load_dwordx4 v[212:215], v156, s[100:101] offset:2112
	s_waitcnt lgkmcnt(3)
	v_mfma_f32_16x16x32_bf16 v[124:127], v[168:171], v[176:179], v[124:127]
	v_mfma_f32_16x16x32_bf16 v[96:99], v[172:175], v[176:179], v[96:99]
	v_mfma_f32_16x16x32_bf16 v[64:67], v[180:183], v[176:179], v[64:67]
	v_mfma_f32_16x16x32_bf16 v[12:15], v[184:187], v[176:179], v[12:15]
	ds_read_b128 v[176:179], v152 offset:21504
	s_waitcnt vmcnt(11)
	ds_write_b128 v228, v[220:223] offset:12480
	global_load_dwordx4 v[220:223], v156, s[100:101] offset:2176
	s_waitcnt lgkmcnt(3)
	v_mfma_f32_16x16x32_bf16 v[116:119], v[168:171], v[188:191], v[116:119]
	v_mfma_f32_16x16x32_bf16 v[84:87], v[172:175], v[188:191], v[84:87]
	v_mfma_f32_16x16x32_bf16 v[56:59], v[180:183], v[188:191], v[56:59]
	v_mfma_f32_16x16x32_bf16 v[8:11], v[184:187], v[188:191], v[8:11]
	ds_read_b128 v[188:191], v152 offset:23040
	s_waitcnt vmcnt(11)
	ds_write_b128 v228, v[224:227] offset:12576
	global_load_dwordx4 v[224:227], v156, s[100:101] offset:2240
	s_waitcnt lgkmcnt(3)
	v_mfma_f32_16x16x32_bf16 v[104:107], v[168:171], v[176:179], v[104:107]
	v_mfma_f32_16x16x32_bf16 v[72:75], v[172:175], v[176:179], v[72:75]
	v_mfma_f32_16x16x32_bf16 v[52:55], v[180:183], v[176:179], v[52:55]
	v_mfma_f32_16x16x32_bf16 v[4:7], v[184:187], v[176:179], v[4:7]
	s_add_u32 s98, s98, s18
	s_addc_u32 s99, s99, s19
	s_add_u32 s100, s100, s10
	s_addc_u32 s101, s101, s11
	s_add_i32 s36, s36, 1
	s_waitcnt lgkmcnt(1)
	v_mfma_f32_16x16x32_bf16 v[92:95], v[168:171], v[188:191], v[92:95]
	v_mfma_f32_16x16x32_bf16 v[60:63], v[172:175], v[188:191], v[60:63]
	v_mfma_f32_16x16x32_bf16 v[48:51], v[180:183], v[188:191], v[48:51]
	v_mfma_f32_16x16x32_bf16 v[0:3], v[184:187], v[188:191], v[0:3]
	s_setprio 0
	s_cmp_lg_u32 s36, 29
	s_waitcnt lgkmcnt(0)
	s_barrier
	s_cbranch_scc1 .LBB0_812
	s_bitcmp1_b32 s36, 0
	s_cselect_b32 s37, 0, 0x9000
	s_setprio 1
	v_or_b32_e32 v152, s37, v164
	v_lshl_add_u32 v184, v167, 1, v152
	ds_read_b128 v[168:171], v184
	ds_read_b128 v[172:175], v184 offset:1536
	ds_read_b128 v[180:183], v184 offset:3072
	ds_read_b128 v[184:187], v184 offset:4608
	v_lshl_add_u32 v152, v165, 1, v152
	ds_read_b128 v[176:179], v152 offset:12288
	ds_read_b128 v[188:191], v152 offset:13824
	s_xor_b32 s37, s37, 0x9000
	v_add3_u32 v228, v166, s37, v161
	s_waitcnt lgkmcnt(1)
	v_mfma_f32_16x16x32_bf16 v[148:151], v[168:171], v[176:179], v[148:151]
	v_mfma_f32_16x16x32_bf16 v[136:139], v[172:175], v[176:179], v[136:139]
	v_mfma_f32_16x16x32_bf16 v[112:115], v[180:183], v[176:179], v[112:115]
	v_mfma_f32_16x16x32_bf16 v[80:83], v[184:187], v[176:179], v[80:83]
	ds_read_b128 v[176:179], v152 offset:15360
	s_waitcnt vmcnt(11)
	ds_write_b128 v228, v[20:23]
	s_waitcnt lgkmcnt(2)
	v_mfma_f32_16x16x32_bf16 v[144:147], v[168:171], v[188:191], v[144:147]
	v_mfma_f32_16x16x32_bf16 v[128:131], v[172:175], v[188:191], v[128:131]
	v_mfma_f32_16x16x32_bf16 v[100:103], v[180:183], v[188:191], v[100:103]
	v_mfma_f32_16x16x32_bf16 v[68:71], v[184:187], v[188:191], v[68:71]
	ds_read_b128 v[188:191], v152 offset:16896
	s_waitcnt vmcnt(10)
	ds_write_b128 v228, v[16:19] offset:96
	v_add_u32_e32 v228, v228, v166
	global_load_dwordx4 v[20:23], v154, s[98:99]
	global_load_dwordx4 v[16:19], v154, s[98:99] offset:64
	s_waitcnt lgkmcnt(3)
	v_mfma_f32_16x16x32_bf16 v[140:143], v[168:171], v[176:179], v[140:143]
	v_mfma_f32_16x16x32_bf16 v[120:123], v[172:175], v[176:179], v[120:123]
	v_mfma_f32_16x16x32_bf16 v[88:91], v[180:183], v[176:179], v[88:91]
	v_mfma_f32_16x16x32_bf16 v[44:47], v[184:187], v[176:179], v[44:47]
	ds_read_b128 v[176:179], v152 offset:18432
	s_waitcnt vmcnt(11)
	ds_write_b128 v228, v[36:39] offset:12288
	global_load_dwordx4 v[36:39], v156, s[100:101] offset:2048
	s_waitcnt lgkmcnt(3)
	v_mfma_f32_16x16x32_bf16 v[132:135], v[168:171], v[188:191], v[132:135]
	v_mfma_f32_16x16x32_bf16 v[108:111], v[172:175], v[188:191], v[108:111]
	v_mfma_f32_16x16x32_bf16 v[76:79], v[180:183], v[188:191], v[76:79]
	v_mfma_f32_16x16x32_bf16 v[40:43], v[184:187], v[188:191], v[40:43]
	ds_read_b128 v[188:191], v152 offset:19968
	s_waitcnt vmcnt(11)
	ds_write_b128 v228, v[32:35] offset:12384
	global_load_dwordx4 v[32:35], v156, s[100:101] offset:2112
	s_waitcnt lgkmcnt(3)
	v_mfma_f32_16x16x32_bf16 v[124:127], v[168:171], v[176:179], v[124:127]
	v_mfma_f32_16x16x32_bf16 v[96:99], v[172:175], v[176:179], v[96:99]
	v_mfma_f32_16x16x32_bf16 v[64:67], v[180:183], v[176:179], v[64:67]
	v_mfma_f32_16x16x32_bf16 v[12:15], v[184:187], v[176:179], v[12:15]
	ds_read_b128 v[176:179], v152 offset:21504
	s_waitcnt vmcnt(11)
	ds_write_b128 v228, v[28:31] offset:12480
	global_load_dwordx4 v[28:31], v156, s[100:101] offset:2176
	s_waitcnt lgkmcnt(3)
	v_mfma_f32_16x16x32_bf16 v[116:119], v[168:171], v[188:191], v[116:119]
	v_mfma_f32_16x16x32_bf16 v[84:87], v[172:175], v[188:191], v[84:87]
	v_mfma_f32_16x16x32_bf16 v[56:59], v[180:183], v[188:191], v[56:59]
	v_mfma_f32_16x16x32_bf16 v[8:11], v[184:187], v[188:191], v[8:11]
	ds_read_b128 v[188:191], v152 offset:23040
	s_waitcnt vmcnt(11)
	ds_write_b128 v228, v[24:27] offset:12576
	global_load_dwordx4 v[24:27], v156, s[100:101] offset:2240
	s_waitcnt lgkmcnt(3)
	v_mfma_f32_16x16x32_bf16 v[104:107], v[168:171], v[176:179], v[104:107]
	v_mfma_f32_16x16x32_bf16 v[72:75], v[172:175], v[176:179], v[72:75]
	v_mfma_f32_16x16x32_bf16 v[52:55], v[180:183], v[176:179], v[52:55]
	v_mfma_f32_16x16x32_bf16 v[4:7], v[184:187], v[176:179], v[4:7]
	s_add_u32 s98, s98, s18
	s_addc_u32 s99, s99, s19
	s_add_u32 s100, s100, s10
	s_addc_u32 s101, s101, s11
	s_add_i32 s36, s36, 1
	s_waitcnt lgkmcnt(1)
	v_mfma_f32_16x16x32_bf16 v[92:95], v[168:171], v[188:191], v[92:95]
	v_mfma_f32_16x16x32_bf16 v[60:63], v[172:175], v[188:191], v[60:63]
	v_mfma_f32_16x16x32_bf16 v[48:51], v[180:183], v[188:191], v[48:51]
	v_mfma_f32_16x16x32_bf16 v[0:3], v[184:187], v[188:191], v[0:3]
	s_setprio 0
	s_waitcnt lgkmcnt(0)
	s_barrier
; DI f32x4 mfma16(bf16x8 a, bf16x8 b, f32x4 c) { return __builtin_amdgcn_mfma_f32_16x16x32_bf16(a, b, c, 0, 0, 0); }
; template <int NI, class XL, class EP>
; DI void gemm_tile(const u16* __restrict__ W, int ldw, int f0, int t0, int K, XL xl, EP ep, unsigned char* smem) {
;     ...
;   for (int it = 0; it < nk; ++it) {
;     const u16* Ws = S0 + (it & 1) * BUF; const u16* Xs = Ws + 128 * LST;
;     __builtin_amdgcn_s_setprio(1);
;     bf16x8 a[4];
; #pragma unroll
;     for (int mi = 0; mi < 4; ++mi) a[mi] = *(const bf16x8*)(Ws + (wf * 64 + mi * 16 + lr) * LST + lq * 8);
; #pragma unroll
;     for (int ni = 0; ni < NI; ++ni) {
;       const bf16x8 b = *(const bf16x8*)(Xs + (wt * (NI * 16) + ni * 16 + lr) * LST + lq * 8);
; #pragma unroll
;       for (int mi = 0; mi < 4; ++mi) acc[mi][ni] = mfma16(a[mi], b, acc[mi][ni]);
;     }
;     __builtin_amdgcn_sched_group_barrier(0x100, 6, 0);
; #pragma unroll
;     for (int ni = 0; ni < NI; ++ni) { __builtin_amdgcn_sched_group_barrier(0x008, 4, 0); if (ni + 2 < NI) __builtin_amdgcn_sched_group_barrier(0x100, 1, 0); }
;     __builtin_amdgcn_s_setprio(0);
;     if (it + 1 < nk) lstore((it + 1) & 1);
;     if (it + 2 < nk) gload(it + 2);
;     __syncthreads();
;   }
	s_bitcmp1_b32 s36, 0
	s_cselect_b32 s37, 0, 0x9000
	s_setprio 1
	v_or_b32_e32 v152, s37, v164
	v_lshl_add_u32 v184, v167, 1, v152
	ds_read_b128 v[168:171], v184
	ds_read_b128 v[172:175], v184 offset:1536
	ds_read_b128 v[180:183], v184 offset:3072
	ds_read_b128 v[184:187], v184 offset:4608
	v_lshl_add_u32 v152, v165, 1, v152
	ds_read_b128 v[176:179], v152 offset:12288
	ds_read_b128 v[188:191], v152 offset:13824
	s_xor_b32 s37, s37, 0x9000
	v_add3_u32 v228, v166, s37, v161
	s_waitcnt lgkmcnt(1)
	v_mfma_f32_16x16x32_bf16 v[148:151], v[168:171], v[176:179], v[148:151]
	v_mfma_f32_16x16x32_bf16 v[136:139], v[172:175], v[176:179], v[136:139]
	v_mfma_f32_16x16x32_bf16 v[112:115], v[180:183], v[176:179], v[112:115]
	v_mfma_f32_16x16x32_bf16 v[80:83], v[184:187], v[176:179], v[80:83]
	ds_read_b128 v[176:179], v152 offset:15360
	s_waitcnt vmcnt(11)
	ds_write_b128 v228, v[200:203]
	s_waitcnt lgkmcnt(2)
	v_mfma_f32_16x16x32_bf16 v[144:147], v[168:171], v[188:191], v[144:147]
	v_mfma_f32_16x16x32_bf16 v[128:131], v[172:175], v[188:191], v[128:131]
	v_mfma_f32_16x16x32_bf16 v[100:103], v[180:183], v[188:191], v[100:103]
	v_mfma_f32_16x16x32_bf16 v[68:71], v[184:187], v[188:191], v[68:71]
	ds_read_b128 v[188:191], v152 offset:16896
	s_waitcnt vmcnt(10)
	ds_write_b128 v228, v[204:207] offset:96
	v_add_u32_e32 v228, v228, v166
	s_waitcnt lgkmcnt(3)
	v_mfma_f32_16x16x32_bf16 v[140:143], v[168:171], v[176:179], v[140:143]
	v_mfma_f32_16x16x32_bf16 v[120:123], v[172:175], v[176:179], v[120:123]
	v_mfma_f32_16x16x32_bf16 v[88:91], v[180:183], v[176:179], v[88:91]
	v_mfma_f32_16x16x32_bf16 v[44:47], v[184:187], v[176:179], v[44:47]
	ds_read_b128 v[176:179], v152 offset:18432
	s_waitcnt vmcnt(9)
	ds_write_b128 v228, v[208:211] offset:12288
	s_waitcnt lgkmcnt(3)
	v_mfma_f32_16x16x32_bf16 v[132:135], v[168:171], v[188:191], v[132:135]
	v_mfma_f32_16x16x32_bf16 v[108:111], v[172:175], v[188:191], v[108:111]
	v_mfma_f32_16x16x32_bf16 v[76:79], v[180:183], v[188:191], v[76:79]
	v_mfma_f32_16x16x32_bf16 v[40:43], v[184:187], v[188:191], v[40:43]
	ds_read_b128 v[188:191], v152 offset:19968
	s_waitcnt vmcnt(8)
	ds_write_b128 v228, v[212:215] offset:12384
	s_waitcnt lgkmcnt(3)
	v_mfma_f32_16x16x32_bf16 v[124:127], v[168:171], v[176:179], v[124:127]
	v_mfma_f32_16x16x32_bf16 v[96:99], v[172:175], v[176:179], v[96:99]
	v_mfma_f32_16x16x32_bf16 v[64:67], v[180:183], v[176:179], v[64:67]
	v_mfma_f32_16x16x32_bf16 v[12:15], v[184:187], v[176:179], v[12:15]
	ds_read_b128 v[176:179], v152 offset:21504
	s_waitcnt vmcnt(7)
	ds_write_b128 v228, v[220:223] offset:12480
	s_waitcnt lgkmcnt(3)
	v_mfma_f32_16x16x32_bf16 v[116:119], v[168:171], v[188:191], v[116:119]
	v_mfma_f32_16x16x32_bf16 v[84:87], v[172:175], v[188:191], v[84:87]
	v_mfma_f32_16x16x32_bf16 v[56:59], v[180:183], v[188:191], v[56:59]
	v_mfma_f32_16x16x32_bf16 v[8:11], v[184:187], v[188:191], v[8:11]
	ds_read_b128 v[188:191], v152 offset:23040
	s_waitcnt vmcnt(6)
	ds_write_b128 v228, v[224:227] offset:12576
	s_waitcnt lgkmcnt(3)
	v_mfma_f32_16x16x32_bf16 v[104:107], v[168:171], v[176:179], v[104:107]
	v_mfma_f32_16x16x32_bf16 v[72:75], v[172:175], v[176:179], v[72:75]
	v_mfma_f32_16x16x32_bf16 v[52:55], v[180:183], v[176:179], v[52:55]
	v_mfma_f32_16x16x32_bf16 v[4:7], v[184:187], v[176:179], v[4:7]
	s_add_u32 s98, s98, s18
	s_addc_u32 s99, s99, s19
	s_add_u32 s100, s100, s10
	s_addc_u32 s101, s101, s11
	s_add_i32 s36, s36, 1
	s_waitcnt lgkmcnt(1)
	v_mfma_f32_16x16x32_bf16 v[92:95], v[168:171], v[188:191], v[92:95]
	v_mfma_f32_16x16x32_bf16 v[60:63], v[172:175], v[188:191], v[60:63]
	v_mfma_f32_16x16x32_bf16 v[48:51], v[180:183], v[188:191], v[48:51]
	v_mfma_f32_16x16x32_bf16 v[0:3], v[184:187], v[188:191], v[0:3]
	s_setprio 0
	s_waitcnt lgkmcnt(0)
	s_barrier
	s_setprio 1
	v_lshl_add_u32 v152, v167, 1, v164
	ds_read_b128 v[154:157], v152
	v_lshl_add_u32 v161, v165, 1, v164
	ds_read_b128 v[164:167], v152 offset:1536
	ds_read_b128 v[172:175], v152 offset:3072
	ds_read_b128 v[176:179], v152 offset:4608
	ds_read_b128 v[168:171], v161 offset:12288
	ds_read_b128 v[180:183], v161 offset:13824
	s_waitcnt lgkmcnt(1)
	v_mfma_f32_16x16x32_bf16 v[148:151], v[154:157], v[168:171], v[148:151]
	v_mfma_f32_16x16x32_bf16 v[136:139], v[164:167], v[168:171], v[136:139]
	v_mfma_f32_16x16x32_bf16 v[112:115], v[172:175], v[168:171], v[112:115]
	v_mfma_f32_16x16x32_bf16 v[80:83], v[176:179], v[168:171], v[80:83]
	ds_read_b128 v[168:171], v161 offset:15360
	s_waitcnt lgkmcnt(1)
	v_mfma_f32_16x16x32_bf16 v[144:147], v[154:157], v[180:183], v[144:147]
	v_mfma_f32_16x16x32_bf16 v[128:131], v[164:167], v[180:183], v[128:131]
	v_mfma_f32_16x16x32_bf16 v[100:103], v[172:175], v[180:183], v[100:103]
	v_mfma_f32_16x16x32_bf16 v[68:71], v[176:179], v[180:183], v[68:71]
	ds_read_b128 v[180:183], v161 offset:16896
	s_waitcnt lgkmcnt(1)
	v_mfma_f32_16x16x32_bf16 v[140:143], v[154:157], v[168:171], v[140:143]
	v_mfma_f32_16x16x32_bf16 v[120:123], v[164:167], v[168:171], v[120:123]
	v_mfma_f32_16x16x32_bf16 v[184:187], v[172:175], v[168:171], v[88:91]
	v_mfma_f32_16x16x32_bf16 v[44:47], v[176:179], v[168:171], v[44:47]
	s_nop 1
	ds_read_b128 v[88:91], v161 offset:18432
	s_waitcnt lgkmcnt(1)
	v_mfma_f32_16x16x32_bf16 v[132:135], v[154:157], v[180:183], v[132:135]
	v_mfma_f32_16x16x32_bf16 v[168:171], v[164:167], v[180:183], v[108:111]
	v_mfma_f32_16x16x32_bf16 v[188:191], v[172:175], v[180:183], v[76:79]
	v_mfma_f32_16x16x32_bf16 v[180:183], v[176:179], v[180:183], v[40:43]
	s_nop 2
	ds_read_b128 v[40:43], v161 offset:19968
	s_waitcnt lgkmcnt(1)
; DI f32x4 mfma16(bf16x8 a, bf16x8 b, f32x4 c) { return __builtin_amdgcn_mfma_f32_16x16x32_bf16(a, b, c, 0, 0, 0); }
; template <int NI, class XL, class EP>
; DI void gemm_tile(const u16* __restrict__ W, int ldw, int f0, int t0, int K, XL xl, EP ep, unsigned char* smem) {
;     ...
;   for (int it = 0; it < nk; ++it) {
;     const u16* Ws = S0 + (it & 1) * BUF; const u16* Xs = Ws + 128 * LST;
;     __builtin_amdgcn_s_setprio(1);
;     bf16x8 a[4];
; #pragma unroll
;     for (int mi = 0; mi < 4; ++mi) a[mi] = *(const bf16x8*)(Ws + (wf * 64 + mi * 16 + lr) * LST + lq * 8);
; #pragma unroll
;     for (int ni = 0; ni < NI; ++ni) {
;       const bf16x8 b = *(const bf16x8*)(Xs + (wt * (NI * 16) + ni * 16 + lr) * LST + lq * 8);
; #pragma unroll
;       for (int mi = 0; mi < 4; ++mi) acc[mi][ni] = mfma16(a[mi], b, acc[mi][ni]);
;     }
;     __builtin_amdgcn_sched_group_barrier(0x100, 6, 0);
; #pragma unroll
;     for (int ni = 0; ni < NI; ++ni) { __builtin_amdgcn_sched_group_barrier(0x008, 4, 0); if (ni + 2 < NI) __builtin_amdgcn_sched_group_barrier(0x100, 1, 0); }
;     __builtin_amdgcn_s_setprio(0);
;     if (it + 1 < nk) lstore((it + 1) & 1);
;     if (it + 2 < nk) gload(it + 2);
;     __syncthreads();
;   }
; DI void phase6(const Params& p, const Sched& sched, unsigned char* smem) {
;     ...
;       constexpr int EST = 136;
;       u16* Ls = (u16*)smem;
;       const int b = tb >> 11;
;       __syncthreads();
; #pragma unroll
;       for (int mi = 0; mi < 4; ++mi) {
;         const int f = fb + mi * 16 + lq * 4; const float4 gm = *(const float4*)(mod + (size_t)b * 6144 + 2048 + f);
	v_mfma_f32_16x16x32_bf16 v[124:127], v[154:157], v[88:91], v[124:127]
	v_mfma_f32_16x16x32_bf16 v[192:195], v[164:167], v[88:91], v[96:99]
	v_mfma_f32_16x16x32_bf16 v[196:199], v[172:175], v[88:91], v[64:67]
	v_mfma_f32_16x16x32_bf16 v[200:203], v[176:179], v[88:91], v[12:15]
	s_nop 2
	ds_read_b128 v[12:15], v161 offset:21504
	s_waitcnt lgkmcnt(1)
	v_mfma_f32_16x16x32_bf16 v[116:119], v[154:157], v[40:43], v[116:119]
	v_mfma_f32_16x16x32_bf16 v[204:207], v[164:167], v[40:43], v[84:87]
	v_mfma_f32_16x16x32_bf16 v[56:59], v[172:175], v[40:43], v[56:59]
	v_mfma_f32_16x16x32_bf16 v[208:211], v[176:179], v[40:43], v[8:11]
	s_nop 2
	ds_read_b128 v[8:11], v161 offset:23040
	s_waitcnt lgkmcnt(1)
	v_mfma_f32_16x16x32_bf16 v[212:215], v[154:157], v[12:15], v[104:107]
	v_mfma_f32_16x16x32_bf16 v[72:75], v[164:167], v[12:15], v[72:75]
	v_mfma_f32_16x16x32_bf16 v[220:223], v[172:175], v[12:15], v[52:55]
	v_mfma_f32_16x16x32_bf16 v[224:227], v[176:179], v[12:15], v[4:7]
	s_waitcnt lgkmcnt(0)
	v_mfma_f32_16x16x32_bf16 v[154:157], v[154:157], v[8:11], v[92:95]
	v_mfma_f32_16x16x32_bf16 v[60:63], v[164:167], v[8:11], v[60:63]
	v_mfma_f32_16x16x32_bf16 v[164:167], v[172:175], v[8:11], v[48:51]
	v_mfma_f32_16x16x32_bf16 v[172:175], v[176:179], v[8:11], v[0:3]
	s_setprio 0
	s_waitcnt vmcnt(5)
	ds_write_b128 v162, v[20:23] offset:36864
	s_waitcnt vmcnt(4)
	ds_write_b128 v162, v[16:19] offset:36960
	s_waitcnt vmcnt(3)
	ds_write_b128 v163, v[36:39] offset:49152
	s_waitcnt vmcnt(2)
	ds_write_b128 v163, v[32:35] offset:49248
	s_waitcnt vmcnt(1)
	ds_write_b128 v163, v[28:31] offset:49344
	s_waitcnt vmcnt(0)
	ds_write_b128 v163, v[24:27] offset:49440
	s_waitcnt lgkmcnt(0)
	s_barrier
	s_lshl_b32 s34, s34, 7
	s_setprio 1
	ds_read_b128 v[28:31], v152 offset:36864
	ds_read_b128 v[176:179], v152 offset:38400
	ds_read_b128 v[228:231], v152 offset:39936
	ds_read_b128 v[232:235], v152 offset:41472
	ds_read_b128 v[0:3], v161 offset:49152
	ds_read_b128 v[4:7], v161 offset:50688
	s_waitcnt lgkmcnt(1)
	v_mfma_f32_16x16x32_bf16 v[88:91], v[28:31], v[0:3], v[148:151]
	v_mfma_f32_16x16x32_bf16 v[64:67], v[176:179], v[0:3], v[136:139]
	v_mfma_f32_16x16x32_bf16 v[32:35], v[228:231], v[0:3], v[112:115]
	v_mfma_f32_16x16x32_bf16 v[0:3], v[232:235], v[0:3], v[80:83]
	ds_read_b128 v[8:11], v161 offset:52224
	s_waitcnt lgkmcnt(1)
	v_mfma_f32_16x16x32_bf16 v[96:99], v[28:31], v[4:7], v[144:147]
	v_mfma_f32_16x16x32_bf16 v[76:79], v[176:179], v[4:7], v[128:131]
	v_mfma_f32_16x16x32_bf16 v[36:39], v[228:231], v[4:7], v[100:103]
	v_mfma_f32_16x16x32_bf16 v[4:7], v[232:235], v[4:7], v[68:71]
	ds_read_b128 v[12:15], v161 offset:53760
	s_waitcnt lgkmcnt(1)
	v_mfma_f32_16x16x32_bf16 v[104:107], v[28:31], v[8:11], v[140:143]
	v_mfma_f32_16x16x32_bf16 v[84:87], v[176:179], v[8:11], v[120:123]
	v_mfma_f32_16x16x32_bf16 v[40:43], v[228:231], v[8:11], v[184:187]
	v_mfma_f32_16x16x32_bf16 v[8:11], v[232:235], v[8:11], v[44:47]
	ds_read_b128 v[16:19], v161 offset:55296
	s_waitcnt lgkmcnt(1)
	v_mfma_f32_16x16x32_bf16 v[108:111], v[28:31], v[12:15], v[132:135]
	v_mfma_f32_16x16x32_bf16 v[92:95], v[176:179], v[12:15], v[168:171]
	v_mfma_f32_16x16x32_bf16 v[44:47], v[228:231], v[12:15], v[188:191]
	v_mfma_f32_16x16x32_bf16 v[12:15], v[232:235], v[12:15], v[180:183]
	ds_read_b128 v[20:23], v161 offset:56832
	s_waitcnt lgkmcnt(1)
	v_mfma_f32_16x16x32_bf16 v[112:115], v[28:31], v[16:19], v[124:127]
	v_mfma_f32_16x16x32_bf16 v[100:103], v[176:179], v[16:19], v[192:195]
	v_mfma_f32_16x16x32_bf16 v[48:51], v[228:231], v[16:19], v[196:199]
	v_mfma_f32_16x16x32_bf16 v[16:19], v[232:235], v[16:19], v[200:203]
	ds_read_b128 v[24:27], v161 offset:58368
	s_waitcnt lgkmcnt(1)
	v_mfma_f32_16x16x32_bf16 v[116:119], v[28:31], v[20:23], v[116:119]
	v_mfma_f32_16x16x32_bf16 v[68:71], v[176:179], v[20:23], v[204:207]
	v_mfma_f32_16x16x32_bf16 v[52:55], v[228:231], v[20:23], v[56:59]
	v_mfma_f32_16x16x32_bf16 v[20:23], v[232:235], v[20:23], v[208:211]
	ds_read_b128 v[128:131], v161 offset:59904
	s_waitcnt lgkmcnt(1)
	v_mfma_f32_16x16x32_bf16 v[120:123], v[28:31], v[24:27], v[212:215]
	v_mfma_f32_16x16x32_bf16 v[80:83], v[176:179], v[24:27], v[72:75]
	v_mfma_f32_16x16x32_bf16 v[56:59], v[228:231], v[24:27], v[220:223]
	v_mfma_f32_16x16x32_bf16 v[24:27], v[232:235], v[24:27], v[224:227]
	s_waitcnt lgkmcnt(0)
	v_mfma_f32_16x16x32_bf16 v[124:127], v[28:31], v[128:131], v[154:157]
	v_mfma_f32_16x16x32_bf16 v[72:75], v[176:179], v[128:131], v[60:63]
	v_mfma_f32_16x16x32_bf16 v[60:63], v[228:231], v[128:131], v[164:167]
	v_mfma_f32_16x16x32_bf16 v[28:31], v[232:235], v[128:131], v[172:175]
	s_setprio 0
	s_ashr_i32 s35, s35, 3
	v_add_u32_e32 v128, s34, v160
	s_mul_hi_i32 s37, s35, 0x6000
	s_mulk_i32 s35, 0x6000
	v_lshl_or_b32 v128, v158, 2, v128
	s_add_u32 s36, s72, s35
	s_addc_u32 s37, s73, s37
	v_ashrrev_i32_e32 v129, 31, v128
	v_lshl_add_u64 v[128:129], v[128:129], 2, s[36:37]
	v_add_co_u32_e32 v140, vcc, s26, v128
	v_mul_u32_u24_e32 v138, 0x88, v159
	s_nop 0
	v_addc_co_u32_e32 v141, vcc, 0, v129, vcc
	v_lshlrev_b32_e32 v136, 1, v160
	v_lshlrev_b32_e32 v137, 3, v158
	v_lshlrev_b32_e32 v138, 1, v138
	s_barrier
	s_barrier
; DI void store4(u16* dst, f32x4 v) { uint2 w; w.x = cvtpk(v[0], v[1]); w.y = cvtpk(v[2], v[3]); *(uint2*)dst = w; }
; DI void phase6(const Params& p, const Sched& sched, unsigned char* smem) {
;     ...
;       const int b = tb >> 11;
;       __syncthreads();
; #pragma unroll
;       for (int mi = 0; mi < 4; ++mi) {
;         const int f = fb + mi * 16 + lq * 4; const float4 gm = *(const float4*)(mod + (size_t)b * 6144 + 2048 + f);
; #pragma unroll
;         for (int ni = 0; ni < 8; ++ni) {
;           const f32x4 o = {gm.x * acc[mi][ni][0], gm.y * acc[mi][ni][1], gm.z * acc[mi][ni][2], gm.w * acc[mi][ni][3]};
;           store4(Ls + (wt * 128 + ni * 16 + lr) * EST + wf * 64 + mi * 16 + lq * 4, o);
;         }
;       }
;       __syncthreads();
	global_load_dwordx4 v[128:131], v[140:141], off
	global_load_dwordx4 v[132:135], v[140:141], off offset:64
	v_add3_u32 v144, v136, v137, v138
	global_load_dwordx4 v[136:139], v[140:141], off offset:128
	v_add_u32_e32 v145, 0x1000, v144
	global_load_dwordx4 v[140:143], v[140:141], off offset:192
	v_add_u32_e32 v146, 0x2000, v144
	v_add_u32_e32 v147, 0x3000, v144
	v_add_u32_e32 v148, 0x4000, v144
	s_add_i32 s31, s31, s78
	s_add_i32 s30, s30, s78
	s_cmp_gt_i32 s31, 63
	s_waitcnt vmcnt(3)
	v_pk_mul_f32 v[88:89], v[88:89], v[128:129]
	v_pk_mul_f32 v[90:91], v[90:91], v[130:131]
	v_pk_mul_f32 v[96:97], v[96:97], v[128:129]
	s_waitcnt vmcnt(1)
	v_pk_mul_f32 v[32:33], v[32:33], v[136:137]
	v_pk_mul_f32 v[34:35], v[34:35], v[138:139]
	s_waitcnt vmcnt(0)
	v_pk_mul_f32 v[0:1], v[0:1], v[140:141]
	v_pk_mul_f32 v[2:3], v[2:3], v[142:143]
	v_cvt_pk_bf16_f32 v32, v32, v33
	v_cvt_pk_bf16_f32 v33, v34, v35
	v_cvt_pk_bf16_f32 v0, v0, v1
	v_cvt_pk_bf16_f32 v1, v2, v3
	v_pk_mul_f32 v[34:35], v[36:37], v[136:137]
	v_pk_mul_f32 v[36:37], v[38:39], v[138:139]
	ds_write2_b64 v144, v[32:33], v[0:1] offset0:8 offset1:12
	v_pk_mul_f32 v[0:1], v[4:5], v[140:141]
	v_pk_mul_f32 v[2:3], v[6:7], v[142:143]
	v_cvt_pk_bf16_f32 v34, v34, v35
	v_cvt_pk_bf16_f32 v35, v36, v37
	v_cvt_pk_bf16_f32 v0, v0, v1
	v_cvt_pk_bf16_f32 v1, v2, v3
	v_pk_mul_f32 v[36:37], v[40:41], v[136:137]
	v_pk_mul_f32 v[38:39], v[42:43], v[138:139]
	ds_write2_b64 v145, v[34:35], v[0:1] offset0:40 offset1:44
	v_pk_mul_f32 v[0:1], v[8:9], v[140:141]
	v_pk_mul_f32 v[2:3], v[10:11], v[142:143]
	v_cvt_pk_bf16_f32 v36, v36, v37
	v_cvt_pk_bf16_f32 v37, v38, v39
	v_cvt_pk_bf16_f32 v0, v0, v1
	v_cvt_pk_bf16_f32 v1, v2, v3
	v_pk_mul_f32 v[38:39], v[44:45], v[136:137]
	v_pk_mul_f32 v[40:41], v[46:47], v[138:139]
	ds_write2_b64 v146, v[36:37], v[0:1] offset0:72 offset1:76
	v_pk_mul_f32 v[0:1], v[12:13], v[140:141]
	v_pk_mul_f32 v[2:3], v[14:15], v[142:143]
	v_cvt_pk_bf16_f32 v38, v38, v39
	v_cvt_pk_bf16_f32 v39, v40, v41
	v_cvt_pk_bf16_f32 v0, v0, v1
	v_cvt_pk_bf16_f32 v1, v2, v3
	v_pk_mul_f32 v[98:99], v[98:99], v[130:131]
	v_pk_mul_f32 v[64:65], v[64:65], v[132:133]
	v_pk_mul_f32 v[66:67], v[66:67], v[134:135]
	v_pk_mul_f32 v[76:77], v[76:77], v[132:133]
	v_pk_mul_f32 v[78:79], v[78:79], v[134:135]
	v_pk_mul_f32 v[40:41], v[48:49], v[136:137]
	v_pk_mul_f32 v[42:43], v[50:51], v[138:139]
	ds_write2_b64 v147, v[38:39], v[0:1] offset0:104 offset1:108
	v_pk_mul_f32 v[0:1], v[16:17], v[140:141]
	v_pk_mul_f32 v[2:3], v[18:19], v[142:143]
	v_cvt_pk_bf16_f32 v88, v88, v89
	v_cvt_pk_bf16_f32 v89, v90, v91
	v_cvt_pk_bf16_f32 v90, v96, v97
	v_cvt_pk_bf16_f32 v91, v98, v99
	v_cvt_pk_bf16_f32 v64, v64, v65
	v_cvt_pk_bf16_f32 v65, v66, v67
	v_cvt_pk_bf16_f32 v66, v76, v77
	v_cvt_pk_bf16_f32 v67, v78, v79
	v_cvt_pk_bf16_f32 v40, v40, v41
	v_cvt_pk_bf16_f32 v41, v42, v43
	v_cvt_pk_bf16_f32 v0, v0, v1
	v_cvt_pk_bf16_f32 v1, v2, v3
	v_pk_mul_f32 v[106:107], v[106:107], v[130:131]
	v_pk_mul_f32 v[116:117], v[116:117], v[128:129]
	v_pk_mul_f32 v[118:119], v[118:119], v[130:131]
	ds_write2_b64 v144, v[88:89], v[64:65] offset1:4
	ds_write2_b64 v145, v[90:91], v[66:67] offset0:32 offset1:36
	v_pk_mul_f32 v[64:65], v[68:69], v[132:133]
	v_pk_mul_f32 v[66:67], v[70:71], v[134:135]
	v_pk_mul_f32 v[42:43], v[52:53], v[136:137]
	v_pk_mul_f32 v[44:45], v[54:55], v[138:139]
	ds_write2_b64 v148, v[40:41], v[0:1] offset0:136 offset1:140
	v_pk_mul_f32 v[0:1], v[20:21], v[140:141]
	v_pk_mul_f32 v[2:3], v[22:23], v[142:143]
	v_cvt_pk_bf16_f32 v97, v106, v107
	v_cvt_pk_bf16_f32 v106, v116, v117
	v_cvt_pk_bf16_f32 v107, v118, v119
	v_cvt_pk_bf16_f32 v64, v64, v65
	v_cvt_pk_bf16_f32 v65, v66, v67
	v_add_u32_e32 v68, 0x5000, v144
	v_cvt_pk_bf16_f32 v42, v42, v43
	v_cvt_pk_bf16_f32 v43, v44, v45
	v_cvt_pk_bf16_f32 v0, v0, v1
	v_cvt_pk_bf16_f32 v1, v2, v3
	v_pk_mul_f32 v[108:109], v[108:109], v[128:129]
	v_pk_mul_f32 v[120:121], v[120:121], v[128:129]
	v_pk_mul_f32 v[122:123], v[122:123], v[130:131]
	ds_write2_b64 v68, v[106:107], v[64:65] offset0:160 offset1:164
	v_pk_mul_f32 v[64:65], v[80:81], v[132:133]
	v_pk_mul_f32 v[66:67], v[82:83], v[134:135]
	v_pk_mul_f32 v[44:45], v[56:57], v[136:137]
	v_pk_mul_f32 v[46:47], v[58:59], v[138:139]
	ds_write2_b64 v68, v[42:43], v[0:1] offset0:168 offset1:172
	v_pk_mul_f32 v[0:1], v[24:25], v[140:141]
	v_pk_mul_f32 v[2:3], v[26:27], v[142:143]
	v_cvt_pk_bf16_f32 v98, v108, v109
	v_cvt_pk_bf16_f32 v108, v120, v121
	v_cvt_pk_bf16_f32 v109, v122, v123
	v_cvt_pk_bf16_f32 v64, v64, v65
	v_cvt_pk_bf16_f32 v65, v66, v67
	v_add_u32_e32 v69, 0x6000, v144
	v_cvt_pk_bf16_f32 v44, v44, v45
	v_cvt_pk_bf16_f32 v45, v46, v47
	v_cvt_pk_bf16_f32 v0, v0, v1
	v_cvt_pk_bf16_f32 v1, v2, v3
	v_pk_mul_f32 v[104:105], v[104:105], v[128:129]
	v_pk_mul_f32 v[110:111], v[110:111], v[130:131]
	v_pk_mul_f32 v[112:113], v[112:113], v[128:129]
	v_pk_mul_f32 v[114:115], v[114:115], v[130:131]
	v_pk_mul_f32 v[124:125], v[124:125], v[128:129]
	v_pk_mul_f32 v[126:127], v[126:127], v[130:131]
	v_pk_mul_f32 v[84:85], v[84:85], v[132:133]
	v_pk_mul_f32 v[86:87], v[86:87], v[134:135]
	v_pk_mul_f32 v[92:93], v[92:93], v[132:133]
	v_pk_mul_f32 v[94:95], v[94:95], v[134:135]
	v_pk_mul_f32 v[100:101], v[100:101], v[132:133]
	v_pk_mul_f32 v[102:103], v[102:103], v[134:135]
	ds_write2_b64 v69, v[108:109], v[64:65] offset0:192 offset1:196
	v_pk_mul_f32 v[64:65], v[72:73], v[132:133]
	v_pk_mul_f32 v[66:67], v[74:75], v[134:135]
	v_pk_mul_f32 v[46:47], v[60:61], v[136:137]
	v_pk_mul_f32 v[48:49], v[62:63], v[138:139]
	ds_write2_b64 v69, v[44:45], v[0:1] offset0:200 offset1:204
	v_pk_mul_f32 v[0:1], v[28:29], v[140:141]
	v_pk_mul_f32 v[2:3], v[30:31], v[142:143]
	v_cvt_pk_bf16_f32 v96, v104, v105
	v_cvt_pk_bf16_f32 v99, v110, v111
	v_cvt_pk_bf16_f32 v104, v112, v113
	v_cvt_pk_bf16_f32 v105, v114, v115
	v_cvt_pk_bf16_f32 v110, v124, v125
	v_cvt_pk_bf16_f32 v111, v126, v127
	v_cvt_pk_bf16_f32 v76, v84, v85
	v_cvt_pk_bf16_f32 v77, v86, v87
	v_cvt_pk_bf16_f32 v78, v92, v93
	v_cvt_pk_bf16_f32 v79, v94, v95
	v_cvt_pk_bf16_f32 v84, v100, v101
	v_cvt_pk_bf16_f32 v85, v102, v103
	v_cvt_pk_bf16_f32 v64, v64, v65
	v_cvt_pk_bf16_f32 v65, v66, v67
	v_add_u32_e32 v66, 0x7000, v144
	v_cvt_pk_bf16_f32 v46, v46, v47
	v_cvt_pk_bf16_f32 v47, v48, v49
	v_cvt_pk_bf16_f32 v0, v0, v1
	v_cvt_pk_bf16_f32 v1, v2, v3
	v_mov_b32_e32 v2, v218
	ds_write2_b64 v146, v[96:97], v[76:77] offset0:64 offset1:68
	ds_write2_b64 v147, v[98:99], v[78:79] offset0:96 offset1:100
	ds_write2_b64 v148, v[104:105], v[84:85] offset0:128 offset1:132
	ds_write2_b64 v66, v[110:111], v[64:65] offset0:224 offset1:228
	ds_write2_b64 v66, v[46:47], v[0:1] offset0:232 offset1:236
	s_waitcnt lgkmcnt(0)
	s_barrier
; DI int tidx() { int t = __builtin_amdgcn_workitem_id_x(); asm volatile("" : "+v"(t)); return t; }
; DI unsigned cvtpk(float lo, float hi) { const f32x2_ v = {lo, hi}; return __builtin_bit_cast(unsigned, __builtin_convertvector(v, bf16x2_)); }
; DI float bflo(unsigned w) { return __uint_as_float(w << 16); }
; DI float bfhi(unsigned w) { return __uint_as_float(w & 0xffff0000u); }
; DI void phase6(const Params& p, const Sched& sched, unsigned char* smem) {
;     ...
;       const int tid = tidx();
; #pragma unroll
;       for (int i = 0; i < 16; ++i) {
;         const int c = tid + 256 * i, row = c >> 4, ch = (c & 15) * 8;
;         const size_t gi = (size_t)(tm * 256 + row) * 1024 + tn * 128 + ch;
;         const u32x4 sv = *(const u32x4*)(Ls + row * EST + ch);
;         const f32x4 x0 = *(const f32x4*)(p.x + gi), x1 = *(const f32x4*)(p.x + gi + 4);
;         u32x4 w;
;         w.x = cvtpk(x0[0] + bflo(sv.x), x0[1] + bfhi(sv.x)); w.y = cvtpk(x0[2] + bflo(sv.y), x0[3] + bfhi(sv.y));
;         w.z = cvtpk(x1[0] + bflo(sv.z), x1[1] + bfhi(sv.z)); w.w = cvtpk(x1[2] + bflo(sv.w), x1[3] + bfhi(sv.w));
;         *(u32x4*)(x1b + gi) = w;
;       }
	s_nop 0
	v_ashrrev_i32_e32 v3, 4, v2
	v_add_u32_e32 v4, s33, v3
	v_lshlrev_b32_e32 v0, 3, v2
	v_ashrrev_i32_e32 v5, 31, v4
	v_and_b32_e32 v1, 0x78, v0
	v_lshlrev_b64 v[16:17], 10, v[4:5]
	v_or3_b32 v16, v16, s34, v1
	v_lshl_add_u64 v[8:9], v[16:17], 2, s[76:77]
	global_load_dwordx4 v[4:7], v[8:9], off
	v_lshlrev_b32_e32 v0, 1, v1
	global_load_dwordx4 v[8:11], v[8:9], off offset:16
	v_mad_u64_u32 v[12:13], s[36:37], v3, s27, v[0:1]
	ds_read_b128 v[12:15], v12
	v_add_u32_e32 v3, 0x100, v2
	v_ashrrev_i32_e32 v3, 4, v3
	s_waitcnt lgkmcnt(0)
	v_lshlrev_b32_e32 v18, 16, v12
	v_and_b32_e32 v19, 0xffff0000, v12
	v_lshlrev_b32_e32 v12, 16, v13
	v_and_b32_e32 v13, 0xffff0000, v13
	s_waitcnt vmcnt(1)
	v_pk_add_f32 v[4:5], v[4:5], v[18:19]
	v_pk_add_f32 v[6:7], v[6:7], v[12:13]
	v_cvt_pk_bf16_f32 v4, v4, v5
	v_cvt_pk_bf16_f32 v5, v6, v7
	v_lshlrev_b32_e32 v6, 16, v14
	v_and_b32_e32 v7, 0xffff0000, v14
	s_waitcnt vmcnt(0)
	v_pk_add_f32 v[6:7], v[8:9], v[6:7]
	v_lshlrev_b32_e32 v8, 16, v15
	v_and_b32_e32 v9, 0xffff0000, v15
	v_pk_add_f32 v[8:9], v[10:11], v[8:9]
	v_cvt_pk_bf16_f32 v6, v6, v7
	v_cvt_pk_bf16_f32 v7, v8, v9
	v_lshl_add_u64 v[8:9], v[16:17], 1, s[12:13]
	global_store_dwordx4 v[8:9], v[4:7], off
	v_add_u32_e32 v12, 0x200, v2
	v_ashrrev_i32_e32 v26, 4, v12
	v_add_u32_e32 v4, s33, v3
	v_ashrrev_i32_e32 v5, 31, v4
	v_lshlrev_b64 v[16:17], 10, v[4:5]
	v_or3_b32 v16, v16, s34, v1
	v_lshl_add_u64 v[8:9], v[16:17], 2, s[76:77]
	global_load_dwordx4 v[4:7], v[8:9], off
	v_mad_u64_u32 v[12:13], s[36:37], v3, s27, v[0:1]
	global_load_dwordx4 v[8:11], v[8:9], off offset:16
	ds_read_b128 v[12:15], v12
	v_add_u32_e32 v18, s33, v26
	v_ashrrev_i32_e32 v19, 31, v18
	v_lshlrev_b64 v[18:19], 10, v[18:19]
	v_or3_b32 v18, v18, s34, v1
	s_waitcnt lgkmcnt(0)
	v_lshlrev_b32_e32 v22, 16, v12
	v_and_b32_e32 v23, 0xffff0000, v12
	v_lshlrev_b32_e32 v12, 16, v13
	v_and_b32_e32 v13, 0xffff0000, v13
	v_lshlrev_b32_e32 v24, 16, v14
	v_and_b32_e32 v25, 0xffff0000, v14
	v_lshlrev_b32_e32 v14, 16, v15
	v_and_b32_e32 v15, 0xffff0000, v15
	v_lshl_add_u64 v[16:17], v[16:17], 1, s[12:13]
	v_lshl_add_u64 v[20:21], v[18:19], 2, s[76:77]
	v_add_u32_e32 v3, 0x300, v2
	v_ashrrev_i32_e32 v3, 4, v3
	v_lshl_add_u64 v[18:19], v[18:19], 1, s[12:13]
	s_waitcnt vmcnt(1)
	v_pk_add_f32 v[4:5], v[4:5], v[22:23]
	v_pk_add_f32 v[6:7], v[6:7], v[12:13]
	v_cvt_pk_bf16_f32 v4, v4, v5
	s_waitcnt vmcnt(0)
	v_pk_add_f32 v[8:9], v[8:9], v[24:25]
	v_pk_add_f32 v[10:11], v[10:11], v[14:15]
	v_cvt_pk_bf16_f32 v5, v6, v7
	v_cvt_pk_bf16_f32 v6, v8, v9
	v_cvt_pk_bf16_f32 v7, v10, v11
	global_store_dwordx4 v[16:17], v[4:7], off
	global_load_dwordx4 v[4:7], v[20:21], off
	v_mad_u64_u32 v[12:13], s[36:37], v26, s27, v[0:1]
	global_load_dwordx4 v[8:11], v[20:21], off offset:16
	ds_read_b128 v[12:15], v12
	v_add_u32_e32 v16, s33, v3
	v_ashrrev_i32_e32 v17, 31, v16
	v_lshlrev_b64 v[16:17], 10, v[16:17]
	v_or3_b32 v16, v16, s34, v1
	s_waitcnt lgkmcnt(0)
	v_lshlrev_b32_e32 v22, 16, v12
	v_and_b32_e32 v23, 0xffff0000, v12
	v_lshlrev_b32_e32 v12, 16, v13
	v_and_b32_e32 v13, 0xffff0000, v13
	v_lshlrev_b32_e32 v24, 16, v14
	v_and_b32_e32 v25, 0xffff0000, v14
	v_lshlrev_b32_e32 v14, 16, v15
	v_and_b32_e32 v15, 0xffff0000, v15
	v_lshl_add_u64 v[20:21], v[16:17], 2, s[76:77]
	v_lshl_add_u64 v[16:17], v[16:17], 1, s[12:13]
	s_waitcnt vmcnt(1)
	v_pk_add_f32 v[4:5], v[4:5], v[22:23]
	v_pk_add_f32 v[6:7], v[6:7], v[12:13]
	v_cvt_pk_bf16_f32 v4, v4, v5
	s_waitcnt vmcnt(0)
	v_pk_add_f32 v[8:9], v[8:9], v[24:25]
	v_pk_add_f32 v[10:11], v[10:11], v[14:15]
	v_cvt_pk_bf16_f32 v5, v6, v7
	v_cvt_pk_bf16_f32 v6, v8, v9
	v_cvt_pk_bf16_f32 v7, v10, v11
	global_store_dwordx4 v[18:19], v[4:7], off
	global_load_dwordx4 v[4:7], v[20:21], off
	v_add_u32_e32 v12, 0x400, v2
	global_load_dwordx4 v[8:11], v[20:21], off offset:16
	v_ashrrev_i32_e32 v26, 4, v12
	v_mad_u64_u32 v[12:13], s[36:37], v3, s27, v[0:1]
	ds_read_b128 v[12:15], v12
	v_add_u32_e32 v18, s33, v26
	v_ashrrev_i32_e32 v19, 31, v18
	v_lshlrev_b64 v[18:19], 10, v[18:19]
	v_or3_b32 v18, v18, s34, v1
	s_waitcnt lgkmcnt(0)
	v_lshlrev_b32_e32 v22, 16, v12
	v_and_b32_e32 v23, 0xffff0000, v12
	v_lshlrev_b32_e32 v12, 16, v13
	v_and_b32_e32 v13, 0xffff0000, v13
	v_lshlrev_b32_e32 v24, 16, v14
	v_and_b32_e32 v25, 0xffff0000, v14
	v_lshlrev_b32_e32 v14, 16, v15
	v_and_b32_e32 v15, 0xffff0000, v15
	v_lshl_add_u64 v[20:21], v[18:19], 2, s[76:77]
	v_add_u32_e32 v3, 0x500, v2
	v_ashrrev_i32_e32 v3, 4, v3
	v_lshl_add_u64 v[18:19], v[18:19], 1, s[12:13]
	s_waitcnt vmcnt(1)
	v_pk_add_f32 v[4:5], v[4:5], v[22:23]
	v_pk_add_f32 v[6:7], v[6:7], v[12:13]
	s_waitcnt vmcnt(0)
	v_pk_add_f32 v[8:9], v[8:9], v[24:25]
	v_pk_add_f32 v[10:11], v[10:11], v[14:15]
	v_cvt_pk_bf16_f32 v4, v4, v5
	v_cvt_pk_bf16_f32 v5, v6, v7
	v_cvt_pk_bf16_f32 v6, v8, v9
	v_cvt_pk_bf16_f32 v7, v10, v11
	global_store_dwordx4 v[16:17], v[4:7], off
	global_load_dwordx4 v[4:7], v[20:21], off
	v_mad_u64_u32 v[12:13], s[36:37], v26, s27, v[0:1]
	global_load_dwordx4 v[8:11], v[20:21], off offset:16
	ds_read_b128 v[12:15], v12
	v_add_u32_e32 v16, s33, v3
	v_ashrrev_i32_e32 v17, 31, v16
	v_lshlrev_b64 v[16:17], 10, v[16:17]
	v_or3_b32 v16, v16, s34, v1
	s_waitcnt lgkmcnt(0)
	v_lshlrev_b32_e32 v22, 16, v12
	v_and_b32_e32 v23, 0xffff0000, v12
	v_lshlrev_b32_e32 v12, 16, v13
	v_and_b32_e32 v13, 0xffff0000, v13
	v_lshlrev_b32_e32 v24, 16, v14
	v_and_b32_e32 v25, 0xffff0000, v14
	v_lshlrev_b32_e32 v14, 16, v15
	v_and_b32_e32 v15, 0xffff0000, v15
	v_lshl_add_u64 v[20:21], v[16:17], 2, s[76:77]
	v_lshl_add_u64 v[16:17], v[16:17], 1, s[12:13]
	s_waitcnt vmcnt(1)
	v_pk_add_f32 v[4:5], v[4:5], v[22:23]
	v_pk_add_f32 v[6:7], v[6:7], v[12:13]
	v_cvt_pk_bf16_f32 v4, v4, v5
	s_waitcnt vmcnt(0)
; DI int tidx() { int t = __builtin_amdgcn_workitem_id_x(); asm volatile("" : "+v"(t)); return t; }
; DI unsigned cvtpk(float lo, float hi) { const f32x2_ v = {lo, hi}; return __builtin_bit_cast(unsigned, __builtin_convertvector(v, bf16x2_)); }
; DI float bflo(unsigned w) { return __uint_as_float(w << 16); }
; DI float bfhi(unsigned w) { return __uint_as_float(w & 0xffff0000u); }
; DI void phase6(const Params& p, const Sched& sched, unsigned char* smem) {
;     ...
;       const int tid = tidx();
; #pragma unroll
;       for (int i = 0; i < 16; ++i) {
;         const int c = tid + 256 * i, row = c >> 4, ch = (c & 15) * 8;
;         const size_t gi = (size_t)(tm * 256 + row) * 1024 + tn * 128 + ch;
;         const u32x4 sv = *(const u32x4*)(Ls + row * EST + ch);
;         const f32x4 x0 = *(const f32x4*)(p.x + gi), x1 = *(const f32x4*)(p.x + gi + 4);
;         u32x4 w;
;         w.x = cvtpk(x0[0] + bflo(sv.x), x0[1] + bfhi(sv.x)); w.y = cvtpk(x0[2] + bflo(sv.y), x0[3] + bfhi(sv.y));
;         w.z = cvtpk(x1[0] + bflo(sv.z), x1[1] + bfhi(sv.z)); w.w = cvtpk(x1[2] + bflo(sv.w), x1[3] + bfhi(sv.w));
;         *(u32x4*)(x1b + gi) = w;
;       }
	v_pk_add_f32 v[8:9], v[8:9], v[24:25]
	v_pk_add_f32 v[10:11], v[10:11], v[14:15]
	v_cvt_pk_bf16_f32 v5, v6, v7
	v_cvt_pk_bf16_f32 v6, v8, v9
	v_cvt_pk_bf16_f32 v7, v10, v11
	global_store_dwordx4 v[18:19], v[4:7], off
	global_load_dwordx4 v[4:7], v[20:21], off
	v_add_u32_e32 v12, 0x600, v2
	global_load_dwordx4 v[8:11], v[20:21], off offset:16
	v_ashrrev_i32_e32 v26, 4, v12
	v_mad_u64_u32 v[12:13], s[36:37], v3, s27, v[0:1]
	ds_read_b128 v[12:15], v12
	v_add_u32_e32 v18, s33, v26
	v_ashrrev_i32_e32 v19, 31, v18
	v_lshlrev_b64 v[18:19], 10, v[18:19]
	v_or3_b32 v18, v18, s34, v1
	s_waitcnt lgkmcnt(0)
	v_lshlrev_b32_e32 v22, 16, v12
	v_and_b32_e32 v23, 0xffff0000, v12
	v_lshlrev_b32_e32 v12, 16, v13
	v_and_b32_e32 v13, 0xffff0000, v13
	v_lshlrev_b32_e32 v24, 16, v14
	v_and_b32_e32 v25, 0xffff0000, v14
	v_lshlrev_b32_e32 v14, 16, v15
	v_and_b32_e32 v15, 0xffff0000, v15
	v_lshl_add_u64 v[20:21], v[18:19], 2, s[76:77]
	v_add_u32_e32 v3, 0x700, v2
	v_ashrrev_i32_e32 v3, 4, v3
	v_lshl_add_u64 v[18:19], v[18:19], 1, s[12:13]
	s_waitcnt vmcnt(1)
	v_pk_add_f32 v[4:5], v[4:5], v[22:23]
	v_pk_add_f32 v[6:7], v[6:7], v[12:13]
	s_waitcnt vmcnt(0)
	v_pk_add_f32 v[8:9], v[8:9], v[24:25]
	v_pk_add_f32 v[10:11], v[10:11], v[14:15]
	v_cvt_pk_bf16_f32 v4, v4, v5
	v_cvt_pk_bf16_f32 v5, v6, v7
	v_cvt_pk_bf16_f32 v6, v8, v9
	v_cvt_pk_bf16_f32 v7, v10, v11
	global_store_dwordx4 v[16:17], v[4:7], off
	global_load_dwordx4 v[4:7], v[20:21], off
	v_mad_u64_u32 v[12:13], s[36:37], v26, s27, v[0:1]
	global_load_dwordx4 v[8:11], v[20:21], off offset:16
	ds_read_b128 v[12:15], v12
	v_add_u32_e32 v16, s33, v3
	v_ashrrev_i32_e32 v17, 31, v16
	v_lshlrev_b64 v[16:17], 10, v[16:17]
	v_or3_b32 v16, v16, s34, v1
	s_waitcnt lgkmcnt(0)
	v_lshlrev_b32_e32 v22, 16, v12
	v_and_b32_e32 v23, 0xffff0000, v12
	v_lshlrev_b32_e32 v12, 16, v13
	v_and_b32_e32 v13, 0xffff0000, v13
	v_lshlrev_b32_e32 v24, 16, v14
	v_and_b32_e32 v25, 0xffff0000, v14
	v_lshlrev_b32_e32 v14, 16, v15
	v_and_b32_e32 v15, 0xffff0000, v15
	v_lshl_add_u64 v[20:21], v[16:17], 2, s[76:77]
	v_lshl_add_u64 v[16:17], v[16:17], 1, s[12:13]
	s_waitcnt vmcnt(1)
	v_pk_add_f32 v[4:5], v[4:5], v[22:23]
	v_pk_add_f32 v[6:7], v[6:7], v[12:13]
	v_cvt_pk_bf16_f32 v4, v4, v5
	s_waitcnt vmcnt(0)
	v_pk_add_f32 v[8:9], v[8:9], v[24:25]
	v_pk_add_f32 v[10:11], v[10:11], v[14:15]
	v_cvt_pk_bf16_f32 v5, v6, v7
	v_cvt_pk_bf16_f32 v6, v8, v9
	v_cvt_pk_bf16_f32 v7, v10, v11
	global_store_dwordx4 v[18:19], v[4:7], off
	global_load_dwordx4 v[4:7], v[20:21], off
	v_add_u32_e32 v12, 0x800, v2
	global_load_dwordx4 v[8:11], v[20:21], off offset:16
	v_ashrrev_i32_e32 v26, 4, v12
	v_mad_u64_u32 v[12:13], s[36:37], v3, s27, v[0:1]
	ds_read_b128 v[12:15], v12
	v_add_u32_e32 v18, s33, v26
	v_ashrrev_i32_e32 v19, 31, v18
	v_lshlrev_b64 v[18:19], 10, v[18:19]
	v_or3_b32 v18, v18, s34, v1
	s_waitcnt lgkmcnt(0)
	v_lshlrev_b32_e32 v22, 16, v12
	v_and_b32_e32 v23, 0xffff0000, v12
	v_lshlrev_b32_e32 v12, 16, v13
	v_and_b32_e32 v13, 0xffff0000, v13
	v_lshlrev_b32_e32 v24, 16, v14
	v_and_b32_e32 v25, 0xffff0000, v14
	v_lshlrev_b32_e32 v14, 16, v15
	v_and_b32_e32 v15, 0xffff0000, v15
	v_lshl_add_u64 v[20:21], v[18:19], 2, s[76:77]
	v_add_u32_e32 v3, 0x900, v2
	v_ashrrev_i32_e32 v3, 4, v3
	v_lshl_add_u64 v[18:19], v[18:19], 1, s[12:13]
	s_waitcnt vmcnt(1)
	v_pk_add_f32 v[4:5], v[4:5], v[22:23]
	v_pk_add_f32 v[6:7], v[6:7], v[12:13]
	s_waitcnt vmcnt(0)
	v_pk_add_f32 v[8:9], v[8:9], v[24:25]
	v_pk_add_f32 v[10:11], v[10:11], v[14:15]
	v_cvt_pk_bf16_f32 v4, v4, v5
	v_cvt_pk_bf16_f32 v5, v6, v7
	v_cvt_pk_bf16_f32 v6, v8, v9
	v_cvt_pk_bf16_f32 v7, v10, v11
	global_store_dwordx4 v[16:17], v[4:7], off
	global_load_dwordx4 v[4:7], v[20:21], off
	v_mad_u64_u32 v[12:13], s[36:37], v26, s27, v[0:1]
	global_load_dwordx4 v[8:11], v[20:21], off offset:16
	ds_read_b128 v[12:15], v12
	v_add_u32_e32 v16, s33, v3
	v_ashrrev_i32_e32 v17, 31, v16
	v_lshlrev_b64 v[16:17], 10, v[16:17]
	v_or3_b32 v16, v16, s34, v1
	s_waitcnt lgkmcnt(0)
	v_lshlrev_b32_e32 v22, 16, v12
	v_and_b32_e32 v23, 0xffff0000, v12
	v_lshlrev_b32_e32 v12, 16, v13
	v_and_b32_e32 v13, 0xffff0000, v13
	v_lshlrev_b32_e32 v24, 16, v14
	v_and_b32_e32 v25, 0xffff0000, v14
	v_lshlrev_b32_e32 v14, 16, v15
	v_and_b32_e32 v15, 0xffff0000, v15
	v_lshl_add_u64 v[20:21], v[16:17], 2, s[76:77]
	v_lshl_add_u64 v[16:17], v[16:17], 1, s[12:13]
	s_waitcnt vmcnt(1)
	v_pk_add_f32 v[4:5], v[4:5], v[22:23]
	v_pk_add_f32 v[6:7], v[6:7], v[12:13]
	v_cvt_pk_bf16_f32 v4, v4, v5
	s_waitcnt vmcnt(0)
	v_pk_add_f32 v[8:9], v[8:9], v[24:25]
	v_pk_add_f32 v[10:11], v[10:11], v[14:15]
	v_cvt_pk_bf16_f32 v5, v6, v7
	v_cvt_pk_bf16_f32 v6, v8, v9
	v_cvt_pk_bf16_f32 v7, v10, v11
	global_store_dwordx4 v[18:19], v[4:7], off
	global_load_dwordx4 v[4:7], v[20:21], off
	v_add_u32_e32 v12, 0xa00, v2
	global_load_dwordx4 v[8:11], v[20:21], off offset:16
	v_ashrrev_i32_e32 v26, 4, v12
	v_mad_u64_u32 v[12:13], s[36:37], v3, s27, v[0:1]
	ds_read_b128 v[12:15], v12
	v_add_u32_e32 v18, s33, v26
	v_ashrrev_i32_e32 v19, 31, v18
	v_lshlrev_b64 v[18:19], 10, v[18:19]
	v_or3_b32 v18, v18, s34, v1
	s_waitcnt lgkmcnt(0)
	v_lshlrev_b32_e32 v22, 16, v12
	v_and_b32_e32 v23, 0xffff0000, v12
	v_lshlrev_b32_e32 v12, 16, v13
	v_and_b32_e32 v13, 0xffff0000, v13
	v_lshlrev_b32_e32 v24, 16, v14
	v_and_b32_e32 v25, 0xffff0000, v14
	v_lshlrev_b32_e32 v14, 16, v15
	v_and_b32_e32 v15, 0xffff0000, v15
	v_lshl_add_u64 v[20:21], v[18:19], 2, s[76:77]
	v_add_u32_e32 v3, 0xb00, v2
	v_ashrrev_i32_e32 v3, 4, v3
	v_lshl_add_u64 v[18:19], v[18:19], 1, s[12:13]
	s_waitcnt vmcnt(1)
	v_pk_add_f32 v[4:5], v[4:5], v[22:23]
	v_pk_add_f32 v[6:7], v[6:7], v[12:13]
	s_waitcnt vmcnt(0)
; DI int tidx() { int t = __builtin_amdgcn_workitem_id_x(); asm volatile("" : "+v"(t)); return t; }
; DI unsigned cvtpk(float lo, float hi) { const f32x2_ v = {lo, hi}; return __builtin_bit_cast(unsigned, __builtin_convertvector(v, bf16x2_)); }
; DI float bflo(unsigned w) { return __uint_as_float(w << 16); }
; DI float bfhi(unsigned w) { return __uint_as_float(w & 0xffff0000u); }
; DI void phase6(const Params& p, const Sched& sched, unsigned char* smem) {
;     ...
;       const int tid = tidx();
; #pragma unroll
;       for (int i = 0; i < 16; ++i) {
;         const int c = tid + 256 * i, row = c >> 4, ch = (c & 15) * 8;
;         const size_t gi = (size_t)(tm * 256 + row) * 1024 + tn * 128 + ch;
;         const u32x4 sv = *(const u32x4*)(Ls + row * EST + ch);
;         const f32x4 x0 = *(const f32x4*)(p.x + gi), x1 = *(const f32x4*)(p.x + gi + 4);
;         u32x4 w;
;         w.x = cvtpk(x0[0] + bflo(sv.x), x0[1] + bfhi(sv.x)); w.y = cvtpk(x0[2] + bflo(sv.y), x0[3] + bfhi(sv.y));
;         w.z = cvtpk(x1[0] + bflo(sv.z), x1[1] + bfhi(sv.z)); w.w = cvtpk(x1[2] + bflo(sv.w), x1[3] + bfhi(sv.w));
;         *(u32x4*)(x1b + gi) = w;
;       }
	v_pk_add_f32 v[8:9], v[8:9], v[24:25]
	v_pk_add_f32 v[10:11], v[10:11], v[14:15]
	v_cvt_pk_bf16_f32 v4, v4, v5
	v_cvt_pk_bf16_f32 v5, v6, v7
	v_cvt_pk_bf16_f32 v6, v8, v9
	v_cvt_pk_bf16_f32 v7, v10, v11
	global_store_dwordx4 v[16:17], v[4:7], off
	global_load_dwordx4 v[4:7], v[20:21], off
	v_mad_u64_u32 v[12:13], s[36:37], v26, s27, v[0:1]
	global_load_dwordx4 v[8:11], v[20:21], off offset:16
	ds_read_b128 v[12:15], v12
	v_add_u32_e32 v16, s33, v3
	v_ashrrev_i32_e32 v17, 31, v16
	v_lshlrev_b64 v[16:17], 10, v[16:17]
	v_or3_b32 v16, v16, s34, v1
	s_waitcnt lgkmcnt(0)
	v_lshlrev_b32_e32 v22, 16, v12
	v_and_b32_e32 v23, 0xffff0000, v12
	v_lshlrev_b32_e32 v12, 16, v13
	v_and_b32_e32 v13, 0xffff0000, v13
	v_lshlrev_b32_e32 v24, 16, v14
	v_and_b32_e32 v25, 0xffff0000, v14
	v_lshlrev_b32_e32 v14, 16, v15
	v_and_b32_e32 v15, 0xffff0000, v15
	v_lshl_add_u64 v[20:21], v[16:17], 2, s[76:77]
	v_lshl_add_u64 v[16:17], v[16:17], 1, s[12:13]
	s_waitcnt vmcnt(1)
	v_pk_add_f32 v[4:5], v[4:5], v[22:23]
	v_pk_add_f32 v[6:7], v[6:7], v[12:13]
	v_cvt_pk_bf16_f32 v4, v4, v5
	s_waitcnt vmcnt(0)
	v_pk_add_f32 v[8:9], v[8:9], v[24:25]
	v_pk_add_f32 v[10:11], v[10:11], v[14:15]
	v_cvt_pk_bf16_f32 v5, v6, v7
	v_cvt_pk_bf16_f32 v6, v8, v9
	v_cvt_pk_bf16_f32 v7, v10, v11
	global_store_dwordx4 v[18:19], v[4:7], off
	global_load_dwordx4 v[4:7], v[20:21], off
	v_add_u32_e32 v12, 0xc00, v2
	global_load_dwordx4 v[8:11], v[20:21], off offset:16
	v_ashrrev_i32_e32 v26, 4, v12
	v_mad_u64_u32 v[12:13], s[36:37], v3, s27, v[0:1]
	ds_read_b128 v[12:15], v12
	v_add_u32_e32 v18, s33, v26
	v_ashrrev_i32_e32 v19, 31, v18
	v_lshlrev_b64 v[18:19], 10, v[18:19]
	v_or3_b32 v18, v18, s34, v1
	s_waitcnt lgkmcnt(0)
	v_lshlrev_b32_e32 v22, 16, v12
	v_and_b32_e32 v23, 0xffff0000, v12
	v_lshlrev_b32_e32 v12, 16, v13
	v_and_b32_e32 v13, 0xffff0000, v13
	v_lshlrev_b32_e32 v24, 16, v14
	v_and_b32_e32 v25, 0xffff0000, v14
	v_lshlrev_b32_e32 v14, 16, v15
	v_and_b32_e32 v15, 0xffff0000, v15
	v_lshl_add_u64 v[20:21], v[18:19], 2, s[76:77]
	v_add_u32_e32 v3, 0xd00, v2
	v_ashrrev_i32_e32 v3, 4, v3
	v_lshl_add_u64 v[18:19], v[18:19], 1, s[12:13]
	s_waitcnt vmcnt(1)
	v_pk_add_f32 v[4:5], v[4:5], v[22:23]
	v_pk_add_f32 v[6:7], v[6:7], v[12:13]
	s_waitcnt vmcnt(0)
	v_pk_add_f32 v[8:9], v[8:9], v[24:25]
	v_pk_add_f32 v[10:11], v[10:11], v[14:15]
	v_cvt_pk_bf16_f32 v4, v4, v5
	v_cvt_pk_bf16_f32 v5, v6, v7
	v_cvt_pk_bf16_f32 v6, v8, v9
	v_cvt_pk_bf16_f32 v7, v10, v11
	global_store_dwordx4 v[16:17], v[4:7], off
	global_load_dwordx4 v[4:7], v[20:21], off
	v_mad_u64_u32 v[12:13], s[36:37], v26, s27, v[0:1]
	global_load_dwordx4 v[8:11], v[20:21], off offset:16
	ds_read_b128 v[12:15], v12
	v_add_u32_e32 v16, s33, v3
	v_ashrrev_i32_e32 v17, 31, v16
	v_lshlrev_b64 v[16:17], 10, v[16:17]
	v_or3_b32 v16, v16, s34, v1
	s_waitcnt lgkmcnt(0)
	v_lshlrev_b32_e32 v22, 16, v12
	v_and_b32_e32 v23, 0xffff0000, v12
	v_lshlrev_b32_e32 v12, 16, v13
	v_and_b32_e32 v13, 0xffff0000, v13
	v_lshlrev_b32_e32 v24, 16, v14
	v_and_b32_e32 v25, 0xffff0000, v14
	v_lshlrev_b32_e32 v14, 16, v15
	v_and_b32_e32 v15, 0xffff0000, v15
	v_lshl_add_u64 v[20:21], v[16:17], 2, s[76:77]
	v_lshl_add_u64 v[16:17], v[16:17], 1, s[12:13]
	s_waitcnt vmcnt(1)
	v_pk_add_f32 v[4:5], v[4:5], v[22:23]
	v_pk_add_f32 v[6:7], v[6:7], v[12:13]
	v_cvt_pk_bf16_f32 v4, v4, v5
	s_waitcnt vmcnt(0)
	v_pk_add_f32 v[8:9], v[8:9], v[24:25]
	v_pk_add_f32 v[10:11], v[10:11], v[14:15]
	v_cvt_pk_bf16_f32 v5, v6, v7
	v_cvt_pk_bf16_f32 v6, v8, v9
	v_cvt_pk_bf16_f32 v7, v10, v11
	global_store_dwordx4 v[18:19], v[4:7], off
	global_load_dwordx4 v[4:7], v[20:21], off
	v_add_u32_e32 v12, 0xe00, v2
	global_load_dwordx4 v[8:11], v[20:21], off offset:16
	v_ashrrev_i32_e32 v26, 4, v12
	v_mad_u64_u32 v[12:13], s[36:37], v3, s27, v[0:1]
	ds_read_b128 v[12:15], v12
	v_add_u32_e32 v18, s33, v26
	v_ashrrev_i32_e32 v19, 31, v18
	v_lshlrev_b64 v[18:19], 10, v[18:19]
	v_or3_b32 v18, v18, s34, v1
	s_waitcnt lgkmcnt(0)
	v_lshlrev_b32_e32 v22, 16, v12
	v_and_b32_e32 v23, 0xffff0000, v12
	v_lshlrev_b32_e32 v12, 16, v13
	v_and_b32_e32 v13, 0xffff0000, v13
	v_lshlrev_b32_e32 v24, 16, v14
	v_and_b32_e32 v25, 0xffff0000, v14
	v_lshlrev_b32_e32 v14, 16, v15
	v_and_b32_e32 v15, 0xffff0000, v15
	v_lshl_add_u64 v[20:21], v[18:19], 2, s[76:77]
	v_add_u32_e32 v2, 0xf00, v2
	v_lshl_add_u64 v[18:19], v[18:19], 1, s[12:13]
	s_waitcnt vmcnt(1)
	v_pk_add_f32 v[4:5], v[4:5], v[22:23]
	v_pk_add_f32 v[6:7], v[6:7], v[12:13]
	s_waitcnt vmcnt(0)
	v_pk_add_f32 v[8:9], v[8:9], v[24:25]
	v_pk_add_f32 v[10:11], v[10:11], v[14:15]
	v_cvt_pk_bf16_f32 v4, v4, v5
	v_cvt_pk_bf16_f32 v5, v6, v7
	v_cvt_pk_bf16_f32 v6, v8, v9
	v_cvt_pk_bf16_f32 v7, v10, v11
	global_store_dwordx4 v[16:17], v[4:7], off
	global_load_dwordx4 v[4:7], v[20:21], off
	v_mad_u64_u32 v[12:13], s[36:37], v26, s27, v[0:1]
	global_load_dwordx4 v[8:11], v[20:21], off offset:16
	ds_read_b128 v[12:15], v12
	v_ashrrev_i32_e32 v24, 4, v2
	v_add_u32_e32 v2, s33, v24
	v_ashrrev_i32_e32 v3, 31, v2
	v_lshlrev_b64 v[16:17], 10, v[2:3]
	s_waitcnt lgkmcnt(0)
	v_lshlrev_b32_e32 v2, 16, v12
	v_and_b32_e32 v3, 0xffff0000, v12
	v_lshlrev_b32_e32 v12, 16, v13
	v_and_b32_e32 v13, 0xffff0000, v13
	v_lshlrev_b32_e32 v22, 16, v14
	v_and_b32_e32 v23, 0xffff0000, v14
	v_lshlrev_b32_e32 v14, 16, v15
	v_and_b32_e32 v15, 0xffff0000, v15
	v_or3_b32 v16, v16, s34, v1
	v_lshl_add_u64 v[20:21], v[16:17], 2, s[76:77]
	v_mad_u64_u32 v[0:1], s[34:35], v24, s27, v[0:1]
	s_waitcnt vmcnt(1)
	v_pk_add_f32 v[2:3], v[4:5], v[2:3]
	v_pk_add_f32 v[4:5], v[6:7], v[12:13]
	v_cvt_pk_bf16_f32 v2, v2, v3
	s_waitcnt vmcnt(0)
	v_pk_add_f32 v[6:7], v[8:9], v[22:23]
	v_pk_add_f32 v[8:9], v[10:11], v[14:15]
	v_cvt_pk_bf16_f32 v3, v4, v5
	v_cvt_pk_bf16_f32 v4, v6, v7
	v_cvt_pk_bf16_f32 v5, v8, v9
	global_store_dwordx4 v[18:19], v[2:5], off
	global_load_dwordx4 v[2:5], v[20:21], off
	ds_read_b128 v[10:13], v0
	global_load_dwordx4 v[6:9], v[20:21], off offset:16
	v_lshl_add_u64 v[14:15], v[16:17], 1, s[12:13]
	s_waitcnt lgkmcnt(0)
	v_lshlrev_b32_e32 v0, 16, v10
	v_and_b32_e32 v1, 0xffff0000, v10
	v_lshlrev_b32_e32 v10, 16, v11
	v_and_b32_e32 v11, 0xffff0000, v11
	v_lshlrev_b32_e32 v16, 16, v12
	v_and_b32_e32 v17, 0xffff0000, v12
	v_lshlrev_b32_e32 v12, 16, v13
	v_and_b32_e32 v13, 0xffff0000, v13
	s_waitcnt vmcnt(1)
	v_pk_add_f32 v[0:1], v[2:3], v[0:1]
	v_pk_add_f32 v[2:3], v[4:5], v[10:11]
	s_waitcnt vmcnt(0)
	v_pk_add_f32 v[4:5], v[6:7], v[16:17]
	v_pk_add_f32 v[6:7], v[8:9], v[12:13]
	v_cvt_pk_bf16_f32 v0, v0, v1
	v_cvt_pk_bf16_f32 v1, v2, v3
	v_cvt_pk_bf16_f32 v2, v4, v5
	v_cvt_pk_bf16_f32 v3, v6, v7
	global_store_dwordx4 v[14:15], v[0:3], off
	s_cbranch_scc0 .LBB0_811
	s_branch .LBB0_808

; DI int tidx() { int t = __builtin_amdgcn_workitem_id_x(); asm volatile("" : "+v"(t)); return t; }
;   DI unsigned rowoff(int r, int sch) const { const int g = r & 3, bc = r >> 2, b = bc / NCMP, c = bc - b * NCMP; return (unsigned)(b * Sn + c * 16) * 512u + g * 64 + sch; }
; template <int NI, class XL, class EP>
; DI void gemm_tile(const u16* __restrict__ W, int ldw, int f0, int t0, int K, XL xl, EP ep, unsigned char* smem) {
;     ...
;   const int tid = tidx(), lane = tid & 63, wave = tid >> 6;
;   const int wf = wave >> 1, wt = wave & 1, lr = lane & 15, lq = lane >> 4;
;   const int srow = tid >> 2, sch = (tid & 3) * 8;
;   f32x4 acc[4][NI];
; #pragma unroll
;   for (int i = 0; i < 4; ++i)
; #pragma unroll
;     for (int j = 0; j < NI; ++j) acc[i][j] = (f32x4){0.f, 0.f, 0.f, 0.f};
;   u32x4 wr[2], xr[XR];
;   const unsigned wbyte = ((unsigned)(f0 + srow * 2) * 32u + sch) * 2u;
;   const unsigned xbyte = xl.rowoff(t0 + srow * XR, sch) * 2u;
;   const int xrs = xl.rstride();
;   const int nk = K >> 5;
;   auto gload = [&](int it) {
;     const int k = it * 32;
;     const char* wb = (const char*)(W + (size_t)(k >> 5) * ldw * 32);
;     const char* xb = (const char*)xl.kbase(k);
; #pragma unroll
;     for (int i = 0; i < 2; ++i) wr[i] = *(const u32x4*)(wb + wbyte + i * 64);
; #pragma unroll
;     for (int i = 0; i < XR; ++i) xr[i] = *(const u32x4*)(xb + xbyte + i * xrs);
;   };
;   auto lstore = [&](int buf) {
;     u16* Ws = S0 + buf * BUF; u16* Xs = Ws + 128 * LST;
; #pragma unroll
;     for (int i = 0; i < 2; ++i) *(u32x4*)(Ws + (srow * 2 + i) * LST + sch) = wr[i];
; #pragma unroll
;     for (int i = 0; i < XR; ++i) *(u32x4*)(Xs + (srow * XR + i) * LST + sch) = xr[i];
;   };
;   gload(0);
;   __syncthreads();
;   lstore(0);
;   __syncthreads();
;   if (nk > 1) gload(1);
.LBB0_944:
	s_ashr_i32 s4, s55, 2
	v_mov_b32_e32 v48, v218
	s_add_i32 s30, s4, s51
	s_and_b32 s4, s55, 3
	s_or_b32 s56, s4, s52
	v_ashrrev_i32_e32 v49, 2, v48
	v_lshlrev_b32_e32 v0, 3, v48
	v_lshlrev_b32_e32 v51, 6, v49
	v_and_b32_e32 v50, 24, v0
	v_lshl_add_u32 v0, s56, 12, v51
	v_or_b32_e32 v0, v0, v50
	v_lshlrev_b32_e32 v54, 1, v0
	v_lshlrev_b32_e32 v0, 6, v48
	v_and_b32_e32 v0, 0xffffff00, v0
	v_lshl_add_u32 v0, s30, 14, v0
	v_lshlrev_b32_e32 v171, 1, v50
	v_readlane_b32 s4, v245, 25
	v_or_b32_e32 v152, v0, v171
	v_readlane_b32 s5, v245, 26
	global_load_dwordx4 v[16:19], v54, s[60:61]
	global_load_dwordx4 v[20:23], v54, s[60:61] offset:64
	s_nop 2
	global_load_dwordx4 v[24:27], v152, s[4:5]
	global_load_dwordx4 v[28:31], v152, s[4:5] offset:64
	global_load_dwordx4 v[32:35], v152, s[4:5] offset:128
	global_load_dwordx4 v[36:39], v152, s[4:5] offset:192
	v_mul_lo_u32 v174, v49, s37
	v_or_b32_e32 v170, v174, v171
	v_add_u32_e32 v169, v170, v174
	s_barrier
	s_and_b32 s5, s54, 3
	s_add_i32 s5, s53, s5
	v_bfe_u32 v168, v48, 4, 2
	v_ashrrev_i32_e32 v155, 7, v48
	v_and_b32_e32 v55, 15, v48
	v_lshlrev_b32_e32 v48, 1, v48
	v_and_or_b32 v154, v48, s44, v55
	v_lshl_add_u32 v48, s5, 12, v51
	v_mov_b32_e32 v0, 0
	v_lshl_or_b32 v49, v155, 6, v55
	v_or_b32_e32 v48, v48, v50
	s_mov_b32 s4, 1
	v_mov_b32_e32 v157, v153
	v_mov_b32_e32 v1, v0
	v_mov_b32_e32 v2, v0
	v_mov_b32_e32 v3, v0
	v_mov_b32_e32 v4, v0
	v_mov_b32_e32 v5, v0
	v_mov_b32_e32 v6, v0
	v_mov_b32_e32 v7, v0
	v_mov_b32_e32 v8, v0
	v_mov_b32_e32 v9, v0
	v_mov_b32_e32 v10, v0
	v_mov_b32_e32 v11, v0
	v_mov_b32_e32 v12, v0
	v_mov_b32_e32 v13, v0
	v_mov_b32_e32 v14, v0
	v_mov_b32_e32 v15, v0
	v_mov_b32_e32 v40, v0
	v_mov_b32_e32 v41, v0
	v_mov_b32_e32 v42, v0
	v_mov_b32_e32 v43, v0
	v_mov_b32_e32 v44, v0
	v_mov_b32_e32 v45, v0
	v_mov_b32_e32 v46, v0
	v_mov_b32_e32 v47, v0
	v_mov_b32_e32 v52, v0
	v_mov_b32_e32 v53, v0
	v_lshlrev_b32_e32 v172, 4, v168
	v_mul_lo_u32 v175, v49, 48
	v_mul_u32_u24_e32 v173, 48, v154
	v_lshlrev_b32_e32 v156, 1, v48
	v_mov_b64_e32 v[158:159], v[152:153]
	v_mov_b32_e32 v55, v0
	v_mov_b32_e32 v80, v0
	v_mov_b32_e32 v81, v0
	v_mov_b32_e32 v82, v0
	v_mov_b32_e32 v83, v0
	v_mov_b32_e32 v48, v0
	v_mov_b32_e32 v49, v0
	v_mov_b32_e32 v50, v0
	v_mov_b32_e32 v51, v0
	v_mov_b32_e32 v56, v0
	v_mov_b32_e32 v57, v0
	v_mov_b32_e32 v58, v0
	v_mov_b32_e32 v59, v0
	v_mov_b32_e32 v60, v0
	v_mov_b32_e32 v61, v0
	v_mov_b32_e32 v62, v0
	v_mov_b32_e32 v63, v0
	v_mov_b32_e32 v68, v0
	s_waitcnt vmcnt(5)
	ds_write_b128 v170, v[16:19]
	s_waitcnt vmcnt(4)
	ds_write_b128 v170, v[20:23] offset:96
	s_waitcnt vmcnt(3)
	ds_write_b128 v169, v[24:27] offset:12288
	s_waitcnt vmcnt(2)
	ds_write_b128 v169, v[28:31] offset:12384
	s_waitcnt vmcnt(1)
	ds_write_b128 v169, v[32:35] offset:12480
	s_waitcnt vmcnt(0)
	ds_write_b128 v169, v[36:39] offset:12576
	s_waitcnt lgkmcnt(0)
	s_barrier
	global_load_dwordx4 v[20:23], v54, s[20:21]
	global_load_dwordx4 v[16:19], v54, s[20:21] offset:64
	global_load_dwordx4 v[36:39], v152, s[18:19]
	global_load_dwordx4 v[32:35], v152, s[18:19] offset:64
	global_load_dwordx4 v[28:31], v152, s[18:19] offset:128
	global_load_dwordx4 v[24:27], v152, s[18:19] offset:192
	s_add_u32 s98, s42, s45
	s_addc_u32 s99, s43, 0
	s_add_u32 s100, s42, s46
	s_addc_u32 s101, s43, 0
	global_load_dwordx4 v[200:203], v156, s[98:99]
	global_load_dwordx4 v[204:207], v156, s[98:99] offset:64
	global_load_dwordx4 v[208:211], v158, s[100:101] offset:2048
	global_load_dwordx4 v[212:215], v158, s[100:101] offset:2112
	global_load_dwordx4 v[220:223], v158, s[100:101] offset:2176
	global_load_dwordx4 v[224:227], v158, s[100:101] offset:2240
	s_add_u32 s98, s98, s28
	s_addc_u32 s99, s99, s29
	s_add_u32 s100, s100, s26
	s_addc_u32 s101, s101, s27
	v_mov_b32_e32 v54, v0
	v_mov_b32_e32 v69, v0
	v_mov_b32_e32 v70, v0
	v_mov_b32_e32 v71, v0
	v_mov_b32_e32 v76, v0
	v_mov_b32_e32 v77, v0
	v_mov_b32_e32 v78, v0
	v_mov_b32_e32 v79, v0
	v_mov_b32_e32 v88, v0
	v_mov_b32_e32 v89, v0
	v_mov_b32_e32 v90, v0
	v_mov_b32_e32 v91, v0
	v_mov_b32_e32 v100, v0
	v_mov_b32_e32 v101, v0
	v_mov_b32_e32 v102, v0
	v_mov_b32_e32 v103, v0
	v_mov_b32_e32 v112, v0
	v_mov_b32_e32 v113, v0
	v_mov_b32_e32 v114, v0
	v_mov_b32_e32 v115, v0
	v_mov_b32_e32 v64, v0
	v_mov_b32_e32 v65, v0
	v_mov_b32_e32 v66, v0
	v_mov_b32_e32 v67, v0
	v_mov_b32_e32 v72, v0
	v_mov_b32_e32 v73, v0
	v_mov_b32_e32 v74, v0
	v_mov_b32_e32 v75, v0
	v_mov_b32_e32 v84, v0
	v_mov_b32_e32 v85, v0
	v_mov_b32_e32 v86, v0
	v_mov_b32_e32 v87, v0
	v_mov_b32_e32 v96, v0
	v_mov_b32_e32 v97, v0
	v_mov_b32_e32 v98, v0
	v_mov_b32_e32 v99, v0
	v_mov_b32_e32 v108, v0
	v_mov_b32_e32 v109, v0
	v_mov_b32_e32 v110, v0
	v_mov_b32_e32 v111, v0
	v_mov_b32_e32 v120, v0
	v_mov_b32_e32 v121, v0
	v_mov_b32_e32 v122, v0
	v_mov_b32_e32 v123, v0
	v_mov_b32_e32 v128, v0
	v_mov_b32_e32 v129, v0
	v_mov_b32_e32 v130, v0
	v_mov_b32_e32 v131, v0
	v_mov_b32_e32 v136, v0
	v_mov_b32_e32 v137, v0
	v_mov_b32_e32 v138, v0
	v_mov_b32_e32 v139, v0
	v_mov_b32_e32 v92, v0
	v_mov_b32_e32 v93, v0
	v_mov_b32_e32 v94, v0
	v_mov_b32_e32 v95, v0
	v_mov_b32_e32 v104, v0
	v_mov_b32_e32 v105, v0
	v_mov_b32_e32 v106, v0
	v_mov_b32_e32 v107, v0
	v_mov_b32_e32 v116, v0
	v_mov_b32_e32 v117, v0
	v_mov_b32_e32 v118, v0
	v_mov_b32_e32 v119, v0
	v_mov_b32_e32 v124, v0
	v_mov_b32_e32 v125, v0
	v_mov_b32_e32 v126, v0
	v_mov_b32_e32 v127, v0
	v_mov_b32_e32 v132, v0
	v_mov_b32_e32 v133, v0
	v_mov_b32_e32 v134, v0
	v_mov_b32_e32 v135, v0
	v_mov_b32_e32 v140, v0
	v_mov_b32_e32 v141, v0
	v_mov_b32_e32 v142, v0
	v_mov_b32_e32 v143, v0
	v_mov_b32_e32 v144, v0
	v_mov_b32_e32 v145, v0
	v_mov_b32_e32 v146, v0
	v_mov_b32_e32 v147, v0
	v_mov_b32_e32 v148, v0
	v_mov_b32_e32 v149, v0
	v_mov_b32_e32 v150, v0
	v_mov_b32_e32 v151, v0
; DI f32x4 mfma16(bf16x8 a, bf16x8 b, f32x4 c) { return __builtin_amdgcn_mfma_f32_16x16x32_bf16(a, b, c, 0, 0, 0); }
; template <int NI, class XL, class EP>
; DI void gemm_tile(const u16* __restrict__ W, int ldw, int f0, int t0, int K, XL xl, EP ep, unsigned char* smem) {
;     ...
;   for (int it = 0; it < nk; ++it) {
;     const u16* Ws = S0 + (it & 1) * BUF; const u16* Xs = Ws + 128 * LST;
;     __builtin_amdgcn_s_setprio(1);
;     bf16x8 a[4];
; #pragma unroll
;     for (int mi = 0; mi < 4; ++mi) a[mi] = *(const bf16x8*)(Ws + (wf * 64 + mi * 16 + lr) * LST + lq * 8);
; #pragma unroll
;     for (int ni = 0; ni < NI; ++ni) {
;       const bf16x8 b = *(const bf16x8*)(Xs + (wt * (NI * 16) + ni * 16 + lr) * LST + lq * 8);
; #pragma unroll
;       for (int mi = 0; mi < 4; ++mi) acc[mi][ni] = mfma16(a[mi], b, acc[mi][ni]);
;     }
;     __builtin_amdgcn_sched_group_barrier(0x100, 6, 0);
; #pragma unroll
;     for (int ni = 0; ni < NI; ++ni) { __builtin_amdgcn_sched_group_barrier(0x008, 4, 0); if (ni + 2 < NI) __builtin_amdgcn_sched_group_barrier(0x100, 1, 0); }
;     __builtin_amdgcn_s_setprio(0);
;     if (it + 1 < nk) lstore((it + 1) & 1);
;     if (it + 2 < nk) gload(it + 2);
;     __syncthreads();
;   }
.LBB0_945:
	s_bitcmp1_b32 s4, 0
	s_cselect_b32 s5, 0, 0x9000
	s_setprio 1
	v_or_b32_e32 v152, s5, v172
	v_lshl_add_u32 v192, v175, 1, v152
	ds_read_b128 v[176:179], v192
	ds_read_b128 v[180:183], v192 offset:1536
	ds_read_b128 v[188:191], v192 offset:3072
	ds_read_b128 v[192:195], v192 offset:4608
	v_lshl_add_u32 v152, v173, 1, v152
	ds_read_b128 v[184:187], v152 offset:12288
	ds_read_b128 v[196:199], v152 offset:13824
	s_xor_b32 s5, s5, 0x9000
	v_add3_u32 v228, v174, s5, v171
	s_waitcnt lgkmcnt(1)
	v_mfma_f32_16x16x32_bf16 v[148:151], v[176:179], v[184:187], v[148:151]
	v_mfma_f32_16x16x32_bf16 v[136:139], v[180:183], v[184:187], v[136:139]
	v_mfma_f32_16x16x32_bf16 v[112:115], v[188:191], v[184:187], v[112:115]
	v_mfma_f32_16x16x32_bf16 v[80:83], v[192:195], v[184:187], v[80:83]
	ds_read_b128 v[184:187], v152 offset:15360
	s_waitcnt vmcnt(11)
	ds_write_b128 v228, v[20:23]
	s_waitcnt lgkmcnt(2)
	v_mfma_f32_16x16x32_bf16 v[144:147], v[176:179], v[196:199], v[144:147]
	v_mfma_f32_16x16x32_bf16 v[128:131], v[180:183], v[196:199], v[128:131]
	v_mfma_f32_16x16x32_bf16 v[100:103], v[188:191], v[196:199], v[100:103]
	v_mfma_f32_16x16x32_bf16 v[52:55], v[192:195], v[196:199], v[52:55]
	ds_read_b128 v[196:199], v152 offset:16896
	s_waitcnt vmcnt(10)
	ds_write_b128 v228, v[16:19] offset:96
	v_add_u32_e32 v228, v228, v174
	global_load_dwordx4 v[20:23], v156, s[98:99]
	global_load_dwordx4 v[16:19], v156, s[98:99] offset:64
	s_waitcnt lgkmcnt(3)
	v_mfma_f32_16x16x32_bf16 v[140:143], v[176:179], v[184:187], v[140:143]
	v_mfma_f32_16x16x32_bf16 v[120:123], v[180:183], v[184:187], v[120:123]
	v_mfma_f32_16x16x32_bf16 v[88:91], v[188:191], v[184:187], v[88:91]
	v_mfma_f32_16x16x32_bf16 v[44:47], v[192:195], v[184:187], v[44:47]
	ds_read_b128 v[184:187], v152 offset:18432
	s_waitcnt vmcnt(11)
	ds_write_b128 v228, v[36:39] offset:12288
	global_load_dwordx4 v[36:39], v158, s[100:101] offset:2048
	s_waitcnt lgkmcnt(3)
	v_mfma_f32_16x16x32_bf16 v[132:135], v[176:179], v[196:199], v[132:135]
	v_mfma_f32_16x16x32_bf16 v[108:111], v[180:183], v[196:199], v[108:111]
	v_mfma_f32_16x16x32_bf16 v[76:79], v[188:191], v[196:199], v[76:79]
	v_mfma_f32_16x16x32_bf16 v[40:43], v[192:195], v[196:199], v[40:43]
	ds_read_b128 v[196:199], v152 offset:19968
	s_waitcnt vmcnt(11)
	ds_write_b128 v228, v[32:35] offset:12384
	global_load_dwordx4 v[32:35], v158, s[100:101] offset:2112
	s_waitcnt lgkmcnt(3)
	v_mfma_f32_16x16x32_bf16 v[124:127], v[176:179], v[184:187], v[124:127]
	v_mfma_f32_16x16x32_bf16 v[96:99], v[180:183], v[184:187], v[96:99]
	v_mfma_f32_16x16x32_bf16 v[68:71], v[188:191], v[184:187], v[68:71]
	v_mfma_f32_16x16x32_bf16 v[12:15], v[192:195], v[184:187], v[12:15]
	ds_read_b128 v[184:187], v152 offset:21504
	s_waitcnt vmcnt(11)
	ds_write_b128 v228, v[28:31] offset:12480
	global_load_dwordx4 v[28:31], v158, s[100:101] offset:2176
	s_waitcnt lgkmcnt(3)
	v_mfma_f32_16x16x32_bf16 v[116:119], v[176:179], v[196:199], v[116:119]
	v_mfma_f32_16x16x32_bf16 v[84:87], v[180:183], v[196:199], v[84:87]
	v_mfma_f32_16x16x32_bf16 v[60:63], v[188:191], v[196:199], v[60:63]
	v_mfma_f32_16x16x32_bf16 v[8:11], v[192:195], v[196:199], v[8:11]
	ds_read_b128 v[196:199], v152 offset:23040
	s_waitcnt vmcnt(11)
	ds_write_b128 v228, v[24:27] offset:12576
	global_load_dwordx4 v[24:27], v158, s[100:101] offset:2240
	s_waitcnt lgkmcnt(3)
	v_mfma_f32_16x16x32_bf16 v[104:107], v[176:179], v[184:187], v[104:107]
	v_mfma_f32_16x16x32_bf16 v[72:75], v[180:183], v[184:187], v[72:75]
	v_mfma_f32_16x16x32_bf16 v[56:59], v[188:191], v[184:187], v[56:59]
	v_mfma_f32_16x16x32_bf16 v[4:7], v[192:195], v[184:187], v[4:7]
	s_add_u32 s98, s98, s28
	s_addc_u32 s99, s99, s29
	s_add_u32 s100, s100, s26
	s_addc_u32 s101, s101, s27
	s_add_i32 s4, s4, 1
	s_waitcnt lgkmcnt(1)
	v_mfma_f32_16x16x32_bf16 v[92:95], v[176:179], v[196:199], v[92:95]
	v_mfma_f32_16x16x32_bf16 v[64:67], v[180:183], v[196:199], v[64:67]
	v_mfma_f32_16x16x32_bf16 v[48:51], v[188:191], v[196:199], v[48:51]
	v_mfma_f32_16x16x32_bf16 v[0:3], v[192:195], v[196:199], v[0:3]
	s_setprio 0
	s_waitcnt lgkmcnt(0)
	s_barrier
	s_bitcmp1_b32 s4, 0
	s_cselect_b32 s5, 0, 0x9000
	s_setprio 1
	v_or_b32_e32 v152, s5, v172
	v_lshl_add_u32 v192, v175, 1, v152
	ds_read_b128 v[176:179], v192
	ds_read_b128 v[180:183], v192 offset:1536
	ds_read_b128 v[188:191], v192 offset:3072
	ds_read_b128 v[192:195], v192 offset:4608
	v_lshl_add_u32 v152, v173, 1, v152
	ds_read_b128 v[184:187], v152 offset:12288
	ds_read_b128 v[196:199], v152 offset:13824
	s_xor_b32 s5, s5, 0x9000
	v_add3_u32 v228, v174, s5, v171
	s_waitcnt lgkmcnt(1)
	v_mfma_f32_16x16x32_bf16 v[148:151], v[176:179], v[184:187], v[148:151]
	v_mfma_f32_16x16x32_bf16 v[136:139], v[180:183], v[184:187], v[136:139]
	v_mfma_f32_16x16x32_bf16 v[112:115], v[188:191], v[184:187], v[112:115]
	v_mfma_f32_16x16x32_bf16 v[80:83], v[192:195], v[184:187], v[80:83]
	ds_read_b128 v[184:187], v152 offset:15360
	s_waitcnt vmcnt(11)
	ds_write_b128 v228, v[200:203]
	s_waitcnt lgkmcnt(2)
	v_mfma_f32_16x16x32_bf16 v[144:147], v[176:179], v[196:199], v[144:147]
	v_mfma_f32_16x16x32_bf16 v[128:131], v[180:183], v[196:199], v[128:131]
	v_mfma_f32_16x16x32_bf16 v[100:103], v[188:191], v[196:199], v[100:103]
	v_mfma_f32_16x16x32_bf16 v[52:55], v[192:195], v[196:199], v[52:55]
	ds_read_b128 v[196:199], v152 offset:16896
	s_waitcnt vmcnt(10)
	ds_write_b128 v228, v[204:207] offset:96
	v_add_u32_e32 v228, v228, v174
	global_load_dwordx4 v[200:203], v156, s[98:99]
	global_load_dwordx4 v[204:207], v156, s[98:99] offset:64
	s_waitcnt lgkmcnt(3)
; DI f32x4 mfma16(bf16x8 a, bf16x8 b, f32x4 c) { return __builtin_amdgcn_mfma_f32_16x16x32_bf16(a, b, c, 0, 0, 0); }
; template <int NI, class XL, class EP>
; DI void gemm_tile(const u16* __restrict__ W, int ldw, int f0, int t0, int K, XL xl, EP ep, unsigned char* smem) {
;     ...
;   for (int it = 0; it < nk; ++it) {
;     const u16* Ws = S0 + (it & 1) * BUF; const u16* Xs = Ws + 128 * LST;
;     __builtin_amdgcn_s_setprio(1);
;     bf16x8 a[4];
; #pragma unroll
;     for (int mi = 0; mi < 4; ++mi) a[mi] = *(const bf16x8*)(Ws + (wf * 64 + mi * 16 + lr) * LST + lq * 8);
; #pragma unroll
;     for (int ni = 0; ni < NI; ++ni) {
;       const bf16x8 b = *(const bf16x8*)(Xs + (wt * (NI * 16) + ni * 16 + lr) * LST + lq * 8);
; #pragma unroll
;       for (int mi = 0; mi < 4; ++mi) acc[mi][ni] = mfma16(a[mi], b, acc[mi][ni]);
;     }
;     __builtin_amdgcn_sched_group_barrier(0x100, 6, 0);
; #pragma unroll
;     for (int ni = 0; ni < NI; ++ni) { __builtin_amdgcn_sched_group_barrier(0x008, 4, 0); if (ni + 2 < NI) __builtin_amdgcn_sched_group_barrier(0x100, 1, 0); }
;     __builtin_amdgcn_s_setprio(0);
;     if (it + 1 < nk) lstore((it + 1) & 1);
;     if (it + 2 < nk) gload(it + 2);
;     __syncthreads();
;   }
	v_mfma_f32_16x16x32_bf16 v[140:143], v[176:179], v[184:187], v[140:143]
	v_mfma_f32_16x16x32_bf16 v[120:123], v[180:183], v[184:187], v[120:123]
	v_mfma_f32_16x16x32_bf16 v[88:91], v[188:191], v[184:187], v[88:91]
	v_mfma_f32_16x16x32_bf16 v[44:47], v[192:195], v[184:187], v[44:47]
	ds_read_b128 v[184:187], v152 offset:18432
	s_waitcnt vmcnt(11)
	ds_write_b128 v228, v[208:211] offset:12288
	global_load_dwordx4 v[208:211], v158, s[100:101] offset:2048
	s_waitcnt lgkmcnt(3)
	v_mfma_f32_16x16x32_bf16 v[132:135], v[176:179], v[196:199], v[132:135]
	v_mfma_f32_16x16x32_bf16 v[108:111], v[180:183], v[196:199], v[108:111]
	v_mfma_f32_16x16x32_bf16 v[76:79], v[188:191], v[196:199], v[76:79]
	v_mfma_f32_16x16x32_bf16 v[40:43], v[192:195], v[196:199], v[40:43]
	ds_read_b128 v[196:199], v152 offset:19968
	s_waitcnt vmcnt(11)
	ds_write_b128 v228, v[212:215] offset:12384
	global_load_dwordx4 v[212:215], v158, s[100:101] offset:2112
	s_waitcnt lgkmcnt(3)
	v_mfma_f32_16x16x32_bf16 v[124:127], v[176:179], v[184:187], v[124:127]
	v_mfma_f32_16x16x32_bf16 v[96:99], v[180:183], v[184:187], v[96:99]
	v_mfma_f32_16x16x32_bf16 v[68:71], v[188:191], v[184:187], v[68:71]
	v_mfma_f32_16x16x32_bf16 v[12:15], v[192:195], v[184:187], v[12:15]
	ds_read_b128 v[184:187], v152 offset:21504
	s_waitcnt vmcnt(11)
	ds_write_b128 v228, v[220:223] offset:12480
	global_load_dwordx4 v[220:223], v158, s[100:101] offset:2176
	s_waitcnt lgkmcnt(3)
	v_mfma_f32_16x16x32_bf16 v[116:119], v[176:179], v[196:199], v[116:119]
	v_mfma_f32_16x16x32_bf16 v[84:87], v[180:183], v[196:199], v[84:87]
	v_mfma_f32_16x16x32_bf16 v[60:63], v[188:191], v[196:199], v[60:63]
	v_mfma_f32_16x16x32_bf16 v[8:11], v[192:195], v[196:199], v[8:11]
	ds_read_b128 v[196:199], v152 offset:23040
	s_waitcnt vmcnt(11)
	ds_write_b128 v228, v[224:227] offset:12576
	global_load_dwordx4 v[224:227], v158, s[100:101] offset:2240
	s_waitcnt lgkmcnt(3)
	v_mfma_f32_16x16x32_bf16 v[104:107], v[176:179], v[184:187], v[104:107]
	v_mfma_f32_16x16x32_bf16 v[72:75], v[180:183], v[184:187], v[72:75]
	v_mfma_f32_16x16x32_bf16 v[56:59], v[188:191], v[184:187], v[56:59]
	v_mfma_f32_16x16x32_bf16 v[4:7], v[192:195], v[184:187], v[4:7]
	s_add_u32 s98, s98, s28
	s_addc_u32 s99, s99, s29
	s_add_u32 s100, s100, s26
	s_addc_u32 s101, s101, s27
	s_add_i32 s4, s4, 1
	s_waitcnt lgkmcnt(1)
	v_mfma_f32_16x16x32_bf16 v[92:95], v[176:179], v[196:199], v[92:95]
	v_mfma_f32_16x16x32_bf16 v[64:67], v[180:183], v[196:199], v[64:67]
	v_mfma_f32_16x16x32_bf16 v[48:51], v[188:191], v[196:199], v[48:51]
	v_mfma_f32_16x16x32_bf16 v[0:3], v[192:195], v[196:199], v[0:3]
	s_setprio 0
	s_cmp_eq_u32 s4, 29
	s_waitcnt lgkmcnt(0)
	s_barrier
	s_cbranch_scc0 .LBB0_945
	s_bitcmp1_b32 s4, 0
	s_cselect_b32 s5, 0, 0x9000
	s_setprio 1
	v_or_b32_e32 v152, s5, v172
	v_lshl_add_u32 v192, v175, 1, v152
	ds_read_b128 v[176:179], v192
	ds_read_b128 v[180:183], v192 offset:1536
	ds_read_b128 v[188:191], v192 offset:3072
	ds_read_b128 v[192:195], v192 offset:4608
	v_lshl_add_u32 v152, v173, 1, v152
	ds_read_b128 v[184:187], v152 offset:12288
	ds_read_b128 v[196:199], v152 offset:13824
	s_xor_b32 s5, s5, 0x9000
	v_add3_u32 v228, v174, s5, v171
	s_waitcnt lgkmcnt(1)
	v_mfma_f32_16x16x32_bf16 v[148:151], v[176:179], v[184:187], v[148:151]
	v_mfma_f32_16x16x32_bf16 v[136:139], v[180:183], v[184:187], v[136:139]
	v_mfma_f32_16x16x32_bf16 v[112:115], v[188:191], v[184:187], v[112:115]
	v_mfma_f32_16x16x32_bf16 v[80:83], v[192:195], v[184:187], v[80:83]
	ds_read_b128 v[184:187], v152 offset:15360
	s_waitcnt vmcnt(11)
	ds_write_b128 v228, v[20:23]
	s_waitcnt lgkmcnt(2)
	v_mfma_f32_16x16x32_bf16 v[144:147], v[176:179], v[196:199], v[144:147]
	v_mfma_f32_16x16x32_bf16 v[128:131], v[180:183], v[196:199], v[128:131]
	v_mfma_f32_16x16x32_bf16 v[100:103], v[188:191], v[196:199], v[100:103]
	v_mfma_f32_16x16x32_bf16 v[52:55], v[192:195], v[196:199], v[52:55]
	ds_read_b128 v[196:199], v152 offset:16896
	s_waitcnt vmcnt(10)
	ds_write_b128 v228, v[16:19] offset:96
	v_add_u32_e32 v228, v228, v174
	global_load_dwordx4 v[20:23], v156, s[98:99]
	global_load_dwordx4 v[16:19], v156, s[98:99] offset:64
	s_waitcnt lgkmcnt(3)
	v_mfma_f32_16x16x32_bf16 v[140:143], v[176:179], v[184:187], v[140:143]
	v_mfma_f32_16x16x32_bf16 v[120:123], v[180:183], v[184:187], v[120:123]
	v_mfma_f32_16x16x32_bf16 v[88:91], v[188:191], v[184:187], v[88:91]
	v_mfma_f32_16x16x32_bf16 v[44:47], v[192:195], v[184:187], v[44:47]
	ds_read_b128 v[184:187], v152 offset:18432
	s_waitcnt vmcnt(11)
	ds_write_b128 v228, v[36:39] offset:12288
	global_load_dwordx4 v[36:39], v158, s[100:101] offset:2048
	s_waitcnt lgkmcnt(3)
	v_mfma_f32_16x16x32_bf16 v[132:135], v[176:179], v[196:199], v[132:135]
	v_mfma_f32_16x16x32_bf16 v[108:111], v[180:183], v[196:199], v[108:111]
	v_mfma_f32_16x16x32_bf16 v[76:79], v[188:191], v[196:199], v[76:79]
	v_mfma_f32_16x16x32_bf16 v[40:43], v[192:195], v[196:199], v[40:43]
	ds_read_b128 v[196:199], v152 offset:19968
	s_waitcnt vmcnt(11)
	ds_write_b128 v228, v[32:35] offset:12384
	global_load_dwordx4 v[32:35], v158, s[100:101] offset:2112
	s_waitcnt lgkmcnt(3)
	v_mfma_f32_16x16x32_bf16 v[124:127], v[176:179], v[184:187], v[124:127]
	v_mfma_f32_16x16x32_bf16 v[96:99], v[180:183], v[184:187], v[96:99]
	v_mfma_f32_16x16x32_bf16 v[68:71], v[188:191], v[184:187], v[68:71]
	v_mfma_f32_16x16x32_bf16 v[12:15], v[192:195], v[184:187], v[12:15]
	ds_read_b128 v[184:187], v152 offset:21504
	s_waitcnt vmcnt(11)
	ds_write_b128 v228, v[28:31] offset:12480
	global_load_dwordx4 v[28:31], v158, s[100:101] offset:2176
	s_waitcnt lgkmcnt(3)
	v_mfma_f32_16x16x32_bf16 v[116:119], v[176:179], v[196:199], v[116:119]
	v_mfma_f32_16x16x32_bf16 v[84:87], v[180:183], v[196:199], v[84:87]
	v_mfma_f32_16x16x32_bf16 v[60:63], v[188:191], v[196:199], v[60:63]
	v_mfma_f32_16x16x32_bf16 v[8:11], v[192:195], v[196:199], v[8:11]
	ds_read_b128 v[196:199], v152 offset:23040
	s_waitcnt vmcnt(11)
	ds_write_b128 v228, v[24:27] offset:12576
	global_load_dwordx4 v[24:27], v158, s[100:101] offset:2240
	s_waitcnt lgkmcnt(3)
	v_mfma_f32_16x16x32_bf16 v[104:107], v[176:179], v[184:187], v[104:107]
	v_mfma_f32_16x16x32_bf16 v[72:75], v[180:183], v[184:187], v[72:75]
	v_mfma_f32_16x16x32_bf16 v[56:59], v[188:191], v[184:187], v[56:59]
	v_mfma_f32_16x16x32_bf16 v[4:7], v[192:195], v[184:187], v[4:7]
	s_add_u32 s98, s98, s28
	s_addc_u32 s99, s99, s29
	s_add_u32 s100, s100, s26
	s_addc_u32 s101, s101, s27
	s_add_i32 s4, s4, 1
	s_waitcnt lgkmcnt(1)
	v_mfma_f32_16x16x32_bf16 v[92:95], v[176:179], v[196:199], v[92:95]
	v_mfma_f32_16x16x32_bf16 v[64:67], v[180:183], v[196:199], v[64:67]
	v_mfma_f32_16x16x32_bf16 v[48:51], v[188:191], v[196:199], v[48:51]
	v_mfma_f32_16x16x32_bf16 v[0:3], v[192:195], v[196:199], v[0:3]
	s_setprio 0
	s_waitcnt lgkmcnt(0)
	s_barrier
; DI f32x4 mfma16(bf16x8 a, bf16x8 b, f32x4 c) { return __builtin_amdgcn_mfma_f32_16x16x32_bf16(a, b, c, 0, 0, 0); }
; template <int NI, class XL, class EP>
; DI void gemm_tile(const u16* __restrict__ W, int ldw, int f0, int t0, int K, XL xl, EP ep, unsigned char* smem) {
;     ...
;   for (int it = 0; it < nk; ++it) {
;     const u16* Ws = S0 + (it & 1) * BUF; const u16* Xs = Ws + 128 * LST;
;     __builtin_amdgcn_s_setprio(1);
;     bf16x8 a[4];
; #pragma unroll
;     for (int mi = 0; mi < 4; ++mi) a[mi] = *(const bf16x8*)(Ws + (wf * 64 + mi * 16 + lr) * LST + lq * 8);
; #pragma unroll
;     for (int ni = 0; ni < NI; ++ni) {
;       const bf16x8 b = *(const bf16x8*)(Xs + (wt * (NI * 16) + ni * 16 + lr) * LST + lq * 8);
; #pragma unroll
;       for (int mi = 0; mi < 4; ++mi) acc[mi][ni] = mfma16(a[mi], b, acc[mi][ni]);
;     }
;     __builtin_amdgcn_sched_group_barrier(0x100, 6, 0);
; #pragma unroll
;     for (int ni = 0; ni < NI; ++ni) { __builtin_amdgcn_sched_group_barrier(0x008, 4, 0); if (ni + 2 < NI) __builtin_amdgcn_sched_group_barrier(0x100, 1, 0); }
;     __builtin_amdgcn_s_setprio(0);
;     if (it + 1 < nk) lstore((it + 1) & 1);
;     if (it + 2 < nk) gload(it + 2);
;     __syncthreads();
;   }
	s_bitcmp1_b32 s4, 0
	s_cselect_b32 s5, 0, 0x9000
	s_setprio 1
	v_or_b32_e32 v152, s5, v172
	v_lshl_add_u32 v192, v175, 1, v152
	ds_read_b128 v[176:179], v192
	ds_read_b128 v[180:183], v192 offset:1536
	ds_read_b128 v[188:191], v192 offset:3072
	ds_read_b128 v[192:195], v192 offset:4608
	v_lshl_add_u32 v152, v173, 1, v152
	ds_read_b128 v[184:187], v152 offset:12288
	ds_read_b128 v[196:199], v152 offset:13824
	s_xor_b32 s5, s5, 0x9000
	v_add3_u32 v228, v174, s5, v171
	s_waitcnt lgkmcnt(1)
	v_mfma_f32_16x16x32_bf16 v[148:151], v[176:179], v[184:187], v[148:151]
	v_mfma_f32_16x16x32_bf16 v[136:139], v[180:183], v[184:187], v[136:139]
	v_mfma_f32_16x16x32_bf16 v[112:115], v[188:191], v[184:187], v[112:115]
	v_mfma_f32_16x16x32_bf16 v[80:83], v[192:195], v[184:187], v[80:83]
	ds_read_b128 v[184:187], v152 offset:15360
	s_waitcnt vmcnt(11)
	ds_write_b128 v228, v[200:203]
	s_waitcnt lgkmcnt(2)
	v_mfma_f32_16x16x32_bf16 v[144:147], v[176:179], v[196:199], v[144:147]
	v_mfma_f32_16x16x32_bf16 v[128:131], v[180:183], v[196:199], v[128:131]
	v_mfma_f32_16x16x32_bf16 v[100:103], v[188:191], v[196:199], v[100:103]
	v_mfma_f32_16x16x32_bf16 v[52:55], v[192:195], v[196:199], v[52:55]
	ds_read_b128 v[196:199], v152 offset:16896
	s_waitcnt vmcnt(10)
	ds_write_b128 v228, v[204:207] offset:96
	v_add_u32_e32 v228, v228, v174
	s_waitcnt lgkmcnt(3)
	v_mfma_f32_16x16x32_bf16 v[140:143], v[176:179], v[184:187], v[140:143]
	v_mfma_f32_16x16x32_bf16 v[120:123], v[180:183], v[184:187], v[120:123]
	v_mfma_f32_16x16x32_bf16 v[88:91], v[188:191], v[184:187], v[88:91]
	v_mfma_f32_16x16x32_bf16 v[44:47], v[192:195], v[184:187], v[44:47]
	ds_read_b128 v[184:187], v152 offset:18432
	s_waitcnt vmcnt(9)
	ds_write_b128 v228, v[208:211] offset:12288
	s_waitcnt lgkmcnt(3)
	v_mfma_f32_16x16x32_bf16 v[132:135], v[176:179], v[196:199], v[132:135]
	v_mfma_f32_16x16x32_bf16 v[108:111], v[180:183], v[196:199], v[108:111]
	v_mfma_f32_16x16x32_bf16 v[76:79], v[188:191], v[196:199], v[76:79]
	v_mfma_f32_16x16x32_bf16 v[40:43], v[192:195], v[196:199], v[40:43]
	ds_read_b128 v[196:199], v152 offset:19968
	s_waitcnt vmcnt(8)
	ds_write_b128 v228, v[212:215] offset:12384
	s_waitcnt lgkmcnt(3)
	v_mfma_f32_16x16x32_bf16 v[124:127], v[176:179], v[184:187], v[124:127]
	v_mfma_f32_16x16x32_bf16 v[96:99], v[180:183], v[184:187], v[96:99]
	v_mfma_f32_16x16x32_bf16 v[68:71], v[188:191], v[184:187], v[68:71]
	v_mfma_f32_16x16x32_bf16 v[12:15], v[192:195], v[184:187], v[12:15]
	ds_read_b128 v[184:187], v152 offset:21504
	s_waitcnt vmcnt(7)
	ds_write_b128 v228, v[220:223] offset:12480
	s_waitcnt lgkmcnt(3)
	v_mfma_f32_16x16x32_bf16 v[116:119], v[176:179], v[196:199], v[116:119]
	v_mfma_f32_16x16x32_bf16 v[84:87], v[180:183], v[196:199], v[84:87]
	v_mfma_f32_16x16x32_bf16 v[60:63], v[188:191], v[196:199], v[60:63]
	v_mfma_f32_16x16x32_bf16 v[8:11], v[192:195], v[196:199], v[8:11]
	ds_read_b128 v[196:199], v152 offset:23040
	s_waitcnt vmcnt(6)
	ds_write_b128 v228, v[224:227] offset:12576
	s_waitcnt lgkmcnt(3)
	v_mfma_f32_16x16x32_bf16 v[104:107], v[176:179], v[184:187], v[104:107]
	v_mfma_f32_16x16x32_bf16 v[72:75], v[180:183], v[184:187], v[72:75]
	v_mfma_f32_16x16x32_bf16 v[56:59], v[188:191], v[184:187], v[56:59]
	v_mfma_f32_16x16x32_bf16 v[4:7], v[192:195], v[184:187], v[4:7]
	s_add_u32 s98, s98, s28
	s_addc_u32 s99, s99, s29
	s_add_u32 s100, s100, s26
	s_addc_u32 s101, s101, s27
	s_add_i32 s4, s4, 1
	s_waitcnt lgkmcnt(1)
	v_mfma_f32_16x16x32_bf16 v[92:95], v[176:179], v[196:199], v[92:95]
	v_mfma_f32_16x16x32_bf16 v[64:67], v[180:183], v[196:199], v[64:67]
	v_mfma_f32_16x16x32_bf16 v[48:51], v[188:191], v[196:199], v[48:51]
	v_mfma_f32_16x16x32_bf16 v[0:3], v[192:195], v[196:199], v[0:3]
	s_setprio 0
	s_waitcnt lgkmcnt(0)
	s_barrier
	s_setprio 1
	v_lshl_add_u32 v152, v175, 1, v172
	ds_read_b128 v[156:159], v152
	v_lshl_add_u32 v171, v173, 1, v172
	ds_read_b128 v[172:175], v152 offset:1536
	ds_read_b128 v[180:183], v152 offset:3072
	ds_read_b128 v[184:187], v152 offset:4608
	ds_read_b128 v[176:179], v171 offset:12288
	ds_read_b128 v[188:191], v171 offset:13824
	s_waitcnt lgkmcnt(1)
	v_mfma_f32_16x16x32_bf16 v[148:151], v[156:159], v[176:179], v[148:151]
	v_mfma_f32_16x16x32_bf16 v[136:139], v[172:175], v[176:179], v[136:139]
	v_mfma_f32_16x16x32_bf16 v[112:115], v[180:183], v[176:179], v[112:115]
	v_mfma_f32_16x16x32_bf16 v[80:83], v[184:187], v[176:179], v[80:83]
	ds_read_b128 v[176:179], v171 offset:15360
	s_waitcnt lgkmcnt(1)
	v_mfma_f32_16x16x32_bf16 v[144:147], v[156:159], v[188:191], v[144:147]
	v_mfma_f32_16x16x32_bf16 v[128:131], v[172:175], v[188:191], v[128:131]
	v_mfma_f32_16x16x32_bf16 v[100:103], v[180:183], v[188:191], v[100:103]
	v_mfma_f32_16x16x32_bf16 v[188:191], v[184:187], v[188:191], v[52:55]
	s_nop 2
	ds_read_b128 v[52:55], v171 offset:16896
	s_waitcnt lgkmcnt(1)
	v_mfma_f32_16x16x32_bf16 v[192:195], v[156:159], v[176:179], v[140:143]
	v_mfma_f32_16x16x32_bf16 v[120:123], v[172:175], v[176:179], v[120:123]
	v_mfma_f32_16x16x32_bf16 v[88:91], v[180:183], v[176:179], v[88:91]
	v_mfma_f32_16x16x32_bf16 v[176:179], v[184:187], v[176:179], v[44:47]
	s_nop 2
	ds_read_b128 v[44:47], v171 offset:18432
	s_waitcnt lgkmcnt(1)
	v_mfma_f32_16x16x32_bf16 v[196:199], v[156:159], v[52:55], v[132:135]
	v_mfma_f32_16x16x32_bf16 v[108:111], v[172:175], v[52:55], v[108:111]
	v_mfma_f32_16x16x32_bf16 v[76:79], v[180:183], v[52:55], v[76:79]
	v_mfma_f32_16x16x32_bf16 v[200:203], v[184:187], v[52:55], v[40:43]
	s_nop 2
	ds_read_b128 v[40:43], v171 offset:19968
	s_waitcnt lgkmcnt(1)
; template <int NI, class XL, class EP>
; DI void gemm_tile(const u16* __restrict__ W, int ldw, int f0, int t0, int K, XL xl, EP ep, unsigned char* smem) {
;     ...
;   for (int it = 0; it < nk; ++it) {
;     const u16* Ws = S0 + (it & 1) * BUF; const u16* Xs = Ws + 128 * LST;
;     __builtin_amdgcn_s_setprio(1);
;     bf16x8 a[4];
; #pragma unroll
;     for (int mi = 0; mi < 4; ++mi) a[mi] = *(const bf16x8*)(Ws + (wf * 64 + mi * 16 + lr) * LST + lq * 8);
; #pragma unroll
;     for (int ni = 0; ni < NI; ++ni) {
;       const bf16x8 b = *(const bf16x8*)(Xs + (wt * (NI * 16) + ni * 16 + lr) * LST + lq * 8);
; #pragma unroll
;       for (int mi = 0; mi < 4; ++mi) acc[mi][ni] = mfma16(a[mi], b, acc[mi][ni]);
;     }
;     __builtin_amdgcn_sched_group_barrier(0x100, 6, 0);
; #pragma unroll
;     for (int ni = 0; ni < NI; ++ni) { __builtin_amdgcn_sched_group_barrier(0x008, 4, 0); if (ni + 2 < NI) __builtin_amdgcn_sched_group_barrier(0x100, 1, 0); }
;     __builtin_amdgcn_s_setprio(0);
;     if (it + 1 < nk) lstore((it + 1) & 1);
;     if (it + 2 < nk) gload(it + 2);
;     __syncthreads();
;   }
;   ep(acc, f0 + wf * 64, t0 + wt * (NI * 16), lr, lq, wf, wt);
; DI void phase8(const Params& p, const Sched& sched, unsigned char* smem) {
;     ...
;       for (int h2 = 0; h2 < 2; ++h2) {
;         const int fl = wf * 16 + lq * 4, fc = (2 * wf + h2) * 16 + lq * 4, F = tn * 64 + fc;
;         __syncthreads();
; #pragma unroll
;         for (int ni = 0; ni < 8; ++ni) *(f32x4*)(gl + (wt * 128 + ni * 16 + lr) * 36 + fl) = acc[2 * h2][ni];
;         __syncthreads();
;         const float4 w0 = *(const float4*)(p.conv_w + F), w1 = *(const float4*)(p.conv_w + FF + F), w2 = *(const float4*)(p.conv_w + 2 * FF + F), cb = *(const float4*)(p.conv_b + F);
; #pragma unroll
;         for (int ni = 0; ni < 8; ++ni) {
;           const int row = wt * 128 + ni * 16 + lr;
;           const f32x4 gv = acc[2 * h2][ni], uv = acc[2 * h2 + 1][ni];
;           if (row >= 2) {
;             const f32x4 g1 = *(const f32x4*)(gl + (row - 1) * 36 + fl), g2 = *(const f32x4*)(gl + (row - 2) * 36 + fl);
;             f32x4 o;
;             o[0] = cb.x + w0.x * g2[0] + w1.x * g1[0] + w2.x * gv[0];
;             o[1] = cb.y + w0.y * g2[1] + w1.y * g1[1] + w2.y * gv[1];
;             o[2] = cb.z + w0.z * g2[2] + w1.z * g1[2] + w2.z * gv[2];
;             o[3] = cb.w + w0.w * g2[3] + w1.w * g1[3] + w2.w * gv[3];
	v_mfma_f32_16x16x32_bf16 v[204:207], v[156:159], v[44:47], v[124:127]
	v_mfma_f32_16x16x32_bf16 v[96:99], v[172:175], v[44:47], v[96:99]
	v_mfma_f32_16x16x32_bf16 v[68:71], v[180:183], v[44:47], v[68:71]
	v_mfma_f32_16x16x32_bf16 v[12:15], v[184:187], v[44:47], v[12:15]
	ds_read_b128 v[44:47], v171 offset:21504
	s_waitcnt lgkmcnt(1)
	v_mfma_f32_16x16x32_bf16 v[208:211], v[156:159], v[40:43], v[116:119]
	v_mfma_f32_16x16x32_bf16 v[84:87], v[172:175], v[40:43], v[84:87]
	v_mfma_f32_16x16x32_bf16 v[212:215], v[180:183], v[40:43], v[60:63]
	v_mfma_f32_16x16x32_bf16 v[8:11], v[184:187], v[40:43], v[8:11]
	ds_read_b128 v[40:43], v171 offset:23040
	s_waitcnt lgkmcnt(1)
	v_mfma_f32_16x16x32_bf16 v[220:223], v[156:159], v[44:47], v[104:107]
	v_mfma_f32_16x16x32_bf16 v[72:75], v[172:175], v[44:47], v[72:75]
	v_mfma_f32_16x16x32_bf16 v[224:227], v[180:183], v[44:47], v[56:59]
	v_mfma_f32_16x16x32_bf16 v[4:7], v[184:187], v[44:47], v[4:7]
	s_waitcnt lgkmcnt(0)
	v_mfma_f32_16x16x32_bf16 v[156:159], v[156:159], v[40:43], v[92:95]
	v_mfma_f32_16x16x32_bf16 v[172:175], v[172:175], v[40:43], v[64:67]
	v_mfma_f32_16x16x32_bf16 v[180:183], v[180:183], v[40:43], v[48:51]
	v_mfma_f32_16x16x32_bf16 v[184:187], v[184:187], v[40:43], v[0:3]
	s_setprio 0
	s_waitcnt vmcnt(5)
	ds_write_b128 v170, v[20:23] offset:36864
	s_waitcnt vmcnt(4)
	ds_write_b128 v170, v[16:19] offset:36960
	s_waitcnt vmcnt(3)
	ds_write_b128 v169, v[36:39] offset:49152
	s_waitcnt vmcnt(2)
	ds_write_b128 v169, v[32:35] offset:49248
	s_waitcnt vmcnt(1)
	ds_write_b128 v169, v[28:31] offset:49344
	s_waitcnt vmcnt(0)
	ds_write_b128 v169, v[24:27] offset:49440
	s_waitcnt lgkmcnt(0)
	s_barrier
	s_setprio 1
	ds_read_b128 v[0:3], v152 offset:36864
	ds_read_b128 v[228:231], v152 offset:38400
	ds_read_b128 v[232:235], v152 offset:39936
	ds_read_b128 v[236:239], v152 offset:41472
	ds_read_b128 v[16:19], v171 offset:49152
	ds_read_b128 v[20:23], v171 offset:50688
	s_waitcnt lgkmcnt(1)
	v_mfma_f32_16x16x32_bf16 v[140:143], v[0:3], v[16:19], v[148:151]
	v_mfma_f32_16x16x32_bf16 v[136:139], v[228:231], v[16:19], v[136:139]
	v_mfma_f32_16x16x32_bf16 v[60:63], v[232:235], v[16:19], v[112:115]
	v_mfma_f32_16x16x32_bf16 v[56:59], v[236:239], v[16:19], v[80:83]
	ds_read_b128 v[16:19], v171 offset:52224
	s_waitcnt lgkmcnt(1)
	v_mfma_f32_16x16x32_bf16 v[132:135], v[0:3], v[20:23], v[144:147]
	v_mfma_f32_16x16x32_bf16 v[128:131], v[228:231], v[20:23], v[128:131]
	v_mfma_f32_16x16x32_bf16 v[52:55], v[232:235], v[20:23], v[100:103]
	v_mfma_f32_16x16x32_bf16 v[48:51], v[236:239], v[20:23], v[188:191]
	ds_read_b128 v[20:23], v171 offset:53760
	s_waitcnt lgkmcnt(1)
	v_mfma_f32_16x16x32_bf16 v[124:127], v[0:3], v[16:19], v[192:195]
	v_mfma_f32_16x16x32_bf16 v[120:123], v[228:231], v[16:19], v[120:123]
	v_mfma_f32_16x16x32_bf16 v[44:47], v[232:235], v[16:19], v[88:91]
	v_mfma_f32_16x16x32_bf16 v[40:43], v[236:239], v[16:19], v[176:179]
	ds_read_b128 v[16:19], v171 offset:55296
	s_waitcnt lgkmcnt(1)
	v_mfma_f32_16x16x32_bf16 v[116:119], v[0:3], v[20:23], v[196:199]
	v_mfma_f32_16x16x32_bf16 v[112:115], v[228:231], v[20:23], v[108:111]
	v_mfma_f32_16x16x32_bf16 v[36:39], v[232:235], v[20:23], v[76:79]
	v_mfma_f32_16x16x32_bf16 v[32:35], v[236:239], v[20:23], v[200:203]
	ds_read_b128 v[64:67], v171 offset:56832
	s_waitcnt lgkmcnt(1)
	v_mfma_f32_16x16x32_bf16 v[108:111], v[0:3], v[16:19], v[204:207]
	v_mfma_f32_16x16x32_bf16 v[104:107], v[228:231], v[16:19], v[96:99]
	v_mfma_f32_16x16x32_bf16 v[28:31], v[232:235], v[16:19], v[68:71]
	v_mfma_f32_16x16x32_bf16 v[24:27], v[236:239], v[16:19], v[12:15]
	s_nop 1
	ds_read_b128 v[68:71], v171 offset:58368
	s_waitcnt lgkmcnt(1)
	v_mfma_f32_16x16x32_bf16 v[100:103], v[0:3], v[64:67], v[208:211]
	v_mfma_f32_16x16x32_bf16 v[96:99], v[228:231], v[64:67], v[84:87]
	v_mfma_f32_16x16x32_bf16 v[20:23], v[232:235], v[64:67], v[212:215]
	v_mfma_f32_16x16x32_bf16 v[16:19], v[236:239], v[64:67], v[8:11]
	ds_read_b128 v[76:79], v171 offset:59904
	s_waitcnt lgkmcnt(1)
	v_mfma_f32_16x16x32_bf16 v[92:95], v[0:3], v[68:71], v[220:223]
	v_mfma_f32_16x16x32_bf16 v[72:75], v[228:231], v[68:71], v[72:75]
	v_mfma_f32_16x16x32_bf16 v[12:15], v[232:235], v[68:71], v[224:227]
	v_mfma_f32_16x16x32_bf16 v[8:11], v[236:239], v[68:71], v[4:7]
	s_waitcnt lgkmcnt(0)
	v_mfma_f32_16x16x32_bf16 v[64:67], v[0:3], v[76:79], v[156:159]
	v_mfma_f32_16x16x32_bf16 v[68:71], v[228:231], v[76:79], v[172:175]
	v_mfma_f32_16x16x32_bf16 v[0:3], v[232:235], v[76:79], v[180:183]
	v_mfma_f32_16x16x32_bf16 v[4:7], v[236:239], v[76:79], v[184:187]
	s_setprio 0
	v_lshlrev_b32_e32 v76, 2, v168
	v_lshl_or_b32 v152, v155, 4, v76
	v_lshl_or_b32 v156, v155, 5, v76
	v_lshlrev_b32_e32 v76, 2, v152
	v_mad_u32_u24 v77, v154, s47, v160
	v_add_u32_e32 v159, v77, v76
	v_mad_u32_u24 v77, v154, s47, v161
	v_add_u32_e32 v168, v77, v76
	v_mad_u32_u24 v77, v154, s47, v162
	s_lshl_b32 s57, s56, 6
	v_add_u32_e32 v169, v77, v76
	v_mad_u32_u24 v77, v154, s47, v163
	v_add_u32_e32 v170, v77, v76
	v_mad_u32_u24 v77, v154, s47, v164
	v_add_u32_e32 v144, s57, v156
	v_add_u32_e32 v171, v77, v76
	v_mad_u32_u24 v77, v154, s47, v165
	v_ashrrev_i32_e32 v145, 31, v144
	v_add_u32_e32 v172, v77, v76
	v_mad_u32_u24 v77, v154, s47, v166
	v_lshlrev_b64 v[146:147], 2, v[144:145]
	v_mad_u32_u24 v158, v154, s47, v76
	v_add_u32_e32 v173, v77, v76
	v_lshl_add_u64 v[148:149], s[68:69], 0, v[146:147]
	v_lshl_add_u64 v[76:77], s[22:23], 0, v[146:147]
	v_lshl_add_u64 v[78:79], s[24:25], 0, v[146:147]
	v_lshl_add_u64 v[150:151], s[70:71], 0, v[146:147]
	s_barrier
	s_barrier
	ds_write_b128 v158, v[140:143]
	ds_write_b128 v159, v[132:135]
	ds_write_b128 v168, v[124:127]
	ds_write_b128 v169, v[116:119]
	ds_write_b128 v170, v[108:111]
	ds_write_b128 v171, v[100:103]
	ds_write_b128 v172, v[92:95]
	ds_write_b128 v173, v[64:67]
	s_waitcnt lgkmcnt(0)
	s_barrier
	global_load_dwordx4 v[84:87], v[148:149], off
	global_load_dwordx4 v[80:83], v[76:77], off
	global_load_dwordx4 v[88:91], v[150:151], off
	v_cmp_gt_u32_e64 s[4:5], 2, v154
	global_load_dwordx4 v[76:79], v[78:79], off
	v_lshl_or_b32 v157, s30, 1, v154
	s_and_saveexec_b64 s[6:7], s[4:5]
	s_xor_b64 s[6:7], exec, s[6:7]
	s_cbranch_execz .LBB0_948
	s_ashr_i32 s31, s30, 31
	s_lshl_b64 s[34:35], s[30:31], 2
	v_or_b32_e32 v155, s34, v154
	v_mov_b64_e32 v[174:175], s[16:17]
	v_mad_u64_u32 v[174:175], s[58:59], v155, s48, v[174:175]
	v_mad_i32_i24 v175, s35, v167, v175
	v_lshl_add_u64 v[174:175], v[174:175], 0, v[146:147]
	global_store_dwordx4 v[174:175], v[140:143], off
	s_nop 1
	v_mov_b64_e32 v[140:141], s[10:11]
	v_mad_u64_u32 v[140:141], s[34:35], v157, s48, v[140:141]
	v_mad_i32_i24 v141, s31, v167, v141
	v_lshl_add_u64 v[140:141], v[140:141], 0, v[146:147]
	global_store_dwordx4 v[140:141], v[136:139], off
; DI void store4(u16* dst, f32x4 v) { uint2 w; w.x = cvtpk(v[0], v[1]); w.y = cvtpk(v[2], v[3]); *(uint2*)dst = w; }
; DI float sigmoidf_(float x) { return 1.0f / (1.0f + __expf(-x)); }
; DI void phase8(const Params& p, const Sched& sched, unsigned char* smem) {
;     ...
;         for (int ni = 0; ni < 8; ++ni) {
;           const int row = wt * 128 + ni * 16 + lr;
;           const f32x4 gv = acc[2 * h2][ni], uv = acc[2 * h2 + 1][ni];
;           if (row >= 2) {
;             const f32x4 g1 = *(const f32x4*)(gl + (row - 1) * 36 + fl), g2 = *(const f32x4*)(gl + (row - 2) * 36 + fl);
;             f32x4 o;
;             o[0] = cb.x + w0.x * g2[0] + w1.x * g1[0] + w2.x * gv[0];
;             o[1] = cb.y + w0.y * g2[1] + w1.y * g1[1] + w2.y * gv[1];
;             o[2] = cb.z + w0.z * g2[2] + w1.z * g1[2] + w2.z * gv[2];
;             o[3] = cb.w + w0.w * g2[3] + w1.w * g1[3] + w2.w * gv[3];
; #pragma unroll
;             for (int j = 0; j < 4; ++j) o[j] = o[j] * sigmoidf_(o[j]) * uv[j];
;             store4(Ls + row * 72 + fc, o);
.LBB0_948:
	s_or_saveexec_b64 s[6:7], s[6:7]
	v_mul_u32_u24_e32 v174, 0x90, v154
	v_lshlrev_b32_e32 v155, 1, v156
	v_lshl_add_u32 v175, v152, 2, v174
	v_add_u32_e32 v152, v155, v174
	v_add_u32_e32 v174, 0xffffff70, v175
	v_add_u32_e32 v175, 0xfffffee0, v175
	s_xor_b64 exec, exec, s[6:7]
	s_cbranch_execz .LBB0_950
	ds_read_b128 v[176:179], v175
	ds_read_b128 v[180:183], v174
	s_waitcnt vmcnt(1) lgkmcnt(1)
	v_pk_fma_f32 v[176:177], v[84:85], v[176:177], v[88:89]
	s_waitcnt lgkmcnt(0)
	v_pk_fma_f32 v[176:177], v[80:81], v[180:181], v[176:177]
	v_pk_fma_f32 v[178:179], v[86:87], v[178:179], v[90:91]
	s_waitcnt vmcnt(0)
	v_pk_fma_f32 v[140:141], v[140:141], v[76:77], v[176:177]
	v_pk_fma_f32 v[178:179], v[82:83], v[182:183], v[178:179]
	v_mul_f32_e32 v176, 0xbfb8aa3b, v140
	v_mul_f32_e32 v177, 0xbfb8aa3b, v141
	v_exp_f32_e32 v176, v176
	v_exp_f32_e32 v177, v177
	v_pk_fma_f32 v[142:143], v[142:143], v[78:79], v[178:179]
	v_pk_add_f32 v[176:177], v[176:177], 1.0 op_sel_hi:[1,0]
	s_nop 0
	v_rcp_f32_e32 v177, v177
	v_mul_f32_e32 v178, 0xbfb8aa3b, v142
	v_mul_f32_e32 v179, 0xbfb8aa3b, v143
	v_exp_f32_e32 v178, v178
	v_exp_f32_e32 v179, v179
	s_nop 0
	v_pk_add_f32 v[178:179], v[178:179], 1.0 op_sel_hi:[1,0]
	v_rcp_f32_e32 v176, v176
	s_nop 0
	v_pk_mul_f32 v[140:141], v[140:141], v[176:177]
	s_nop 0
	v_pk_mul_f32 v[136:137], v[136:137], v[140:141]
	v_rcp_f32_e32 v141, v179
	v_rcp_f32_e32 v140, v178
	s_nop 0
	v_pk_mul_f32 v[140:141], v[142:143], v[140:141]
	v_cvt_pk_bf16_f32 v136, v136, v137
	v_pk_mul_f32 v[138:139], v[138:139], v[140:141]
	s_nop 0
	v_cvt_pk_bf16_f32 v137, v138, v139
	ds_write_b64 v152, v[136:137] offset:36864
.LBB0_950:
	s_or_b64 exec, exec, s[6:7]
	v_add_u32_e32 v137, 0xfffffee0, v159
	v_add_u32_e32 v136, 0xffffff70, v159
	ds_read_b128 v[138:141], v137
	ds_read_b128 v[176:179], v136
	v_or_b32_e32 v142, 16, v154
	s_waitcnt vmcnt(1) lgkmcnt(1)
	v_pk_fma_f32 v[138:139], v[84:85], v[138:139], v[88:89]
	s_waitcnt lgkmcnt(0)
	v_pk_fma_f32 v[138:139], v[80:81], v[176:177], v[138:139]
	v_pk_fma_f32 v[140:141], v[86:87], v[140:141], v[90:91]
	s_waitcnt vmcnt(0)
	v_pk_fma_f32 v[132:133], v[132:133], v[76:77], v[138:139]
	v_pk_fma_f32 v[140:141], v[82:83], v[178:179], v[140:141]
	v_mul_f32_e32 v138, 0xbfb8aa3b, v132
	v_mul_f32_e32 v139, 0xbfb8aa3b, v133
	v_exp_f32_e32 v138, v138
	v_exp_f32_e32 v139, v139
	v_pk_fma_f32 v[134:135], v[134:135], v[78:79], v[140:141]
	v_pk_add_f32 v[138:139], v[138:139], 1.0 op_sel_hi:[1,0]
	s_nop 0
	v_rcp_f32_e32 v139, v139
	v_mul_f32_e32 v140, 0xbfb8aa3b, v134
	v_mul_f32_e32 v141, 0xbfb8aa3b, v135
	v_exp_f32_e32 v140, v140
	v_exp_f32_e32 v141, v141
	s_nop 0
	v_pk_add_f32 v[140:141], v[140:141], 1.0 op_sel_hi:[1,0]
	v_rcp_f32_e32 v138, v138
	s_nop 0
	v_pk_mul_f32 v[132:133], v[132:133], v[138:139]
	s_nop 0
	v_pk_mul_f32 v[132:133], v[128:129], v[132:133]
	v_rcp_f32_e32 v129, v141
	v_rcp_f32_e32 v128, v140
	s_nop 0
	v_pk_mul_f32 v[128:129], v[134:135], v[128:129]
	v_cvt_pk_bf16_f32 v132, v132, v133
	v_pk_mul_f32 v[130:131], v[130:131], v[128:129]
	v_mul_u32_u24_e32 v128, 0x48, v142
	v_lshl_add_u32 v128, v128, 1, v155
	v_cvt_pk_bf16_f32 v133, v130, v131
	ds_write_b64 v128, v[132:133] offset:36864
	v_add_u32_e32 v130, 0xfffffee0, v168
	v_add_u32_e32 v129, 0xffffff70, v168
	ds_read_b128 v[132:135], v130
	ds_read_b128 v[138:141], v129
	s_waitcnt lgkmcnt(1)
	v_pk_fma_f32 v[132:133], v[84:85], v[132:133], v[88:89]
	s_waitcnt lgkmcnt(0)
	v_pk_fma_f32 v[132:133], v[80:81], v[138:139], v[132:133]
	v_pk_fma_f32 v[134:135], v[86:87], v[134:135], v[90:91]
	v_pk_fma_f32 v[124:125], v[124:125], v[76:77], v[132:133]
	v_pk_fma_f32 v[134:135], v[82:83], v[140:141], v[134:135]
	v_mul_f32_e32 v131, 0xbfb8aa3b, v124
	v_exp_f32_e32 v132, v131
	v_mul_f32_e32 v131, 0xbfb8aa3b, v125
	v_exp_f32_e32 v133, v131
	v_pk_fma_f32 v[126:127], v[126:127], v[78:79], v[134:135]
	v_pk_add_f32 v[132:133], v[132:133], 1.0 op_sel_hi:[1,0]
	s_nop 0
	v_mul_f32_e32 v134, 0xbfb8aa3b, v126
	v_mul_f32_e32 v135, 0xbfb8aa3b, v127
	v_exp_f32_e32 v134, v134
	v_rcp_f32_e32 v133, v133
	v_exp_f32_e32 v135, v135
	s_nop 0
	v_pk_add_f32 v[134:135], v[134:135], 1.0 op_sel_hi:[1,0]
	v_rcp_f32_e32 v132, v132
	s_nop 0
	v_pk_mul_f32 v[124:125], v[124:125], v[132:133]
	s_nop 0
	v_pk_mul_f32 v[120:121], v[120:121], v[124:125]
	v_rcp_f32_e32 v125, v135
	v_rcp_f32_e32 v124, v134
	s_nop 0
	v_pk_mul_f32 v[124:125], v[126:127], v[124:125]
	v_cvt_pk_bf16_f32 v120, v120, v121
	v_pk_mul_f32 v[122:123], v[122:123], v[124:125]
	s_nop 0
	v_cvt_pk_bf16_f32 v121, v122, v123
	ds_write_b64 v128, v[120:121] offset:39168
	v_add_u32_e32 v121, 0xfffffee0, v169
	v_add_u32_e32 v120, 0xffffff70, v169
	ds_read_b128 v[122:125], v121
	ds_read_b128 v[132:135], v120
	s_waitcnt lgkmcnt(1)
	v_pk_fma_f32 v[122:123], v[84:85], v[122:123], v[88:89]
	s_waitcnt lgkmcnt(0)
	v_pk_fma_f32 v[122:123], v[80:81], v[132:133], v[122:123]
	v_pk_fma_f32 v[124:125], v[86:87], v[124:125], v[90:91]
	v_pk_fma_f32 v[116:117], v[116:117], v[76:77], v[122:123]
	v_pk_fma_f32 v[124:125], v[82:83], v[134:135], v[124:125]
	v_mul_f32_e32 v122, 0xbfb8aa3b, v116
	v_mul_f32_e32 v123, 0xbfb8aa3b, v117
	v_exp_f32_e32 v122, v122
	v_exp_f32_e32 v123, v123
	v_pk_fma_f32 v[118:119], v[118:119], v[78:79], v[124:125]
	v_pk_add_f32 v[122:123], v[122:123], 1.0 op_sel_hi:[1,0]
	s_nop 0
	v_mul_f32_e32 v124, 0xbfb8aa3b, v118
	v_mul_f32_e32 v125, 0xbfb8aa3b, v119
	v_exp_f32_e32 v124, v124
	v_rcp_f32_e32 v123, v123
	v_exp_f32_e32 v125, v125
	s_nop 0
	v_pk_add_f32 v[124:125], v[124:125], 1.0 op_sel_hi:[1,0]
	v_rcp_f32_e32 v122, v122
	s_nop 0
	v_pk_mul_f32 v[116:117], v[116:117], v[122:123]
	s_nop 0
	v_pk_mul_f32 v[112:113], v[112:113], v[116:117]
	v_rcp_f32_e32 v117, v125
	v_rcp_f32_e32 v116, v124
	s_nop 0
	v_pk_mul_f32 v[116:117], v[118:119], v[116:117]
	v_cvt_pk_bf16_f32 v112, v112, v113
	v_pk_mul_f32 v[114:115], v[114:115], v[116:117]
	s_nop 0
	v_cvt_pk_bf16_f32 v113, v114, v115
	ds_write_b64 v128, v[112:113] offset:41472
	v_add_u32_e32 v113, 0xfffffee0, v170
	v_add_u32_e32 v112, 0xffffff70, v170
	ds_read_b128 v[114:117], v113
	ds_read_b128 v[122:125], v112
	s_waitcnt lgkmcnt(1)
; DI float sigmoidf_(float x) { return 1.0f / (1.0f + __expf(-x)); }
; DI void store4(u16* dst, f32x4 v) { uint2 w; w.x = cvtpk(v[0], v[1]); w.y = cvtpk(v[2], v[3]); *(uint2*)dst = w; }
; DI void phase8(const Params& p, const Sched& sched, unsigned char* smem) {
;     ...
;         for (int ni = 0; ni < 8; ++ni) {
;           const int row = wt * 128 + ni * 16 + lr;
;           const f32x4 gv = acc[2 * h2][ni], uv = acc[2 * h2 + 1][ni];
;           if (row >= 2) {
;             const f32x4 g1 = *(const f32x4*)(gl + (row - 1) * 36 + fl), g2 = *(const f32x4*)(gl + (row - 2) * 36 + fl);
;             f32x4 o;
;             o[0] = cb.x + w0.x * g2[0] + w1.x * g1[0] + w2.x * gv[0];
;             o[1] = cb.y + w0.y * g2[1] + w1.y * g1[1] + w2.y * gv[1];
;             o[2] = cb.z + w0.z * g2[2] + w1.z * g1[2] + w2.z * gv[2];
;             o[3] = cb.w + w0.w * g2[3] + w1.w * g1[3] + w2.w * gv[3];
; #pragma unroll
;             for (int j = 0; j < 4; ++j) o[j] = o[j] * sigmoidf_(o[j]) * uv[j];
;             store4(Ls + row * 72 + fc, o);
;           } else {
;             *(f32x4*)(gside + ((size_t)tm * 4 + row) * FF + F) = gv;
;             *(f32x4*)(uside + ((size_t)tm * 2 + row) * FF + F) = uv;
;           }
;           if (row >= 254) *(f32x4*)(gside + ((size_t)tm * 4 + 2 + (row - 254)) * FF + F) = gv;
	v_pk_fma_f32 v[114:115], v[84:85], v[114:115], v[88:89]
	s_waitcnt lgkmcnt(0)
	v_pk_fma_f32 v[114:115], v[80:81], v[122:123], v[114:115]
	v_pk_fma_f32 v[116:117], v[86:87], v[116:117], v[90:91]
	v_pk_fma_f32 v[108:109], v[108:109], v[76:77], v[114:115]
	v_pk_fma_f32 v[116:117], v[82:83], v[124:125], v[116:117]
	v_mul_f32_e32 v114, 0xbfb8aa3b, v108
	v_mul_f32_e32 v115, 0xbfb8aa3b, v109
	v_exp_f32_e32 v114, v114
	v_exp_f32_e32 v115, v115
	v_pk_fma_f32 v[110:111], v[110:111], v[78:79], v[116:117]
	v_pk_add_f32 v[114:115], v[114:115], 1.0 op_sel_hi:[1,0]
	s_nop 0
	v_mul_f32_e32 v116, 0xbfb8aa3b, v110
	v_mul_f32_e32 v117, 0xbfb8aa3b, v111
	v_exp_f32_e32 v116, v116
	v_rcp_f32_e32 v115, v115
	v_exp_f32_e32 v117, v117
	s_nop 0
	v_pk_add_f32 v[116:117], v[116:117], 1.0 op_sel_hi:[1,0]
	v_rcp_f32_e32 v114, v114
	s_nop 0
	v_pk_mul_f32 v[108:109], v[108:109], v[114:115]
	s_nop 0
	v_pk_mul_f32 v[104:105], v[104:105], v[108:109]
	v_rcp_f32_e32 v109, v117
	v_rcp_f32_e32 v108, v116
	s_nop 0
	v_pk_mul_f32 v[108:109], v[110:111], v[108:109]
	v_cvt_pk_bf16_f32 v104, v104, v105
	v_pk_mul_f32 v[106:107], v[106:107], v[108:109]
	s_nop 0
	v_cvt_pk_bf16_f32 v105, v106, v107
	ds_write_b64 v128, v[104:105] offset:43776
	v_add_u32_e32 v105, 0xfffffee0, v171
	v_add_u32_e32 v104, 0xffffff70, v171
	ds_read_b128 v[106:109], v105
	ds_read_b128 v[114:117], v104
	s_waitcnt lgkmcnt(1)
	v_pk_fma_f32 v[106:107], v[84:85], v[106:107], v[88:89]
	s_waitcnt lgkmcnt(0)
	v_pk_fma_f32 v[106:107], v[80:81], v[114:115], v[106:107]
	v_pk_fma_f32 v[108:109], v[86:87], v[108:109], v[90:91]
	v_pk_fma_f32 v[100:101], v[100:101], v[76:77], v[106:107]
	v_pk_fma_f32 v[108:109], v[82:83], v[116:117], v[108:109]
	v_mul_f32_e32 v106, 0xbfb8aa3b, v100
	v_mul_f32_e32 v107, 0xbfb8aa3b, v101
	v_exp_f32_e32 v106, v106
	v_exp_f32_e32 v107, v107
	v_pk_fma_f32 v[102:103], v[102:103], v[78:79], v[108:109]
	v_pk_add_f32 v[106:107], v[106:107], 1.0 op_sel_hi:[1,0]
	s_nop 0
	v_mul_f32_e32 v108, 0xbfb8aa3b, v102
	v_mul_f32_e32 v109, 0xbfb8aa3b, v103
	v_exp_f32_e32 v108, v108
	v_rcp_f32_e32 v107, v107
	v_exp_f32_e32 v109, v109
	s_nop 0
	v_pk_add_f32 v[108:109], v[108:109], 1.0 op_sel_hi:[1,0]
	v_rcp_f32_e32 v106, v106
	s_nop 0
	v_pk_mul_f32 v[100:101], v[100:101], v[106:107]
	s_nop 0
	v_pk_mul_f32 v[96:97], v[96:97], v[100:101]
	v_rcp_f32_e32 v101, v109
	v_rcp_f32_e32 v100, v108
	s_nop 0
	v_pk_mul_f32 v[100:101], v[102:103], v[100:101]
	v_cvt_pk_bf16_f32 v96, v96, v97
	v_pk_mul_f32 v[98:99], v[98:99], v[100:101]
	s_nop 0
	v_cvt_pk_bf16_f32 v97, v98, v99
	ds_write_b64 v128, v[96:97] offset:46080
	v_add_u32_e32 v97, 0xfffffee0, v172
	v_add_u32_e32 v96, 0xffffff70, v172
	ds_read_b128 v[98:101], v97
	ds_read_b128 v[106:109], v96
	s_waitcnt lgkmcnt(1)
	v_pk_fma_f32 v[98:99], v[84:85], v[98:99], v[88:89]
	s_waitcnt lgkmcnt(0)
	v_pk_fma_f32 v[98:99], v[80:81], v[106:107], v[98:99]
	v_pk_fma_f32 v[100:101], v[86:87], v[100:101], v[90:91]
	v_pk_fma_f32 v[92:93], v[92:93], v[76:77], v[98:99]
	v_pk_fma_f32 v[100:101], v[82:83], v[108:109], v[100:101]
	v_mul_f32_e32 v98, 0xbfb8aa3b, v92
	v_mul_f32_e32 v99, 0xbfb8aa3b, v93
	v_exp_f32_e32 v98, v98
	v_exp_f32_e32 v99, v99
	v_pk_fma_f32 v[94:95], v[94:95], v[78:79], v[100:101]
	v_pk_add_f32 v[98:99], v[98:99], 1.0 op_sel_hi:[1,0]
	s_nop 0
	v_mul_f32_e32 v100, 0xbfb8aa3b, v94
	v_mul_f32_e32 v101, 0xbfb8aa3b, v95
	v_exp_f32_e32 v100, v100
	v_rcp_f32_e32 v99, v99
	v_exp_f32_e32 v101, v101
	s_nop 0
	v_pk_add_f32 v[100:101], v[100:101], 1.0 op_sel_hi:[1,0]
	v_rcp_f32_e32 v98, v98
	s_nop 0
	v_pk_mul_f32 v[92:93], v[92:93], v[98:99]
	s_nop 0
	v_pk_mul_f32 v[72:73], v[72:73], v[92:93]
	v_rcp_f32_e32 v93, v101
	v_rcp_f32_e32 v92, v100
	s_nop 0
	v_pk_mul_f32 v[92:93], v[94:95], v[92:93]
	v_cvt_pk_bf16_f32 v72, v72, v73
	v_pk_mul_f32 v[74:75], v[74:75], v[92:93]
	v_add_u32_e32 v93, 0xfffffee0, v173
	v_cvt_pk_bf16_f32 v73, v74, v75
	ds_write_b64 v128, v[72:73] offset:48384
	v_add_u32_e32 v92, 0xffffff70, v173
	ds_read_b128 v[72:75], v93
	ds_read_b128 v[98:101], v92
	s_waitcnt lgkmcnt(1)
	v_pk_fma_f32 v[72:73], v[84:85], v[72:73], v[88:89]
	s_waitcnt lgkmcnt(0)
	v_pk_fma_f32 v[72:73], v[80:81], v[98:99], v[72:73]
	v_pk_fma_f32 v[74:75], v[86:87], v[74:75], v[90:91]
	v_pk_fma_f32 v[72:73], v[64:65], v[76:77], v[72:73]
	v_pk_fma_f32 v[74:75], v[82:83], v[100:101], v[74:75]
	v_mul_f32_e32 v76, 0xbfb8aa3b, v72
	v_mul_f32_e32 v77, 0xbfb8aa3b, v73
	v_exp_f32_e32 v76, v76
	v_exp_f32_e32 v77, v77
	v_pk_fma_f32 v[74:75], v[66:67], v[78:79], v[74:75]
	v_or_b32_e32 v84, 0x70, v154
	v_mul_f32_e32 v78, 0xbfb8aa3b, v74
	v_pk_add_f32 v[76:77], v[76:77], 1.0 op_sel_hi:[1,0]
	v_mul_f32_e32 v79, 0xbfb8aa3b, v75
	v_exp_f32_e32 v78, v78
	v_exp_f32_e32 v79, v79
	v_rcp_f32_e32 v77, v77
	v_pk_add_f32 v[78:79], v[78:79], 1.0 op_sel_hi:[1,0]
	v_rcp_f32_e32 v76, v76
	s_nop 0
	v_pk_mul_f32 v[72:73], v[72:73], v[76:77]
	s_nop 0
	v_pk_mul_f32 v[68:69], v[68:69], v[72:73]
	v_rcp_f32_e32 v73, v79
	v_rcp_f32_e32 v72, v78
	s_nop 0
	v_pk_mul_f32 v[72:73], v[74:75], v[72:73]
	v_cvt_pk_bf16_f32 v68, v68, v69
	v_pk_mul_f32 v[70:71], v[70:71], v[72:73]
	v_cmp_lt_u32_e64 s[6:7], s49, v84
	v_cvt_pk_bf16_f32 v69, v70, v71
	ds_write_b64 v128, v[68:69] offset:50688
	s_and_saveexec_b64 s[34:35], s[6:7]
	s_cbranch_execz .LBB0_952
	s_ashr_i32 s31, s30, 31
	s_lshl_b64 s[58:59], s[30:31], 2
	s_add_u32 s58, s58, 0xffffff74
	v_mov_b32_e32 v155, v153
	s_addc_u32 s59, s59, -1
	v_lshl_add_u64 v[68:69], s[58:59], 0, v[154:155]
	v_mov_b64_e32 v[70:71], s[16:17]
	v_mad_u64_u32 v[70:71], s[58:59], v68, s48, v[70:71]
	v_mad_i32_i24 v71, v69, s48, v71
	v_lshl_add_u64 v[68:69], v[144:145], 2, v[70:71]
	global_store_dwordx4 v[68:69], v[64:67], off

; DI float sigmoidf_(float x) { return 1.0f / (1.0f + __expf(-x)); }
; DI void store4(u16* dst, f32x4 v) { uint2 w; w.x = cvtpk(v[0], v[1]); w.y = cvtpk(v[2], v[3]); *(uint2*)dst = w; }
; DI void phase8(const Params& p, const Sched& sched, unsigned char* smem) {
;     ...
;       for (int h2 = 0; h2 < 2; ++h2) {
;         const int fl = wf * 16 + lq * 4, fc = (2 * wf + h2) * 16 + lq * 4, F = tn * 64 + fc;
;         __syncthreads();
; #pragma unroll
;         for (int ni = 0; ni < 8; ++ni) *(f32x4*)(gl + (wt * 128 + ni * 16 + lr) * 36 + fl) = acc[2 * h2][ni];
;         __syncthreads();
;         const float4 w0 = *(const float4*)(p.conv_w + F), w1 = *(const float4*)(p.conv_w + FF + F), w2 = *(const float4*)(p.conv_w + 2 * FF + F), cb = *(const float4*)(p.conv_b + F);
; #pragma unroll
;         for (int ni = 0; ni < 8; ++ni) {
;           const int row = wt * 128 + ni * 16 + lr;
;           const f32x4 gv = acc[2 * h2][ni], uv = acc[2 * h2 + 1][ni];
;           if (row >= 2) {
;             const f32x4 g1 = *(const f32x4*)(gl + (row - 1) * 36 + fl), g2 = *(const f32x4*)(gl + (row - 2) * 36 + fl);
;             f32x4 o;
;             o[0] = cb.x + w0.x * g2[0] + w1.x * g1[0] + w2.x * gv[0];
;             o[1] = cb.y + w0.y * g2[1] + w1.y * g1[1] + w2.y * gv[1];
;             o[2] = cb.z + w0.z * g2[2] + w1.z * g1[2] + w2.z * gv[2];
;             o[3] = cb.w + w0.w * g2[3] + w1.w * g1[3] + w2.w * gv[3];
; #pragma unroll
;             for (int j = 0; j < 4; ++j) o[j] = o[j] * sigmoidf_(o[j]) * uv[j];
;             store4(Ls + row * 72 + fc, o);
.LBB0_954:
	s_andn2_saveexec_b64 s[4:5], s[4:5]
	s_cbranch_execz .LBB0_956
	ds_read_b128 v[80:83], v175
	ds_read_b128 v[84:87], v174
	s_waitcnt vmcnt(0) lgkmcnt(1)
	v_pk_fma_f32 v[80:81], v[72:73], v[80:81], v[76:77]
	s_waitcnt lgkmcnt(0)
	v_pk_fma_f32 v[80:81], v[68:69], v[84:85], v[80:81]
	v_pk_fma_f32 v[82:83], v[74:75], v[82:83], v[78:79]
	v_pk_fma_f32 v[60:61], v[60:61], v[64:65], v[80:81]
	v_pk_fma_f32 v[82:83], v[70:71], v[86:87], v[82:83]
	v_mul_f32_e32 v80, 0xbfb8aa3b, v60
	v_mul_f32_e32 v81, 0xbfb8aa3b, v61
	v_exp_f32_e32 v80, v80
	v_exp_f32_e32 v81, v81
	v_pk_fma_f32 v[62:63], v[62:63], v[66:67], v[82:83]
	v_pk_add_f32 v[80:81], v[80:81], 1.0 op_sel_hi:[1,0]
	s_nop 0
	v_rcp_f32_e32 v81, v81
	v_mul_f32_e32 v82, 0xbfb8aa3b, v62
	v_mul_f32_e32 v83, 0xbfb8aa3b, v63
	v_exp_f32_e32 v82, v82
	v_exp_f32_e32 v83, v83
	s_nop 0
	v_pk_add_f32 v[82:83], v[82:83], 1.0 op_sel_hi:[1,0]
	v_rcp_f32_e32 v80, v80
	s_nop 0
	v_pk_mul_f32 v[60:61], v[60:61], v[80:81]
	s_nop 0
	v_pk_mul_f32 v[56:57], v[56:57], v[60:61]
	v_rcp_f32_e32 v61, v83
	v_rcp_f32_e32 v60, v82
	s_nop 0
	v_pk_mul_f32 v[60:61], v[62:63], v[60:61]
	v_cvt_pk_bf16_f32 v56, v56, v57
	v_pk_mul_f32 v[58:59], v[58:59], v[60:61]
	s_nop 0
	v_cvt_pk_bf16_f32 v57, v58, v59
	ds_write_b64 v152, v[56:57] offset:36896
.LBB0_956:
	s_or_b64 exec, exec, s[4:5]
	ds_read_b128 v[56:59], v137
	ds_read_b128 v[60:63], v136
	s_waitcnt vmcnt(0) lgkmcnt(1)
	v_pk_fma_f32 v[56:57], v[72:73], v[56:57], v[76:77]
	s_waitcnt lgkmcnt(0)
	v_pk_fma_f32 v[56:57], v[68:69], v[60:61], v[56:57]
	v_pk_fma_f32 v[58:59], v[74:75], v[58:59], v[78:79]
	v_pk_fma_f32 v[52:53], v[52:53], v[64:65], v[56:57]
	v_pk_fma_f32 v[58:59], v[70:71], v[62:63], v[58:59]
	v_mul_f32_e32 v56, 0xbfb8aa3b, v52
	v_mul_f32_e32 v57, 0xbfb8aa3b, v53
	v_exp_f32_e32 v56, v56
	v_exp_f32_e32 v57, v57
	v_pk_fma_f32 v[54:55], v[54:55], v[66:67], v[58:59]
	v_pk_add_f32 v[56:57], v[56:57], 1.0 op_sel_hi:[1,0]
	s_nop 0
	v_rcp_f32_e32 v57, v57
	v_mul_f32_e32 v58, 0xbfb8aa3b, v54
	v_mul_f32_e32 v59, 0xbfb8aa3b, v55
	v_exp_f32_e32 v58, v58
	v_exp_f32_e32 v59, v59
	s_nop 0
	v_pk_add_f32 v[58:59], v[58:59], 1.0 op_sel_hi:[1,0]
	v_rcp_f32_e32 v56, v56
	s_nop 0
	v_pk_mul_f32 v[52:53], v[52:53], v[56:57]
	s_nop 0
	v_pk_mul_f32 v[48:49], v[48:49], v[52:53]
	v_rcp_f32_e32 v53, v59
	v_rcp_f32_e32 v52, v58
	s_nop 0
	v_pk_mul_f32 v[52:53], v[54:55], v[52:53]
	v_cvt_pk_bf16_f32 v48, v48, v49
	v_pk_mul_f32 v[50:51], v[50:51], v[52:53]
	s_nop 0
	v_cvt_pk_bf16_f32 v49, v50, v51
	ds_write_b64 v128, v[48:49] offset:36896
	ds_read_b128 v[48:51], v130
	ds_read_b128 v[52:55], v129
	s_waitcnt lgkmcnt(1)
	v_pk_fma_f32 v[48:49], v[72:73], v[48:49], v[76:77]
	s_waitcnt lgkmcnt(0)
	v_pk_fma_f32 v[48:49], v[68:69], v[52:53], v[48:49]
	v_pk_fma_f32 v[50:51], v[74:75], v[50:51], v[78:79]
	v_pk_fma_f32 v[44:45], v[44:45], v[64:65], v[48:49]
	v_pk_fma_f32 v[50:51], v[70:71], v[54:55], v[50:51]
	v_mul_f32_e32 v48, 0xbfb8aa3b, v44
	v_mul_f32_e32 v49, 0xbfb8aa3b, v45
	v_exp_f32_e32 v48, v48
	v_exp_f32_e32 v49, v49
	v_pk_fma_f32 v[46:47], v[46:47], v[66:67], v[50:51]
	v_pk_add_f32 v[48:49], v[48:49], 1.0 op_sel_hi:[1,0]
	s_nop 0
	v_mul_f32_e32 v50, 0xbfb8aa3b, v46
	v_mul_f32_e32 v51, 0xbfb8aa3b, v47
	v_exp_f32_e32 v50, v50
	v_rcp_f32_e32 v49, v49
	v_exp_f32_e32 v51, v51
	s_nop 0
	v_pk_add_f32 v[50:51], v[50:51], 1.0 op_sel_hi:[1,0]
	v_rcp_f32_e32 v48, v48
	s_nop 0
	v_pk_mul_f32 v[44:45], v[44:45], v[48:49]
	s_nop 0
	v_pk_mul_f32 v[40:41], v[40:41], v[44:45]
	v_rcp_f32_e32 v45, v51
	v_rcp_f32_e32 v44, v50
	s_nop 0
	v_pk_mul_f32 v[44:45], v[46:47], v[44:45]
	v_cvt_pk_bf16_f32 v40, v40, v41
	v_pk_mul_f32 v[42:43], v[42:43], v[44:45]
	s_nop 0
	v_cvt_pk_bf16_f32 v41, v42, v43
	ds_write_b64 v128, v[40:41] offset:39200
	ds_read_b128 v[40:43], v121
	ds_read_b128 v[44:47], v120
	s_waitcnt lgkmcnt(1)
	v_pk_fma_f32 v[40:41], v[72:73], v[40:41], v[76:77]
	s_waitcnt lgkmcnt(0)
	v_pk_fma_f32 v[40:41], v[68:69], v[44:45], v[40:41]
	v_pk_fma_f32 v[42:43], v[74:75], v[42:43], v[78:79]
	v_pk_fma_f32 v[36:37], v[36:37], v[64:65], v[40:41]
	v_pk_fma_f32 v[42:43], v[70:71], v[46:47], v[42:43]
	v_mul_f32_e32 v40, 0xbfb8aa3b, v36
	v_mul_f32_e32 v41, 0xbfb8aa3b, v37
	v_exp_f32_e32 v40, v40
	v_exp_f32_e32 v41, v41
	v_pk_fma_f32 v[38:39], v[38:39], v[66:67], v[42:43]
	v_pk_add_f32 v[40:41], v[40:41], 1.0 op_sel_hi:[1,0]
	s_nop 0
	v_mul_f32_e32 v42, 0xbfb8aa3b, v38
	v_mul_f32_e32 v43, 0xbfb8aa3b, v39
	v_exp_f32_e32 v42, v42
	v_rcp_f32_e32 v41, v41
	v_exp_f32_e32 v43, v43
	s_nop 0
	v_pk_add_f32 v[42:43], v[42:43], 1.0 op_sel_hi:[1,0]
	v_rcp_f32_e32 v40, v40
	s_nop 0
	v_pk_mul_f32 v[36:37], v[36:37], v[40:41]
	s_nop 0
	v_pk_mul_f32 v[32:33], v[32:33], v[36:37]
	v_rcp_f32_e32 v37, v43
	v_rcp_f32_e32 v36, v42
	s_nop 0
	v_pk_mul_f32 v[36:37], v[38:39], v[36:37]
	v_cvt_pk_bf16_f32 v32, v32, v33
	v_pk_mul_f32 v[34:35], v[34:35], v[36:37]
	s_nop 0
	v_cvt_pk_bf16_f32 v33, v34, v35
	ds_write_b64 v128, v[32:33] offset:41504
	ds_read_b128 v[32:35], v113
	ds_read_b128 v[36:39], v112
	s_waitcnt lgkmcnt(1)
	v_pk_fma_f32 v[32:33], v[72:73], v[32:33], v[76:77]
	s_waitcnt lgkmcnt(0)
; DI void store4(u16* dst, f32x4 v) { uint2 w; w.x = cvtpk(v[0], v[1]); w.y = cvtpk(v[2], v[3]); *(uint2*)dst = w; }
; DI float sigmoidf_(float x) { return 1.0f / (1.0f + __expf(-x)); }
; DI void phase8(const Params& p, const Sched& sched, unsigned char* smem) {
;     ...
;         for (int ni = 0; ni < 8; ++ni) {
;           const int row = wt * 128 + ni * 16 + lr;
;           const f32x4 gv = acc[2 * h2][ni], uv = acc[2 * h2 + 1][ni];
;           if (row >= 2) {
;             const f32x4 g1 = *(const f32x4*)(gl + (row - 1) * 36 + fl), g2 = *(const f32x4*)(gl + (row - 2) * 36 + fl);
;             f32x4 o;
;             o[0] = cb.x + w0.x * g2[0] + w1.x * g1[0] + w2.x * gv[0];
;             o[1] = cb.y + w0.y * g2[1] + w1.y * g1[1] + w2.y * gv[1];
;             o[2] = cb.z + w0.z * g2[2] + w1.z * g1[2] + w2.z * gv[2];
;             o[3] = cb.w + w0.w * g2[3] + w1.w * g1[3] + w2.w * gv[3];
; #pragma unroll
;             for (int j = 0; j < 4; ++j) o[j] = o[j] * sigmoidf_(o[j]) * uv[j];
;             store4(Ls + row * 72 + fc, o);
;           } else {
;             *(f32x4*)(gside + ((size_t)tm * 4 + row) * FF + F) = gv;
;             *(f32x4*)(uside + ((size_t)tm * 2 + row) * FF + F) = uv;
;           }
;           if (row >= 254) *(f32x4*)(gside + ((size_t)tm * 4 + 2 + (row - 254)) * FF + F) = gv;
	v_pk_fma_f32 v[32:33], v[68:69], v[36:37], v[32:33]
	v_pk_fma_f32 v[34:35], v[74:75], v[34:35], v[78:79]
	v_pk_fma_f32 v[28:29], v[28:29], v[64:65], v[32:33]
	v_pk_fma_f32 v[34:35], v[70:71], v[38:39], v[34:35]
	v_mul_f32_e32 v32, 0xbfb8aa3b, v28
	v_mul_f32_e32 v33, 0xbfb8aa3b, v29
	v_exp_f32_e32 v32, v32
	v_exp_f32_e32 v33, v33
	v_pk_fma_f32 v[30:31], v[30:31], v[66:67], v[34:35]
	v_pk_add_f32 v[32:33], v[32:33], 1.0 op_sel_hi:[1,0]
	s_nop 0
	v_mul_f32_e32 v34, 0xbfb8aa3b, v30
	v_mul_f32_e32 v35, 0xbfb8aa3b, v31
	v_exp_f32_e32 v34, v34
	v_rcp_f32_e32 v33, v33
	v_exp_f32_e32 v35, v35
	s_nop 0
	v_pk_add_f32 v[34:35], v[34:35], 1.0 op_sel_hi:[1,0]
	v_rcp_f32_e32 v32, v32
	s_nop 0
	v_pk_mul_f32 v[28:29], v[28:29], v[32:33]
	s_nop 0
	v_pk_mul_f32 v[24:25], v[24:25], v[28:29]
	v_rcp_f32_e32 v29, v35
	v_rcp_f32_e32 v28, v34
	s_nop 0
	v_pk_mul_f32 v[28:29], v[30:31], v[28:29]
	v_cvt_pk_bf16_f32 v24, v24, v25
	v_pk_mul_f32 v[26:27], v[26:27], v[28:29]
	s_nop 0
	v_cvt_pk_bf16_f32 v25, v26, v27
	ds_write_b64 v128, v[24:25] offset:43808
	ds_read_b128 v[24:27], v105
	ds_read_b128 v[28:31], v104
	s_waitcnt lgkmcnt(1)
	v_pk_fma_f32 v[24:25], v[72:73], v[24:25], v[76:77]
	s_waitcnt lgkmcnt(0)
	v_pk_fma_f32 v[24:25], v[68:69], v[28:29], v[24:25]
	v_pk_fma_f32 v[26:27], v[74:75], v[26:27], v[78:79]
	v_pk_fma_f32 v[20:21], v[20:21], v[64:65], v[24:25]
	v_pk_fma_f32 v[26:27], v[70:71], v[30:31], v[26:27]
	v_mul_f32_e32 v24, 0xbfb8aa3b, v20
	v_mul_f32_e32 v25, 0xbfb8aa3b, v21
	v_exp_f32_e32 v24, v24
	v_exp_f32_e32 v25, v25
	v_pk_fma_f32 v[22:23], v[22:23], v[66:67], v[26:27]
	v_pk_add_f32 v[24:25], v[24:25], 1.0 op_sel_hi:[1,0]
	s_nop 0
	v_mul_f32_e32 v26, 0xbfb8aa3b, v22
	v_mul_f32_e32 v27, 0xbfb8aa3b, v23
	v_exp_f32_e32 v26, v26
	v_rcp_f32_e32 v25, v25
	v_exp_f32_e32 v27, v27
	s_nop 0
	v_pk_add_f32 v[26:27], v[26:27], 1.0 op_sel_hi:[1,0]
	v_rcp_f32_e32 v24, v24
	s_nop 0
	v_pk_mul_f32 v[20:21], v[20:21], v[24:25]
	s_nop 0
	v_pk_mul_f32 v[16:17], v[16:17], v[20:21]
	v_rcp_f32_e32 v21, v27
	v_rcp_f32_e32 v20, v26
	s_nop 0
	v_pk_mul_f32 v[20:21], v[22:23], v[20:21]
	v_cvt_pk_bf16_f32 v16, v16, v17
	v_pk_mul_f32 v[18:19], v[18:19], v[20:21]
	s_nop 0
	v_cvt_pk_bf16_f32 v17, v18, v19
	ds_write_b64 v128, v[16:17] offset:46112
	ds_read_b128 v[16:19], v97
	ds_read_b128 v[20:23], v96
	s_waitcnt lgkmcnt(1)
	v_pk_fma_f32 v[16:17], v[72:73], v[16:17], v[76:77]
	s_waitcnt lgkmcnt(0)
	v_pk_fma_f32 v[16:17], v[68:69], v[20:21], v[16:17]
	v_pk_fma_f32 v[18:19], v[74:75], v[18:19], v[78:79]
	v_pk_fma_f32 v[12:13], v[12:13], v[64:65], v[16:17]
	v_pk_fma_f32 v[18:19], v[70:71], v[22:23], v[18:19]
	v_mul_f32_e32 v16, 0xbfb8aa3b, v12
	v_mul_f32_e32 v17, 0xbfb8aa3b, v13
	v_exp_f32_e32 v16, v16
	v_exp_f32_e32 v17, v17
	v_pk_fma_f32 v[14:15], v[14:15], v[66:67], v[18:19]
	v_pk_add_f32 v[16:17], v[16:17], 1.0 op_sel_hi:[1,0]
	s_nop 0
	v_mul_f32_e32 v18, 0xbfb8aa3b, v14
	v_mul_f32_e32 v19, 0xbfb8aa3b, v15
	v_exp_f32_e32 v18, v18
	v_rcp_f32_e32 v17, v17
	v_exp_f32_e32 v19, v19
	s_nop 0
	v_pk_add_f32 v[18:19], v[18:19], 1.0 op_sel_hi:[1,0]
	v_rcp_f32_e32 v16, v16
	s_nop 0
	v_pk_mul_f32 v[12:13], v[12:13], v[16:17]
	s_nop 0
	v_pk_mul_f32 v[8:9], v[8:9], v[12:13]
	v_rcp_f32_e32 v13, v19
	v_rcp_f32_e32 v12, v18
	s_nop 0
	v_pk_mul_f32 v[12:13], v[14:15], v[12:13]
	v_cvt_pk_bf16_f32 v8, v8, v9
	v_pk_mul_f32 v[10:11], v[10:11], v[12:13]
	s_nop 0
	v_cvt_pk_bf16_f32 v9, v10, v11
	ds_write_b64 v128, v[8:9] offset:48416
	ds_read_b128 v[8:11], v93
	ds_read_b128 v[12:15], v92
	s_waitcnt lgkmcnt(1)
	v_pk_fma_f32 v[8:9], v[72:73], v[8:9], v[76:77]
	s_waitcnt lgkmcnt(0)
	v_pk_fma_f32 v[8:9], v[68:69], v[12:13], v[8:9]
	v_pk_fma_f32 v[10:11], v[74:75], v[10:11], v[78:79]
	v_pk_fma_f32 v[8:9], v[0:1], v[64:65], v[8:9]
	v_pk_fma_f32 v[10:11], v[70:71], v[14:15], v[10:11]
	v_mul_f32_e32 v12, 0xbfb8aa3b, v8
	v_mul_f32_e32 v13, 0xbfb8aa3b, v9
	v_exp_f32_e32 v12, v12
	v_exp_f32_e32 v13, v13
	v_pk_fma_f32 v[10:11], v[2:3], v[66:67], v[10:11]
	v_pk_add_f32 v[12:13], v[12:13], 1.0 op_sel_hi:[1,0]
	s_nop 0
	v_mul_f32_e32 v14, 0xbfb8aa3b, v10
	v_mul_f32_e32 v15, 0xbfb8aa3b, v11
	v_exp_f32_e32 v14, v14
	v_rcp_f32_e32 v13, v13
	v_exp_f32_e32 v15, v15
	s_nop 0
	v_pk_add_f32 v[14:15], v[14:15], 1.0 op_sel_hi:[1,0]
	v_rcp_f32_e32 v12, v12
	s_nop 0
	v_pk_mul_f32 v[8:9], v[8:9], v[12:13]
	s_nop 0
	v_pk_mul_f32 v[4:5], v[4:5], v[8:9]
	v_rcp_f32_e32 v9, v15
	v_rcp_f32_e32 v8, v14
	s_nop 0
	v_pk_mul_f32 v[8:9], v[10:11], v[8:9]
	v_cvt_pk_bf16_f32 v4, v4, v5
	v_pk_mul_f32 v[6:7], v[6:7], v[8:9]
	s_nop 0
	v_cvt_pk_bf16_f32 v5, v6, v7
	ds_write_b64 v128, v[4:5] offset:50720
	s_and_saveexec_b64 s[4:5], s[6:7]
	s_cbranch_execz .LBB0_958
	s_ashr_i32 s31, s30, 31
	s_lshl_b64 s[6:7], s[30:31], 2
	s_add_u32 s6, s6, 0xffffff74
	v_mov_b32_e32 v155, v153
	s_addc_u32 s7, s7, -1
	v_lshl_add_u64 v[4:5], s[6:7], 0, v[154:155]
	v_mov_b64_e32 v[6:7], s[16:17]
	v_mad_u64_u32 v[6:7], s[6:7], v4, s48, v[6:7]
	v_mad_i32_i24 v7, v5, s48, v7
	v_lshl_add_u64 v[4:5], v[144:145], 2, v[6:7]
	global_store_dwordx4 v[4:5], v[0:3], off offset:64

; DI int tidx() { int t = __builtin_amdgcn_workitem_id_x(); asm volatile("" : "+v"(t)); return t; }
; DI void store4(u16* dst, f32x4 v) { uint2 w; w.x = cvtpk(v[0], v[1]); w.y = cvtpk(v[2], v[3]); *(uint2*)dst = w; }
; DI float sigmoidf_(float x) { return 1.0f / (1.0f + __expf(-x)); }
; DI void phase8b(const Params& p, int bid, int nblk) {
;     ...
;   for (int i = bid * 256 + tidx(); i < total; i += nblk * 256) {
;     const int f4 = i % (FF / 4), rr = i / (FF / 4), r = rr & 1, tm = rr >> 1, F = f4 * 4;
;     const bool first = (tm & 7) == 0;
;     const f32x4 z = {0.f, 0.f, 0.f, 0.f};
;     const f32x4 gv = *(const f32x4*)(gside + ((size_t)tm * 4 + r) * FF + F);
;     f32x4 g1, g2;
;     if (r == 1) { g1 = *(const f32x4*)(gside + ((size_t)tm * 4 + 0) * FF + F); g2 = first ? z : *(const f32x4*)(gside + ((size_t)(tm - 1) * 4 + 3) * FF + F); }
;     else { g1 = first ? z : *(const f32x4*)(gside + ((size_t)(tm - 1) * 4 + 3) * FF + F); g2 = first ? z : *(const f32x4*)(gside + ((size_t)(tm - 1) * 4 + 2) * FF + F); }
;     const f32x4 uv = *(const f32x4*)(uside + ((size_t)tm * 2 + r) * FF + F);
;     const f32x4 w0 = *(const f32x4*)(p.conv_w + F), w1 = *(const f32x4*)(p.conv_w + FF + F), w2 = *(const f32x4*)(p.conv_w + 2 * FF + F), cb = *(const f32x4*)(p.conv_b + F);
;     f32x4 o = cb + w0 * g2 + w1 * g1 + w2 * gv;
; #pragma unroll
;     for (int j = 0; j < 4; ++j) o[j] = o[j] * sigmoidf_(o[j]) * uv[j];
;     store4(act + ((size_t)(F >> 5) * Tn + (size_t)tm * 256 + r) * 32 + (F & 31), o);
.LBB0_1028:
	s_or_b64 exec, exec, s[0:1]
	v_lshlrev_b64 v[2:3], 2, v[16:17]
	v_lshl_add_u64 v[24:25], s[68:69], 0, v[2:3]
	v_lshl_add_u64 v[28:29], s[70:71], 0, v[2:3]
	global_load_dwordx4 v[24:27], v[24:25], off
	v_lshl_add_u64 v[32:33], s[20:21], 0, v[2:3]
	global_load_dwordx4 v[28:31], v[28:29], off
	v_lshl_add_u64 v[36:37], s[22:23], 0, v[2:3]
	global_load_dwordx4 v[32:35], v[32:33], off
	v_sub_u32_e32 v0, v20, v23
	global_load_dwordx4 v[36:39], v[36:37], off
	v_lshl_or_b32 v23, v18, 1, v22
	v_lshlrev_b64 v[40:41], 8, v[18:19]
	v_and_b32_e32 v18, 28, v16
	v_mul_hi_i32_i24_e32 v17, 0x2c00, v23
	v_mul_i32_i24_e32 v16, 0x2c00, v23
	v_lshl_add_u64 v[16:17], s[10:11], 0, v[16:17]
	v_lshl_add_u64 v[2:3], v[16:17], 0, v[2:3]
	v_ashrrev_i32_e32 v42, 3, v0
	v_lshlrev_b32_e32 v0, 1, v18
	global_load_dwordx4 v[16:19], v[2:3], off
	v_ashrrev_i32_e32 v43, 31, v42
	v_lshlrev_b64 v[2:3], 16, v[42:43]
	v_lshl_add_u64 v[2:3], v[2:3], 0, v[40:41]
	v_or_b32_e32 v2, v2, v22
	v_lshlrev_b64 v[2:3], 6, v[2:3]
	v_lshl_add_u64 v[2:3], s[8:9], 0, v[2:3]
	v_lshl_add_u64 v[2:3], v[2:3], 0, v[0:1]
	v_add_u32_e32 v20, s64, v20
	v_cmp_lt_i32_e32 vcc, s30, v20
	s_or_b64 s[24:25], vcc, s[24:25]
	v_add_u32_e32 v21, s28, v21
	s_waitcnt vmcnt(3)
	v_pk_fma_f32 v[12:13], v[12:13], v[24:25], v[28:29]
	v_pk_fma_f32 v[14:15], v[14:15], v[26:27], v[30:31]
	s_waitcnt vmcnt(2)
	v_pk_fma_f32 v[8:9], v[8:9], v[32:33], v[12:13]
	v_pk_fma_f32 v[10:11], v[10:11], v[34:35], v[14:15]
	s_waitcnt vmcnt(1)
	v_pk_fma_f32 v[4:5], v[4:5], v[36:37], v[8:9]
	v_pk_fma_f32 v[6:7], v[6:7], v[38:39], v[10:11]
	v_mul_f32_e32 v8, 0xbfb8aa3b, v4
	v_mul_f32_e32 v9, 0xbfb8aa3b, v5
	v_exp_f32_e32 v8, v8
	v_exp_f32_e32 v9, v9
	v_mul_f32_e32 v10, 0xbfb8aa3b, v6
	v_mul_f32_e32 v11, 0xbfb8aa3b, v7
	v_exp_f32_e32 v10, v10
	v_exp_f32_e32 v11, v11
	v_pk_add_f32 v[8:9], v[8:9], 1.0 op_sel_hi:[1,0]
	v_pk_add_f32 v[10:11], v[10:11], 1.0 op_sel_hi:[1,0]
	s_mov_b64 vcc, s[0:1]
	v_rcp_f32_e32 v9, v9
	s_mov_b64 vcc, s[4:5]
	v_rcp_f32_e32 v8, v8
	s_mov_b64 vcc, s[6:7]
	v_pk_mul_f32 v[4:5], v[4:5], v[8:9]
	v_rcp_f32_e32 v9, v11
	v_rcp_f32_e32 v8, v10
	s_nop 0
	v_pk_mul_f32 v[6:7], v[6:7], v[8:9]
	s_waitcnt vmcnt(0)
	v_pk_mul_f32 v[4:5], v[16:17], v[4:5]
	v_pk_mul_f32 v[6:7], v[18:19], v[6:7]
	v_cvt_pk_bf16_f32 v4, v4, v5
	v_cvt_pk_bf16_f32 v5, v6, v7
	global_store_dwordx2 v[2:3], v[4:5], off
	s_andn2_b64 exec, exec, s[24:25]
	s_cbranch_execz .LBB0_1037

;   DI unsigned rowoff(int r, int sch) const { const int g = r & 3, bc = r >> 2, b = bc / NCMP, c = bc - b * NCMP; return (unsigned)(b * Sn + c * 16) * 512u + g * 64 + sch; }
; template <int NI, class XL, class EP>
; DI void gemm_tile(const u16* __restrict__ W, int ldw, int f0, int t0, int K, XL xl, EP ep, unsigned char* smem) {
;     ...
;   f32x4 acc[4][NI];
; #pragma unroll
;   for (int i = 0; i < 4; ++i)
; #pragma unroll
;     for (int j = 0; j < NI; ++j) acc[i][j] = (f32x4){0.f, 0.f, 0.f, 0.f};
;   u32x4 wr[2], xr[XR];
;   const unsigned wbyte = ((unsigned)(f0 + srow * 2) * 32u + sch) * 2u;
;   const unsigned xbyte = xl.rowoff(t0 + srow * XR, sch) * 2u;
;   const int xrs = xl.rstride();
;   const int nk = K >> 5;
;   auto gload = [&](int it) {
;     const int k = it * 32;
;     const char* wb = (const char*)(W + (size_t)(k >> 5) * ldw * 32);
;     const char* xb = (const char*)xl.kbase(k);
; #pragma unroll
;     for (int i = 0; i < 2; ++i) wr[i] = *(const u32x4*)(wb + wbyte + i * 64);
; #pragma unroll
;     for (int i = 0; i < XR; ++i) xr[i] = *(const u32x4*)(xb + xbyte + i * xrs);
;   };
;   auto lstore = [&](int buf) {
;     u16* Ws = S0 + buf * BUF; u16* Xs = Ws + 128 * LST;
; #pragma unroll
;     for (int i = 0; i < 2; ++i) *(u32x4*)(Ws + (srow * 2 + i) * LST + sch) = wr[i];
; #pragma unroll
;     for (int i = 0; i < XR; ++i) *(u32x4*)(Xs + (srow * XR + i) * LST + sch) = xr[i];
;   };
;   gload(0);
;   __syncthreads();
;   lstore(0);
;   __syncthreads();
;   if (nk > 1) gload(1);
.LBB0_1094:
	v_mov_b32_e32 v46, v218
	s_and_b32 s30, s28, 7
	v_ashrrev_i32_e32 v47, 2, v46
	v_lshlrev_b32_e32 v0, 3, v46
	v_lshlrev_b32_e32 v49, 6, v47
	s_ashr_i32 s34, s28, 3
	v_and_b32_e32 v48, 24, v0
	v_lshl_add_u32 v0, s30, 12, v49
	s_add_i32 s31, s34, s26
	v_or_b32_e32 v0, v0, v48
	s_lshl_b32 s29, s31, 8
	v_lshlrev_b32_e32 v50, 1, v0
	v_and_b32_e32 v0, 0x3fffffc, v46
	v_add_u32_e32 v0, s29, v0
	v_lshlrev_b32_e32 v161, 1, v48
	v_lshl_or_b32 v51, v0, 6, v161
	global_load_dwordx4 v[16:19], v50, s[4:5]
	global_load_dwordx4 v[20:23], v50, s[4:5] offset:64
	global_load_dwordx4 v[24:27], v51, s[8:9]
	global_load_dwordx4 v[28:31], v51, s[8:9] offset:64
	global_load_dwordx4 v[32:35], v51, s[8:9] offset:128
	global_load_dwordx4 v[36:39], v51, s[8:9] offset:192
	v_mul_lo_u32 v166, v47, s20
	v_or_b32_e32 v162, v166, v161
	v_add_u32_e32 v163, v162, v166
	s_barrier
	v_bfe_u32 v158, v46, 4, 2
	v_and_b32_e32 v52, 15, v46
	v_ashrrev_i32_e32 v53, 1, v46
	v_lshlrev_b32_e32 v54, 1, v46
	v_lshlrev_b32_e32 v46, 6, v46
	s_and_b32 s35, s27, 7
	s_add_i32 s34, s18, s34
	v_and_b32_e32 v46, 0xffffff00, v46
	v_and_b32_e32 v160, 0xffffffc0, v53
	v_lshl_add_u32 v46, s34, 14, v46
	v_lshl_add_u32 v49, s35, 12, v49
	v_mov_b32_e32 v0, 0
	v_and_or_b32 v159, v54, s21, v52
	v_or_b32_e32 v47, v160, v52
	v_or_b32_e32 v152, v46, v161
	v_or_b32_e32 v46, v49, v48
	s_mov_b32 s33, 1
	v_mov_b32_e32 v155, v153
	v_mov_b32_e32 v1, v0
	v_mov_b32_e32 v2, v0
	v_mov_b32_e32 v3, v0
	v_mov_b32_e32 v4, v0
	v_mov_b32_e32 v5, v0
	v_mov_b32_e32 v6, v0
	v_mov_b32_e32 v7, v0
	v_mov_b32_e32 v8, v0
	v_mov_b32_e32 v9, v0
	v_mov_b32_e32 v10, v0
	v_mov_b32_e32 v11, v0
	v_mov_b32_e32 v12, v0
	v_mov_b32_e32 v13, v0
	v_mov_b32_e32 v14, v0
	v_mov_b32_e32 v15, v0
	v_mov_b32_e32 v40, v0
	v_mov_b32_e32 v41, v0
	v_mov_b32_e32 v42, v0
	v_mov_b32_e32 v43, v0
	v_mov_b32_e32 v44, v0
	v_mov_b32_e32 v45, v0
	v_lshlrev_b32_e32 v164, 4, v158
	v_mul_u32_u24_e32 v165, 48, v159
	v_mul_lo_u32 v167, v47, 48
	v_lshlrev_b32_e32 v154, 1, v46
	v_mov_b64_e32 v[156:157], v[152:153]
	v_mov_b32_e32 v46, v0
	v_mov_b32_e32 v47, v0
	v_mov_b32_e32 v68, v0
	v_mov_b32_e32 v69, v0
	v_mov_b32_e32 v70, v0
	v_mov_b32_e32 v71, v0
	v_mov_b32_e32 v80, v0
	v_mov_b32_e32 v81, v0
	v_mov_b32_e32 v82, v0
	v_mov_b32_e32 v83, v0
	v_mov_b32_e32 v48, v0
	v_mov_b32_e32 v49, v0
	v_mov_b32_e32 v52, v0
	v_mov_b32_e32 v53, v0
	v_mov_b32_e32 v54, v0
	v_mov_b32_e32 v55, v0
	v_mov_b32_e32 v56, v0
	v_mov_b32_e32 v57, v0
	v_mov_b32_e32 v58, v0
	s_waitcnt vmcnt(5)
	ds_write_b128 v162, v[16:19]
	s_waitcnt vmcnt(4)
	ds_write_b128 v162, v[20:23] offset:96
	s_waitcnt vmcnt(3)
	ds_write_b128 v163, v[24:27] offset:12288
	s_waitcnt vmcnt(2)
	ds_write_b128 v163, v[28:31] offset:12384
	s_waitcnt vmcnt(1)
	ds_write_b128 v163, v[32:35] offset:12480
	s_waitcnt vmcnt(0)
	ds_write_b128 v163, v[36:39] offset:12576
	s_waitcnt lgkmcnt(0)
	s_barrier
	global_load_dwordx4 v[20:23], v50, s[10:11]
	global_load_dwordx4 v[16:19], v50, s[10:11] offset:64
	global_load_dwordx4 v[36:39], v51, s[6:7]
	global_load_dwordx4 v[32:35], v51, s[6:7] offset:64
	global_load_dwordx4 v[28:31], v51, s[6:7] offset:128
	global_load_dwordx4 v[24:27], v51, s[6:7] offset:192
	s_add_u32 s98, s42, s22
	s_addc_u32 s99, s43, 0
	s_add_u32 s100, s42, s23
	s_addc_u32 s101, s43, 0
	global_load_dwordx4 v[200:203], v154, s[98:99]
	global_load_dwordx4 v[204:207], v154, s[98:99] offset:64
	global_load_dwordx4 v[208:211], v156, s[100:101] offset:2048
	global_load_dwordx4 v[212:215], v156, s[100:101] offset:2112
	global_load_dwordx4 v[220:223], v156, s[100:101] offset:2176
	global_load_dwordx4 v[224:227], v156, s[100:101] offset:2240
	s_add_u32 s98, s98, s16
	s_addc_u32 s99, s99, s17
	s_add_u32 s100, s100, s14
	s_addc_u32 s101, s101, s15
	v_mov_b32_e32 v50, v0
	v_mov_b32_e32 v51, v0
	v_mov_b32_e32 v59, v0
	v_mov_b32_e32 v64, v0
	v_mov_b32_e32 v65, v0
	v_mov_b32_e32 v66, v0
	v_mov_b32_e32 v67, v0
	v_mov_b32_e32 v76, v0
	v_mov_b32_e32 v77, v0
	v_mov_b32_e32 v78, v0
	v_mov_b32_e32 v79, v0
	v_mov_b32_e32 v88, v0
	v_mov_b32_e32 v89, v0
	v_mov_b32_e32 v90, v0
	v_mov_b32_e32 v91, v0
	v_mov_b32_e32 v100, v0
	v_mov_b32_e32 v101, v0
	v_mov_b32_e32 v102, v0
	v_mov_b32_e32 v103, v0
	v_mov_b32_e32 v112, v0
	v_mov_b32_e32 v113, v0
	v_mov_b32_e32 v114, v0
	v_mov_b32_e32 v115, v0
	v_mov_b32_e32 v60, v0
	v_mov_b32_e32 v61, v0
	v_mov_b32_e32 v62, v0
	v_mov_b32_e32 v63, v0
	v_mov_b32_e32 v72, v0
	v_mov_b32_e32 v73, v0
	v_mov_b32_e32 v74, v0
	v_mov_b32_e32 v75, v0
	v_mov_b32_e32 v84, v0
	v_mov_b32_e32 v85, v0
	v_mov_b32_e32 v86, v0
	v_mov_b32_e32 v87, v0
	v_mov_b32_e32 v96, v0
	v_mov_b32_e32 v97, v0
	v_mov_b32_e32 v98, v0
	v_mov_b32_e32 v99, v0
	v_mov_b32_e32 v108, v0
	v_mov_b32_e32 v109, v0
	v_mov_b32_e32 v110, v0
	v_mov_b32_e32 v111, v0
	v_mov_b32_e32 v120, v0
	v_mov_b32_e32 v121, v0
	v_mov_b32_e32 v122, v0
	v_mov_b32_e32 v123, v0
	v_mov_b32_e32 v128, v0
	v_mov_b32_e32 v129, v0
	v_mov_b32_e32 v130, v0
	v_mov_b32_e32 v131, v0
	v_mov_b32_e32 v136, v0
	v_mov_b32_e32 v137, v0
	v_mov_b32_e32 v138, v0
	v_mov_b32_e32 v139, v0
	v_mov_b32_e32 v92, v0
	v_mov_b32_e32 v93, v0
	v_mov_b32_e32 v94, v0
	v_mov_b32_e32 v95, v0
	v_mov_b32_e32 v104, v0
	v_mov_b32_e32 v105, v0
	v_mov_b32_e32 v106, v0
	v_mov_b32_e32 v107, v0
	v_mov_b32_e32 v116, v0
	v_mov_b32_e32 v117, v0
	v_mov_b32_e32 v118, v0
	v_mov_b32_e32 v119, v0
	v_mov_b32_e32 v124, v0
	v_mov_b32_e32 v125, v0
	v_mov_b32_e32 v126, v0
	v_mov_b32_e32 v127, v0
	v_mov_b32_e32 v132, v0
	v_mov_b32_e32 v133, v0
	v_mov_b32_e32 v134, v0
	v_mov_b32_e32 v135, v0
	v_mov_b32_e32 v140, v0
	v_mov_b32_e32 v141, v0
	v_mov_b32_e32 v142, v0
	v_mov_b32_e32 v143, v0
	v_mov_b32_e32 v144, v0
	v_mov_b32_e32 v145, v0
	v_mov_b32_e32 v146, v0
	v_mov_b32_e32 v147, v0
	v_mov_b32_e32 v148, v0
	v_mov_b32_e32 v149, v0
	v_mov_b32_e32 v150, v0
	v_mov_b32_e32 v151, v0
; DI f32x4 mfma16(bf16x8 a, bf16x8 b, f32x4 c) { return __builtin_amdgcn_mfma_f32_16x16x32_bf16(a, b, c, 0, 0, 0); }
; template <int NI, class XL, class EP>
; DI void gemm_tile(const u16* __restrict__ W, int ldw, int f0, int t0, int K, XL xl, EP ep, unsigned char* smem) {
;     ...
;   for (int it = 0; it < nk; ++it) {
;     const u16* Ws = S0 + (it & 1) * BUF; const u16* Xs = Ws + 128 * LST;
;     __builtin_amdgcn_s_setprio(1);
;     bf16x8 a[4];
; #pragma unroll
;     for (int mi = 0; mi < 4; ++mi) a[mi] = *(const bf16x8*)(Ws + (wf * 64 + mi * 16 + lr) * LST + lq * 8);
; #pragma unroll
;     for (int ni = 0; ni < NI; ++ni) {
;       const bf16x8 b = *(const bf16x8*)(Xs + (wt * (NI * 16) + ni * 16 + lr) * LST + lq * 8);
; #pragma unroll
;       for (int mi = 0; mi < 4; ++mi) acc[mi][ni] = mfma16(a[mi], b, acc[mi][ni]);
;     }
;     __builtin_amdgcn_sched_group_barrier(0x100, 6, 0);
; #pragma unroll
;     for (int ni = 0; ni < NI; ++ni) { __builtin_amdgcn_sched_group_barrier(0x008, 4, 0); if (ni + 2 < NI) __builtin_amdgcn_sched_group_barrier(0x100, 1, 0); }
;     __builtin_amdgcn_s_setprio(0);
;     if (it + 1 < nk) lstore((it + 1) & 1);
;     if (it + 2 < nk) gload(it + 2);
;     __syncthreads();
.LBB0_1095:
	s_bitcmp1_b32 s33, 0
	s_cselect_b32 s34, 0, 0x9000
	s_setprio 1
	v_or_b32_e32 v152, s34, v164
	v_lshl_add_u32 v184, v167, 1, v152
	ds_read_b128 v[168:171], v184
	ds_read_b128 v[172:175], v184 offset:1536
	ds_read_b128 v[180:183], v184 offset:3072
	ds_read_b128 v[184:187], v184 offset:4608
	v_lshl_add_u32 v152, v165, 1, v152
	ds_read_b128 v[176:179], v152 offset:12288
	ds_read_b128 v[188:191], v152 offset:13824
	s_xor_b32 s34, s34, 0x9000
	v_add3_u32 v228, v166, s34, v161
	s_waitcnt lgkmcnt(1)
	v_mfma_f32_16x16x32_bf16 v[148:151], v[168:171], v[176:179], v[148:151]
	v_mfma_f32_16x16x32_bf16 v[136:139], v[172:175], v[176:179], v[136:139]
	v_mfma_f32_16x16x32_bf16 v[112:115], v[180:183], v[176:179], v[112:115]
	v_mfma_f32_16x16x32_bf16 v[80:83], v[184:187], v[176:179], v[80:83]
	ds_read_b128 v[176:179], v152 offset:15360
	s_waitcnt vmcnt(11)
	ds_write_b128 v228, v[20:23]
	s_waitcnt lgkmcnt(2)
	v_mfma_f32_16x16x32_bf16 v[144:147], v[168:171], v[188:191], v[144:147]
	v_mfma_f32_16x16x32_bf16 v[128:131], v[172:175], v[188:191], v[128:131]
	v_mfma_f32_16x16x32_bf16 v[100:103], v[180:183], v[188:191], v[100:103]
	v_mfma_f32_16x16x32_bf16 v[68:71], v[184:187], v[188:191], v[68:71]
	ds_read_b128 v[188:191], v152 offset:16896
	s_waitcnt vmcnt(10)
	ds_write_b128 v228, v[16:19] offset:96
	v_add_u32_e32 v228, v228, v166
	global_load_dwordx4 v[20:23], v154, s[98:99]
	global_load_dwordx4 v[16:19], v154, s[98:99] offset:64
	s_waitcnt lgkmcnt(3)
	v_mfma_f32_16x16x32_bf16 v[140:143], v[168:171], v[176:179], v[140:143]
	v_mfma_f32_16x16x32_bf16 v[120:123], v[172:175], v[176:179], v[120:123]
	v_mfma_f32_16x16x32_bf16 v[88:91], v[180:183], v[176:179], v[88:91]
	v_mfma_f32_16x16x32_bf16 v[44:47], v[184:187], v[176:179], v[44:47]
	ds_read_b128 v[176:179], v152 offset:18432
	s_waitcnt vmcnt(11)
	ds_write_b128 v228, v[36:39] offset:12288
	global_load_dwordx4 v[36:39], v156, s[100:101] offset:2048
	s_waitcnt lgkmcnt(3)
	v_mfma_f32_16x16x32_bf16 v[132:135], v[168:171], v[188:191], v[132:135]
	v_mfma_f32_16x16x32_bf16 v[108:111], v[172:175], v[188:191], v[108:111]
	v_mfma_f32_16x16x32_bf16 v[76:79], v[180:183], v[188:191], v[76:79]
	v_mfma_f32_16x16x32_bf16 v[40:43], v[184:187], v[188:191], v[40:43]
	ds_read_b128 v[188:191], v152 offset:19968
	s_waitcnt vmcnt(11)
	ds_write_b128 v228, v[32:35] offset:12384
	global_load_dwordx4 v[32:35], v156, s[100:101] offset:2112
	s_waitcnt lgkmcnt(3)
	v_mfma_f32_16x16x32_bf16 v[124:127], v[168:171], v[176:179], v[124:127]
	v_mfma_f32_16x16x32_bf16 v[96:99], v[172:175], v[176:179], v[96:99]
	v_mfma_f32_16x16x32_bf16 v[64:67], v[180:183], v[176:179], v[64:67]
	v_mfma_f32_16x16x32_bf16 v[12:15], v[184:187], v[176:179], v[12:15]
	ds_read_b128 v[176:179], v152 offset:21504
	s_waitcnt vmcnt(11)
	ds_write_b128 v228, v[28:31] offset:12480
	global_load_dwordx4 v[28:31], v156, s[100:101] offset:2176
	s_waitcnt lgkmcnt(3)
	v_mfma_f32_16x16x32_bf16 v[116:119], v[168:171], v[188:191], v[116:119]
	v_mfma_f32_16x16x32_bf16 v[84:87], v[172:175], v[188:191], v[84:87]
	v_mfma_f32_16x16x32_bf16 v[56:59], v[180:183], v[188:191], v[56:59]
	v_mfma_f32_16x16x32_bf16 v[8:11], v[184:187], v[188:191], v[8:11]
	ds_read_b128 v[188:191], v152 offset:23040
	s_waitcnt vmcnt(11)
	ds_write_b128 v228, v[24:27] offset:12576
	global_load_dwordx4 v[24:27], v156, s[100:101] offset:2240
	s_waitcnt lgkmcnt(3)
	v_mfma_f32_16x16x32_bf16 v[104:107], v[168:171], v[176:179], v[104:107]
	v_mfma_f32_16x16x32_bf16 v[72:75], v[172:175], v[176:179], v[72:75]
	v_mfma_f32_16x16x32_bf16 v[52:55], v[180:183], v[176:179], v[52:55]
	v_mfma_f32_16x16x32_bf16 v[4:7], v[184:187], v[176:179], v[4:7]
	s_add_u32 s98, s98, s16
	s_addc_u32 s99, s99, s17
	s_add_u32 s100, s100, s14
	s_addc_u32 s101, s101, s15
	s_add_i32 s33, s33, 1
	s_waitcnt lgkmcnt(1)
	v_mfma_f32_16x16x32_bf16 v[92:95], v[168:171], v[188:191], v[92:95]
	v_mfma_f32_16x16x32_bf16 v[60:63], v[172:175], v[188:191], v[60:63]
	v_mfma_f32_16x16x32_bf16 v[48:51], v[180:183], v[188:191], v[48:51]
	v_mfma_f32_16x16x32_bf16 v[0:3], v[184:187], v[188:191], v[0:3]
	s_setprio 0
	s_waitcnt lgkmcnt(0)
	s_barrier
	s_bitcmp1_b32 s33, 0
	s_cselect_b32 s34, 0, 0x9000
	s_setprio 1
	v_or_b32_e32 v152, s34, v164
	v_lshl_add_u32 v184, v167, 1, v152
	ds_read_b128 v[168:171], v184
	ds_read_b128 v[172:175], v184 offset:1536
	ds_read_b128 v[180:183], v184 offset:3072
	ds_read_b128 v[184:187], v184 offset:4608
	v_lshl_add_u32 v152, v165, 1, v152
	ds_read_b128 v[176:179], v152 offset:12288
	ds_read_b128 v[188:191], v152 offset:13824
	s_xor_b32 s34, s34, 0x9000
	v_add3_u32 v228, v166, s34, v161
	s_waitcnt lgkmcnt(1)
	v_mfma_f32_16x16x32_bf16 v[148:151], v[168:171], v[176:179], v[148:151]
	v_mfma_f32_16x16x32_bf16 v[136:139], v[172:175], v[176:179], v[136:139]
	v_mfma_f32_16x16x32_bf16 v[112:115], v[180:183], v[176:179], v[112:115]
	v_mfma_f32_16x16x32_bf16 v[80:83], v[184:187], v[176:179], v[80:83]
	ds_read_b128 v[176:179], v152 offset:15360
	s_waitcnt vmcnt(11)
	ds_write_b128 v228, v[200:203]
	s_waitcnt lgkmcnt(2)
	v_mfma_f32_16x16x32_bf16 v[144:147], v[168:171], v[188:191], v[144:147]
	v_mfma_f32_16x16x32_bf16 v[128:131], v[172:175], v[188:191], v[128:131]
	v_mfma_f32_16x16x32_bf16 v[100:103], v[180:183], v[188:191], v[100:103]
	v_mfma_f32_16x16x32_bf16 v[68:71], v[184:187], v[188:191], v[68:71]
	ds_read_b128 v[188:191], v152 offset:16896
	s_waitcnt vmcnt(10)
	ds_write_b128 v228, v[204:207] offset:96
	v_add_u32_e32 v228, v228, v166
	global_load_dwordx4 v[200:203], v154, s[98:99]
	global_load_dwordx4 v[204:207], v154, s[98:99] offset:64
	s_waitcnt lgkmcnt(3)
; DI f32x4 mfma16(bf16x8 a, bf16x8 b, f32x4 c) { return __builtin_amdgcn_mfma_f32_16x16x32_bf16(a, b, c, 0, 0, 0); }
; template <int NI, class XL, class EP>
; DI void gemm_tile(const u16* __restrict__ W, int ldw, int f0, int t0, int K, XL xl, EP ep, unsigned char* smem) {
;     ...
;   for (int it = 0; it < nk; ++it) {
;     const u16* Ws = S0 + (it & 1) * BUF; const u16* Xs = Ws + 128 * LST;
;     __builtin_amdgcn_s_setprio(1);
;     bf16x8 a[4];
; #pragma unroll
;     for (int mi = 0; mi < 4; ++mi) a[mi] = *(const bf16x8*)(Ws + (wf * 64 + mi * 16 + lr) * LST + lq * 8);
; #pragma unroll
;     for (int ni = 0; ni < NI; ++ni) {
;       const bf16x8 b = *(const bf16x8*)(Xs + (wt * (NI * 16) + ni * 16 + lr) * LST + lq * 8);
; #pragma unroll
;       for (int mi = 0; mi < 4; ++mi) acc[mi][ni] = mfma16(a[mi], b, acc[mi][ni]);
;     }
;     __builtin_amdgcn_sched_group_barrier(0x100, 6, 0);
; #pragma unroll
;     for (int ni = 0; ni < NI; ++ni) { __builtin_amdgcn_sched_group_barrier(0x008, 4, 0); if (ni + 2 < NI) __builtin_amdgcn_sched_group_barrier(0x100, 1, 0); }
;     __builtin_amdgcn_s_setprio(0);
;     if (it + 1 < nk) lstore((it + 1) & 1);
;     if (it + 2 < nk) gload(it + 2);
;     __syncthreads();
	v_mfma_f32_16x16x32_bf16 v[140:143], v[168:171], v[176:179], v[140:143]
	v_mfma_f32_16x16x32_bf16 v[120:123], v[172:175], v[176:179], v[120:123]
	v_mfma_f32_16x16x32_bf16 v[88:91], v[180:183], v[176:179], v[88:91]
	v_mfma_f32_16x16x32_bf16 v[44:47], v[184:187], v[176:179], v[44:47]
	ds_read_b128 v[176:179], v152 offset:18432
	s_waitcnt vmcnt(11)
	ds_write_b128 v228, v[208:211] offset:12288
	global_load_dwordx4 v[208:211], v156, s[100:101] offset:2048
	s_waitcnt lgkmcnt(3)
	v_mfma_f32_16x16x32_bf16 v[132:135], v[168:171], v[188:191], v[132:135]
	v_mfma_f32_16x16x32_bf16 v[108:111], v[172:175], v[188:191], v[108:111]
	v_mfma_f32_16x16x32_bf16 v[76:79], v[180:183], v[188:191], v[76:79]
	v_mfma_f32_16x16x32_bf16 v[40:43], v[184:187], v[188:191], v[40:43]
	ds_read_b128 v[188:191], v152 offset:19968
	s_waitcnt vmcnt(11)
	ds_write_b128 v228, v[212:215] offset:12384
	global_load_dwordx4 v[212:215], v156, s[100:101] offset:2112
	s_waitcnt lgkmcnt(3)
	v_mfma_f32_16x16x32_bf16 v[124:127], v[168:171], v[176:179], v[124:127]
	v_mfma_f32_16x16x32_bf16 v[96:99], v[172:175], v[176:179], v[96:99]
	v_mfma_f32_16x16x32_bf16 v[64:67], v[180:183], v[176:179], v[64:67]
	v_mfma_f32_16x16x32_bf16 v[12:15], v[184:187], v[176:179], v[12:15]
	ds_read_b128 v[176:179], v152 offset:21504
	s_waitcnt vmcnt(11)
	ds_write_b128 v228, v[220:223] offset:12480
	global_load_dwordx4 v[220:223], v156, s[100:101] offset:2176
	s_waitcnt lgkmcnt(3)
	v_mfma_f32_16x16x32_bf16 v[116:119], v[168:171], v[188:191], v[116:119]
	v_mfma_f32_16x16x32_bf16 v[84:87], v[172:175], v[188:191], v[84:87]
	v_mfma_f32_16x16x32_bf16 v[56:59], v[180:183], v[188:191], v[56:59]
	v_mfma_f32_16x16x32_bf16 v[8:11], v[184:187], v[188:191], v[8:11]
	ds_read_b128 v[188:191], v152 offset:23040
	s_waitcnt vmcnt(11)
	ds_write_b128 v228, v[224:227] offset:12576
	global_load_dwordx4 v[224:227], v156, s[100:101] offset:2240
	s_waitcnt lgkmcnt(3)
	v_mfma_f32_16x16x32_bf16 v[104:107], v[168:171], v[176:179], v[104:107]
	v_mfma_f32_16x16x32_bf16 v[72:75], v[172:175], v[176:179], v[72:75]
	v_mfma_f32_16x16x32_bf16 v[52:55], v[180:183], v[176:179], v[52:55]
	v_mfma_f32_16x16x32_bf16 v[4:7], v[184:187], v[176:179], v[4:7]
	s_add_u32 s98, s98, s16
	s_addc_u32 s99, s99, s17
	s_add_u32 s100, s100, s14
	s_addc_u32 s101, s101, s15
	s_add_i32 s33, s33, 1
	s_waitcnt lgkmcnt(1)
	v_mfma_f32_16x16x32_bf16 v[92:95], v[168:171], v[188:191], v[92:95]
	v_mfma_f32_16x16x32_bf16 v[60:63], v[172:175], v[188:191], v[60:63]
	v_mfma_f32_16x16x32_bf16 v[48:51], v[180:183], v[188:191], v[48:51]
	v_mfma_f32_16x16x32_bf16 v[0:3], v[184:187], v[188:191], v[0:3]
	s_setprio 0
	s_cmpk_lg_i32 s33, 85
	s_waitcnt lgkmcnt(0)
	s_barrier
	s_cbranch_scc1 .LBB0_1095
	s_bitcmp1_b32 s33, 0
	s_cselect_b32 s34, 0, 0x9000
	s_setprio 1
	v_or_b32_e32 v152, s34, v164
	v_lshl_add_u32 v184, v167, 1, v152
	ds_read_b128 v[168:171], v184
	ds_read_b128 v[172:175], v184 offset:1536
	ds_read_b128 v[180:183], v184 offset:3072
	ds_read_b128 v[184:187], v184 offset:4608
	v_lshl_add_u32 v152, v165, 1, v152
	ds_read_b128 v[176:179], v152 offset:12288
	ds_read_b128 v[188:191], v152 offset:13824
	s_xor_b32 s34, s34, 0x9000
	v_add3_u32 v228, v166, s34, v161
	s_waitcnt lgkmcnt(1)
	v_mfma_f32_16x16x32_bf16 v[148:151], v[168:171], v[176:179], v[148:151]
	v_mfma_f32_16x16x32_bf16 v[136:139], v[172:175], v[176:179], v[136:139]
	v_mfma_f32_16x16x32_bf16 v[112:115], v[180:183], v[176:179], v[112:115]
	v_mfma_f32_16x16x32_bf16 v[80:83], v[184:187], v[176:179], v[80:83]
	ds_read_b128 v[176:179], v152 offset:15360
	s_waitcnt vmcnt(11)
	ds_write_b128 v228, v[20:23]
	s_waitcnt lgkmcnt(2)
	v_mfma_f32_16x16x32_bf16 v[144:147], v[168:171], v[188:191], v[144:147]
	v_mfma_f32_16x16x32_bf16 v[128:131], v[172:175], v[188:191], v[128:131]
	v_mfma_f32_16x16x32_bf16 v[100:103], v[180:183], v[188:191], v[100:103]
	v_mfma_f32_16x16x32_bf16 v[68:71], v[184:187], v[188:191], v[68:71]
	ds_read_b128 v[188:191], v152 offset:16896
	s_waitcnt vmcnt(10)
	ds_write_b128 v228, v[16:19] offset:96
	v_add_u32_e32 v228, v228, v166
	global_load_dwordx4 v[20:23], v154, s[98:99]
	global_load_dwordx4 v[16:19], v154, s[98:99] offset:64
	s_waitcnt lgkmcnt(3)
	v_mfma_f32_16x16x32_bf16 v[140:143], v[168:171], v[176:179], v[140:143]
	v_mfma_f32_16x16x32_bf16 v[120:123], v[172:175], v[176:179], v[120:123]
	v_mfma_f32_16x16x32_bf16 v[88:91], v[180:183], v[176:179], v[88:91]
	v_mfma_f32_16x16x32_bf16 v[44:47], v[184:187], v[176:179], v[44:47]
	ds_read_b128 v[176:179], v152 offset:18432
	s_waitcnt vmcnt(11)
	ds_write_b128 v228, v[36:39] offset:12288
	global_load_dwordx4 v[36:39], v156, s[100:101] offset:2048
	s_waitcnt lgkmcnt(3)
	v_mfma_f32_16x16x32_bf16 v[132:135], v[168:171], v[188:191], v[132:135]
	v_mfma_f32_16x16x32_bf16 v[108:111], v[172:175], v[188:191], v[108:111]
	v_mfma_f32_16x16x32_bf16 v[76:79], v[180:183], v[188:191], v[76:79]
	v_mfma_f32_16x16x32_bf16 v[40:43], v[184:187], v[188:191], v[40:43]
	ds_read_b128 v[188:191], v152 offset:19968
	s_waitcnt vmcnt(11)
	ds_write_b128 v228, v[32:35] offset:12384
	global_load_dwordx4 v[32:35], v156, s[100:101] offset:2112
	s_waitcnt lgkmcnt(3)
	v_mfma_f32_16x16x32_bf16 v[124:127], v[168:171], v[176:179], v[124:127]
	v_mfma_f32_16x16x32_bf16 v[96:99], v[172:175], v[176:179], v[96:99]
	v_mfma_f32_16x16x32_bf16 v[64:67], v[180:183], v[176:179], v[64:67]
	v_mfma_f32_16x16x32_bf16 v[12:15], v[184:187], v[176:179], v[12:15]
	ds_read_b128 v[176:179], v152 offset:21504
	s_waitcnt vmcnt(11)
	ds_write_b128 v228, v[28:31] offset:12480
	global_load_dwordx4 v[28:31], v156, s[100:101] offset:2176
	s_waitcnt lgkmcnt(3)
	v_mfma_f32_16x16x32_bf16 v[116:119], v[168:171], v[188:191], v[116:119]
	v_mfma_f32_16x16x32_bf16 v[84:87], v[172:175], v[188:191], v[84:87]
	v_mfma_f32_16x16x32_bf16 v[56:59], v[180:183], v[188:191], v[56:59]
	v_mfma_f32_16x16x32_bf16 v[8:11], v[184:187], v[188:191], v[8:11]
	ds_read_b128 v[188:191], v152 offset:23040
	s_waitcnt vmcnt(11)
	ds_write_b128 v228, v[24:27] offset:12576
	global_load_dwordx4 v[24:27], v156, s[100:101] offset:2240
	s_waitcnt lgkmcnt(3)
	v_mfma_f32_16x16x32_bf16 v[104:107], v[168:171], v[176:179], v[104:107]
	v_mfma_f32_16x16x32_bf16 v[72:75], v[172:175], v[176:179], v[72:75]
	v_mfma_f32_16x16x32_bf16 v[52:55], v[180:183], v[176:179], v[52:55]
	v_mfma_f32_16x16x32_bf16 v[4:7], v[184:187], v[176:179], v[4:7]
	s_add_u32 s98, s98, s16
	s_addc_u32 s99, s99, s17
	s_add_u32 s100, s100, s14
	s_addc_u32 s101, s101, s15
	s_add_i32 s33, s33, 1
	s_waitcnt lgkmcnt(1)
	v_mfma_f32_16x16x32_bf16 v[92:95], v[168:171], v[188:191], v[92:95]
	v_mfma_f32_16x16x32_bf16 v[60:63], v[172:175], v[188:191], v[60:63]
	v_mfma_f32_16x16x32_bf16 v[48:51], v[180:183], v[188:191], v[48:51]
	v_mfma_f32_16x16x32_bf16 v[0:3], v[184:187], v[188:191], v[0:3]
	s_setprio 0
	s_waitcnt lgkmcnt(0)
	s_barrier
; DI f32x4 mfma16(bf16x8 a, bf16x8 b, f32x4 c) { return __builtin_amdgcn_mfma_f32_16x16x32_bf16(a, b, c, 0, 0, 0); }
; template <int NI, class XL, class EP>
; DI void gemm_tile(const u16* __restrict__ W, int ldw, int f0, int t0, int K, XL xl, EP ep, unsigned char* smem) {
;     ...
;   for (int it = 0; it < nk; ++it) {
;     const u16* Ws = S0 + (it & 1) * BUF; const u16* Xs = Ws + 128 * LST;
;     __builtin_amdgcn_s_setprio(1);
;     bf16x8 a[4];
; #pragma unroll
;     for (int mi = 0; mi < 4; ++mi) a[mi] = *(const bf16x8*)(Ws + (wf * 64 + mi * 16 + lr) * LST + lq * 8);
; #pragma unroll
;     for (int ni = 0; ni < NI; ++ni) {
;       const bf16x8 b = *(const bf16x8*)(Xs + (wt * (NI * 16) + ni * 16 + lr) * LST + lq * 8);
; #pragma unroll
;       for (int mi = 0; mi < 4; ++mi) acc[mi][ni] = mfma16(a[mi], b, acc[mi][ni]);
;     }
;     __builtin_amdgcn_sched_group_barrier(0x100, 6, 0);
; #pragma unroll
;     for (int ni = 0; ni < NI; ++ni) { __builtin_amdgcn_sched_group_barrier(0x008, 4, 0); if (ni + 2 < NI) __builtin_amdgcn_sched_group_barrier(0x100, 1, 0); }
;     __builtin_amdgcn_s_setprio(0);
;     if (it + 1 < nk) lstore((it + 1) & 1);
;     if (it + 2 < nk) gload(it + 2);
;     __syncthreads();
	s_bitcmp1_b32 s33, 0
	s_cselect_b32 s34, 0, 0x9000
	s_setprio 1
	v_or_b32_e32 v152, s34, v164
	v_lshl_add_u32 v184, v167, 1, v152
	ds_read_b128 v[168:171], v184
	ds_read_b128 v[172:175], v184 offset:1536
	ds_read_b128 v[180:183], v184 offset:3072
	ds_read_b128 v[184:187], v184 offset:4608
	v_lshl_add_u32 v152, v165, 1, v152
	ds_read_b128 v[176:179], v152 offset:12288
	ds_read_b128 v[188:191], v152 offset:13824
	s_xor_b32 s34, s34, 0x9000
	v_add3_u32 v228, v166, s34, v161
	s_waitcnt lgkmcnt(1)
	v_mfma_f32_16x16x32_bf16 v[148:151], v[168:171], v[176:179], v[148:151]
	v_mfma_f32_16x16x32_bf16 v[136:139], v[172:175], v[176:179], v[136:139]
	v_mfma_f32_16x16x32_bf16 v[112:115], v[180:183], v[176:179], v[112:115]
	v_mfma_f32_16x16x32_bf16 v[80:83], v[184:187], v[176:179], v[80:83]
	ds_read_b128 v[176:179], v152 offset:15360
	s_waitcnt vmcnt(11)
	ds_write_b128 v228, v[200:203]
	s_waitcnt lgkmcnt(2)
	v_mfma_f32_16x16x32_bf16 v[144:147], v[168:171], v[188:191], v[144:147]
	v_mfma_f32_16x16x32_bf16 v[128:131], v[172:175], v[188:191], v[128:131]
	v_mfma_f32_16x16x32_bf16 v[100:103], v[180:183], v[188:191], v[100:103]
	v_mfma_f32_16x16x32_bf16 v[68:71], v[184:187], v[188:191], v[68:71]
	ds_read_b128 v[188:191], v152 offset:16896
	s_waitcnt vmcnt(10)
	ds_write_b128 v228, v[204:207] offset:96
	v_add_u32_e32 v228, v228, v166
	s_waitcnt lgkmcnt(3)
	v_mfma_f32_16x16x32_bf16 v[140:143], v[168:171], v[176:179], v[140:143]
	v_mfma_f32_16x16x32_bf16 v[120:123], v[172:175], v[176:179], v[120:123]
	v_mfma_f32_16x16x32_bf16 v[88:91], v[180:183], v[176:179], v[88:91]
	v_mfma_f32_16x16x32_bf16 v[44:47], v[184:187], v[176:179], v[44:47]
	ds_read_b128 v[176:179], v152 offset:18432
	s_waitcnt vmcnt(9)
	ds_write_b128 v228, v[208:211] offset:12288
	s_waitcnt lgkmcnt(3)
	v_mfma_f32_16x16x32_bf16 v[132:135], v[168:171], v[188:191], v[132:135]
	v_mfma_f32_16x16x32_bf16 v[108:111], v[172:175], v[188:191], v[108:111]
	v_mfma_f32_16x16x32_bf16 v[76:79], v[180:183], v[188:191], v[76:79]
	v_mfma_f32_16x16x32_bf16 v[40:43], v[184:187], v[188:191], v[40:43]
	ds_read_b128 v[188:191], v152 offset:19968
	s_waitcnt vmcnt(8)
	ds_write_b128 v228, v[212:215] offset:12384
	s_waitcnt lgkmcnt(3)
	v_mfma_f32_16x16x32_bf16 v[124:127], v[168:171], v[176:179], v[124:127]
	v_mfma_f32_16x16x32_bf16 v[96:99], v[172:175], v[176:179], v[96:99]
	v_mfma_f32_16x16x32_bf16 v[64:67], v[180:183], v[176:179], v[64:67]
	v_mfma_f32_16x16x32_bf16 v[12:15], v[184:187], v[176:179], v[12:15]
	ds_read_b128 v[176:179], v152 offset:21504
	s_waitcnt vmcnt(7)
	ds_write_b128 v228, v[220:223] offset:12480
	s_waitcnt lgkmcnt(3)
	v_mfma_f32_16x16x32_bf16 v[116:119], v[168:171], v[188:191], v[116:119]
	v_mfma_f32_16x16x32_bf16 v[84:87], v[172:175], v[188:191], v[84:87]
	v_mfma_f32_16x16x32_bf16 v[56:59], v[180:183], v[188:191], v[56:59]
	v_mfma_f32_16x16x32_bf16 v[8:11], v[184:187], v[188:191], v[8:11]
	ds_read_b128 v[188:191], v152 offset:23040
	s_waitcnt vmcnt(6)
	ds_write_b128 v228, v[224:227] offset:12576
	s_waitcnt lgkmcnt(3)
	v_mfma_f32_16x16x32_bf16 v[104:107], v[168:171], v[176:179], v[104:107]
	v_mfma_f32_16x16x32_bf16 v[72:75], v[172:175], v[176:179], v[72:75]
	v_mfma_f32_16x16x32_bf16 v[52:55], v[180:183], v[176:179], v[52:55]
	v_mfma_f32_16x16x32_bf16 v[4:7], v[184:187], v[176:179], v[4:7]
	s_add_u32 s98, s98, s16
	s_addc_u32 s99, s99, s17
	s_add_u32 s100, s100, s14
	s_addc_u32 s101, s101, s15
	s_add_i32 s33, s33, 1
	s_waitcnt lgkmcnt(1)
	v_mfma_f32_16x16x32_bf16 v[92:95], v[168:171], v[188:191], v[92:95]
	v_mfma_f32_16x16x32_bf16 v[60:63], v[172:175], v[188:191], v[60:63]
	v_mfma_f32_16x16x32_bf16 v[48:51], v[180:183], v[188:191], v[48:51]
	v_mfma_f32_16x16x32_bf16 v[0:3], v[184:187], v[188:191], v[0:3]
	s_setprio 0
	s_waitcnt lgkmcnt(0)
	s_barrier
	s_setprio 1
	v_lshl_add_u32 v152, v167, 1, v164
	ds_read_b128 v[154:157], v152
	v_lshl_add_u32 v161, v165, 1, v164
	ds_read_b128 v[164:167], v152 offset:1536
	ds_read_b128 v[172:175], v152 offset:3072
	ds_read_b128 v[176:179], v152 offset:4608
	ds_read_b128 v[168:171], v161 offset:12288
	ds_read_b128 v[180:183], v161 offset:13824
	s_waitcnt lgkmcnt(1)
	v_mfma_f32_16x16x32_bf16 v[148:151], v[154:157], v[168:171], v[148:151]
	v_mfma_f32_16x16x32_bf16 v[136:139], v[164:167], v[168:171], v[136:139]
	v_mfma_f32_16x16x32_bf16 v[112:115], v[172:175], v[168:171], v[112:115]
	v_mfma_f32_16x16x32_bf16 v[80:83], v[176:179], v[168:171], v[80:83]
	ds_read_b128 v[168:171], v161 offset:15360
	s_waitcnt lgkmcnt(1)
	v_mfma_f32_16x16x32_bf16 v[144:147], v[154:157], v[180:183], v[144:147]
	v_mfma_f32_16x16x32_bf16 v[128:131], v[164:167], v[180:183], v[128:131]
	v_mfma_f32_16x16x32_bf16 v[100:103], v[172:175], v[180:183], v[100:103]
	v_mfma_f32_16x16x32_bf16 v[68:71], v[176:179], v[180:183], v[68:71]
	ds_read_b128 v[180:183], v161 offset:16896
	s_waitcnt lgkmcnt(1)
	v_mfma_f32_16x16x32_bf16 v[140:143], v[154:157], v[168:171], v[140:143]
	v_mfma_f32_16x16x32_bf16 v[120:123], v[164:167], v[168:171], v[120:123]
	v_mfma_f32_16x16x32_bf16 v[184:187], v[172:175], v[168:171], v[88:91]
	v_mfma_f32_16x16x32_bf16 v[44:47], v[176:179], v[168:171], v[44:47]
	s_nop 1
	ds_read_b128 v[88:91], v161 offset:18432
	s_waitcnt lgkmcnt(1)
	v_mfma_f32_16x16x32_bf16 v[132:135], v[154:157], v[180:183], v[132:135]
	v_mfma_f32_16x16x32_bf16 v[168:171], v[164:167], v[180:183], v[108:111]
	v_mfma_f32_16x16x32_bf16 v[188:191], v[172:175], v[180:183], v[76:79]
	v_mfma_f32_16x16x32_bf16 v[180:183], v[176:179], v[180:183], v[40:43]
	s_nop 2
	ds_read_b128 v[40:43], v161 offset:19968
	s_waitcnt lgkmcnt(1)
; DI f32x4 mfma16(bf16x8 a, bf16x8 b, f32x4 c) { return __builtin_amdgcn_mfma_f32_16x16x32_bf16(a, b, c, 0, 0, 0); }
; template <int NI, class XL, class EP>
; DI void gemm_tile(const u16* __restrict__ W, int ldw, int f0, int t0, int K, XL xl, EP ep, unsigned char* smem) {
;     ...
;   for (int it = 0; it < nk; ++it) {
;     const u16* Ws = S0 + (it & 1) * BUF; const u16* Xs = Ws + 128 * LST;
;     __builtin_amdgcn_s_setprio(1);
;     bf16x8 a[4];
; #pragma unroll
;     for (int mi = 0; mi < 4; ++mi) a[mi] = *(const bf16x8*)(Ws + (wf * 64 + mi * 16 + lr) * LST + lq * 8);
; #pragma unroll
;     for (int ni = 0; ni < NI; ++ni) {
;       const bf16x8 b = *(const bf16x8*)(Xs + (wt * (NI * 16) + ni * 16 + lr) * LST + lq * 8);
; #pragma unroll
;       for (int mi = 0; mi < 4; ++mi) acc[mi][ni] = mfma16(a[mi], b, acc[mi][ni]);
;     }
;     __builtin_amdgcn_sched_group_barrier(0x100, 6, 0);
; #pragma unroll
;     for (int ni = 0; ni < NI; ++ni) { __builtin_amdgcn_sched_group_barrier(0x008, 4, 0); if (ni + 2 < NI) __builtin_amdgcn_sched_group_barrier(0x100, 1, 0); }
;     __builtin_amdgcn_s_setprio(0);
;     if (it + 1 < nk) lstore((it + 1) & 1);
;     if (it + 2 < nk) gload(it + 2);
;     __syncthreads();
;   }
;   ep(acc, f0 + wf * 64, t0 + wt * (NI * 16), lr, lq, wf, wt);
; DI void phase9(const Params& p, const Sched& sched, unsigned char* smem) {
;     ...
;       const int b = tb >> 11;
;       __syncthreads();
; #pragma unroll
;       for (int mi = 0; mi < 4; ++mi) {
;         const int f = fb + mi * 16 + lq * 4; const float4 gm = *(const float4*)(mod + (size_t)b * 6144 + 5120 + f);
	v_mfma_f32_16x16x32_bf16 v[124:127], v[154:157], v[88:91], v[124:127]
	v_mfma_f32_16x16x32_bf16 v[192:195], v[164:167], v[88:91], v[96:99]
	v_mfma_f32_16x16x32_bf16 v[196:199], v[172:175], v[88:91], v[64:67]
	v_mfma_f32_16x16x32_bf16 v[200:203], v[176:179], v[88:91], v[12:15]
	s_nop 2
	ds_read_b128 v[12:15], v161 offset:21504
	s_waitcnt lgkmcnt(1)
	v_mfma_f32_16x16x32_bf16 v[116:119], v[154:157], v[40:43], v[116:119]
	v_mfma_f32_16x16x32_bf16 v[204:207], v[164:167], v[40:43], v[84:87]
	v_mfma_f32_16x16x32_bf16 v[56:59], v[172:175], v[40:43], v[56:59]
	v_mfma_f32_16x16x32_bf16 v[208:211], v[176:179], v[40:43], v[8:11]
	s_nop 2
	ds_read_b128 v[8:11], v161 offset:23040
	s_waitcnt lgkmcnt(1)
	v_mfma_f32_16x16x32_bf16 v[212:215], v[154:157], v[12:15], v[104:107]
	v_mfma_f32_16x16x32_bf16 v[72:75], v[164:167], v[12:15], v[72:75]
	v_mfma_f32_16x16x32_bf16 v[220:223], v[172:175], v[12:15], v[52:55]
	v_mfma_f32_16x16x32_bf16 v[224:227], v[176:179], v[12:15], v[4:7]
	s_waitcnt lgkmcnt(0)
	v_mfma_f32_16x16x32_bf16 v[154:157], v[154:157], v[8:11], v[92:95]
	v_mfma_f32_16x16x32_bf16 v[60:63], v[164:167], v[8:11], v[60:63]
	v_mfma_f32_16x16x32_bf16 v[164:167], v[172:175], v[8:11], v[48:51]
	v_mfma_f32_16x16x32_bf16 v[172:175], v[176:179], v[8:11], v[0:3]
	s_setprio 0
	s_waitcnt vmcnt(5)
	ds_write_b128 v162, v[20:23] offset:36864
	s_waitcnt vmcnt(4)
	ds_write_b128 v162, v[16:19] offset:36960
	s_waitcnt vmcnt(3)
	ds_write_b128 v163, v[36:39] offset:49152
	s_waitcnt vmcnt(2)
	ds_write_b128 v163, v[32:35] offset:49248
	s_waitcnt vmcnt(1)
	ds_write_b128 v163, v[28:31] offset:49344
	s_waitcnt vmcnt(0)
	ds_write_b128 v163, v[24:27] offset:49440
	s_waitcnt lgkmcnt(0)
	s_barrier
	s_lshl_b32 s30, s30, 7
	s_setprio 1
	ds_read_b128 v[28:31], v152 offset:36864
	ds_read_b128 v[176:179], v152 offset:38400
	ds_read_b128 v[228:231], v152 offset:39936
	ds_read_b128 v[232:235], v152 offset:41472
	ds_read_b128 v[0:3], v161 offset:49152
	ds_read_b128 v[4:7], v161 offset:50688
	s_waitcnt lgkmcnt(1)
	v_mfma_f32_16x16x32_bf16 v[88:91], v[28:31], v[0:3], v[148:151]
	v_mfma_f32_16x16x32_bf16 v[64:67], v[176:179], v[0:3], v[136:139]
	v_mfma_f32_16x16x32_bf16 v[32:35], v[228:231], v[0:3], v[112:115]
	v_mfma_f32_16x16x32_bf16 v[0:3], v[232:235], v[0:3], v[80:83]
	ds_read_b128 v[8:11], v161 offset:52224
	s_waitcnt lgkmcnt(1)
	v_mfma_f32_16x16x32_bf16 v[96:99], v[28:31], v[4:7], v[144:147]
	v_mfma_f32_16x16x32_bf16 v[76:79], v[176:179], v[4:7], v[128:131]
	v_mfma_f32_16x16x32_bf16 v[36:39], v[228:231], v[4:7], v[100:103]
	v_mfma_f32_16x16x32_bf16 v[4:7], v[232:235], v[4:7], v[68:71]
	ds_read_b128 v[12:15], v161 offset:53760
	s_waitcnt lgkmcnt(1)
	v_mfma_f32_16x16x32_bf16 v[104:107], v[28:31], v[8:11], v[140:143]
	v_mfma_f32_16x16x32_bf16 v[84:87], v[176:179], v[8:11], v[120:123]
	v_mfma_f32_16x16x32_bf16 v[40:43], v[228:231], v[8:11], v[184:187]
	v_mfma_f32_16x16x32_bf16 v[8:11], v[232:235], v[8:11], v[44:47]
	ds_read_b128 v[16:19], v161 offset:55296
	s_waitcnt lgkmcnt(1)
	v_mfma_f32_16x16x32_bf16 v[108:111], v[28:31], v[12:15], v[132:135]
	v_mfma_f32_16x16x32_bf16 v[92:95], v[176:179], v[12:15], v[168:171]
	v_mfma_f32_16x16x32_bf16 v[44:47], v[228:231], v[12:15], v[188:191]
	v_mfma_f32_16x16x32_bf16 v[12:15], v[232:235], v[12:15], v[180:183]
	ds_read_b128 v[20:23], v161 offset:56832
	s_waitcnt lgkmcnt(1)
	v_mfma_f32_16x16x32_bf16 v[112:115], v[28:31], v[16:19], v[124:127]
	v_mfma_f32_16x16x32_bf16 v[100:103], v[176:179], v[16:19], v[192:195]
	v_mfma_f32_16x16x32_bf16 v[48:51], v[228:231], v[16:19], v[196:199]
	v_mfma_f32_16x16x32_bf16 v[16:19], v[232:235], v[16:19], v[200:203]
	ds_read_b128 v[24:27], v161 offset:58368
	s_waitcnt lgkmcnt(1)
	v_mfma_f32_16x16x32_bf16 v[116:119], v[28:31], v[20:23], v[116:119]
	v_mfma_f32_16x16x32_bf16 v[68:71], v[176:179], v[20:23], v[204:207]
	v_mfma_f32_16x16x32_bf16 v[52:55], v[228:231], v[20:23], v[56:59]
	v_mfma_f32_16x16x32_bf16 v[20:23], v[232:235], v[20:23], v[208:211]
	ds_read_b128 v[128:131], v161 offset:59904
	s_waitcnt lgkmcnt(1)
	v_mfma_f32_16x16x32_bf16 v[120:123], v[28:31], v[24:27], v[212:215]
	v_mfma_f32_16x16x32_bf16 v[80:83], v[176:179], v[24:27], v[72:75]
	v_mfma_f32_16x16x32_bf16 v[56:59], v[228:231], v[24:27], v[220:223]
	v_mfma_f32_16x16x32_bf16 v[24:27], v[232:235], v[24:27], v[224:227]
	s_waitcnt lgkmcnt(0)
	v_mfma_f32_16x16x32_bf16 v[124:127], v[28:31], v[128:131], v[154:157]
	v_mfma_f32_16x16x32_bf16 v[72:75], v[176:179], v[128:131], v[60:63]
	v_mfma_f32_16x16x32_bf16 v[60:63], v[228:231], v[128:131], v[164:167]
	v_mfma_f32_16x16x32_bf16 v[28:31], v[232:235], v[128:131], v[172:175]
	s_setprio 0
	s_ashr_i32 s31, s31, 3
	v_add_u32_e32 v128, s30, v160
	s_mul_hi_i32 s33, s31, 0x6000
	s_mulk_i32 s31, 0x6000
	v_lshl_or_b32 v128, v158, 2, v128
	s_add_u32 s34, s72, s31
	s_addc_u32 s35, s73, s33
	v_ashrrev_i32_e32 v129, 31, v128
	v_lshl_add_u64 v[128:129], v[128:129], 2, s[34:35]
	v_add_co_u32_e32 v140, vcc, s24, v128
	v_mul_u32_u24_e32 v138, 0x88, v159
	s_nop 0
	v_addc_co_u32_e32 v141, vcc, 0, v129, vcc
	v_lshlrev_b32_e32 v136, 1, v160
	v_lshlrev_b32_e32 v137, 3, v158
	v_lshlrev_b32_e32 v138, 1, v138
	s_barrier
	s_barrier
; DI void store4(u16* dst, f32x4 v) { uint2 w; w.x = cvtpk(v[0], v[1]); w.y = cvtpk(v[2], v[3]); *(uint2*)dst = w; }
; DI void phase9(const Params& p, const Sched& sched, unsigned char* smem) {
;     ...
;       __syncthreads();
; #pragma unroll
;       for (int mi = 0; mi < 4; ++mi) {
;         const int f = fb + mi * 16 + lq * 4; const float4 gm = *(const float4*)(mod + (size_t)b * 6144 + 5120 + f);
; #pragma unroll
;         for (int ni = 0; ni < 8; ++ni) {
;           const f32x4 o = {gm.x * acc[mi][ni][0], gm.y * acc[mi][ni][1], gm.z * acc[mi][ni][2], gm.w * acc[mi][ni][3]};
;           store4(Ls + (wt * 128 + ni * 16 + lr) * EST + wf * 64 + mi * 16 + lq * 4, o);
;         }
;       }
;       __syncthreads();
	global_load_dwordx4 v[128:131], v[140:141], off
	global_load_dwordx4 v[132:135], v[140:141], off offset:64
	v_add3_u32 v144, v136, v137, v138
	global_load_dwordx4 v[136:139], v[140:141], off offset:128
	v_add_u32_e32 v145, 0x1000, v144
	global_load_dwordx4 v[140:143], v[140:141], off offset:192
	v_add_u32_e32 v146, 0x2000, v144
	v_add_u32_e32 v147, 0x3000, v144
	v_add_u32_e32 v148, 0x4000, v144
	s_add_i32 s28, s28, s78
	s_add_i32 s27, s27, s78
	s_cmp_gt_i32 s28, 63
	s_waitcnt vmcnt(3)
	v_pk_mul_f32 v[88:89], v[88:89], v[128:129]
	v_pk_mul_f32 v[90:91], v[90:91], v[130:131]
	v_pk_mul_f32 v[96:97], v[96:97], v[128:129]
	s_waitcnt vmcnt(1)
	v_pk_mul_f32 v[32:33], v[32:33], v[136:137]
	v_pk_mul_f32 v[34:35], v[34:35], v[138:139]
	s_waitcnt vmcnt(0)
	v_pk_mul_f32 v[0:1], v[0:1], v[140:141]
	v_pk_mul_f32 v[2:3], v[2:3], v[142:143]
	v_cvt_pk_bf16_f32 v32, v32, v33
	v_cvt_pk_bf16_f32 v33, v34, v35
	v_cvt_pk_bf16_f32 v0, v0, v1
	v_cvt_pk_bf16_f32 v1, v2, v3
	v_pk_mul_f32 v[34:35], v[36:37], v[136:137]
	v_pk_mul_f32 v[36:37], v[38:39], v[138:139]
	ds_write2_b64 v144, v[32:33], v[0:1] offset0:8 offset1:12
	v_pk_mul_f32 v[0:1], v[4:5], v[140:141]
	v_pk_mul_f32 v[2:3], v[6:7], v[142:143]
	v_cvt_pk_bf16_f32 v34, v34, v35
	v_cvt_pk_bf16_f32 v35, v36, v37
	v_cvt_pk_bf16_f32 v0, v0, v1
	v_cvt_pk_bf16_f32 v1, v2, v3
	v_pk_mul_f32 v[36:37], v[40:41], v[136:137]
	v_pk_mul_f32 v[38:39], v[42:43], v[138:139]
	ds_write2_b64 v145, v[34:35], v[0:1] offset0:40 offset1:44
	v_pk_mul_f32 v[0:1], v[8:9], v[140:141]
	v_pk_mul_f32 v[2:3], v[10:11], v[142:143]
	v_cvt_pk_bf16_f32 v36, v36, v37
	v_cvt_pk_bf16_f32 v37, v38, v39
	v_cvt_pk_bf16_f32 v0, v0, v1
	v_cvt_pk_bf16_f32 v1, v2, v3
	v_pk_mul_f32 v[38:39], v[44:45], v[136:137]
	v_pk_mul_f32 v[40:41], v[46:47], v[138:139]
	ds_write2_b64 v146, v[36:37], v[0:1] offset0:72 offset1:76
	v_pk_mul_f32 v[0:1], v[12:13], v[140:141]
	v_pk_mul_f32 v[2:3], v[14:15], v[142:143]
	v_cvt_pk_bf16_f32 v38, v38, v39
	v_cvt_pk_bf16_f32 v39, v40, v41
	v_cvt_pk_bf16_f32 v0, v0, v1
	v_cvt_pk_bf16_f32 v1, v2, v3
	v_pk_mul_f32 v[98:99], v[98:99], v[130:131]
	v_pk_mul_f32 v[64:65], v[64:65], v[132:133]
	v_pk_mul_f32 v[66:67], v[66:67], v[134:135]
	v_pk_mul_f32 v[76:77], v[76:77], v[132:133]
	v_pk_mul_f32 v[78:79], v[78:79], v[134:135]
	v_pk_mul_f32 v[40:41], v[48:49], v[136:137]
	v_pk_mul_f32 v[42:43], v[50:51], v[138:139]
	ds_write2_b64 v147, v[38:39], v[0:1] offset0:104 offset1:108
	v_pk_mul_f32 v[0:1], v[16:17], v[140:141]
	v_pk_mul_f32 v[2:3], v[18:19], v[142:143]
	v_cvt_pk_bf16_f32 v88, v88, v89
	v_cvt_pk_bf16_f32 v89, v90, v91
	v_cvt_pk_bf16_f32 v90, v96, v97
	v_cvt_pk_bf16_f32 v91, v98, v99
	v_cvt_pk_bf16_f32 v64, v64, v65
	v_cvt_pk_bf16_f32 v65, v66, v67
	v_cvt_pk_bf16_f32 v66, v76, v77
	v_cvt_pk_bf16_f32 v67, v78, v79
	v_cvt_pk_bf16_f32 v40, v40, v41
	v_cvt_pk_bf16_f32 v41, v42, v43
	v_cvt_pk_bf16_f32 v0, v0, v1
	v_cvt_pk_bf16_f32 v1, v2, v3
	v_pk_mul_f32 v[106:107], v[106:107], v[130:131]
	v_pk_mul_f32 v[116:117], v[116:117], v[128:129]
	v_pk_mul_f32 v[118:119], v[118:119], v[130:131]
	ds_write2_b64 v144, v[88:89], v[64:65] offset1:4
	ds_write2_b64 v145, v[90:91], v[66:67] offset0:32 offset1:36
	v_pk_mul_f32 v[64:65], v[68:69], v[132:133]
	v_pk_mul_f32 v[66:67], v[70:71], v[134:135]
	v_pk_mul_f32 v[42:43], v[52:53], v[136:137]
	v_pk_mul_f32 v[44:45], v[54:55], v[138:139]
	ds_write2_b64 v148, v[40:41], v[0:1] offset0:136 offset1:140
	v_pk_mul_f32 v[0:1], v[20:21], v[140:141]
	v_pk_mul_f32 v[2:3], v[22:23], v[142:143]
	v_cvt_pk_bf16_f32 v97, v106, v107
	v_cvt_pk_bf16_f32 v106, v116, v117
	v_cvt_pk_bf16_f32 v107, v118, v119
	v_cvt_pk_bf16_f32 v64, v64, v65
	v_cvt_pk_bf16_f32 v65, v66, v67
	v_add_u32_e32 v68, 0x5000, v144
	v_cvt_pk_bf16_f32 v42, v42, v43
	v_cvt_pk_bf16_f32 v43, v44, v45
	v_cvt_pk_bf16_f32 v0, v0, v1
	v_cvt_pk_bf16_f32 v1, v2, v3
	v_pk_mul_f32 v[108:109], v[108:109], v[128:129]
	v_pk_mul_f32 v[120:121], v[120:121], v[128:129]
	v_pk_mul_f32 v[122:123], v[122:123], v[130:131]
	ds_write2_b64 v68, v[106:107], v[64:65] offset0:160 offset1:164
	v_pk_mul_f32 v[64:65], v[80:81], v[132:133]
	v_pk_mul_f32 v[66:67], v[82:83], v[134:135]
	v_pk_mul_f32 v[44:45], v[56:57], v[136:137]
	v_pk_mul_f32 v[46:47], v[58:59], v[138:139]
	ds_write2_b64 v68, v[42:43], v[0:1] offset0:168 offset1:172
	v_pk_mul_f32 v[0:1], v[24:25], v[140:141]
	v_pk_mul_f32 v[2:3], v[26:27], v[142:143]
	v_cvt_pk_bf16_f32 v98, v108, v109
	v_cvt_pk_bf16_f32 v108, v120, v121
	v_cvt_pk_bf16_f32 v109, v122, v123
	v_cvt_pk_bf16_f32 v64, v64, v65
	v_cvt_pk_bf16_f32 v65, v66, v67
	v_add_u32_e32 v69, 0x6000, v144
	v_cvt_pk_bf16_f32 v44, v44, v45
	v_cvt_pk_bf16_f32 v45, v46, v47
	v_cvt_pk_bf16_f32 v0, v0, v1
	v_cvt_pk_bf16_f32 v1, v2, v3
	v_pk_mul_f32 v[104:105], v[104:105], v[128:129]
	v_pk_mul_f32 v[110:111], v[110:111], v[130:131]
	v_pk_mul_f32 v[112:113], v[112:113], v[128:129]
	v_pk_mul_f32 v[114:115], v[114:115], v[130:131]
	v_pk_mul_f32 v[124:125], v[124:125], v[128:129]
	v_pk_mul_f32 v[126:127], v[126:127], v[130:131]
	v_pk_mul_f32 v[84:85], v[84:85], v[132:133]
	v_pk_mul_f32 v[86:87], v[86:87], v[134:135]
	v_pk_mul_f32 v[92:93], v[92:93], v[132:133]
	v_pk_mul_f32 v[94:95], v[94:95], v[134:135]
	v_pk_mul_f32 v[100:101], v[100:101], v[132:133]
	v_pk_mul_f32 v[102:103], v[102:103], v[134:135]
	ds_write2_b64 v69, v[108:109], v[64:65] offset0:192 offset1:196
	v_pk_mul_f32 v[64:65], v[72:73], v[132:133]
	v_pk_mul_f32 v[66:67], v[74:75], v[134:135]
	v_pk_mul_f32 v[46:47], v[60:61], v[136:137]
	v_pk_mul_f32 v[48:49], v[62:63], v[138:139]
	ds_write2_b64 v69, v[44:45], v[0:1] offset0:200 offset1:204
	v_pk_mul_f32 v[0:1], v[28:29], v[140:141]
	v_pk_mul_f32 v[2:3], v[30:31], v[142:143]
	v_cvt_pk_bf16_f32 v96, v104, v105
	v_cvt_pk_bf16_f32 v99, v110, v111
	v_cvt_pk_bf16_f32 v104, v112, v113
	v_cvt_pk_bf16_f32 v105, v114, v115
	v_cvt_pk_bf16_f32 v110, v124, v125
	v_cvt_pk_bf16_f32 v111, v126, v127
	v_cvt_pk_bf16_f32 v76, v84, v85
	v_cvt_pk_bf16_f32 v77, v86, v87
	v_cvt_pk_bf16_f32 v78, v92, v93
	v_cvt_pk_bf16_f32 v79, v94, v95
	v_cvt_pk_bf16_f32 v84, v100, v101
	v_cvt_pk_bf16_f32 v85, v102, v103
	v_cvt_pk_bf16_f32 v64, v64, v65
	v_cvt_pk_bf16_f32 v65, v66, v67
	v_add_u32_e32 v66, 0x7000, v144
	v_cvt_pk_bf16_f32 v46, v46, v47
	v_cvt_pk_bf16_f32 v47, v48, v49
	v_cvt_pk_bf16_f32 v0, v0, v1
	v_cvt_pk_bf16_f32 v1, v2, v3
	v_mov_b32_e32 v2, v218
	ds_write2_b64 v146, v[96:97], v[76:77] offset0:64 offset1:68
	ds_write2_b64 v147, v[98:99], v[78:79] offset0:96 offset1:100
	ds_write2_b64 v148, v[104:105], v[84:85] offset0:128 offset1:132
	ds_write2_b64 v66, v[110:111], v[64:65] offset0:224 offset1:228
	ds_write2_b64 v66, v[46:47], v[0:1] offset0:232 offset1:236
	s_waitcnt lgkmcnt(0)
	s_barrier
; DI int tidx() { int t = __builtin_amdgcn_workitem_id_x(); asm volatile("" : "+v"(t)); return t; }
; DI unsigned cvtpk(float lo, float hi) { const f32x2_ v = {lo, hi}; return __builtin_bit_cast(unsigned, __builtin_convertvector(v, bf16x2_)); }
; DI float bflo(unsigned w) { return __uint_as_float(w << 16); }
; DI float bfhi(unsigned w) { return __uint_as_float(w & 0xffff0000u); }
; DI void phase9(const Params& p, const Sched& sched, unsigned char* smem) {
;     ...
;       const int tid = tidx();
; #pragma unroll
;       for (int i = 0; i < 16; ++i) {
;         const int c = tid + 256 * i, row = c >> 4, ch = (c & 15) * 8;
;         const size_t gi = (size_t)(tm * 256 + row) * 1024 + tn * 128 + ch;
;         const u32x4 sv = *(const u32x4*)(Ls + row * EST + ch), xv = *(const u32x4*)(x1b + gi);
;         u32x4 w;
;         w.x = cvtpk(bflo(xv.x) + bflo(sv.x), bfhi(xv.x) + bfhi(sv.x)); w.y = cvtpk(bflo(xv.y) + bflo(sv.y), bfhi(xv.y) + bfhi(sv.y));
;         w.z = cvtpk(bflo(xv.z) + bflo(sv.z), bfhi(xv.z) + bfhi(sv.z)); w.w = cvtpk(bflo(xv.w) + bflo(sv.w), bfhi(xv.w) + bfhi(sv.w));
;         *(u32x4*)(x2b + gi) = w;
;       }
	s_nop 0
	v_ashrrev_i32_e32 v3, 4, v2
	v_add_u32_e32 v4, s29, v3
	v_lshlrev_b32_e32 v0, 3, v2
	v_ashrrev_i32_e32 v5, 31, v4
	v_and_b32_e32 v1, 0x78, v0
	v_lshlrev_b64 v[4:5], 10, v[4:5]
	v_or3_b32 v4, v4, s30, v1
	v_lshlrev_b64 v[12:13], 1, v[4:5]
	v_lshl_add_u64 v[4:5], s[12:13], 0, v[12:13]
	global_load_dwordx4 v[4:7], v[4:5], off
	v_lshlrev_b32_e32 v0, 1, v1
	v_mad_u64_u32 v[8:9], s[34:35], v3, s25, v[0:1]
	ds_read_b128 v[8:11], v8
	v_add_u32_e32 v3, 0x100, v2
	v_ashrrev_i32_e32 v3, 4, v3
	s_waitcnt lgkmcnt(0)
	v_lshlrev_b32_e32 v16, 16, v8
	v_and_b32_e32 v17, 0xffff0000, v8
	v_lshlrev_b32_e32 v8, 16, v9
	v_and_b32_e32 v9, 0xffff0000, v9
	s_waitcnt vmcnt(0)
	v_lshlrev_b32_e32 v14, 16, v4
	v_and_b32_e32 v15, 0xffff0000, v4
	v_pk_add_f32 v[14:15], v[16:17], v[14:15]
	s_nop 0
	v_cvt_pk_bf16_f32 v4, v14, v15
	v_lshlrev_b32_e32 v14, 16, v5
	v_and_b32_e32 v15, 0xffff0000, v5
	v_pk_add_f32 v[8:9], v[8:9], v[14:15]
	v_lshlrev_b32_e32 v14, 16, v10
	v_cvt_pk_bf16_f32 v5, v8, v9
	v_lshlrev_b32_e32 v8, 16, v6
	v_and_b32_e32 v9, 0xffff0000, v6
	v_and_b32_e32 v15, 0xffff0000, v10
	v_pk_add_f32 v[8:9], v[14:15], v[8:9]
	v_lshlrev_b32_e32 v10, 16, v11
	v_cvt_pk_bf16_f32 v6, v8, v9
	v_lshlrev_b32_e32 v8, 16, v7
	v_and_b32_e32 v9, 0xffff0000, v7
	v_and_b32_e32 v11, 0xffff0000, v11
	v_pk_add_f32 v[8:9], v[10:11], v[8:9]
	s_nop 0
	v_cvt_pk_bf16_f32 v7, v8, v9
	v_lshl_add_u64 v[8:9], s[2:3], 0, v[12:13]
	global_store_dwordx4 v[8:9], v[4:7], off
	v_mad_u64_u32 v[8:9], s[34:35], v3, s25, v[0:1]
	s_nop 0
	v_add_u32_e32 v4, s29, v3
	v_ashrrev_i32_e32 v5, 31, v4
	v_lshlrev_b64 v[4:5], 10, v[4:5]
	v_or3_b32 v4, v4, s30, v1
	v_lshlrev_b64 v[12:13], 1, v[4:5]
	v_lshl_add_u64 v[4:5], s[12:13], 0, v[12:13]
	global_load_dwordx4 v[4:7], v[4:5], off
	ds_read_b128 v[8:11], v8
	v_add_u32_e32 v3, 0x200, v2
	v_ashrrev_i32_e32 v3, 4, v3
	v_lshl_add_u64 v[12:13], s[2:3], 0, v[12:13]
	s_waitcnt lgkmcnt(0)
	v_lshlrev_b32_e32 v14, 16, v8
	v_and_b32_e32 v15, 0xffff0000, v8
	v_lshlrev_b32_e32 v8, 16, v9
	v_and_b32_e32 v9, 0xffff0000, v9
	v_lshlrev_b32_e32 v16, 16, v10
	v_and_b32_e32 v17, 0xffff0000, v10
	v_lshlrev_b32_e32 v10, 16, v11
	v_and_b32_e32 v11, 0xffff0000, v11
	s_waitcnt vmcnt(0)
	v_lshlrev_b32_e32 v18, 16, v4
	v_and_b32_e32 v19, 0xffff0000, v4
	v_lshlrev_b32_e32 v4, 16, v5
	v_and_b32_e32 v5, 0xffff0000, v5
	v_lshlrev_b32_e32 v20, 16, v6
	v_and_b32_e32 v21, 0xffff0000, v6
	v_lshlrev_b32_e32 v6, 16, v7
	v_and_b32_e32 v7, 0xffff0000, v7
	v_pk_add_f32 v[14:15], v[14:15], v[18:19]
	v_pk_add_f32 v[8:9], v[8:9], v[4:5]
	v_pk_add_f32 v[16:17], v[16:17], v[20:21]
	v_pk_add_f32 v[10:11], v[10:11], v[6:7]
	v_cvt_pk_bf16_f32 v4, v14, v15
	v_cvt_pk_bf16_f32 v5, v8, v9
	v_cvt_pk_bf16_f32 v6, v16, v17
	v_cvt_pk_bf16_f32 v7, v10, v11
	global_store_dwordx4 v[12:13], v[4:7], off
	v_add_u32_e32 v8, 0x300, v2
	v_ashrrev_i32_e32 v26, 4, v8
	v_add_u32_e32 v4, s29, v3
	v_ashrrev_i32_e32 v5, 31, v4
	v_lshlrev_b64 v[4:5], 10, v[4:5]
	v_or3_b32 v4, v4, s30, v1
	v_lshlrev_b64 v[12:13], 1, v[4:5]
	v_lshl_add_u64 v[4:5], s[12:13], 0, v[12:13]
	global_load_dwordx4 v[4:7], v[4:5], off
	v_mad_u64_u32 v[8:9], s[34:35], v3, s25, v[0:1]
	ds_read_b128 v[8:11], v8
	v_add_u32_e32 v14, s29, v26
	v_ashrrev_i32_e32 v15, 31, v14
	v_lshlrev_b64 v[14:15], 10, v[14:15]
	v_or3_b32 v14, v14, s30, v1
	s_waitcnt lgkmcnt(0)
	v_lshlrev_b32_e32 v18, 16, v8
	v_and_b32_e32 v19, 0xffff0000, v8
	v_lshlrev_b32_e32 v8, 16, v9
	v_and_b32_e32 v9, 0xffff0000, v9
	v_lshlrev_b32_e32 v20, 16, v10
	v_and_b32_e32 v21, 0xffff0000, v10
	v_lshlrev_b32_e32 v10, 16, v11
	v_and_b32_e32 v11, 0xffff0000, v11
	v_lshlrev_b64 v[14:15], 1, v[14:15]
	v_lshl_add_u64 v[12:13], s[2:3], 0, v[12:13]
	v_lshl_add_u64 v[16:17], s[12:13], 0, v[14:15]
	v_add_u32_e32 v3, 0x400, v2
	v_ashrrev_i32_e32 v3, 4, v3
	v_lshl_add_u64 v[14:15], s[2:3], 0, v[14:15]
	s_waitcnt vmcnt(0)
	v_lshlrev_b32_e32 v22, 16, v4
	v_and_b32_e32 v23, 0xffff0000, v4
	v_lshlrev_b32_e32 v4, 16, v5
	v_and_b32_e32 v5, 0xffff0000, v5
	v_lshlrev_b32_e32 v24, 16, v6
	v_and_b32_e32 v25, 0xffff0000, v6
	v_lshlrev_b32_e32 v6, 16, v7
	v_and_b32_e32 v7, 0xffff0000, v7
	v_pk_add_f32 v[18:19], v[18:19], v[22:23]
	v_pk_add_f32 v[8:9], v[8:9], v[4:5]
	v_pk_add_f32 v[20:21], v[20:21], v[24:25]
	v_pk_add_f32 v[10:11], v[10:11], v[6:7]
	v_cvt_pk_bf16_f32 v4, v18, v19
	v_cvt_pk_bf16_f32 v5, v8, v9
	v_cvt_pk_bf16_f32 v6, v20, v21
	v_cvt_pk_bf16_f32 v7, v10, v11
	global_store_dwordx4 v[12:13], v[4:7], off
	global_load_dwordx4 v[4:7], v[16:17], off
	v_mad_u64_u32 v[8:9], s[34:35], v26, s25, v[0:1]
	ds_read_b128 v[8:11], v8
	v_add_u32_e32 v12, s29, v3
	v_ashrrev_i32_e32 v13, 31, v12
	v_lshlrev_b64 v[12:13], 10, v[12:13]
	v_or3_b32 v12, v12, s30, v1
	s_waitcnt lgkmcnt(0)
	v_lshlrev_b32_e32 v18, 16, v8
	v_and_b32_e32 v19, 0xffff0000, v8
	v_lshlrev_b32_e32 v8, 16, v9
	v_and_b32_e32 v9, 0xffff0000, v9
	v_lshlrev_b32_e32 v20, 16, v10
	v_and_b32_e32 v21, 0xffff0000, v10
	v_lshlrev_b32_e32 v10, 16, v11
	v_and_b32_e32 v11, 0xffff0000, v11
	v_lshlrev_b64 v[12:13], 1, v[12:13]
	v_lshl_add_u64 v[16:17], s[12:13], 0, v[12:13]
	v_lshl_add_u64 v[12:13], s[2:3], 0, v[12:13]
	s_waitcnt vmcnt(0)
	v_lshlrev_b32_e32 v22, 16, v4
	v_and_b32_e32 v23, 0xffff0000, v4
	v_lshlrev_b32_e32 v4, 16, v5
	v_and_b32_e32 v5, 0xffff0000, v5
	v_lshlrev_b32_e32 v24, 16, v6
	v_and_b32_e32 v25, 0xffff0000, v6
	v_lshlrev_b32_e32 v6, 16, v7
	v_and_b32_e32 v7, 0xffff0000, v7
	v_pk_add_f32 v[18:19], v[18:19], v[22:23]
	v_pk_add_f32 v[8:9], v[8:9], v[4:5]
	v_pk_add_f32 v[20:21], v[20:21], v[24:25]
	v_pk_add_f32 v[10:11], v[10:11], v[6:7]
	v_cvt_pk_bf16_f32 v4, v18, v19
	v_cvt_pk_bf16_f32 v5, v8, v9
	v_cvt_pk_bf16_f32 v6, v20, v21
	v_cvt_pk_bf16_f32 v7, v10, v11
	global_store_dwordx4 v[14:15], v[4:7], off
	global_load_dwordx4 v[4:7], v[16:17], off
	v_add_u32_e32 v8, 0x500, v2
	v_ashrrev_i32_e32 v26, 4, v8
	v_mad_u64_u32 v[8:9], s[34:35], v3, s25, v[0:1]
	ds_read_b128 v[8:11], v8
	v_add_u32_e32 v14, s29, v26
	v_ashrrev_i32_e32 v15, 31, v14
	v_lshlrev_b64 v[14:15], 10, v[14:15]
	v_or3_b32 v14, v14, s30, v1
	s_waitcnt lgkmcnt(0)
; DI int tidx() { int t = __builtin_amdgcn_workitem_id_x(); asm volatile("" : "+v"(t)); return t; }
; DI unsigned cvtpk(float lo, float hi) { const f32x2_ v = {lo, hi}; return __builtin_bit_cast(unsigned, __builtin_convertvector(v, bf16x2_)); }
; DI float bflo(unsigned w) { return __uint_as_float(w << 16); }
; DI float bfhi(unsigned w) { return __uint_as_float(w & 0xffff0000u); }
; DI void phase9(const Params& p, const Sched& sched, unsigned char* smem) {
;     ...
;       const int tid = tidx();
; #pragma unroll
;       for (int i = 0; i < 16; ++i) {
;         const int c = tid + 256 * i, row = c >> 4, ch = (c & 15) * 8;
;         const size_t gi = (size_t)(tm * 256 + row) * 1024 + tn * 128 + ch;
;         const u32x4 sv = *(const u32x4*)(Ls + row * EST + ch), xv = *(const u32x4*)(x1b + gi);
;         u32x4 w;
;         w.x = cvtpk(bflo(xv.x) + bflo(sv.x), bfhi(xv.x) + bfhi(sv.x)); w.y = cvtpk(bflo(xv.y) + bflo(sv.y), bfhi(xv.y) + bfhi(sv.y));
;         w.z = cvtpk(bflo(xv.z) + bflo(sv.z), bfhi(xv.z) + bfhi(sv.z)); w.w = cvtpk(bflo(xv.w) + bflo(sv.w), bfhi(xv.w) + bfhi(sv.w));
;         *(u32x4*)(x2b + gi) = w;
;       }
	v_lshlrev_b32_e32 v18, 16, v8
	v_and_b32_e32 v19, 0xffff0000, v8
	v_lshlrev_b32_e32 v8, 16, v9
	v_and_b32_e32 v9, 0xffff0000, v9
	v_lshlrev_b32_e32 v20, 16, v10
	v_and_b32_e32 v21, 0xffff0000, v10
	v_lshlrev_b32_e32 v10, 16, v11
	v_and_b32_e32 v11, 0xffff0000, v11
	v_lshlrev_b64 v[14:15], 1, v[14:15]
	v_lshl_add_u64 v[16:17], s[12:13], 0, v[14:15]
	v_add_u32_e32 v3, 0x600, v2
	v_ashrrev_i32_e32 v3, 4, v3
	v_lshl_add_u64 v[14:15], s[2:3], 0, v[14:15]
	s_waitcnt vmcnt(0)
	v_lshlrev_b32_e32 v22, 16, v4
	v_and_b32_e32 v23, 0xffff0000, v4
	v_lshlrev_b32_e32 v4, 16, v5
	v_and_b32_e32 v5, 0xffff0000, v5
	v_lshlrev_b32_e32 v24, 16, v6
	v_and_b32_e32 v25, 0xffff0000, v6
	v_lshlrev_b32_e32 v6, 16, v7
	v_and_b32_e32 v7, 0xffff0000, v7
	v_pk_add_f32 v[18:19], v[18:19], v[22:23]
	v_pk_add_f32 v[8:9], v[8:9], v[4:5]
	v_pk_add_f32 v[20:21], v[20:21], v[24:25]
	v_pk_add_f32 v[10:11], v[10:11], v[6:7]
	v_cvt_pk_bf16_f32 v4, v18, v19
	v_cvt_pk_bf16_f32 v5, v8, v9
	v_cvt_pk_bf16_f32 v6, v20, v21
	v_cvt_pk_bf16_f32 v7, v10, v11
	global_store_dwordx4 v[12:13], v[4:7], off
	global_load_dwordx4 v[4:7], v[16:17], off
	v_mad_u64_u32 v[8:9], s[34:35], v26, s25, v[0:1]
	ds_read_b128 v[8:11], v8
	v_add_u32_e32 v12, s29, v3
	v_ashrrev_i32_e32 v13, 31, v12
	v_lshlrev_b64 v[12:13], 10, v[12:13]
	v_or3_b32 v12, v12, s30, v1
	s_waitcnt lgkmcnt(0)
	v_lshlrev_b32_e32 v18, 16, v8
	v_and_b32_e32 v19, 0xffff0000, v8
	v_lshlrev_b32_e32 v8, 16, v9
	v_and_b32_e32 v9, 0xffff0000, v9
	v_lshlrev_b32_e32 v20, 16, v10
	v_and_b32_e32 v21, 0xffff0000, v10
	v_lshlrev_b32_e32 v10, 16, v11
	v_and_b32_e32 v11, 0xffff0000, v11
	v_lshlrev_b64 v[12:13], 1, v[12:13]
	v_lshl_add_u64 v[16:17], s[12:13], 0, v[12:13]
	v_lshl_add_u64 v[12:13], s[2:3], 0, v[12:13]
	s_waitcnt vmcnt(0)
	v_lshlrev_b32_e32 v22, 16, v4
	v_and_b32_e32 v23, 0xffff0000, v4
	v_lshlrev_b32_e32 v4, 16, v5
	v_and_b32_e32 v5, 0xffff0000, v5
	v_lshlrev_b32_e32 v24, 16, v6
	v_and_b32_e32 v25, 0xffff0000, v6
	v_lshlrev_b32_e32 v6, 16, v7
	v_and_b32_e32 v7, 0xffff0000, v7
	v_pk_add_f32 v[18:19], v[18:19], v[22:23]
	v_pk_add_f32 v[8:9], v[8:9], v[4:5]
	v_pk_add_f32 v[20:21], v[20:21], v[24:25]
	v_pk_add_f32 v[10:11], v[10:11], v[6:7]
	v_cvt_pk_bf16_f32 v4, v18, v19
	v_cvt_pk_bf16_f32 v5, v8, v9
	v_cvt_pk_bf16_f32 v6, v20, v21
	v_cvt_pk_bf16_f32 v7, v10, v11
	global_store_dwordx4 v[14:15], v[4:7], off
	global_load_dwordx4 v[4:7], v[16:17], off
	v_add_u32_e32 v8, 0x700, v2
	v_ashrrev_i32_e32 v26, 4, v8
	v_mad_u64_u32 v[8:9], s[34:35], v3, s25, v[0:1]
	ds_read_b128 v[8:11], v8
	v_add_u32_e32 v14, s29, v26
	v_ashrrev_i32_e32 v15, 31, v14
	v_lshlrev_b64 v[14:15], 10, v[14:15]
	v_or3_b32 v14, v14, s30, v1
	s_waitcnt lgkmcnt(0)
	v_lshlrev_b32_e32 v18, 16, v8
	v_and_b32_e32 v19, 0xffff0000, v8
	v_lshlrev_b32_e32 v8, 16, v9
	v_and_b32_e32 v9, 0xffff0000, v9
	v_lshlrev_b32_e32 v20, 16, v10
	v_and_b32_e32 v21, 0xffff0000, v10
	v_lshlrev_b32_e32 v10, 16, v11
	v_and_b32_e32 v11, 0xffff0000, v11
	v_lshlrev_b64 v[14:15], 1, v[14:15]
	v_lshl_add_u64 v[16:17], s[12:13], 0, v[14:15]
	v_add_u32_e32 v3, 0x800, v2
	v_ashrrev_i32_e32 v3, 4, v3
	v_lshl_add_u64 v[14:15], s[2:3], 0, v[14:15]
	s_waitcnt vmcnt(0)
	v_lshlrev_b32_e32 v22, 16, v4
	v_and_b32_e32 v23, 0xffff0000, v4
	v_lshlrev_b32_e32 v4, 16, v5
	v_and_b32_e32 v5, 0xffff0000, v5
	v_lshlrev_b32_e32 v24, 16, v6
	v_and_b32_e32 v25, 0xffff0000, v6
	v_lshlrev_b32_e32 v6, 16, v7
	v_and_b32_e32 v7, 0xffff0000, v7
	v_pk_add_f32 v[18:19], v[18:19], v[22:23]
	v_pk_add_f32 v[8:9], v[8:9], v[4:5]
	v_pk_add_f32 v[20:21], v[20:21], v[24:25]
	v_pk_add_f32 v[10:11], v[10:11], v[6:7]
	v_cvt_pk_bf16_f32 v4, v18, v19
	v_cvt_pk_bf16_f32 v5, v8, v9
	v_cvt_pk_bf16_f32 v6, v20, v21
	v_cvt_pk_bf16_f32 v7, v10, v11
	global_store_dwordx4 v[12:13], v[4:7], off
	global_load_dwordx4 v[4:7], v[16:17], off
	v_mad_u64_u32 v[8:9], s[34:35], v26, s25, v[0:1]
	ds_read_b128 v[8:11], v8
	v_add_u32_e32 v12, s29, v3
	v_ashrrev_i32_e32 v13, 31, v12
	v_lshlrev_b64 v[12:13], 10, v[12:13]
	v_or3_b32 v12, v12, s30, v1
	s_waitcnt lgkmcnt(0)
	v_lshlrev_b32_e32 v18, 16, v8
	v_and_b32_e32 v19, 0xffff0000, v8
	v_lshlrev_b32_e32 v8, 16, v9
	v_and_b32_e32 v9, 0xffff0000, v9
	v_lshlrev_b32_e32 v20, 16, v10
	v_and_b32_e32 v21, 0xffff0000, v10
	v_lshlrev_b32_e32 v10, 16, v11
	v_and_b32_e32 v11, 0xffff0000, v11
	v_lshlrev_b64 v[12:13], 1, v[12:13]
	v_lshl_add_u64 v[16:17], s[12:13], 0, v[12:13]
	v_lshl_add_u64 v[12:13], s[2:3], 0, v[12:13]
	s_waitcnt vmcnt(0)
	v_lshlrev_b32_e32 v22, 16, v4
	v_and_b32_e32 v23, 0xffff0000, v4
	v_lshlrev_b32_e32 v4, 16, v5
	v_and_b32_e32 v5, 0xffff0000, v5
	v_lshlrev_b32_e32 v24, 16, v6
	v_and_b32_e32 v25, 0xffff0000, v6
	v_lshlrev_b32_e32 v6, 16, v7
	v_and_b32_e32 v7, 0xffff0000, v7
	v_pk_add_f32 v[18:19], v[18:19], v[22:23]
	v_pk_add_f32 v[8:9], v[8:9], v[4:5]
	v_pk_add_f32 v[20:21], v[20:21], v[24:25]
	v_pk_add_f32 v[10:11], v[10:11], v[6:7]
	v_cvt_pk_bf16_f32 v4, v18, v19
	v_cvt_pk_bf16_f32 v5, v8, v9
	v_cvt_pk_bf16_f32 v6, v20, v21
	v_cvt_pk_bf16_f32 v7, v10, v11
	global_store_dwordx4 v[14:15], v[4:7], off
	global_load_dwordx4 v[4:7], v[16:17], off
	v_add_u32_e32 v8, 0x900, v2
	v_ashrrev_i32_e32 v26, 4, v8
	v_mad_u64_u32 v[8:9], s[34:35], v3, s25, v[0:1]
	ds_read_b128 v[8:11], v8
	v_add_u32_e32 v14, s29, v26
	v_ashrrev_i32_e32 v15, 31, v14
	v_lshlrev_b64 v[14:15], 10, v[14:15]
	v_or3_b32 v14, v14, s30, v1
	s_waitcnt lgkmcnt(0)
	v_lshlrev_b32_e32 v18, 16, v8
	v_and_b32_e32 v19, 0xffff0000, v8
	v_lshlrev_b32_e32 v8, 16, v9
	v_and_b32_e32 v9, 0xffff0000, v9
	v_lshlrev_b32_e32 v20, 16, v10
	v_and_b32_e32 v21, 0xffff0000, v10
	v_lshlrev_b32_e32 v10, 16, v11
	v_and_b32_e32 v11, 0xffff0000, v11
	v_lshlrev_b64 v[14:15], 1, v[14:15]
	v_lshl_add_u64 v[16:17], s[12:13], 0, v[14:15]
	v_add_u32_e32 v3, 0xa00, v2
	v_ashrrev_i32_e32 v3, 4, v3
	v_lshl_add_u64 v[14:15], s[2:3], 0, v[14:15]
	s_waitcnt vmcnt(0)
; DI int tidx() { int t = __builtin_amdgcn_workitem_id_x(); asm volatile("" : "+v"(t)); return t; }
; DI unsigned cvtpk(float lo, float hi) { const f32x2_ v = {lo, hi}; return __builtin_bit_cast(unsigned, __builtin_convertvector(v, bf16x2_)); }
; DI float bflo(unsigned w) { return __uint_as_float(w << 16); }
; DI float bfhi(unsigned w) { return __uint_as_float(w & 0xffff0000u); }
; DI void phase9(const Params& p, const Sched& sched, unsigned char* smem) {
;     ...
;       const int tid = tidx();
; #pragma unroll
;       for (int i = 0; i < 16; ++i) {
;         const int c = tid + 256 * i, row = c >> 4, ch = (c & 15) * 8;
;         const size_t gi = (size_t)(tm * 256 + row) * 1024 + tn * 128 + ch;
;         const u32x4 sv = *(const u32x4*)(Ls + row * EST + ch), xv = *(const u32x4*)(x1b + gi);
;         u32x4 w;
;         w.x = cvtpk(bflo(xv.x) + bflo(sv.x), bfhi(xv.x) + bfhi(sv.x)); w.y = cvtpk(bflo(xv.y) + bflo(sv.y), bfhi(xv.y) + bfhi(sv.y));
;         w.z = cvtpk(bflo(xv.z) + bflo(sv.z), bfhi(xv.z) + bfhi(sv.z)); w.w = cvtpk(bflo(xv.w) + bflo(sv.w), bfhi(xv.w) + bfhi(sv.w));
;         *(u32x4*)(x2b + gi) = w;
;       }
	v_lshlrev_b32_e32 v22, 16, v4
	v_and_b32_e32 v23, 0xffff0000, v4
	v_lshlrev_b32_e32 v4, 16, v5
	v_and_b32_e32 v5, 0xffff0000, v5
	v_lshlrev_b32_e32 v24, 16, v6
	v_and_b32_e32 v25, 0xffff0000, v6
	v_lshlrev_b32_e32 v6, 16, v7
	v_and_b32_e32 v7, 0xffff0000, v7
	v_pk_add_f32 v[18:19], v[18:19], v[22:23]
	v_pk_add_f32 v[8:9], v[8:9], v[4:5]
	v_pk_add_f32 v[20:21], v[20:21], v[24:25]
	v_pk_add_f32 v[10:11], v[10:11], v[6:7]
	v_cvt_pk_bf16_f32 v4, v18, v19
	v_cvt_pk_bf16_f32 v5, v8, v9
	v_cvt_pk_bf16_f32 v6, v20, v21
	v_cvt_pk_bf16_f32 v7, v10, v11
	global_store_dwordx4 v[12:13], v[4:7], off
	global_load_dwordx4 v[4:7], v[16:17], off
	v_mad_u64_u32 v[8:9], s[34:35], v26, s25, v[0:1]
	ds_read_b128 v[8:11], v8
	v_add_u32_e32 v12, s29, v3
	v_ashrrev_i32_e32 v13, 31, v12
	v_lshlrev_b64 v[12:13], 10, v[12:13]
	v_or3_b32 v12, v12, s30, v1
	s_waitcnt lgkmcnt(0)
	v_lshlrev_b32_e32 v18, 16, v8
	v_and_b32_e32 v19, 0xffff0000, v8
	v_lshlrev_b32_e32 v8, 16, v9
	v_and_b32_e32 v9, 0xffff0000, v9
	v_lshlrev_b32_e32 v20, 16, v10
	v_and_b32_e32 v21, 0xffff0000, v10
	v_lshlrev_b32_e32 v10, 16, v11
	v_and_b32_e32 v11, 0xffff0000, v11
	v_lshlrev_b64 v[12:13], 1, v[12:13]
	v_lshl_add_u64 v[16:17], s[12:13], 0, v[12:13]
	v_lshl_add_u64 v[12:13], s[2:3], 0, v[12:13]
	s_waitcnt vmcnt(0)
	v_lshlrev_b32_e32 v22, 16, v4
	v_and_b32_e32 v23, 0xffff0000, v4
	v_lshlrev_b32_e32 v4, 16, v5
	v_and_b32_e32 v5, 0xffff0000, v5
	v_lshlrev_b32_e32 v24, 16, v6
	v_and_b32_e32 v25, 0xffff0000, v6
	v_lshlrev_b32_e32 v6, 16, v7
	v_and_b32_e32 v7, 0xffff0000, v7
	v_pk_add_f32 v[18:19], v[18:19], v[22:23]
	v_pk_add_f32 v[8:9], v[8:9], v[4:5]
	v_pk_add_f32 v[20:21], v[20:21], v[24:25]
	v_pk_add_f32 v[10:11], v[10:11], v[6:7]
	v_cvt_pk_bf16_f32 v4, v18, v19
	v_cvt_pk_bf16_f32 v5, v8, v9
	v_cvt_pk_bf16_f32 v6, v20, v21
	v_cvt_pk_bf16_f32 v7, v10, v11
	global_store_dwordx4 v[14:15], v[4:7], off
	global_load_dwordx4 v[4:7], v[16:17], off
	v_add_u32_e32 v8, 0xb00, v2
	v_ashrrev_i32_e32 v26, 4, v8
	v_mad_u64_u32 v[8:9], s[34:35], v3, s25, v[0:1]
	ds_read_b128 v[8:11], v8
	v_add_u32_e32 v14, s29, v26
	v_ashrrev_i32_e32 v15, 31, v14
	v_lshlrev_b64 v[14:15], 10, v[14:15]
	v_or3_b32 v14, v14, s30, v1
	s_waitcnt lgkmcnt(0)
	v_lshlrev_b32_e32 v18, 16, v8
	v_and_b32_e32 v19, 0xffff0000, v8
	v_lshlrev_b32_e32 v8, 16, v9
	v_and_b32_e32 v9, 0xffff0000, v9
	v_lshlrev_b32_e32 v20, 16, v10
	v_and_b32_e32 v21, 0xffff0000, v10
	v_lshlrev_b32_e32 v10, 16, v11
	v_and_b32_e32 v11, 0xffff0000, v11
	v_lshlrev_b64 v[14:15], 1, v[14:15]
	v_lshl_add_u64 v[16:17], s[12:13], 0, v[14:15]
	v_add_u32_e32 v3, 0xc00, v2
	v_ashrrev_i32_e32 v3, 4, v3
	v_lshl_add_u64 v[14:15], s[2:3], 0, v[14:15]
	s_waitcnt vmcnt(0)
	v_lshlrev_b32_e32 v22, 16, v4
	v_and_b32_e32 v23, 0xffff0000, v4
	v_lshlrev_b32_e32 v4, 16, v5
	v_and_b32_e32 v5, 0xffff0000, v5
	v_lshlrev_b32_e32 v24, 16, v6
	v_and_b32_e32 v25, 0xffff0000, v6
	v_lshlrev_b32_e32 v6, 16, v7
	v_and_b32_e32 v7, 0xffff0000, v7
	v_pk_add_f32 v[18:19], v[18:19], v[22:23]
	v_pk_add_f32 v[8:9], v[8:9], v[4:5]
	v_pk_add_f32 v[20:21], v[20:21], v[24:25]
	v_pk_add_f32 v[10:11], v[10:11], v[6:7]
	v_cvt_pk_bf16_f32 v4, v18, v19
	v_cvt_pk_bf16_f32 v5, v8, v9
	v_cvt_pk_bf16_f32 v6, v20, v21
	v_cvt_pk_bf16_f32 v7, v10, v11
	global_store_dwordx4 v[12:13], v[4:7], off
	global_load_dwordx4 v[4:7], v[16:17], off
	v_mad_u64_u32 v[8:9], s[34:35], v26, s25, v[0:1]
	ds_read_b128 v[8:11], v8
	v_add_u32_e32 v12, s29, v3
	v_ashrrev_i32_e32 v13, 31, v12
	v_lshlrev_b64 v[12:13], 10, v[12:13]
	v_or3_b32 v12, v12, s30, v1
	s_waitcnt lgkmcnt(0)
	v_lshlrev_b32_e32 v18, 16, v8
	v_and_b32_e32 v19, 0xffff0000, v8
	v_lshlrev_b32_e32 v8, 16, v9
	v_and_b32_e32 v9, 0xffff0000, v9
	v_lshlrev_b32_e32 v20, 16, v10
	v_and_b32_e32 v21, 0xffff0000, v10
	v_lshlrev_b32_e32 v10, 16, v11
	v_and_b32_e32 v11, 0xffff0000, v11
	v_lshlrev_b64 v[12:13], 1, v[12:13]
	v_lshl_add_u64 v[16:17], s[12:13], 0, v[12:13]
	v_lshl_add_u64 v[12:13], s[2:3], 0, v[12:13]
	s_waitcnt vmcnt(0)
	v_lshlrev_b32_e32 v22, 16, v4
	v_and_b32_e32 v23, 0xffff0000, v4
	v_lshlrev_b32_e32 v4, 16, v5
	v_and_b32_e32 v5, 0xffff0000, v5
	v_lshlrev_b32_e32 v24, 16, v6
	v_and_b32_e32 v25, 0xffff0000, v6
	v_lshlrev_b32_e32 v6, 16, v7
	v_and_b32_e32 v7, 0xffff0000, v7
	v_pk_add_f32 v[18:19], v[18:19], v[22:23]
	v_pk_add_f32 v[8:9], v[8:9], v[4:5]
	v_pk_add_f32 v[20:21], v[20:21], v[24:25]
	v_pk_add_f32 v[10:11], v[10:11], v[6:7]
	v_cvt_pk_bf16_f32 v4, v18, v19
	v_cvt_pk_bf16_f32 v5, v8, v9
	v_cvt_pk_bf16_f32 v6, v20, v21
	v_cvt_pk_bf16_f32 v7, v10, v11
	global_store_dwordx4 v[14:15], v[4:7], off
	global_load_dwordx4 v[4:7], v[16:17], off
	v_add_u32_e32 v8, 0xd00, v2
	v_ashrrev_i32_e32 v26, 4, v8
	v_mad_u64_u32 v[8:9], s[34:35], v3, s25, v[0:1]
	ds_read_b128 v[8:11], v8
	v_add_u32_e32 v14, s29, v26
	v_ashrrev_i32_e32 v15, 31, v14
	v_lshlrev_b64 v[14:15], 10, v[14:15]
	v_or3_b32 v14, v14, s30, v1
	s_waitcnt lgkmcnt(0)
; DI int tidx() { int t = __builtin_amdgcn_workitem_id_x(); asm volatile("" : "+v"(t)); return t; }
; DI unsigned cvtpk(float lo, float hi) { const f32x2_ v = {lo, hi}; return __builtin_bit_cast(unsigned, __builtin_convertvector(v, bf16x2_)); }
; DI float bflo(unsigned w) { return __uint_as_float(w << 16); }
; DI float bfhi(unsigned w) { return __uint_as_float(w & 0xffff0000u); }
; template <class F> DI void for_tiles_st(int ntm, int ntn, const Sched& sc, F f) {
;   if ((ntn & 7) == 0) {
;     const int nsn = ntn >> 3, nsuper = (ntm >> 3) * nsn;
;     for (int sp = sc.xd; sp < nsuper; sp += sc.nx) {
;       const int sm = sp / nsn, sn = sp - sm * nsn;
;       for (int qq = sc.rank; qq < 64; qq += sc.nloc) f(sm * 8 + (qq >> 3), sn * 8 + (qq & 7));
;     }
;   } else {
;     const int nsn = ntn >> 2, nsuper = (ntm >> 4) * nsn;
;     for (int sp = sc.xd; sp < nsuper; sp += sc.nx) {
;       const int sm = sp / nsn, sn = sp - sm * nsn;
;       for (int qq = sc.rank; qq < 64; qq += sc.nloc) f(sm * 16 + (qq >> 2), sn * 4 + (qq & 3));
;     }
;   }
; DI void phase9(const Params& p, const Sched& sched, unsigned char* smem) {
;     ...
;       const int tid = tidx();
; #pragma unroll
;       for (int i = 0; i < 16; ++i) {
;         const int c = tid + 256 * i, row = c >> 4, ch = (c & 15) * 8;
;         const size_t gi = (size_t)(tm * 256 + row) * 1024 + tn * 128 + ch;
;         const u32x4 sv = *(const u32x4*)(Ls + row * EST + ch), xv = *(const u32x4*)(x1b + gi);
;         u32x4 w;
;         w.x = cvtpk(bflo(xv.x) + bflo(sv.x), bfhi(xv.x) + bfhi(sv.x)); w.y = cvtpk(bflo(xv.y) + bflo(sv.y), bfhi(xv.y) + bfhi(sv.y));
;         w.z = cvtpk(bflo(xv.z) + bflo(sv.z), bfhi(xv.z) + bfhi(sv.z)); w.w = cvtpk(bflo(xv.w) + bflo(sv.w), bfhi(xv.w) + bfhi(sv.w));
;         *(u32x4*)(x2b + gi) = w;
;       }
;     }, smem);
;   });
	v_lshlrev_b32_e32 v18, 16, v8
	v_and_b32_e32 v19, 0xffff0000, v8
	v_lshlrev_b32_e32 v8, 16, v9
	v_and_b32_e32 v9, 0xffff0000, v9
	v_lshlrev_b32_e32 v20, 16, v10
	v_and_b32_e32 v21, 0xffff0000, v10
	v_lshlrev_b32_e32 v10, 16, v11
	v_and_b32_e32 v11, 0xffff0000, v11
	v_lshlrev_b64 v[14:15], 1, v[14:15]
	v_lshl_add_u64 v[16:17], s[12:13], 0, v[14:15]
	v_add_u32_e32 v3, 0xe00, v2
	v_ashrrev_i32_e32 v3, 4, v3
	v_lshl_add_u64 v[14:15], s[2:3], 0, v[14:15]
	v_add_u32_e32 v2, 0xf00, v2
	s_waitcnt vmcnt(0)
	v_lshlrev_b32_e32 v22, 16, v4
	v_and_b32_e32 v23, 0xffff0000, v4
	v_lshlrev_b32_e32 v4, 16, v5
	v_and_b32_e32 v5, 0xffff0000, v5
	v_lshlrev_b32_e32 v24, 16, v6
	v_and_b32_e32 v25, 0xffff0000, v6
	v_lshlrev_b32_e32 v6, 16, v7
	v_and_b32_e32 v7, 0xffff0000, v7
	v_pk_add_f32 v[18:19], v[18:19], v[22:23]
	v_pk_add_f32 v[8:9], v[8:9], v[4:5]
	v_pk_add_f32 v[20:21], v[20:21], v[24:25]
	v_pk_add_f32 v[10:11], v[10:11], v[6:7]
	v_cvt_pk_bf16_f32 v4, v18, v19
	v_cvt_pk_bf16_f32 v5, v8, v9
	v_cvt_pk_bf16_f32 v6, v20, v21
	v_cvt_pk_bf16_f32 v7, v10, v11
	global_store_dwordx4 v[12:13], v[4:7], off
	global_load_dwordx4 v[4:7], v[16:17], off
	v_mad_u64_u32 v[8:9], s[34:35], v26, s25, v[0:1]
	ds_read_b128 v[8:11], v8
	v_add_u32_e32 v12, s29, v3
	v_ashrrev_i32_e32 v13, 31, v12
	v_lshlrev_b64 v[12:13], 10, v[12:13]
	v_or3_b32 v12, v12, s30, v1
	s_waitcnt lgkmcnt(0)
	v_lshlrev_b32_e32 v18, 16, v8
	v_and_b32_e32 v19, 0xffff0000, v8
	v_lshlrev_b32_e32 v8, 16, v9
	v_and_b32_e32 v9, 0xffff0000, v9
	v_lshlrev_b32_e32 v20, 16, v10
	v_and_b32_e32 v21, 0xffff0000, v10
	v_lshlrev_b32_e32 v10, 16, v11
	v_and_b32_e32 v11, 0xffff0000, v11
	v_lshlrev_b64 v[12:13], 1, v[12:13]
	v_lshl_add_u64 v[16:17], s[12:13], 0, v[12:13]
	v_lshl_add_u64 v[12:13], s[2:3], 0, v[12:13]
	s_waitcnt vmcnt(0)
	v_lshlrev_b32_e32 v22, 16, v4
	v_and_b32_e32 v23, 0xffff0000, v4
	v_lshlrev_b32_e32 v4, 16, v5
	v_and_b32_e32 v5, 0xffff0000, v5
	v_lshlrev_b32_e32 v24, 16, v6
	v_and_b32_e32 v25, 0xffff0000, v6
	v_lshlrev_b32_e32 v6, 16, v7
	v_and_b32_e32 v7, 0xffff0000, v7
	v_pk_add_f32 v[18:19], v[18:19], v[22:23]
	v_pk_add_f32 v[8:9], v[8:9], v[4:5]
	v_pk_add_f32 v[20:21], v[20:21], v[24:25]
	v_pk_add_f32 v[10:11], v[10:11], v[6:7]
	v_cvt_pk_bf16_f32 v4, v18, v19
	v_cvt_pk_bf16_f32 v5, v8, v9
	v_cvt_pk_bf16_f32 v6, v20, v21
	v_cvt_pk_bf16_f32 v7, v10, v11
	global_store_dwordx4 v[14:15], v[4:7], off
	global_load_dwordx4 v[4:7], v[16:17], off
	v_mad_u64_u32 v[8:9], s[34:35], v3, s25, v[0:1]
	v_ashrrev_i32_e32 v24, 4, v2
	ds_read_b128 v[8:11], v8
	v_add_u32_e32 v2, s29, v24
	v_ashrrev_i32_e32 v3, 31, v2
	v_lshlrev_b64 v[2:3], 10, v[2:3]
	v_or3_b32 v2, v2, s30, v1
	v_lshlrev_b64 v[14:15], 1, v[2:3]
	s_waitcnt lgkmcnt(0)
	v_lshlrev_b32_e32 v2, 16, v8
	v_and_b32_e32 v3, 0xffff0000, v8
	v_lshlrev_b32_e32 v8, 16, v9
	v_and_b32_e32 v9, 0xffff0000, v9
	v_lshlrev_b32_e32 v18, 16, v10
	v_and_b32_e32 v19, 0xffff0000, v10
	v_lshlrev_b32_e32 v10, 16, v11
	v_and_b32_e32 v11, 0xffff0000, v11
	v_lshl_add_u64 v[16:17], s[12:13], 0, v[14:15]
	v_mad_u64_u32 v[0:1], s[30:31], v24, s25, v[0:1]
	s_waitcnt vmcnt(0)
	v_lshlrev_b32_e32 v20, 16, v4
	v_and_b32_e32 v21, 0xffff0000, v4
	v_lshlrev_b32_e32 v4, 16, v5
	v_and_b32_e32 v5, 0xffff0000, v5
	v_lshlrev_b32_e32 v22, 16, v6
	v_and_b32_e32 v23, 0xffff0000, v6
	v_lshlrev_b32_e32 v6, 16, v7
	v_and_b32_e32 v7, 0xffff0000, v7
	v_pk_add_f32 v[2:3], v[2:3], v[20:21]
	v_pk_add_f32 v[4:5], v[8:9], v[4:5]
	v_pk_add_f32 v[8:9], v[18:19], v[22:23]
	v_pk_add_f32 v[6:7], v[10:11], v[6:7]
	v_cvt_pk_bf16_f32 v2, v2, v3
	v_cvt_pk_bf16_f32 v3, v4, v5
	v_cvt_pk_bf16_f32 v4, v8, v9
	v_cvt_pk_bf16_f32 v5, v6, v7
	global_store_dwordx4 v[12:13], v[2:5], off
	global_load_dwordx4 v[2:5], v[16:17], off
	ds_read_b128 v[6:9], v0
	v_lshl_add_u64 v[10:11], s[2:3], 0, v[14:15]
	s_waitcnt lgkmcnt(0)
	v_lshlrev_b32_e32 v0, 16, v6
	v_and_b32_e32 v1, 0xffff0000, v6
	v_lshlrev_b32_e32 v6, 16, v7
	v_and_b32_e32 v7, 0xffff0000, v7
	v_lshlrev_b32_e32 v12, 16, v8
	v_and_b32_e32 v13, 0xffff0000, v8
	v_lshlrev_b32_e32 v8, 16, v9
	v_and_b32_e32 v9, 0xffff0000, v9
	s_waitcnt vmcnt(0)
	v_lshlrev_b32_e32 v14, 16, v2
	v_and_b32_e32 v15, 0xffff0000, v2
	v_lshlrev_b32_e32 v2, 16, v3
	v_and_b32_e32 v3, 0xffff0000, v3
	v_lshlrev_b32_e32 v16, 16, v4
	v_and_b32_e32 v17, 0xffff0000, v4
	v_lshlrev_b32_e32 v4, 16, v5
	v_and_b32_e32 v5, 0xffff0000, v5
	v_pk_add_f32 v[0:1], v[0:1], v[14:15]
	v_pk_add_f32 v[2:3], v[6:7], v[2:3]
	v_pk_add_f32 v[6:7], v[12:13], v[16:17]
	v_pk_add_f32 v[4:5], v[8:9], v[4:5]
	v_cvt_pk_bf16_f32 v0, v0, v1
	v_cvt_pk_bf16_f32 v1, v2, v3
	v_cvt_pk_bf16_f32 v2, v6, v7
	v_cvt_pk_bf16_f32 v3, v4, v5
	global_store_dwordx4 v[10:11], v[0:3], off
	s_cbranch_scc0 .LBB0_1094
	s_branch .LBB0_1091
